# speedup vs baseline: 1.0080x; 1.0080x over previous
; #define STAGE(P, GP, ktrel) do { const GAS char* _g = (GP) + (ktrel) * (BK * 2); \
;     __builtin_amdgcn_global_load_lds((const GAS unsigned*)(_g + so0), (unsigned*)((char*)(P) + tid_ * 16), 16, 0, 0); \
;     __builtin_amdgcn_global_load_lds((const GAS unsigned*)(_g + so1), (unsigned*)((char*)(P) + tid_ * 16 + 8192), 16, 0, 0); } while (0)
; #define WAIT_V(n) asm volatile("s_waitcnt vmcnt(" #n ")" ::: "memory")
; #define WAIT_L(n) asm volatile("s_waitcnt lgkmcnt(" #n ")" ::: "memory")
; #define BAR __builtin_amdgcn_s_barrier()
; #define SCHED __builtin_amdgcn_sched_barrier(0)
; #define LDA(dst, b, h) for (int m = 0; m < 4; ++m) for (int k = 0; k < 2; ++k) \
;     dst[m][k] = *reinterpret_cast<const bf16x8*>((char*)SA(b, h) + lds_byte(wr * 64 + m * 16 + fr, k * 32 + fq * 8))
; #define LDB(dst, b, h) for (int n = 0; n < 2; ++n) for (int k = 0; k < 2; ++k) \
;     dst[n][k] = *reinterpret_cast<const bf16x8*>((char*)SB(b, h) + lds_byte(wc * 32 + n * 16 + fr, k * 32 + fq * 8))
; #define MMA(ai, bj, At_, Bt_) do { __builtin_amdgcn_s_setprio(1); \
;     for (int m = 0; m < 4; ++m) for (int n = 0; n < 2; ++n) for (int k = 0; k < 2; ++k) \
;       acc[ai][bj][m][n] = __builtin_amdgcn_mfma_f32_16x16x32_bf16(At_[m][k], Bt_[n][k], acc[ai][bj][m][n], 0, 0, 0); \
;     __builtin_amdgcn_s_setprio(0); } while (0)
; template <int K, int LD = K>
; __device__ __forceinline__ void gemm_main(const GAS bf16* A, const GAS bf16* Bt, int brow, int bcol, f32x4 (&acc)[2][2][4][2]) {
;     ...
;     LDB(B0, 0, 0); SCHED; LDA(At, 0, 0); STAGE(SA(1, 1), pA1, 1);
;     WAIT_L(8); BAR; WAIT_L(0); MMA(0, 0, At, B0); BAR; SCHED;
;     LDB(B1, 0, 1); STAGE(SB(0, 0), pB0, 2);
;     BAR; WAIT_L(0); MMA(0, 1, At, B1); BAR;
;     LDA(At, 0, 1); STAGE(SA(0, 0), pA0, 2);
;     BAR; WAIT_L(0); MMA(1, 0, At, B0); BAR; SCHED;
;     STAGE(SB(0, 1), pB1, 2);
;     WAIT_V(6); BAR; MMA(1, 1, At, B1); BAR;
.LBB0_89:
	ds_read_b128 v[162:165], v144
	ds_read_b128 v[166:169], v144 offset:1024
	ds_read_b128 v[174:177], v144 offset:2048
	ds_read_b128 v[178:181], v144 offset:3072
	v_lshl_add_u64 v[230:231], s[14:15], 0, v[130:131]
	v_readfirstlane_b32 s24, v151
	v_lshl_add_u64 v[214:215], v[230:231], 0, s[8:9]
	s_mov_b32 m0, s24
	v_lshl_add_u64 v[232:233], s[14:15], 0, v[132:133]
	v_readfirstlane_b32 s24, v150
	ds_read_b128 v[182:185], v140
	ds_read_b128 v[186:189], v140 offset:1024
	ds_read_b128 v[190:193], v139
	ds_read_b128 v[194:197], v139 offset:1024
	ds_read_b128 v[198:201], v138
	ds_read_b128 v[202:205], v138 offset:1024
	ds_read_b128 v[206:209], v137
	ds_read_b128 v[210:213], v137 offset:1024
	global_load_lds_dwordx4 v[214:215], off
	v_lshl_add_u64 v[214:215], v[232:233], 0, s[8:9]
	s_mov_b32 m0, s24
	s_nop 0
	global_load_lds_dwordx4 v[214:215], off
	s_waitcnt lgkmcnt(8)
	s_barrier
	s_waitcnt lgkmcnt(0)
	s_setprio 1
	s_waitcnt lgkmcnt(0)
	v_mfma_f32_16x16x32_bf16 v[126:129], v[182:185], v[162:165], v[126:129]
	v_mfma_f32_16x16x32_bf16 v[122:125], v[182:185], v[174:177], v[122:125]
	v_mfma_f32_16x16x32_bf16 v[118:121], v[190:193], v[162:165], v[118:121]
	v_mfma_f32_16x16x32_bf16 v[114:117], v[190:193], v[174:177], v[114:117]
	v_mfma_f32_16x16x32_bf16 v[110:113], v[198:201], v[162:165], v[110:113]
	v_mfma_f32_16x16x32_bf16 v[106:109], v[198:201], v[174:177], v[106:109]
	v_mfma_f32_16x16x32_bf16 v[102:105], v[206:209], v[162:165], v[102:105]
	v_mfma_f32_16x16x32_bf16 v[98:101], v[206:209], v[174:177], v[98:101]
	v_mfma_f32_16x16x32_bf16 v[126:129], v[186:189], v[166:169], v[126:129]
	v_mfma_f32_16x16x32_bf16 v[122:125], v[186:189], v[178:181], v[122:125]
	v_mfma_f32_16x16x32_bf16 v[118:121], v[194:197], v[166:169], v[118:121]
	v_mfma_f32_16x16x32_bf16 v[114:117], v[194:197], v[178:181], v[114:117]
	v_mfma_f32_16x16x32_bf16 v[110:113], v[202:205], v[166:169], v[110:113]
	v_mfma_f32_16x16x32_bf16 v[106:109], v[202:205], v[178:181], v[106:109]
	v_mfma_f32_16x16x32_bf16 v[102:105], v[210:213], v[166:169], v[102:105]
	v_mfma_f32_16x16x32_bf16 v[98:101], v[210:213], v[178:181], v[98:101]
	s_setprio 0
	s_barrier
	v_lshl_add_u64 v[234:235], s[22:23], 0, v[130:131]
	v_readfirstlane_b32 s24, v146
	v_lshl_add_u64 v[236:237], v[234:235], 0, s[10:11]
	s_mov_b32 m0, s24
	ds_read_b128 v[214:217], v143
	ds_read_b128 v[218:221], v143 offset:1024
	ds_read_b128 v[222:225], v143 offset:2048
	ds_read_b128 v[226:229], v143 offset:3072
	global_load_lds_dwordx4 v[236:237], off
	v_lshl_add_u64 v[236:237], s[22:23], 0, v[132:133]
	v_readfirstlane_b32 s24, v157
	v_lshl_add_u64 v[238:239], v[236:237], 0, s[10:11]
	s_mov_b32 m0, s24
	s_add_u32 s22, s22, 0x100
	global_load_lds_dwordx4 v[238:239], off
	s_waitcnt vmcnt(10)
	s_barrier
	s_waitcnt lgkmcnt(0)
	s_addc_u32 s23, s23, 0
	s_setprio 1
	s_waitcnt lgkmcnt(0)
	v_mfma_f32_16x16x32_bf16 v[94:97], v[182:185], v[214:217], v[94:97]
	v_mfma_f32_16x16x32_bf16 v[90:93], v[182:185], v[222:225], v[90:93]
	v_mfma_f32_16x16x32_bf16 v[86:89], v[190:193], v[214:217], v[86:89]
	v_mfma_f32_16x16x32_bf16 v[82:85], v[190:193], v[222:225], v[82:85]
	v_mfma_f32_16x16x32_bf16 v[78:81], v[198:201], v[214:217], v[78:81]
	v_mfma_f32_16x16x32_bf16 v[74:77], v[198:201], v[222:225], v[74:77]
	v_mfma_f32_16x16x32_bf16 v[70:73], v[206:209], v[214:217], v[70:73]
	v_mfma_f32_16x16x32_bf16 v[66:69], v[206:209], v[222:225], v[66:69]
	v_mfma_f32_16x16x32_bf16 v[94:97], v[186:189], v[218:221], v[94:97]
	v_mfma_f32_16x16x32_bf16 v[90:93], v[186:189], v[226:229], v[90:93]
	v_mfma_f32_16x16x32_bf16 v[86:89], v[194:197], v[218:221], v[86:89]
	v_mfma_f32_16x16x32_bf16 v[82:85], v[194:197], v[226:229], v[82:85]
	v_mfma_f32_16x16x32_bf16 v[78:81], v[202:205], v[218:221], v[78:81]
	v_mfma_f32_16x16x32_bf16 v[74:77], v[202:205], v[226:229], v[74:77]
	v_mfma_f32_16x16x32_bf16 v[70:73], v[210:213], v[218:221], v[70:73]
	v_mfma_f32_16x16x32_bf16 v[66:69], v[210:213], v[226:229], v[66:69]
	s_setprio 0
	v_lshl_add_u64 v[238:239], s[20:21], 0, v[130:131]
	v_readfirstlane_b32 s24, v145
	v_lshl_add_u64 v[240:241], v[238:239], 0, s[10:11]
	s_mov_b32 m0, s24
	s_barrier
	ds_read_b128 v[182:185], v140 offset:16384
	ds_read_b128 v[186:189], v140 offset:17408
	ds_read_b128 v[190:193], v139 offset:16384
	ds_read_b128 v[194:197], v139 offset:17408
	ds_read_b128 v[198:201], v138 offset:16384
	ds_read_b128 v[202:205], v138 offset:17408
	ds_read_b128 v[206:209], v137 offset:16384
	ds_read_b128 v[210:213], v137 offset:17408
	global_load_lds_dwordx4 v[240:241], off
	v_lshl_add_u64 v[240:241], s[20:21], 0, v[132:133]
	v_readfirstlane_b32 s24, v152
	v_lshl_add_u64 v[242:243], v[240:241], 0, s[10:11]
	s_mov_b32 m0, s24
	s_add_u32 s20, s20, 0x100
	global_load_lds_dwordx4 v[242:243], off
	s_barrier
	s_waitcnt lgkmcnt(0)
	s_addc_u32 s21, s21, 0
	s_setprio 1
	s_waitcnt lgkmcnt(0)
	v_mfma_f32_16x16x32_bf16 v[62:65], v[182:185], v[162:165], v[62:65]
	v_mfma_f32_16x16x32_bf16 v[58:61], v[182:185], v[174:177], v[58:61]
	v_mfma_f32_16x16x32_bf16 v[54:57], v[190:193], v[162:165], v[54:57]
	v_mfma_f32_16x16x32_bf16 v[50:53], v[190:193], v[174:177], v[50:53]
	v_mfma_f32_16x16x32_bf16 v[46:49], v[198:201], v[162:165], v[46:49]
	v_mfma_f32_16x16x32_bf16 v[42:45], v[198:201], v[174:177], v[42:45]
	v_mfma_f32_16x16x32_bf16 v[38:41], v[206:209], v[162:165], v[38:41]
	v_mfma_f32_16x16x32_bf16 v[34:37], v[206:209], v[174:177], v[34:37]
	v_mfma_f32_16x16x32_bf16 v[62:65], v[186:189], v[166:169], v[62:65]
	v_mfma_f32_16x16x32_bf16 v[58:61], v[186:189], v[178:181], v[58:61]
	v_mfma_f32_16x16x32_bf16 v[54:57], v[194:197], v[166:169], v[54:57]
	v_mfma_f32_16x16x32_bf16 v[50:53], v[194:197], v[178:181], v[50:53]
	v_mfma_f32_16x16x32_bf16 v[46:49], v[202:205], v[166:169], v[46:49]
	v_mfma_f32_16x16x32_bf16 v[42:45], v[202:205], v[178:181], v[42:45]
	v_mfma_f32_16x16x32_bf16 v[38:41], v[210:213], v[166:169], v[38:41]
	v_mfma_f32_16x16x32_bf16 v[34:37], v[210:213], v[178:181], v[34:37]
	s_setprio 0
	s_barrier
; #define STAGE(P, GP, ktrel) do { const GAS char* _g = (GP) + (ktrel) * (BK * 2); \
;     __builtin_amdgcn_global_load_lds((const GAS unsigned*)(_g + so0), (unsigned*)((char*)(P) + tid_ * 16), 16, 0, 0); \
;     __builtin_amdgcn_global_load_lds((const GAS unsigned*)(_g + so1), (unsigned*)((char*)(P) + tid_ * 16 + 8192), 16, 0, 0); } while (0)
; #define WAIT_V(n) asm volatile("s_waitcnt vmcnt(" #n ")" ::: "memory")
; #define WAIT_L(n) asm volatile("s_waitcnt lgkmcnt(" #n ")" ::: "memory")
; #define BAR __builtin_amdgcn_s_barrier()
; #define SCHED __builtin_amdgcn_sched_barrier(0)
; #define LDA(dst, b, h) for (int m = 0; m < 4; ++m) for (int k = 0; k < 2; ++k) \
;     dst[m][k] = *reinterpret_cast<const bf16x8*>((char*)SA(b, h) + lds_byte(wr * 64 + m * 16 + fr, k * 32 + fq * 8))
; #define LDB(dst, b, h) for (int n = 0; n < 2; ++n) for (int k = 0; k < 2; ++k) \
;     dst[n][k] = *reinterpret_cast<const bf16x8*>((char*)SB(b, h) + lds_byte(wc * 32 + n * 16 + fr, k * 32 + fq * 8))
; #define MMA(ai, bj, At_, Bt_) do { __builtin_amdgcn_s_setprio(1); \
;     for (int m = 0; m < 4; ++m) for (int n = 0; n < 2; ++n) for (int k = 0; k < 2; ++k) \
;       acc[ai][bj][m][n] = __builtin_amdgcn_mfma_f32_16x16x32_bf16(At_[m][k], Bt_[n][k], acc[ai][bj][m][n], 0, 0, 0); \
;     __builtin_amdgcn_s_setprio(0); } while (0)
; template <int K, int LD = K>
; __device__ __forceinline__ void gemm_main(const GAS bf16* A, const GAS bf16* Bt, int brow, int bcol, f32x4 (&acc)[2][2][4][2]) {
;     ...
;     WAIT_V(6); BAR; MMA(1, 1, At, B1); BAR;
;     LDB(B0, 1, 0); SCHED; LDA(At, 1, 0); STAGE(SA(0, 1), pA1, 2);
;     WAIT_L(8); BAR; WAIT_L(0); MMA(0, 0, At, B0); BAR; SCHED;
;     LDB(B1, 1, 1); STAGE(SB(1, 0), pB0, 3);
;     BAR; WAIT_L(0); MMA(0, 1, At, B1); BAR;
;     LDA(At, 1, 1); STAGE(SA(1, 0), pA0, 3);
;     BAR; WAIT_L(0); MMA(1, 0, At, B0); BAR; SCHED;
;     STAGE(SB(1, 1), pB1, 3);
;     WAIT_V(6); BAR; MMA(1, 1, At, B1); BAR;
	v_lshl_add_u64 v[242:243], s[18:19], 0, v[130:131]
	v_readfirstlane_b32 s24, v147
	v_lshl_add_u64 v[162:163], v[242:243], 0, s[10:11]
	s_mov_b32 m0, s24
	v_lshl_add_u64 v[244:245], s[18:19], 0, v[132:133]
	v_readfirstlane_b32 s24, v158
	global_load_lds_dwordx4 v[162:163], off
	v_lshl_add_u64 v[162:163], v[244:245], 0, s[10:11]
	s_mov_b32 m0, s24
	s_add_u32 s18, s18, 0x100
	global_load_lds_dwordx4 v[162:163], off
	s_waitcnt vmcnt(8)
	s_addc_u32 s19, s19, 0
	s_barrier
	s_setprio 1
	v_mfma_f32_16x16x32_bf16 v[30:33], v[182:185], v[214:217], v[30:33]
	v_mfma_f32_16x16x32_bf16 v[26:29], v[182:185], v[222:225], v[26:29]
	v_mfma_f32_16x16x32_bf16 v[22:25], v[190:193], v[214:217], v[22:25]
	v_mfma_f32_16x16x32_bf16 v[18:21], v[190:193], v[222:225], v[18:21]
	v_mfma_f32_16x16x32_bf16 v[14:17], v[198:201], v[214:217], v[14:17]
	v_mfma_f32_16x16x32_bf16 v[10:13], v[198:201], v[222:225], v[10:13]
	v_mfma_f32_16x16x32_bf16 v[6:9], v[206:209], v[214:217], v[6:9]
	v_mfma_f32_16x16x32_bf16 v[2:5], v[206:209], v[222:225], v[2:5]
	v_mfma_f32_16x16x32_bf16 v[30:33], v[186:189], v[218:221], v[30:33]
	v_mfma_f32_16x16x32_bf16 v[26:29], v[186:189], v[226:229], v[26:29]
	v_mfma_f32_16x16x32_bf16 v[22:25], v[194:197], v[218:221], v[22:25]
	v_mfma_f32_16x16x32_bf16 v[18:21], v[194:197], v[226:229], v[18:21]
	v_mfma_f32_16x16x32_bf16 v[14:17], v[202:205], v[218:221], v[14:17]
	v_mfma_f32_16x16x32_bf16 v[10:13], v[202:205], v[226:229], v[10:13]
	v_mfma_f32_16x16x32_bf16 v[6:9], v[210:213], v[218:221], v[6:9]
	v_mfma_f32_16x16x32_bf16 v[2:5], v[210:213], v[226:229], v[2:5]
	s_setprio 0
	s_barrier
	ds_read_b128 v[162:165], v142
	ds_read_b128 v[166:169], v142 offset:1024
	ds_read_b128 v[174:177], v142 offset:2048
	ds_read_b128 v[178:181], v142 offset:3072
	v_readfirstlane_b32 s24, v153
	v_lshl_add_u64 v[214:215], v[230:231], 0, s[10:11]
	s_mov_b32 m0, s24
	v_readfirstlane_b32 s24, v154
	ds_read_b128 v[182:185], v140 offset:32768
	ds_read_b128 v[186:189], v140 offset:33792
	ds_read_b128 v[190:193], v139 offset:32768
	ds_read_b128 v[194:197], v139 offset:33792
	ds_read_b128 v[198:201], v138 offset:32768
	ds_read_b128 v[202:205], v138 offset:33792
	ds_read_b128 v[206:209], v137 offset:32768
	ds_read_b128 v[210:213], v137 offset:33792
	global_load_lds_dwordx4 v[214:215], off
	v_lshl_add_u64 v[214:215], v[232:233], 0, s[10:11]
	s_mov_b32 m0, s24
	s_add_u32 s14, s14, 0x100
	global_load_lds_dwordx4 v[214:215], off
	s_waitcnt lgkmcnt(8)
	s_barrier
	s_waitcnt lgkmcnt(0)
	s_addc_u32 s15, s15, 0
	s_setprio 1
	s_waitcnt lgkmcnt(0)
	v_mfma_f32_16x16x32_bf16 v[126:129], v[182:185], v[162:165], v[126:129]
	v_mfma_f32_16x16x32_bf16 v[122:125], v[182:185], v[174:177], v[122:125]
	v_mfma_f32_16x16x32_bf16 v[118:121], v[190:193], v[162:165], v[118:121]
	v_mfma_f32_16x16x32_bf16 v[114:117], v[190:193], v[174:177], v[114:117]
	v_mfma_f32_16x16x32_bf16 v[110:113], v[198:201], v[162:165], v[110:113]
	v_mfma_f32_16x16x32_bf16 v[106:109], v[198:201], v[174:177], v[106:109]
	v_mfma_f32_16x16x32_bf16 v[102:105], v[206:209], v[162:165], v[102:105]
	v_mfma_f32_16x16x32_bf16 v[98:101], v[206:209], v[174:177], v[98:101]
	v_mfma_f32_16x16x32_bf16 v[126:129], v[186:189], v[166:169], v[126:129]
	v_mfma_f32_16x16x32_bf16 v[122:125], v[186:189], v[178:181], v[122:125]
	v_mfma_f32_16x16x32_bf16 v[118:121], v[194:197], v[166:169], v[118:121]
	v_mfma_f32_16x16x32_bf16 v[114:117], v[194:197], v[178:181], v[114:117]
	v_mfma_f32_16x16x32_bf16 v[110:113], v[202:205], v[166:169], v[110:113]
	v_mfma_f32_16x16x32_bf16 v[106:109], v[202:205], v[178:181], v[106:109]
	v_mfma_f32_16x16x32_bf16 v[102:105], v[210:213], v[166:169], v[102:105]
	v_mfma_f32_16x16x32_bf16 v[98:101], v[210:213], v[178:181], v[98:101]
	s_setprio 0
	s_barrier
	v_readfirstlane_b32 s24, v148
	v_lshl_add_u64 v[230:231], v[234:235], 0, s[12:13]
	s_mov_b32 m0, s24
	v_readfirstlane_b32 s24, v159
	ds_read_b128 v[214:217], v141
	ds_read_b128 v[218:221], v141 offset:1024
	ds_read_b128 v[222:225], v141 offset:2048
	ds_read_b128 v[226:229], v141 offset:3072
	global_load_lds_dwordx4 v[230:231], off
	v_lshl_add_u64 v[230:231], v[236:237], 0, s[12:13]
	s_mov_b32 m0, s24
	s_nop 0
	global_load_lds_dwordx4 v[230:231], off
	s_waitcnt vmcnt(10)
	s_barrier
	s_waitcnt lgkmcnt(0)
	s_setprio 1
	s_waitcnt lgkmcnt(0)
	v_mfma_f32_16x16x32_bf16 v[94:97], v[182:185], v[214:217], v[94:97]
	v_mfma_f32_16x16x32_bf16 v[90:93], v[182:185], v[222:225], v[90:93]
	v_mfma_f32_16x16x32_bf16 v[86:89], v[190:193], v[214:217], v[86:89]
	v_mfma_f32_16x16x32_bf16 v[82:85], v[190:193], v[222:225], v[82:85]
	v_mfma_f32_16x16x32_bf16 v[78:81], v[198:201], v[214:217], v[78:81]
	v_mfma_f32_16x16x32_bf16 v[74:77], v[198:201], v[222:225], v[74:77]
	v_mfma_f32_16x16x32_bf16 v[70:73], v[206:209], v[214:217], v[70:73]
	v_mfma_f32_16x16x32_bf16 v[66:69], v[206:209], v[222:225], v[66:69]
	v_mfma_f32_16x16x32_bf16 v[94:97], v[186:189], v[218:221], v[94:97]
	v_mfma_f32_16x16x32_bf16 v[90:93], v[186:189], v[226:229], v[90:93]
	v_mfma_f32_16x16x32_bf16 v[86:89], v[194:197], v[218:221], v[86:89]
	v_mfma_f32_16x16x32_bf16 v[82:85], v[194:197], v[226:229], v[82:85]
	v_mfma_f32_16x16x32_bf16 v[78:81], v[202:205], v[218:221], v[78:81]
	v_mfma_f32_16x16x32_bf16 v[74:77], v[202:205], v[226:229], v[74:77]
	v_mfma_f32_16x16x32_bf16 v[70:73], v[210:213], v[218:221], v[70:73]
	v_mfma_f32_16x16x32_bf16 v[66:69], v[210:213], v[226:229], v[66:69]
	s_setprio 0
	v_readfirstlane_b32 s24, v155
	v_lshl_add_u64 v[230:231], v[238:239], 0, s[12:13]
	s_mov_b32 m0, s24
	v_readfirstlane_b32 s24, v156
	s_barrier
; #define STAGE(P, GP, ktrel) do { const GAS char* _g = (GP) + (ktrel) * (BK * 2); \
;     __builtin_amdgcn_global_load_lds((const GAS unsigned*)(_g + so0), (unsigned*)((char*)(P) + tid_ * 16), 16, 0, 0); \
;     __builtin_amdgcn_global_load_lds((const GAS unsigned*)(_g + so1), (unsigned*)((char*)(P) + tid_ * 16 + 8192), 16, 0, 0); } while (0)
; #define WAIT_V(n) asm volatile("s_waitcnt vmcnt(" #n ")" ::: "memory")
; #define WAIT_L(n) asm volatile("s_waitcnt lgkmcnt(" #n ")" ::: "memory")
; #define BAR __builtin_amdgcn_s_barrier()
; #define SCHED __builtin_amdgcn_sched_barrier(0)
; #define LDA(dst, b, h) for (int m = 0; m < 4; ++m) for (int k = 0; k < 2; ++k) \
;     dst[m][k] = *reinterpret_cast<const bf16x8*>((char*)SA(b, h) + lds_byte(wr * 64 + m * 16 + fr, k * 32 + fq * 8))
; #define LDB(dst, b, h) for (int n = 0; n < 2; ++n) for (int k = 0; k < 2; ++k) \
;     dst[n][k] = *reinterpret_cast<const bf16x8*>((char*)SB(b, h) + lds_byte(wc * 32 + n * 16 + fr, k * 32 + fq * 8))
; #define MMA(ai, bj, At_, Bt_) do { __builtin_amdgcn_s_setprio(1); \
;     for (int m = 0; m < 4; ++m) for (int n = 0; n < 2; ++n) for (int k = 0; k < 2; ++k) \
;       acc[ai][bj][m][n] = __builtin_amdgcn_mfma_f32_16x16x32_bf16(At_[m][k], Bt_[n][k], acc[ai][bj][m][n], 0, 0, 0); \
;     __builtin_amdgcn_s_setprio(0); } while (0)
; template <int K, int LD = K>
; __device__ __forceinline__ void gemm_main(const GAS bf16* A, const GAS bf16* Bt, int brow, int bcol, f32x4 (&acc)[2][2][4][2]) {
;     ...
;     LDA(At, 1, 1); STAGE(SA(1, 0), pA0, 3);
;     BAR; WAIT_L(0); MMA(1, 0, At, B0); BAR; SCHED;
;     STAGE(SB(1, 1), pB1, 3);
;     WAIT_V(6); BAR; MMA(1, 1, At, B1); BAR;
;     pA0 += 4 * BK; pA1 += 4 * BK; pB0 += 4 * BK; pB1 += 4 * BK;
;     asm volatile("" : "+s"(pA0), "+s"(pA1), "+s"(pB0), "+s"(pB1));
;   }
;   { LDB(B0, 0, 0); LDA(At, 0, 0); STAGE(SA(1, 1), pA1, 1);
;     BAR; WAIT_L(0); MMA(0, 0, At, B0); BAR;
;     LDB(B1, 0, 1); BAR; WAIT_L(0); MMA(0, 1, At, B1); BAR;
;     LDA(At, 0, 1); WAIT_V(4); BAR; WAIT_L(0); MMA(1, 0, At, B0); MMA(1, 1, At, B1); BAR; }
	ds_read_b128 v[182:185], v140 offset:49152
	ds_read_b128 v[186:189], v140 offset:50176
	ds_read_b128 v[190:193], v139 offset:49152
	ds_read_b128 v[194:197], v139 offset:50176
	ds_read_b128 v[198:201], v138 offset:49152
	ds_read_b128 v[202:205], v138 offset:50176
	ds_read_b128 v[206:209], v137 offset:49152
	ds_read_b128 v[210:213], v137 offset:50176
	global_load_lds_dwordx4 v[230:231], off
	v_lshl_add_u64 v[230:231], v[240:241], 0, s[12:13]
	s_mov_b32 m0, s24
	s_nop 0
	global_load_lds_dwordx4 v[230:231], off
	s_barrier
	s_waitcnt lgkmcnt(0)
	s_setprio 1
	s_waitcnt lgkmcnt(0)
	v_mfma_f32_16x16x32_bf16 v[62:65], v[182:185], v[162:165], v[62:65]
	v_mfma_f32_16x16x32_bf16 v[58:61], v[182:185], v[174:177], v[58:61]
	v_mfma_f32_16x16x32_bf16 v[54:57], v[190:193], v[162:165], v[54:57]
	v_mfma_f32_16x16x32_bf16 v[50:53], v[190:193], v[174:177], v[50:53]
	v_mfma_f32_16x16x32_bf16 v[46:49], v[198:201], v[162:165], v[46:49]
	v_mfma_f32_16x16x32_bf16 v[42:45], v[198:201], v[174:177], v[42:45]
	v_mfma_f32_16x16x32_bf16 v[38:41], v[206:209], v[162:165], v[38:41]
	v_mfma_f32_16x16x32_bf16 v[34:37], v[206:209], v[174:177], v[34:37]
	v_mfma_f32_16x16x32_bf16 v[62:65], v[186:189], v[166:169], v[62:65]
	v_mfma_f32_16x16x32_bf16 v[58:61], v[186:189], v[178:181], v[58:61]
	v_mfma_f32_16x16x32_bf16 v[54:57], v[194:197], v[166:169], v[54:57]
	v_mfma_f32_16x16x32_bf16 v[50:53], v[194:197], v[178:181], v[50:53]
	v_mfma_f32_16x16x32_bf16 v[46:49], v[202:205], v[166:169], v[46:49]
	v_mfma_f32_16x16x32_bf16 v[42:45], v[202:205], v[178:181], v[42:45]
	v_mfma_f32_16x16x32_bf16 v[38:41], v[210:213], v[166:169], v[38:41]
	v_mfma_f32_16x16x32_bf16 v[34:37], v[210:213], v[178:181], v[34:37]
	s_setprio 0
	s_barrier
	v_readfirstlane_b32 s24, v149
	v_lshl_add_u64 v[162:163], v[242:243], 0, s[12:13]
	s_mov_b32 m0, s24
	v_readfirstlane_b32 s24, v160
	global_load_lds_dwordx4 v[162:163], off
	v_lshl_add_u64 v[162:163], v[244:245], 0, s[12:13]
	s_mov_b32 m0, s24
	s_nop 0
	global_load_lds_dwordx4 v[162:163], off
	s_waitcnt vmcnt(8)
	s_barrier
	s_setprio 1
	v_mfma_f32_16x16x32_bf16 v[30:33], v[182:185], v[214:217], v[30:33]
	v_mfma_f32_16x16x32_bf16 v[26:29], v[182:185], v[222:225], v[26:29]
	v_mfma_f32_16x16x32_bf16 v[22:25], v[190:193], v[214:217], v[22:25]
	v_mfma_f32_16x16x32_bf16 v[18:21], v[190:193], v[222:225], v[18:21]
	v_mfma_f32_16x16x32_bf16 v[14:17], v[198:201], v[214:217], v[14:17]
	v_mfma_f32_16x16x32_bf16 v[10:13], v[198:201], v[222:225], v[10:13]
	v_mfma_f32_16x16x32_bf16 v[6:9], v[206:209], v[214:217], v[6:9]
	v_mfma_f32_16x16x32_bf16 v[2:5], v[206:209], v[222:225], v[2:5]
	v_mfma_f32_16x16x32_bf16 v[30:33], v[186:189], v[218:221], v[30:33]
	v_mfma_f32_16x16x32_bf16 v[26:29], v[186:189], v[226:229], v[26:29]
	v_mfma_f32_16x16x32_bf16 v[22:25], v[194:197], v[218:221], v[22:25]
	v_mfma_f32_16x16x32_bf16 v[18:21], v[194:197], v[226:229], v[18:21]
	v_mfma_f32_16x16x32_bf16 v[14:17], v[202:205], v[218:221], v[14:17]
	v_mfma_f32_16x16x32_bf16 v[10:13], v[202:205], v[226:229], v[10:13]
	v_mfma_f32_16x16x32_bf16 v[6:9], v[210:213], v[218:221], v[6:9]
	v_mfma_f32_16x16x32_bf16 v[2:5], v[210:213], v[226:229], v[2:5]
	s_setprio 0
	s_add_i32 s17, s17, 2
	s_cmp_lt_u32 s17, 12
	s_barrier
	s_cbranch_scc1 .LBB0_89
	ds_read_b128 v[146:149], v144
	ds_read_b128 v[152:155], v144 offset:1024
	ds_read_b128 v[156:159], v144 offset:2048
	ds_read_b128 v[160:163], v144 offset:3072
	ds_read_b128 v[164:167], v140
	ds_read_b128 v[174:177], v140 offset:1024
	ds_read_b128 v[178:181], v139
	ds_read_b128 v[182:185], v139 offset:1024
	ds_read_b128 v[186:189], v138
	ds_read_b128 v[190:193], v138 offset:1024
	ds_read_b128 v[194:197], v137
	ds_read_b128 v[198:201], v137 offset:1024
	v_lshl_add_u64 v[144:145], s[14:15], 0, v[130:131]
	v_readfirstlane_b32 s17, v151
	v_lshl_add_u64 v[144:145], v[144:145], 0, s[8:9]
	s_mov_b32 m0, s17
	v_lshl_add_u64 v[132:133], s[14:15], 0, v[132:133]
	v_readfirstlane_b32 s14, v150
	global_load_lds_dwordx4 v[144:145], off
	v_lshl_add_u64 v[132:133], v[132:133], 0, s[8:9]
	s_mov_b32 m0, s14
	s_nop 0
	global_load_lds_dwordx4 v[132:133], off
	s_barrier
	s_waitcnt lgkmcnt(0)
	s_setprio 1
	s_waitcnt lgkmcnt(0)
	v_mfma_f32_16x16x32_bf16 v[126:129], v[164:167], v[146:149], v[126:129]
	v_mfma_f32_16x16x32_bf16 v[122:125], v[164:167], v[156:159], v[122:125]
	v_mfma_f32_16x16x32_bf16 v[110:113], v[186:189], v[146:149], v[110:113]
	v_mfma_f32_16x16x32_bf16 v[106:109], v[186:189], v[156:159], v[106:109]
	v_mfma_f32_16x16x32_bf16 v[126:129], v[174:177], v[152:155], v[126:129]
	v_mfma_f32_16x16x32_bf16 v[122:125], v[174:177], v[160:163], v[122:125]
	v_mfma_f32_16x16x32_bf16 v[118:121], v[178:181], v[146:149], v[118:121]
	v_mfma_f32_16x16x32_bf16 v[114:117], v[178:181], v[156:159], v[114:117]
	v_mfma_f32_16x16x32_bf16 v[110:113], v[190:193], v[152:155], v[110:113]
	v_mfma_f32_16x16x32_bf16 v[106:109], v[190:193], v[160:163], v[106:109]
	v_mfma_f32_16x16x32_bf16 v[102:105], v[194:197], v[146:149], v[102:105]
	v_mfma_f32_16x16x32_bf16 v[98:101], v[194:197], v[156:159], v[98:101]
	v_mfma_f32_16x16x32_bf16 v[202:205], v[182:185], v[152:155], v[118:121]
	v_mfma_f32_16x16x32_bf16 v[206:209], v[182:185], v[160:163], v[114:117]
	v_mfma_f32_16x16x32_bf16 v[210:213], v[198:201], v[152:155], v[102:105]
	v_mfma_f32_16x16x32_bf16 v[214:217], v[198:201], v[160:163], v[98:101]
	s_setprio 0
	s_barrier
	s_nop 1
	ds_read_b128 v[98:101], v143
	ds_read_b128 v[102:105], v143 offset:1024
	ds_read_b128 v[114:117], v143 offset:2048
	ds_read_b128 v[118:121], v143 offset:3072
	s_waitcnt vmcnt(8)
	s_barrier
; #define WAIT_V(n) asm volatile("s_waitcnt vmcnt(" #n ")" ::: "memory")
; #define WAIT_L(n) asm volatile("s_waitcnt lgkmcnt(" #n ")" ::: "memory")
; #define BAR __builtin_amdgcn_s_barrier()
; #define LDA(dst, b, h) for (int m = 0; m < 4; ++m) for (int k = 0; k < 2; ++k) \
;     dst[m][k] = *reinterpret_cast<const bf16x8*>((char*)SA(b, h) + lds_byte(wr * 64 + m * 16 + fr, k * 32 + fq * 8))
; #define LDB(dst, b, h) for (int n = 0; n < 2; ++n) for (int k = 0; k < 2; ++k) \
;     dst[n][k] = *reinterpret_cast<const bf16x8*>((char*)SB(b, h) + lds_byte(wc * 32 + n * 16 + fr, k * 32 + fq * 8))
; #define MMA(ai, bj, At_, Bt_) do { __builtin_amdgcn_s_setprio(1); \
;     for (int m = 0; m < 4; ++m) for (int n = 0; n < 2; ++n) for (int k = 0; k < 2; ++k) \
;       acc[ai][bj][m][n] = __builtin_amdgcn_mfma_f32_16x16x32_bf16(At_[m][k], Bt_[n][k], acc[ai][bj][m][n], 0, 0, 0); \
;     __builtin_amdgcn_s_setprio(0); } while (0)
; template <int K, int LD = K>
; __device__ __forceinline__ void gemm_main(const GAS bf16* A, const GAS bf16* Bt, int brow, int bcol, f32x4 (&acc)[2][2][4][2]) {
;     ...
;     LDA(At, 0, 1); WAIT_V(4); BAR; WAIT_L(0); MMA(1, 0, At, B0); MMA(1, 1, At, B1); BAR; }
;   { LDB(B0, 1, 0); LDA(At, 1, 0); WAIT_V(2); BAR; WAIT_L(0); MMA(0, 0, At, B0); BAR;
	s_waitcnt lgkmcnt(0)
	s_setprio 1
	s_waitcnt lgkmcnt(0)
	v_mfma_f32_16x16x32_bf16 v[94:97], v[164:167], v[98:101], v[94:97]
	v_mfma_f32_16x16x32_bf16 v[90:93], v[164:167], v[114:117], v[90:93]
	v_mfma_f32_16x16x32_bf16 v[78:81], v[186:189], v[98:101], v[78:81]
	v_mfma_f32_16x16x32_bf16 v[74:77], v[186:189], v[114:117], v[74:77]
	v_mfma_f32_16x16x32_bf16 v[94:97], v[174:177], v[102:105], v[94:97]
	v_mfma_f32_16x16x32_bf16 v[90:93], v[174:177], v[118:121], v[90:93]
	v_mfma_f32_16x16x32_bf16 v[86:89], v[178:181], v[98:101], v[86:89]
	v_mfma_f32_16x16x32_bf16 v[82:85], v[178:181], v[114:117], v[82:85]
	v_mfma_f32_16x16x32_bf16 v[78:81], v[190:193], v[102:105], v[78:81]
	v_mfma_f32_16x16x32_bf16 v[74:77], v[190:193], v[118:121], v[74:77]
	v_mfma_f32_16x16x32_bf16 v[70:73], v[194:197], v[98:101], v[70:73]
	v_mfma_f32_16x16x32_bf16 v[66:69], v[194:197], v[114:117], v[66:69]
	v_mfma_f32_16x16x32_bf16 v[164:167], v[182:185], v[102:105], v[86:89]
	v_mfma_f32_16x16x32_bf16 v[174:177], v[182:185], v[118:121], v[82:85]
	v_mfma_f32_16x16x32_bf16 v[178:181], v[198:201], v[102:105], v[70:73]
	v_mfma_f32_16x16x32_bf16 v[182:185], v[198:201], v[118:121], v[66:69]
	s_setprio 0
	s_barrier
	s_nop 1
	ds_read_b128 v[66:69], v140 offset:16384
	ds_read_b128 v[70:73], v140 offset:17408
	ds_read_b128 v[82:85], v139 offset:16384
	ds_read_b128 v[86:89], v139 offset:17408
	ds_read_b128 v[186:189], v138 offset:16384
	ds_read_b128 v[190:193], v138 offset:17408
	ds_read_b128 v[194:197], v137 offset:16384
	ds_read_b128 v[198:201], v137 offset:17408
	s_waitcnt vmcnt(4)
	s_barrier
	s_waitcnt lgkmcnt(0)
	s_setprio 1
	s_waitcnt lgkmcnt(0)
	v_mfma_f32_16x16x32_bf16 v[62:65], v[66:69], v[146:149], v[62:65]
	v_mfma_f32_16x16x32_bf16 v[58:61], v[66:69], v[156:159], v[58:61]
	v_mfma_f32_16x16x32_bf16 v[46:49], v[186:189], v[146:149], v[46:49]
	v_mfma_f32_16x16x32_bf16 v[38:41], v[194:197], v[146:149], v[38:41]
	v_mfma_f32_16x16x32_bf16 v[62:65], v[70:73], v[152:155], v[62:65]
	v_mfma_f32_16x16x32_bf16 v[58:61], v[70:73], v[160:163], v[58:61]
	v_mfma_f32_16x16x32_bf16 v[54:57], v[82:85], v[146:149], v[54:57]
	v_mfma_f32_16x16x32_bf16 v[50:53], v[82:85], v[156:159], v[50:53]
	v_mfma_f32_16x16x32_bf16 v[46:49], v[190:193], v[152:155], v[46:49]
	v_mfma_f32_16x16x32_bf16 v[42:45], v[186:189], v[156:159], v[42:45]
	v_mfma_f32_16x16x32_bf16 v[38:41], v[198:201], v[152:155], v[38:41]
	v_mfma_f32_16x16x32_bf16 v[34:37], v[194:197], v[156:159], v[34:37]
	v_mfma_f32_16x16x32_bf16 v[218:221], v[86:89], v[152:155], v[54:57]
	v_mfma_f32_16x16x32_bf16 v[222:225], v[86:89], v[160:163], v[50:53]
	v_mfma_f32_16x16x32_bf16 v[226:229], v[190:193], v[160:163], v[42:45]
	v_mfma_f32_16x16x32_bf16 v[144:147], v[198:201], v[160:163], v[34:37]
	s_setprio 0
	s_setprio 1
	v_mfma_f32_16x16x32_bf16 v[30:33], v[66:69], v[98:101], v[30:33]
	v_mfma_f32_16x16x32_bf16 v[26:29], v[66:69], v[114:117], v[26:29]
	v_mfma_f32_16x16x32_bf16 v[14:17], v[186:189], v[98:101], v[14:17]
	v_mfma_f32_16x16x32_bf16 v[6:9], v[194:197], v[98:101], v[6:9]
	v_mfma_f32_16x16x32_bf16 v[30:33], v[70:73], v[102:105], v[30:33]
	v_mfma_f32_16x16x32_bf16 v[26:29], v[70:73], v[118:121], v[26:29]
	v_mfma_f32_16x16x32_bf16 v[22:25], v[82:85], v[98:101], v[22:25]
	v_mfma_f32_16x16x32_bf16 v[18:21], v[82:85], v[114:117], v[18:21]
	v_mfma_f32_16x16x32_bf16 v[14:17], v[190:193], v[102:105], v[14:17]
	v_mfma_f32_16x16x32_bf16 v[10:13], v[186:189], v[114:117], v[10:13]
	v_mfma_f32_16x16x32_bf16 v[6:9], v[198:201], v[102:105], v[6:9]
	v_mfma_f32_16x16x32_bf16 v[2:5], v[194:197], v[114:117], v[2:5]
	v_mfma_f32_16x16x32_bf16 v[148:151], v[86:89], v[102:105], v[22:25]
	v_mfma_f32_16x16x32_bf16 v[152:155], v[86:89], v[118:121], v[18:21]
	v_mfma_f32_16x16x32_bf16 v[156:159], v[190:193], v[118:121], v[10:13]
	v_mfma_f32_16x16x32_bf16 v[160:163], v[198:201], v[118:121], v[2:5]
	s_setprio 0
	s_barrier
	s_nop 1
	ds_read_b128 v[2:5], v142
	ds_read_b128 v[10:13], v142 offset:1024
	ds_read_b128 v[186:189], v142 offset:2048
	ds_read_b128 v[190:193], v142 offset:3072
	ds_read_b128 v[18:21], v140 offset:32768
	ds_read_b128 v[22:25], v140 offset:33792
	ds_read_b128 v[34:37], v139 offset:32768
	ds_read_b128 v[42:45], v139 offset:33792
	ds_read_b128 v[50:53], v138 offset:32768
	ds_read_b128 v[54:57], v138 offset:33792
	ds_read_b128 v[194:197], v137 offset:32768
	ds_read_b128 v[198:201], v137 offset:33792
	s_waitcnt vmcnt(2)
	s_barrier
; #define WAIT_V(n) asm volatile("s_waitcnt vmcnt(" #n ")" ::: "memory")
; #define WAIT_L(n) asm volatile("s_waitcnt lgkmcnt(" #n ")" ::: "memory")
; #define BAR __builtin_amdgcn_s_barrier()
; #define LDA(dst, b, h) for (int m = 0; m < 4; ++m) for (int k = 0; k < 2; ++k) \
;     dst[m][k] = *reinterpret_cast<const bf16x8*>((char*)SA(b, h) + lds_byte(wr * 64 + m * 16 + fr, k * 32 + fq * 8))
; #define LDB(dst, b, h) for (int n = 0; n < 2; ++n) for (int k = 0; k < 2; ++k) \
;     dst[n][k] = *reinterpret_cast<const bf16x8*>((char*)SB(b, h) + lds_byte(wc * 32 + n * 16 + fr, k * 32 + fq * 8))
; #define MMA(ai, bj, At_, Bt_) do { __builtin_amdgcn_s_setprio(1); \
;     for (int m = 0; m < 4; ++m) for (int n = 0; n < 2; ++n) for (int k = 0; k < 2; ++k) \
;       acc[ai][bj][m][n] = __builtin_amdgcn_mfma_f32_16x16x32_bf16(At_[m][k], Bt_[n][k], acc[ai][bj][m][n], 0, 0, 0); \
;     __builtin_amdgcn_s_setprio(0); } while (0)
; template <int K, int LD = K>
; __device__ __forceinline__ void gemm_main(const GAS bf16* A, const GAS bf16* Bt, int brow, int bcol, f32x4 (&acc)[2][2][4][2]) {
;     ...
;   { LDB(B0, 1, 0); LDA(At, 1, 0); WAIT_V(2); BAR; WAIT_L(0); MMA(0, 0, At, B0); BAR;
;     LDB(B1, 1, 1); WAIT_V(0); BAR; WAIT_L(0); MMA(0, 1, At, B1); BAR;
;     LDA(At, 1, 1); BAR; WAIT_L(0); MMA(1, 0, At, B0); MMA(1, 1, At, B1); BAR; }
;   if (wr == 0) BAR;
	s_waitcnt lgkmcnt(0)
	s_setprio 1
	s_waitcnt lgkmcnt(0)
	v_mfma_f32_16x16x32_bf16 v[66:69], v[18:21], v[2:5], v[126:129]
	v_mfma_f32_16x16x32_bf16 v[118:121], v[22:25], v[10:13], v[66:69]
	v_mfma_f32_16x16x32_bf16 v[66:69], v[18:21], v[186:189], v[122:125]
	v_mfma_f32_16x16x32_bf16 v[114:117], v[22:25], v[190:193], v[66:69]
	v_mfma_f32_16x16x32_bf16 v[66:69], v[34:37], v[2:5], v[202:205]
	v_mfma_f32_16x16x32_bf16 v[102:105], v[42:45], v[10:13], v[66:69]
	v_mfma_f32_16x16x32_bf16 v[66:69], v[34:37], v[186:189], v[206:209]
	v_mfma_f32_16x16x32_bf16 v[98:101], v[42:45], v[190:193], v[66:69]
	v_mfma_f32_16x16x32_bf16 v[66:69], v[50:53], v[2:5], v[110:113]
	v_mfma_f32_16x16x32_bf16 v[86:89], v[54:57], v[10:13], v[66:69]
	v_mfma_f32_16x16x32_bf16 v[66:69], v[50:53], v[186:189], v[106:109]
	v_mfma_f32_16x16x32_bf16 v[82:85], v[54:57], v[190:193], v[66:69]
	v_mfma_f32_16x16x32_bf16 v[66:69], v[194:197], v[2:5], v[210:213]
	v_mfma_f32_16x16x32_bf16 v[70:73], v[198:201], v[10:13], v[66:69]
	v_mfma_f32_16x16x32_bf16 v[66:69], v[194:197], v[186:189], v[214:217]
	v_mfma_f32_16x16x32_bf16 v[66:69], v[198:201], v[190:193], v[66:69]
	s_setprio 0
	s_barrier
	ds_read_b128 v[202:205], v141
	ds_read_b128 v[206:209], v141 offset:1024
	ds_read_b128 v[210:213], v141 offset:2048
	ds_read_b128 v[214:217], v141 offset:3072
	s_waitcnt vmcnt(0)
	s_barrier
	s_waitcnt lgkmcnt(0)
	s_setprio 1
	s_waitcnt lgkmcnt(0)
	v_mfma_f32_16x16x32_bf16 v[94:97], v[18:21], v[202:205], v[94:97]
	v_mfma_f32_16x16x32_bf16 v[18:21], v[18:21], v[210:213], v[90:93]
	v_mfma_f32_16x16x32_bf16 v[122:125], v[22:25], v[214:217], v[18:21]
	v_mfma_f32_16x16x32_bf16 v[18:21], v[34:37], v[202:205], v[164:167]
	v_mfma_f32_16x16x32_bf16 v[110:113], v[42:45], v[206:209], v[18:21]
	v_mfma_f32_16x16x32_bf16 v[18:21], v[34:37], v[210:213], v[174:177]
	v_mfma_f32_16x16x32_bf16 v[106:109], v[42:45], v[214:217], v[18:21]
	v_mfma_f32_16x16x32_bf16 v[18:21], v[50:53], v[202:205], v[78:81]
	v_mfma_f32_16x16x32_bf16 v[126:129], v[22:25], v[206:209], v[94:97]
	v_mfma_f32_16x16x32_bf16 v[94:97], v[54:57], v[206:209], v[18:21]
	v_mfma_f32_16x16x32_bf16 v[18:21], v[50:53], v[210:213], v[74:77]
	v_mfma_f32_16x16x32_bf16 v[90:93], v[54:57], v[214:217], v[18:21]
	v_mfma_f32_16x16x32_bf16 v[18:21], v[194:197], v[202:205], v[178:181]
	v_mfma_f32_16x16x32_bf16 v[78:81], v[198:201], v[206:209], v[18:21]
	v_mfma_f32_16x16x32_bf16 v[18:21], v[194:197], v[210:213], v[182:185]
	v_mfma_f32_16x16x32_bf16 v[74:77], v[198:201], v[214:217], v[18:21]
	s_setprio 0
	s_barrier
	ds_read_b128 v[164:167], v140 offset:49152
	ds_read_b128 v[140:143], v140 offset:50176
	ds_read_b128 v[174:177], v139 offset:49152
	ds_read_b128 v[178:181], v139 offset:50176
	ds_read_b128 v[182:185], v138 offset:49152
	ds_read_b128 v[194:197], v138 offset:50176
	ds_read_b128 v[198:201], v137 offset:49152
	ds_read_b128 v[230:233], v137 offset:50176
	s_barrier
	s_waitcnt lgkmcnt(0)
	s_setprio 1
	s_waitcnt lgkmcnt(0)
	v_mfma_f32_16x16x32_bf16 v[18:21], v[164:167], v[2:5], v[62:65]
	v_mfma_f32_16x16x32_bf16 v[54:57], v[140:143], v[10:13], v[18:21]
	v_mfma_f32_16x16x32_bf16 v[18:21], v[164:167], v[186:189], v[58:61]
	v_mfma_f32_16x16x32_bf16 v[50:53], v[140:143], v[190:193], v[18:21]
	v_mfma_f32_16x16x32_bf16 v[18:21], v[174:177], v[2:5], v[218:221]
	v_mfma_f32_16x16x32_bf16 v[42:45], v[178:181], v[10:13], v[18:21]
	v_mfma_f32_16x16x32_bf16 v[18:21], v[174:177], v[186:189], v[222:225]
	v_mfma_f32_16x16x32_bf16 v[34:37], v[178:181], v[190:193], v[18:21]
	v_mfma_f32_16x16x32_bf16 v[18:21], v[182:185], v[2:5], v[46:49]
	v_mfma_f32_16x16x32_bf16 v[2:5], v[198:201], v[2:5], v[38:41]
	v_mfma_f32_16x16x32_bf16 v[22:25], v[194:197], v[10:13], v[18:21]
	v_mfma_f32_16x16x32_bf16 v[18:21], v[182:185], v[186:189], v[226:229]
	v_mfma_f32_16x16x32_bf16 v[10:13], v[230:233], v[10:13], v[2:5]
	v_mfma_f32_16x16x32_bf16 v[2:5], v[198:201], v[186:189], v[144:147]
	v_mfma_f32_16x16x32_bf16 v[18:21], v[194:197], v[190:193], v[18:21]
	v_mfma_f32_16x16x32_bf16 v[2:5], v[230:233], v[190:193], v[2:5]
	s_setprio 0
	s_setprio 1
	v_mfma_f32_16x16x32_bf16 v[26:29], v[164:167], v[210:213], v[26:29]
	v_mfma_f32_16x16x32_bf16 v[30:33], v[164:167], v[202:205], v[30:33]
	v_mfma_f32_16x16x32_bf16 v[58:61], v[140:143], v[214:217], v[26:29]
	v_mfma_f32_16x16x32_bf16 v[26:29], v[174:177], v[202:205], v[148:151]
	v_mfma_f32_16x16x32_bf16 v[14:17], v[182:185], v[202:205], v[14:17]
	v_mfma_f32_16x16x32_bf16 v[62:65], v[140:143], v[206:209], v[30:33]
	v_mfma_f32_16x16x32_bf16 v[46:49], v[178:181], v[206:209], v[26:29]
	v_mfma_f32_16x16x32_bf16 v[26:29], v[174:177], v[210:213], v[152:155]
	v_mfma_f32_16x16x32_bf16 v[30:33], v[194:197], v[206:209], v[14:17]
	v_mfma_f32_16x16x32_bf16 v[14:17], v[182:185], v[210:213], v[156:159]
	v_mfma_f32_16x16x32_bf16 v[6:9], v[198:201], v[202:205], v[6:9]
	v_mfma_f32_16x16x32_bf16 v[38:41], v[178:181], v[214:217], v[26:29]
	v_mfma_f32_16x16x32_bf16 v[26:29], v[194:197], v[214:217], v[14:17]
	v_mfma_f32_16x16x32_bf16 v[14:17], v[230:233], v[206:209], v[6:9]
	v_mfma_f32_16x16x32_bf16 v[6:9], v[198:201], v[210:213], v[160:163]
	v_mfma_f32_16x16x32_bf16 v[6:9], v[230:233], v[214:217], v[6:9]
	s_setprio 0
	v_cmp_gt_u32_e32 vcc, s34, v136
	s_barrier
	s_and_saveexec_b64 s[14:15], vcc
	s_cbranch_execz .LBB0_92
	s_barrier

; #define STAGE(P, GP, ktrel) do { const GAS char* _g = (GP) + (ktrel) * (BK * 2); \
;     __builtin_amdgcn_global_load_lds((const GAS unsigned*)(_g + so0), (unsigned*)((char*)(P) + tid_ * 16), 16, 0, 0); \
;     __builtin_amdgcn_global_load_lds((const GAS unsigned*)(_g + so1), (unsigned*)((char*)(P) + tid_ * 16 + 8192), 16, 0, 0); } while (0)
; #define WAIT_V(n) asm volatile("s_waitcnt vmcnt(" #n ")" ::: "memory")
; #define WAIT_L(n) asm volatile("s_waitcnt lgkmcnt(" #n ")" ::: "memory")
; #define BAR __builtin_amdgcn_s_barrier()
; #define SCHED __builtin_amdgcn_sched_barrier(0)
; #define LDA(dst, b, h) for (int m = 0; m < 4; ++m) for (int k = 0; k < 2; ++k) \
;     dst[m][k] = *reinterpret_cast<const bf16x8*>((char*)SA(b, h) + lds_byte(wr * 64 + m * 16 + fr, k * 32 + fq * 8))
; #define LDB(dst, b, h) for (int n = 0; n < 2; ++n) for (int k = 0; k < 2; ++k) \
;     dst[n][k] = *reinterpret_cast<const bf16x8*>((char*)SB(b, h) + lds_byte(wc * 32 + n * 16 + fr, k * 32 + fq * 8))
; #define MMA(ai, bj, At_, Bt_) do { __builtin_amdgcn_s_setprio(1); \
;     for (int m = 0; m < 4; ++m) for (int n = 0; n < 2; ++n) for (int k = 0; k < 2; ++k) \
;       acc[ai][bj][m][n] = __builtin_amdgcn_mfma_f32_16x16x32_bf16(At_[m][k], Bt_[n][k], acc[ai][bj][m][n], 0, 0, 0); \
;     __builtin_amdgcn_s_setprio(0); } while (0)
; template <int K, int LD = K>
; __device__ __forceinline__ void gemm_main(const GAS bf16* A, const GAS bf16* Bt, int brow, int bcol, f32x4 (&acc)[2][2][4][2]) {
;     ...
;     LDB(B0, 0, 0); SCHED; LDA(At, 0, 0); STAGE(SA(1, 1), pA1, 1);
;     WAIT_L(8); BAR; WAIT_L(0); MMA(0, 0, At, B0); BAR; SCHED;
;     LDB(B1, 0, 1); STAGE(SB(0, 0), pB0, 2);
;     BAR; WAIT_L(0); MMA(0, 1, At, B1); BAR;
;     LDA(At, 0, 1); STAGE(SA(0, 0), pA0, 2);
;     BAR; WAIT_L(0); MMA(1, 0, At, B0); BAR; SCHED;
;     STAGE(SB(0, 1), pB1, 2);
;     WAIT_V(6); BAR; MMA(1, 1, At, B1); BAR;
.LBB0_230:
	ds_read_b128 v[160:163], v144
	ds_read_b128 v[164:167], v144 offset:1024
	ds_read_b128 v[174:177], v144 offset:2048
	ds_read_b128 v[178:181], v144 offset:3072
	v_lshl_add_u64 v[168:169], s[12:13], 0, v[130:131]
	v_readfirstlane_b32 s23, v143
	v_lshl_add_u64 v[214:215], v[168:169], 0, s[6:7]
	s_mov_b32 m0, s23
	v_lshl_add_u64 v[230:231], s[12:13], 0, v[132:133]
	v_readfirstlane_b32 s23, v142
	ds_read_b128 v[182:185], v138
	ds_read_b128 v[186:189], v138 offset:1024
	ds_read_b128 v[190:193], v137
	ds_read_b128 v[194:197], v137 offset:1024
	ds_read_b128 v[198:201], v136
	ds_read_b128 v[202:205], v136 offset:1024
	ds_read_b128 v[206:209], v135
	ds_read_b128 v[210:213], v135 offset:1024
	global_load_lds_dwordx4 v[214:215], off
	v_lshl_add_u64 v[214:215], v[230:231], 0, s[6:7]
	s_mov_b32 m0, s23
	s_nop 0
	global_load_lds_dwordx4 v[214:215], off
	s_waitcnt lgkmcnt(8)
	s_barrier
	s_waitcnt lgkmcnt(0)
	s_setprio 1
	s_waitcnt lgkmcnt(0)
	v_mfma_f32_16x16x32_bf16 v[126:129], v[182:185], v[160:163], v[126:129]
	v_mfma_f32_16x16x32_bf16 v[122:125], v[182:185], v[174:177], v[122:125]
	v_mfma_f32_16x16x32_bf16 v[118:121], v[190:193], v[160:163], v[118:121]
	v_mfma_f32_16x16x32_bf16 v[114:117], v[190:193], v[174:177], v[114:117]
	v_mfma_f32_16x16x32_bf16 v[110:113], v[198:201], v[160:163], v[110:113]
	v_mfma_f32_16x16x32_bf16 v[106:109], v[198:201], v[174:177], v[106:109]
	v_mfma_f32_16x16x32_bf16 v[102:105], v[206:209], v[160:163], v[102:105]
	v_mfma_f32_16x16x32_bf16 v[98:101], v[206:209], v[174:177], v[98:101]
	v_mfma_f32_16x16x32_bf16 v[126:129], v[186:189], v[164:167], v[126:129]
	v_mfma_f32_16x16x32_bf16 v[122:125], v[186:189], v[178:181], v[122:125]
	v_mfma_f32_16x16x32_bf16 v[118:121], v[194:197], v[164:167], v[118:121]
	v_mfma_f32_16x16x32_bf16 v[114:117], v[194:197], v[178:181], v[114:117]
	v_mfma_f32_16x16x32_bf16 v[110:113], v[202:205], v[164:167], v[110:113]
	v_mfma_f32_16x16x32_bf16 v[106:109], v[202:205], v[178:181], v[106:109]
	v_mfma_f32_16x16x32_bf16 v[102:105], v[210:213], v[164:167], v[102:105]
	v_mfma_f32_16x16x32_bf16 v[98:101], v[210:213], v[178:181], v[98:101]
	s_setprio 0
	s_barrier
	v_lshl_add_u64 v[232:233], s[20:21], 0, v[130:131]
	v_readfirstlane_b32 s23, v151
	v_lshl_add_u64 v[234:235], v[232:233], 0, s[8:9]
	s_mov_b32 m0, s23
	ds_read_b128 v[214:217], v141
	ds_read_b128 v[218:221], v141 offset:1024
	ds_read_b128 v[222:225], v141 offset:2048
	ds_read_b128 v[226:229], v141 offset:3072
	global_load_lds_dwordx4 v[234:235], off
	v_lshl_add_u64 v[234:235], s[20:21], 0, v[132:133]
	v_readfirstlane_b32 s23, v152
	v_lshl_add_u64 v[236:237], v[234:235], 0, s[8:9]
	s_mov_b32 m0, s23
	s_add_u32 s20, s20, 0x100
	global_load_lds_dwordx4 v[236:237], off
	s_waitcnt vmcnt(10)
	s_barrier
	s_waitcnt lgkmcnt(0)
	s_addc_u32 s21, s21, 0
	s_setprio 1
	s_waitcnt lgkmcnt(0)
	v_mfma_f32_16x16x32_bf16 v[94:97], v[182:185], v[214:217], v[94:97]
	v_mfma_f32_16x16x32_bf16 v[90:93], v[182:185], v[222:225], v[90:93]
	v_mfma_f32_16x16x32_bf16 v[86:89], v[190:193], v[214:217], v[86:89]
	v_mfma_f32_16x16x32_bf16 v[82:85], v[190:193], v[222:225], v[82:85]
	v_mfma_f32_16x16x32_bf16 v[78:81], v[198:201], v[214:217], v[78:81]
	v_mfma_f32_16x16x32_bf16 v[74:77], v[198:201], v[222:225], v[74:77]
	v_mfma_f32_16x16x32_bf16 v[70:73], v[206:209], v[214:217], v[70:73]
	v_mfma_f32_16x16x32_bf16 v[66:69], v[206:209], v[222:225], v[66:69]
	v_mfma_f32_16x16x32_bf16 v[94:97], v[186:189], v[218:221], v[94:97]
	v_mfma_f32_16x16x32_bf16 v[90:93], v[186:189], v[226:229], v[90:93]
	v_mfma_f32_16x16x32_bf16 v[86:89], v[194:197], v[218:221], v[86:89]
	v_mfma_f32_16x16x32_bf16 v[82:85], v[194:197], v[226:229], v[82:85]
	v_mfma_f32_16x16x32_bf16 v[78:81], v[202:205], v[218:221], v[78:81]
	v_mfma_f32_16x16x32_bf16 v[74:77], v[202:205], v[226:229], v[74:77]
	v_mfma_f32_16x16x32_bf16 v[70:73], v[210:213], v[218:221], v[70:73]
	v_mfma_f32_16x16x32_bf16 v[66:69], v[210:213], v[226:229], v[66:69]
	s_setprio 0
	v_lshl_add_u64 v[236:237], s[18:19], 0, v[130:131]
	v_readfirstlane_b32 s23, v145
	v_lshl_add_u64 v[238:239], v[236:237], 0, s[8:9]
	s_mov_b32 m0, s23
	s_barrier
	ds_read_b128 v[182:185], v138 offset:16384
	ds_read_b128 v[186:189], v138 offset:17408
	ds_read_b128 v[190:193], v137 offset:16384
	ds_read_b128 v[194:197], v137 offset:17408
	ds_read_b128 v[198:201], v136 offset:16384
	ds_read_b128 v[202:205], v136 offset:17408
	ds_read_b128 v[206:209], v135 offset:16384
	ds_read_b128 v[210:213], v135 offset:17408
	global_load_lds_dwordx4 v[238:239], off
	v_lshl_add_u64 v[238:239], s[18:19], 0, v[132:133]
	v_readfirstlane_b32 s23, v146
	v_lshl_add_u64 v[240:241], v[238:239], 0, s[8:9]
	s_mov_b32 m0, s23
	s_add_u32 s18, s18, 0x100
	global_load_lds_dwordx4 v[240:241], off
	s_barrier
	s_waitcnt lgkmcnt(0)
	s_addc_u32 s19, s19, 0
	s_setprio 1
	s_waitcnt lgkmcnt(0)
	v_mfma_f32_16x16x32_bf16 v[62:65], v[182:185], v[160:163], v[62:65]
	v_mfma_f32_16x16x32_bf16 v[58:61], v[182:185], v[174:177], v[58:61]
	v_mfma_f32_16x16x32_bf16 v[54:57], v[190:193], v[160:163], v[54:57]
	v_mfma_f32_16x16x32_bf16 v[50:53], v[190:193], v[174:177], v[50:53]
	v_mfma_f32_16x16x32_bf16 v[46:49], v[198:201], v[160:163], v[46:49]
	v_mfma_f32_16x16x32_bf16 v[42:45], v[198:201], v[174:177], v[42:45]
	v_mfma_f32_16x16x32_bf16 v[38:41], v[206:209], v[160:163], v[38:41]
	v_mfma_f32_16x16x32_bf16 v[34:37], v[206:209], v[174:177], v[34:37]
	v_mfma_f32_16x16x32_bf16 v[62:65], v[186:189], v[164:167], v[62:65]
	v_mfma_f32_16x16x32_bf16 v[58:61], v[186:189], v[178:181], v[58:61]
	v_mfma_f32_16x16x32_bf16 v[54:57], v[194:197], v[164:167], v[54:57]
	v_mfma_f32_16x16x32_bf16 v[50:53], v[194:197], v[178:181], v[50:53]
	v_mfma_f32_16x16x32_bf16 v[46:49], v[202:205], v[164:167], v[46:49]
	v_mfma_f32_16x16x32_bf16 v[42:45], v[202:205], v[178:181], v[42:45]
	v_mfma_f32_16x16x32_bf16 v[38:41], v[210:213], v[164:167], v[38:41]
	v_mfma_f32_16x16x32_bf16 v[34:37], v[210:213], v[178:181], v[34:37]
	s_setprio 0
	s_barrier
; #define STAGE(P, GP, ktrel) do { const GAS char* _g = (GP) + (ktrel) * (BK * 2); \
;     __builtin_amdgcn_global_load_lds((const GAS unsigned*)(_g + so0), (unsigned*)((char*)(P) + tid_ * 16), 16, 0, 0); \
;     __builtin_amdgcn_global_load_lds((const GAS unsigned*)(_g + so1), (unsigned*)((char*)(P) + tid_ * 16 + 8192), 16, 0, 0); } while (0)
; #define WAIT_V(n) asm volatile("s_waitcnt vmcnt(" #n ")" ::: "memory")
; #define WAIT_L(n) asm volatile("s_waitcnt lgkmcnt(" #n ")" ::: "memory")
; #define BAR __builtin_amdgcn_s_barrier()
; #define SCHED __builtin_amdgcn_sched_barrier(0)
; #define LDA(dst, b, h) for (int m = 0; m < 4; ++m) for (int k = 0; k < 2; ++k) \
;     dst[m][k] = *reinterpret_cast<const bf16x8*>((char*)SA(b, h) + lds_byte(wr * 64 + m * 16 + fr, k * 32 + fq * 8))
; #define LDB(dst, b, h) for (int n = 0; n < 2; ++n) for (int k = 0; k < 2; ++k) \
;     dst[n][k] = *reinterpret_cast<const bf16x8*>((char*)SB(b, h) + lds_byte(wc * 32 + n * 16 + fr, k * 32 + fq * 8))
; #define MMA(ai, bj, At_, Bt_) do { __builtin_amdgcn_s_setprio(1); \
;     for (int m = 0; m < 4; ++m) for (int n = 0; n < 2; ++n) for (int k = 0; k < 2; ++k) \
;       acc[ai][bj][m][n] = __builtin_amdgcn_mfma_f32_16x16x32_bf16(At_[m][k], Bt_[n][k], acc[ai][bj][m][n], 0, 0, 0); \
;     __builtin_amdgcn_s_setprio(0); } while (0)
; template <int K, int LD = K>
; __device__ __forceinline__ void gemm_main(const GAS bf16* A, const GAS bf16* Bt, int brow, int bcol, f32x4 (&acc)[2][2][4][2]) {
;     ...
;     WAIT_V(6); BAR; MMA(1, 1, At, B1); BAR;
;     LDB(B0, 1, 0); SCHED; LDA(At, 1, 0); STAGE(SA(0, 1), pA1, 2);
;     WAIT_L(8); BAR; WAIT_L(0); MMA(0, 0, At, B0); BAR; SCHED;
;     LDB(B1, 1, 1); STAGE(SB(1, 0), pB0, 3);
;     BAR; WAIT_L(0); MMA(0, 1, At, B1); BAR;
;     LDA(At, 1, 1); STAGE(SA(1, 0), pA0, 3);
;     BAR; WAIT_L(0); MMA(1, 0, At, B0); BAR; SCHED;
;     STAGE(SB(1, 1), pB1, 3);
;     WAIT_V(6); BAR; MMA(1, 1, At, B1); BAR;
	v_lshl_add_u64 v[240:241], s[16:17], 0, v[130:131]
	v_readfirstlane_b32 s23, v153
	v_lshl_add_u64 v[160:161], v[240:241], 0, s[8:9]
	s_mov_b32 m0, s23
	v_lshl_add_u64 v[242:243], s[16:17], 0, v[132:133]
	v_readfirstlane_b32 s23, v155
	global_load_lds_dwordx4 v[160:161], off
	v_lshl_add_u64 v[160:161], v[242:243], 0, s[8:9]
	s_mov_b32 m0, s23
	s_add_u32 s16, s16, 0x100
	global_load_lds_dwordx4 v[160:161], off
	s_waitcnt vmcnt(8)
	s_addc_u32 s17, s17, 0
	s_barrier
	s_setprio 1
	v_mfma_f32_16x16x32_bf16 v[30:33], v[182:185], v[214:217], v[30:33]
	v_mfma_f32_16x16x32_bf16 v[26:29], v[182:185], v[222:225], v[26:29]
	v_mfma_f32_16x16x32_bf16 v[22:25], v[190:193], v[214:217], v[22:25]
	v_mfma_f32_16x16x32_bf16 v[18:21], v[190:193], v[222:225], v[18:21]
	v_mfma_f32_16x16x32_bf16 v[14:17], v[198:201], v[214:217], v[14:17]
	v_mfma_f32_16x16x32_bf16 v[10:13], v[198:201], v[222:225], v[10:13]
	v_mfma_f32_16x16x32_bf16 v[6:9], v[206:209], v[214:217], v[6:9]
	v_mfma_f32_16x16x32_bf16 v[2:5], v[206:209], v[222:225], v[2:5]
	v_mfma_f32_16x16x32_bf16 v[30:33], v[186:189], v[218:221], v[30:33]
	v_mfma_f32_16x16x32_bf16 v[26:29], v[186:189], v[226:229], v[26:29]
	v_mfma_f32_16x16x32_bf16 v[22:25], v[194:197], v[218:221], v[22:25]
	v_mfma_f32_16x16x32_bf16 v[18:21], v[194:197], v[226:229], v[18:21]
	v_mfma_f32_16x16x32_bf16 v[14:17], v[202:205], v[218:221], v[14:17]
	v_mfma_f32_16x16x32_bf16 v[10:13], v[202:205], v[226:229], v[10:13]
	v_mfma_f32_16x16x32_bf16 v[6:9], v[210:213], v[218:221], v[6:9]
	v_mfma_f32_16x16x32_bf16 v[2:5], v[210:213], v[226:229], v[2:5]
	s_setprio 0
	s_barrier
	ds_read_b128 v[160:163], v140
	ds_read_b128 v[164:167], v140 offset:1024
	ds_read_b128 v[174:177], v140 offset:2048
	ds_read_b128 v[178:181], v140 offset:3072
	v_readfirstlane_b32 s23, v147
	v_lshl_add_u64 v[168:169], v[168:169], 0, s[8:9]
	s_mov_b32 m0, s23
	v_readfirstlane_b32 s23, v148
	ds_read_b128 v[182:185], v138 offset:32768
	ds_read_b128 v[186:189], v138 offset:33792
	ds_read_b128 v[190:193], v137 offset:32768
	ds_read_b128 v[194:197], v137 offset:33792
	ds_read_b128 v[198:201], v136 offset:32768
	ds_read_b128 v[202:205], v136 offset:33792
	ds_read_b128 v[206:209], v135 offset:32768
	ds_read_b128 v[210:213], v135 offset:33792
	global_load_lds_dwordx4 v[168:169], off
	v_lshl_add_u64 v[168:169], v[230:231], 0, s[8:9]
	s_mov_b32 m0, s23
	s_add_u32 s12, s12, 0x100
	global_load_lds_dwordx4 v[168:169], off
	s_waitcnt lgkmcnt(8)
	s_barrier
	s_waitcnt lgkmcnt(0)
	s_addc_u32 s13, s13, 0
	s_setprio 1
	s_waitcnt lgkmcnt(0)
	v_mfma_f32_16x16x32_bf16 v[126:129], v[182:185], v[160:163], v[126:129]
	v_mfma_f32_16x16x32_bf16 v[122:125], v[182:185], v[174:177], v[122:125]
	v_mfma_f32_16x16x32_bf16 v[118:121], v[190:193], v[160:163], v[118:121]
	v_mfma_f32_16x16x32_bf16 v[114:117], v[190:193], v[174:177], v[114:117]
	v_mfma_f32_16x16x32_bf16 v[110:113], v[198:201], v[160:163], v[110:113]
	v_mfma_f32_16x16x32_bf16 v[106:109], v[198:201], v[174:177], v[106:109]
	v_mfma_f32_16x16x32_bf16 v[102:105], v[206:209], v[160:163], v[102:105]
	v_mfma_f32_16x16x32_bf16 v[98:101], v[206:209], v[174:177], v[98:101]
	v_mfma_f32_16x16x32_bf16 v[126:129], v[186:189], v[164:167], v[126:129]
	v_mfma_f32_16x16x32_bf16 v[122:125], v[186:189], v[178:181], v[122:125]
	v_mfma_f32_16x16x32_bf16 v[118:121], v[194:197], v[164:167], v[118:121]
	v_mfma_f32_16x16x32_bf16 v[114:117], v[194:197], v[178:181], v[114:117]
	v_mfma_f32_16x16x32_bf16 v[110:113], v[202:205], v[164:167], v[110:113]
	v_mfma_f32_16x16x32_bf16 v[106:109], v[202:205], v[178:181], v[106:109]
	v_mfma_f32_16x16x32_bf16 v[102:105], v[210:213], v[164:167], v[102:105]
	v_mfma_f32_16x16x32_bf16 v[98:101], v[210:213], v[178:181], v[98:101]
	s_setprio 0
	s_barrier
	v_readfirstlane_b32 s23, v156
	v_lshl_add_u64 v[168:169], v[232:233], 0, s[10:11]
	s_mov_b32 m0, s23
	v_readfirstlane_b32 s23, v157
	ds_read_b128 v[214:217], v139
	ds_read_b128 v[218:221], v139 offset:1024
	ds_read_b128 v[222:225], v139 offset:2048
	ds_read_b128 v[226:229], v139 offset:3072
	global_load_lds_dwordx4 v[168:169], off
	v_lshl_add_u64 v[168:169], v[234:235], 0, s[10:11]
	s_mov_b32 m0, s23
	s_nop 0
	global_load_lds_dwordx4 v[168:169], off
	s_waitcnt vmcnt(10)
	s_barrier
	s_waitcnt lgkmcnt(0)
	s_setprio 1
	s_waitcnt lgkmcnt(0)
	v_mfma_f32_16x16x32_bf16 v[94:97], v[182:185], v[214:217], v[94:97]
	v_mfma_f32_16x16x32_bf16 v[90:93], v[182:185], v[222:225], v[90:93]
	v_mfma_f32_16x16x32_bf16 v[86:89], v[190:193], v[214:217], v[86:89]
	v_mfma_f32_16x16x32_bf16 v[82:85], v[190:193], v[222:225], v[82:85]
	v_mfma_f32_16x16x32_bf16 v[78:81], v[198:201], v[214:217], v[78:81]
	v_mfma_f32_16x16x32_bf16 v[74:77], v[198:201], v[222:225], v[74:77]
	v_mfma_f32_16x16x32_bf16 v[70:73], v[206:209], v[214:217], v[70:73]
	v_mfma_f32_16x16x32_bf16 v[66:69], v[206:209], v[222:225], v[66:69]
	v_mfma_f32_16x16x32_bf16 v[94:97], v[186:189], v[218:221], v[94:97]
	v_mfma_f32_16x16x32_bf16 v[90:93], v[186:189], v[226:229], v[90:93]
	v_mfma_f32_16x16x32_bf16 v[86:89], v[194:197], v[218:221], v[86:89]
	v_mfma_f32_16x16x32_bf16 v[82:85], v[194:197], v[226:229], v[82:85]
	v_mfma_f32_16x16x32_bf16 v[78:81], v[202:205], v[218:221], v[78:81]
	v_mfma_f32_16x16x32_bf16 v[74:77], v[202:205], v[226:229], v[74:77]
	v_mfma_f32_16x16x32_bf16 v[70:73], v[210:213], v[218:221], v[70:73]
	v_mfma_f32_16x16x32_bf16 v[66:69], v[210:213], v[226:229], v[66:69]
	s_setprio 0
	v_readfirstlane_b32 s23, v149
	v_lshl_add_u64 v[168:169], v[236:237], 0, s[10:11]
	s_mov_b32 m0, s23
	v_readfirstlane_b32 s23, v150
	s_barrier
; #define STAGE(P, GP, ktrel) do { const GAS char* _g = (GP) + (ktrel) * (BK * 2); \
;     __builtin_amdgcn_global_load_lds((const GAS unsigned*)(_g + so0), (unsigned*)((char*)(P) + tid_ * 16), 16, 0, 0); \
;     __builtin_amdgcn_global_load_lds((const GAS unsigned*)(_g + so1), (unsigned*)((char*)(P) + tid_ * 16 + 8192), 16, 0, 0); } while (0)
; #define WAIT_V(n) asm volatile("s_waitcnt vmcnt(" #n ")" ::: "memory")
; #define WAIT_L(n) asm volatile("s_waitcnt lgkmcnt(" #n ")" ::: "memory")
; #define BAR __builtin_amdgcn_s_barrier()
; #define SCHED __builtin_amdgcn_sched_barrier(0)
; #define LDA(dst, b, h) for (int m = 0; m < 4; ++m) for (int k = 0; k < 2; ++k) \
;     dst[m][k] = *reinterpret_cast<const bf16x8*>((char*)SA(b, h) + lds_byte(wr * 64 + m * 16 + fr, k * 32 + fq * 8))
; #define LDB(dst, b, h) for (int n = 0; n < 2; ++n) for (int k = 0; k < 2; ++k) \
;     dst[n][k] = *reinterpret_cast<const bf16x8*>((char*)SB(b, h) + lds_byte(wc * 32 + n * 16 + fr, k * 32 + fq * 8))
; #define MMA(ai, bj, At_, Bt_) do { __builtin_amdgcn_s_setprio(1); \
;     for (int m = 0; m < 4; ++m) for (int n = 0; n < 2; ++n) for (int k = 0; k < 2; ++k) \
;       acc[ai][bj][m][n] = __builtin_amdgcn_mfma_f32_16x16x32_bf16(At_[m][k], Bt_[n][k], acc[ai][bj][m][n], 0, 0, 0); \
;     __builtin_amdgcn_s_setprio(0); } while (0)
; template <int K, int LD = K>
; __device__ __forceinline__ void gemm_main(const GAS bf16* A, const GAS bf16* Bt, int brow, int bcol, f32x4 (&acc)[2][2][4][2]) {
;     ...
;     LDA(At, 1, 1); STAGE(SA(1, 0), pA0, 3);
;     BAR; WAIT_L(0); MMA(1, 0, At, B0); BAR; SCHED;
;     STAGE(SB(1, 1), pB1, 3);
;     WAIT_V(6); BAR; MMA(1, 1, At, B1); BAR;
;     pA0 += 4 * BK; pA1 += 4 * BK; pB0 += 4 * BK; pB1 += 4 * BK;
;     asm volatile("" : "+s"(pA0), "+s"(pA1), "+s"(pB0), "+s"(pB1));
;   }
;   { LDB(B0, 0, 0); LDA(At, 0, 0); STAGE(SA(1, 1), pA1, 1);
;     BAR; WAIT_L(0); MMA(0, 0, At, B0); BAR;
;     LDB(B1, 0, 1); BAR; WAIT_L(0); MMA(0, 1, At, B1); BAR;
;     LDA(At, 0, 1); WAIT_V(4); BAR; WAIT_L(0); MMA(1, 0, At, B0); MMA(1, 1, At, B1); BAR; }
	ds_read_b128 v[182:185], v138 offset:49152
	ds_read_b128 v[186:189], v138 offset:50176
	ds_read_b128 v[190:193], v137 offset:49152
	ds_read_b128 v[194:197], v137 offset:50176
	ds_read_b128 v[198:201], v136 offset:49152
	ds_read_b128 v[202:205], v136 offset:50176
	ds_read_b128 v[206:209], v135 offset:49152
	ds_read_b128 v[210:213], v135 offset:50176
	global_load_lds_dwordx4 v[168:169], off
	v_lshl_add_u64 v[168:169], v[238:239], 0, s[10:11]
	s_mov_b32 m0, s23
	s_nop 0
	global_load_lds_dwordx4 v[168:169], off
	s_barrier
	s_waitcnt lgkmcnt(0)
	s_setprio 1
	s_waitcnt lgkmcnt(0)
	v_mfma_f32_16x16x32_bf16 v[62:65], v[182:185], v[160:163], v[62:65]
	v_mfma_f32_16x16x32_bf16 v[58:61], v[182:185], v[174:177], v[58:61]
	v_mfma_f32_16x16x32_bf16 v[54:57], v[190:193], v[160:163], v[54:57]
	v_mfma_f32_16x16x32_bf16 v[50:53], v[190:193], v[174:177], v[50:53]
	v_mfma_f32_16x16x32_bf16 v[46:49], v[198:201], v[160:163], v[46:49]
	v_mfma_f32_16x16x32_bf16 v[42:45], v[198:201], v[174:177], v[42:45]
	v_mfma_f32_16x16x32_bf16 v[38:41], v[206:209], v[160:163], v[38:41]
	v_mfma_f32_16x16x32_bf16 v[34:37], v[206:209], v[174:177], v[34:37]
	v_mfma_f32_16x16x32_bf16 v[62:65], v[186:189], v[164:167], v[62:65]
	v_mfma_f32_16x16x32_bf16 v[58:61], v[186:189], v[178:181], v[58:61]
	v_mfma_f32_16x16x32_bf16 v[54:57], v[194:197], v[164:167], v[54:57]
	v_mfma_f32_16x16x32_bf16 v[50:53], v[194:197], v[178:181], v[50:53]
	v_mfma_f32_16x16x32_bf16 v[46:49], v[202:205], v[164:167], v[46:49]
	v_mfma_f32_16x16x32_bf16 v[42:45], v[202:205], v[178:181], v[42:45]
	v_mfma_f32_16x16x32_bf16 v[38:41], v[210:213], v[164:167], v[38:41]
	v_mfma_f32_16x16x32_bf16 v[34:37], v[210:213], v[178:181], v[34:37]
	s_setprio 0
	s_barrier
	v_readfirstlane_b32 s23, v158
	v_lshl_add_u64 v[160:161], v[240:241], 0, s[10:11]
	s_mov_b32 m0, s23
	v_readfirstlane_b32 s23, v159
	global_load_lds_dwordx4 v[160:161], off
	v_lshl_add_u64 v[160:161], v[242:243], 0, s[10:11]
	s_mov_b32 m0, s23
	s_nop 0
	global_load_lds_dwordx4 v[160:161], off
	s_waitcnt vmcnt(8)
	s_barrier
	s_setprio 1
	v_mfma_f32_16x16x32_bf16 v[30:33], v[182:185], v[214:217], v[30:33]
	v_mfma_f32_16x16x32_bf16 v[26:29], v[182:185], v[222:225], v[26:29]
	v_mfma_f32_16x16x32_bf16 v[22:25], v[190:193], v[214:217], v[22:25]
	v_mfma_f32_16x16x32_bf16 v[18:21], v[190:193], v[222:225], v[18:21]
	v_mfma_f32_16x16x32_bf16 v[14:17], v[198:201], v[214:217], v[14:17]
	v_mfma_f32_16x16x32_bf16 v[10:13], v[198:201], v[222:225], v[10:13]
	v_mfma_f32_16x16x32_bf16 v[6:9], v[206:209], v[214:217], v[6:9]
	v_mfma_f32_16x16x32_bf16 v[2:5], v[206:209], v[222:225], v[2:5]
	v_mfma_f32_16x16x32_bf16 v[30:33], v[186:189], v[218:221], v[30:33]
	v_mfma_f32_16x16x32_bf16 v[26:29], v[186:189], v[226:229], v[26:29]
	v_mfma_f32_16x16x32_bf16 v[22:25], v[194:197], v[218:221], v[22:25]
	v_mfma_f32_16x16x32_bf16 v[18:21], v[194:197], v[226:229], v[18:21]
	v_mfma_f32_16x16x32_bf16 v[14:17], v[202:205], v[218:221], v[14:17]
	v_mfma_f32_16x16x32_bf16 v[10:13], v[202:205], v[226:229], v[10:13]
	v_mfma_f32_16x16x32_bf16 v[6:9], v[210:213], v[218:221], v[6:9]
	v_mfma_f32_16x16x32_bf16 v[2:5], v[210:213], v[226:229], v[2:5]
	s_setprio 0
	s_add_i32 s22, s22, 2
	s_cmp_lt_u32 s22, 40
	s_barrier
	s_cbranch_scc1 .LBB0_230
	ds_read_b128 v[146:149], v144
	ds_read_b128 v[150:153], v144 offset:1024
	ds_read_b128 v[156:159], v144 offset:2048
	ds_read_b128 v[160:163], v144 offset:3072
	ds_read_b128 v[164:167], v138
	ds_read_b128 v[174:177], v138 offset:1024
	ds_read_b128 v[178:181], v137
	ds_read_b128 v[182:185], v137 offset:1024
	ds_read_b128 v[186:189], v136
	ds_read_b128 v[190:193], v136 offset:1024
	ds_read_b128 v[194:197], v135
	ds_read_b128 v[198:201], v135 offset:1024
	v_lshl_add_u64 v[144:145], s[12:13], 0, v[130:131]
	v_readfirstlane_b32 s16, v143
	v_lshl_add_u64 v[144:145], v[144:145], 0, s[6:7]
	s_mov_b32 m0, s16
	v_lshl_add_u64 v[132:133], s[12:13], 0, v[132:133]
	v_readfirstlane_b32 s12, v142
	global_load_lds_dwordx4 v[144:145], off
	v_lshl_add_u64 v[132:133], v[132:133], 0, s[6:7]
	s_mov_b32 m0, s12
	s_nop 0
	global_load_lds_dwordx4 v[132:133], off
	s_barrier
	s_waitcnt lgkmcnt(0)
	s_setprio 1
	s_waitcnt lgkmcnt(0)
	v_mfma_f32_16x16x32_bf16 v[126:129], v[164:167], v[146:149], v[126:129]
	v_mfma_f32_16x16x32_bf16 v[122:125], v[164:167], v[156:159], v[122:125]
	v_mfma_f32_16x16x32_bf16 v[110:113], v[186:189], v[146:149], v[110:113]
	v_mfma_f32_16x16x32_bf16 v[106:109], v[186:189], v[156:159], v[106:109]
	v_mfma_f32_16x16x32_bf16 v[126:129], v[174:177], v[150:153], v[126:129]
	v_mfma_f32_16x16x32_bf16 v[122:125], v[174:177], v[160:163], v[122:125]
	v_mfma_f32_16x16x32_bf16 v[118:121], v[178:181], v[146:149], v[118:121]
	v_mfma_f32_16x16x32_bf16 v[114:117], v[178:181], v[156:159], v[114:117]
	v_mfma_f32_16x16x32_bf16 v[110:113], v[190:193], v[150:153], v[110:113]
	v_mfma_f32_16x16x32_bf16 v[106:109], v[190:193], v[160:163], v[106:109]
	v_mfma_f32_16x16x32_bf16 v[102:105], v[194:197], v[146:149], v[102:105]
	v_mfma_f32_16x16x32_bf16 v[98:101], v[194:197], v[156:159], v[98:101]
	v_mfma_f32_16x16x32_bf16 v[142:145], v[182:185], v[150:153], v[118:121]
	v_mfma_f32_16x16x32_bf16 v[202:205], v[182:185], v[160:163], v[114:117]
	v_mfma_f32_16x16x32_bf16 v[206:209], v[198:201], v[150:153], v[102:105]
	v_mfma_f32_16x16x32_bf16 v[210:213], v[198:201], v[160:163], v[98:101]
	s_setprio 0
	s_barrier
	s_nop 1
	ds_read_b128 v[98:101], v141
	ds_read_b128 v[102:105], v141 offset:1024
	ds_read_b128 v[114:117], v141 offset:2048
	ds_read_b128 v[118:121], v141 offset:3072
	s_waitcnt vmcnt(8)
	s_barrier
; #define WAIT_V(n) asm volatile("s_waitcnt vmcnt(" #n ")" ::: "memory")
; #define WAIT_L(n) asm volatile("s_waitcnt lgkmcnt(" #n ")" ::: "memory")
; #define BAR __builtin_amdgcn_s_barrier()
; #define LDA(dst, b, h) for (int m = 0; m < 4; ++m) for (int k = 0; k < 2; ++k) \
;     dst[m][k] = *reinterpret_cast<const bf16x8*>((char*)SA(b, h) + lds_byte(wr * 64 + m * 16 + fr, k * 32 + fq * 8))
; #define LDB(dst, b, h) for (int n = 0; n < 2; ++n) for (int k = 0; k < 2; ++k) \
;     dst[n][k] = *reinterpret_cast<const bf16x8*>((char*)SB(b, h) + lds_byte(wc * 32 + n * 16 + fr, k * 32 + fq * 8))
; #define MMA(ai, bj, At_, Bt_) do { __builtin_amdgcn_s_setprio(1); \
;     for (int m = 0; m < 4; ++m) for (int n = 0; n < 2; ++n) for (int k = 0; k < 2; ++k) \
;       acc[ai][bj][m][n] = __builtin_amdgcn_mfma_f32_16x16x32_bf16(At_[m][k], Bt_[n][k], acc[ai][bj][m][n], 0, 0, 0); \
;     __builtin_amdgcn_s_setprio(0); } while (0)
; template <int K, int LD = K>
; __device__ __forceinline__ void gemm_main(const GAS bf16* A, const GAS bf16* Bt, int brow, int bcol, f32x4 (&acc)[2][2][4][2]) {
;     ...
;     LDA(At, 0, 1); WAIT_V(4); BAR; WAIT_L(0); MMA(1, 0, At, B0); MMA(1, 1, At, B1); BAR; }
;   { LDB(B0, 1, 0); LDA(At, 1, 0); WAIT_V(2); BAR; WAIT_L(0); MMA(0, 0, At, B0); BAR;
	s_waitcnt lgkmcnt(0)
	s_setprio 1
	s_waitcnt lgkmcnt(0)
	v_mfma_f32_16x16x32_bf16 v[94:97], v[164:167], v[98:101], v[94:97]
	v_mfma_f32_16x16x32_bf16 v[90:93], v[164:167], v[114:117], v[90:93]
	v_mfma_f32_16x16x32_bf16 v[78:81], v[186:189], v[98:101], v[78:81]
	v_mfma_f32_16x16x32_bf16 v[74:77], v[186:189], v[114:117], v[74:77]
	v_mfma_f32_16x16x32_bf16 v[94:97], v[174:177], v[102:105], v[94:97]
	v_mfma_f32_16x16x32_bf16 v[90:93], v[174:177], v[118:121], v[90:93]
	v_mfma_f32_16x16x32_bf16 v[86:89], v[178:181], v[98:101], v[86:89]
	v_mfma_f32_16x16x32_bf16 v[82:85], v[178:181], v[114:117], v[82:85]
	v_mfma_f32_16x16x32_bf16 v[78:81], v[190:193], v[102:105], v[78:81]
	v_mfma_f32_16x16x32_bf16 v[74:77], v[190:193], v[118:121], v[74:77]
	v_mfma_f32_16x16x32_bf16 v[70:73], v[194:197], v[98:101], v[70:73]
	v_mfma_f32_16x16x32_bf16 v[66:69], v[194:197], v[114:117], v[66:69]
	v_mfma_f32_16x16x32_bf16 v[164:167], v[182:185], v[102:105], v[86:89]
	v_mfma_f32_16x16x32_bf16 v[174:177], v[182:185], v[118:121], v[82:85]
	v_mfma_f32_16x16x32_bf16 v[178:181], v[198:201], v[102:105], v[70:73]
	v_mfma_f32_16x16x32_bf16 v[182:185], v[198:201], v[118:121], v[66:69]
	s_setprio 0
	s_barrier
	s_nop 1
	ds_read_b128 v[66:69], v138 offset:16384
	ds_read_b128 v[70:73], v138 offset:17408
	ds_read_b128 v[82:85], v137 offset:16384
	ds_read_b128 v[86:89], v137 offset:17408
	ds_read_b128 v[186:189], v136 offset:16384
	ds_read_b128 v[190:193], v136 offset:17408
	ds_read_b128 v[194:197], v135 offset:16384
	ds_read_b128 v[198:201], v135 offset:17408
	s_waitcnt vmcnt(4)
	s_barrier
	s_waitcnt lgkmcnt(0)
	s_setprio 1
	s_waitcnt lgkmcnt(0)
	v_mfma_f32_16x16x32_bf16 v[62:65], v[66:69], v[146:149], v[62:65]
	v_mfma_f32_16x16x32_bf16 v[58:61], v[66:69], v[156:159], v[58:61]
	v_mfma_f32_16x16x32_bf16 v[46:49], v[186:189], v[146:149], v[46:49]
	v_mfma_f32_16x16x32_bf16 v[42:45], v[186:189], v[156:159], v[42:45]
	v_mfma_f32_16x16x32_bf16 v[62:65], v[70:73], v[150:153], v[62:65]
	v_mfma_f32_16x16x32_bf16 v[58:61], v[70:73], v[160:163], v[58:61]
	v_mfma_f32_16x16x32_bf16 v[54:57], v[82:85], v[146:149], v[54:57]
	v_mfma_f32_16x16x32_bf16 v[50:53], v[82:85], v[156:159], v[50:53]
	v_mfma_f32_16x16x32_bf16 v[46:49], v[190:193], v[150:153], v[46:49]
	v_mfma_f32_16x16x32_bf16 v[42:45], v[190:193], v[160:163], v[42:45]
	v_mfma_f32_16x16x32_bf16 v[38:41], v[194:197], v[146:149], v[38:41]
	v_mfma_f32_16x16x32_bf16 v[34:37], v[194:197], v[156:159], v[34:37]
	v_mfma_f32_16x16x32_bf16 v[214:217], v[86:89], v[150:153], v[54:57]
	v_mfma_f32_16x16x32_bf16 v[218:221], v[86:89], v[160:163], v[50:53]
	v_mfma_f32_16x16x32_bf16 v[146:149], v[198:201], v[150:153], v[38:41]
	v_mfma_f32_16x16x32_bf16 v[150:153], v[198:201], v[160:163], v[34:37]
	s_setprio 0
	s_setprio 1
	v_mfma_f32_16x16x32_bf16 v[30:33], v[66:69], v[98:101], v[30:33]
	v_mfma_f32_16x16x32_bf16 v[26:29], v[66:69], v[114:117], v[26:29]
	v_mfma_f32_16x16x32_bf16 v[14:17], v[186:189], v[98:101], v[14:17]
	v_mfma_f32_16x16x32_bf16 v[10:13], v[186:189], v[114:117], v[10:13]
	v_mfma_f32_16x16x32_bf16 v[30:33], v[70:73], v[102:105], v[30:33]
	v_mfma_f32_16x16x32_bf16 v[26:29], v[70:73], v[118:121], v[26:29]
	v_mfma_f32_16x16x32_bf16 v[22:25], v[82:85], v[98:101], v[22:25]
	v_mfma_f32_16x16x32_bf16 v[18:21], v[82:85], v[114:117], v[18:21]
	v_mfma_f32_16x16x32_bf16 v[14:17], v[190:193], v[102:105], v[14:17]
	v_mfma_f32_16x16x32_bf16 v[10:13], v[190:193], v[118:121], v[10:13]
	v_mfma_f32_16x16x32_bf16 v[6:9], v[194:197], v[98:101], v[6:9]
	v_mfma_f32_16x16x32_bf16 v[2:5], v[194:197], v[114:117], v[2:5]
	v_mfma_f32_16x16x32_bf16 v[156:159], v[86:89], v[102:105], v[22:25]
	v_mfma_f32_16x16x32_bf16 v[160:163], v[86:89], v[118:121], v[18:21]
	v_mfma_f32_16x16x32_bf16 v[186:189], v[198:201], v[102:105], v[6:9]
	v_mfma_f32_16x16x32_bf16 v[190:193], v[198:201], v[118:121], v[2:5]
	s_setprio 0
	s_barrier
	s_nop 1
	ds_read_b128 v[2:5], v140
	ds_read_b128 v[6:9], v140 offset:1024
	ds_read_b128 v[194:197], v140 offset:2048
	ds_read_b128 v[198:201], v140 offset:3072
	ds_read_b128 v[18:21], v138 offset:32768
	ds_read_b128 v[22:25], v138 offset:33792
	ds_read_b128 v[34:37], v137 offset:32768
	ds_read_b128 v[38:41], v137 offset:33792
	ds_read_b128 v[50:53], v136 offset:32768
	ds_read_b128 v[54:57], v136 offset:33792
	ds_read_b128 v[222:225], v135 offset:32768
	ds_read_b128 v[226:229], v135 offset:33792
	s_waitcnt vmcnt(2)
	s_barrier
; #define WAIT_V(n) asm volatile("s_waitcnt vmcnt(" #n ")" ::: "memory")
; #define WAIT_L(n) asm volatile("s_waitcnt lgkmcnt(" #n ")" ::: "memory")
; #define BAR __builtin_amdgcn_s_barrier()
; #define LDA(dst, b, h) for (int m = 0; m < 4; ++m) for (int k = 0; k < 2; ++k) \
;     dst[m][k] = *reinterpret_cast<const bf16x8*>((char*)SA(b, h) + lds_byte(wr * 64 + m * 16 + fr, k * 32 + fq * 8))
; #define LDB(dst, b, h) for (int n = 0; n < 2; ++n) for (int k = 0; k < 2; ++k) \
;     dst[n][k] = *reinterpret_cast<const bf16x8*>((char*)SB(b, h) + lds_byte(wc * 32 + n * 16 + fr, k * 32 + fq * 8))
; #define MMA(ai, bj, At_, Bt_) do { __builtin_amdgcn_s_setprio(1); \
;     for (int m = 0; m < 4; ++m) for (int n = 0; n < 2; ++n) for (int k = 0; k < 2; ++k) \
;       acc[ai][bj][m][n] = __builtin_amdgcn_mfma_f32_16x16x32_bf16(At_[m][k], Bt_[n][k], acc[ai][bj][m][n], 0, 0, 0); \
;     __builtin_amdgcn_s_setprio(0); } while (0)
; template <int K, int LD = K>
; __device__ __forceinline__ void gemm_main(const GAS bf16* A, const GAS bf16* Bt, int brow, int bcol, f32x4 (&acc)[2][2][4][2]) {
;     ...
;   { LDB(B0, 1, 0); LDA(At, 1, 0); WAIT_V(2); BAR; WAIT_L(0); MMA(0, 0, At, B0); BAR;
;     LDB(B1, 1, 1); WAIT_V(0); BAR; WAIT_L(0); MMA(0, 1, At, B1); BAR;
;     LDA(At, 1, 1); BAR; WAIT_L(0); MMA(1, 0, At, B0); MMA(1, 1, At, B1); BAR; }
;   if (wr == 0) BAR;
	s_waitcnt lgkmcnt(0)
	s_setprio 1
	s_waitcnt lgkmcnt(0)
	v_mfma_f32_16x16x32_bf16 v[66:69], v[18:21], v[2:5], v[126:129]
	v_mfma_f32_16x16x32_bf16 v[118:121], v[22:25], v[6:9], v[66:69]
	v_mfma_f32_16x16x32_bf16 v[66:69], v[18:21], v[194:197], v[122:125]
	v_mfma_f32_16x16x32_bf16 v[114:117], v[22:25], v[198:201], v[66:69]
	v_mfma_f32_16x16x32_bf16 v[66:69], v[34:37], v[2:5], v[142:145]
	v_mfma_f32_16x16x32_bf16 v[102:105], v[38:41], v[6:9], v[66:69]
	v_mfma_f32_16x16x32_bf16 v[66:69], v[34:37], v[194:197], v[202:205]
	v_mfma_f32_16x16x32_bf16 v[98:101], v[38:41], v[198:201], v[66:69]
	v_mfma_f32_16x16x32_bf16 v[66:69], v[50:53], v[2:5], v[110:113]
	v_mfma_f32_16x16x32_bf16 v[86:89], v[54:57], v[6:9], v[66:69]
	v_mfma_f32_16x16x32_bf16 v[66:69], v[50:53], v[194:197], v[106:109]
	v_mfma_f32_16x16x32_bf16 v[82:85], v[54:57], v[198:201], v[66:69]
	v_mfma_f32_16x16x32_bf16 v[66:69], v[222:225], v[2:5], v[206:209]
	v_mfma_f32_16x16x32_bf16 v[70:73], v[226:229], v[6:9], v[66:69]
	v_mfma_f32_16x16x32_bf16 v[66:69], v[222:225], v[194:197], v[210:213]
	v_mfma_f32_16x16x32_bf16 v[66:69], v[226:229], v[198:201], v[66:69]
	s_setprio 0
	s_barrier
	ds_read_b128 v[140:143], v139
	ds_read_b128 v[202:205], v139 offset:1024
	ds_read_b128 v[206:209], v139 offset:2048
	ds_read_b128 v[210:213], v139 offset:3072
	s_waitcnt vmcnt(0)
	s_barrier
	s_waitcnt lgkmcnt(0)
	s_setprio 1
	s_waitcnt lgkmcnt(0)
	v_mfma_f32_16x16x32_bf16 v[94:97], v[18:21], v[140:143], v[94:97]
	v_mfma_f32_16x16x32_bf16 v[18:21], v[18:21], v[206:209], v[90:93]
	v_mfma_f32_16x16x32_bf16 v[122:125], v[22:25], v[210:213], v[18:21]
	v_mfma_f32_16x16x32_bf16 v[18:21], v[34:37], v[140:143], v[164:167]
	v_mfma_f32_16x16x32_bf16 v[110:113], v[38:41], v[202:205], v[18:21]
	v_mfma_f32_16x16x32_bf16 v[18:21], v[34:37], v[206:209], v[174:177]
	v_mfma_f32_16x16x32_bf16 v[106:109], v[38:41], v[210:213], v[18:21]
	v_mfma_f32_16x16x32_bf16 v[18:21], v[50:53], v[140:143], v[78:81]
	v_mfma_f32_16x16x32_bf16 v[126:129], v[22:25], v[202:205], v[94:97]
	v_mfma_f32_16x16x32_bf16 v[94:97], v[54:57], v[202:205], v[18:21]
	v_mfma_f32_16x16x32_bf16 v[18:21], v[50:53], v[206:209], v[74:77]
	v_mfma_f32_16x16x32_bf16 v[90:93], v[54:57], v[210:213], v[18:21]
	v_mfma_f32_16x16x32_bf16 v[18:21], v[222:225], v[140:143], v[178:181]
	v_mfma_f32_16x16x32_bf16 v[78:81], v[226:229], v[202:205], v[18:21]
	v_mfma_f32_16x16x32_bf16 v[18:21], v[222:225], v[206:209], v[182:185]
	v_mfma_f32_16x16x32_bf16 v[74:77], v[226:229], v[210:213], v[18:21]
	s_setprio 0
	s_barrier
	ds_read_b128 v[164:167], v138 offset:49152
	ds_read_b128 v[174:177], v138 offset:50176
	ds_read_b128 v[178:181], v137 offset:49152
	ds_read_b128 v[182:185], v137 offset:50176
	ds_read_b128 v[222:225], v136 offset:49152
	ds_read_b128 v[136:139], v136 offset:50176
	ds_read_b128 v[226:229], v135 offset:49152
	ds_read_b128 v[230:233], v135 offset:50176
	s_barrier
	s_waitcnt lgkmcnt(0)
	s_setprio 1
	s_waitcnt lgkmcnt(0)
	v_mfma_f32_16x16x32_bf16 v[18:21], v[164:167], v[2:5], v[62:65]
	v_mfma_f32_16x16x32_bf16 v[54:57], v[174:177], v[6:9], v[18:21]
	v_mfma_f32_16x16x32_bf16 v[18:21], v[164:167], v[194:197], v[58:61]
	v_mfma_f32_16x16x32_bf16 v[50:53], v[174:177], v[198:201], v[18:21]
	v_mfma_f32_16x16x32_bf16 v[18:21], v[178:181], v[2:5], v[214:217]
	v_mfma_f32_16x16x32_bf16 v[38:41], v[182:185], v[6:9], v[18:21]
	v_mfma_f32_16x16x32_bf16 v[18:21], v[178:181], v[194:197], v[218:221]
	v_mfma_f32_16x16x32_bf16 v[34:37], v[182:185], v[198:201], v[18:21]
	v_mfma_f32_16x16x32_bf16 v[18:21], v[222:225], v[2:5], v[46:49]
	v_mfma_f32_16x16x32_bf16 v[2:5], v[226:229], v[2:5], v[146:149]
	v_mfma_f32_16x16x32_bf16 v[22:25], v[136:139], v[6:9], v[18:21]
	v_mfma_f32_16x16x32_bf16 v[18:21], v[222:225], v[194:197], v[42:45]
	v_mfma_f32_16x16x32_bf16 v[6:9], v[230:233], v[6:9], v[2:5]
	v_mfma_f32_16x16x32_bf16 v[2:5], v[226:229], v[194:197], v[150:153]
	v_mfma_f32_16x16x32_bf16 v[18:21], v[136:139], v[198:201], v[18:21]
	v_mfma_f32_16x16x32_bf16 v[2:5], v[230:233], v[198:201], v[2:5]
	s_setprio 0
	s_setprio 1
	v_mfma_f32_16x16x32_bf16 v[26:29], v[164:167], v[206:209], v[26:29]
	v_mfma_f32_16x16x32_bf16 v[58:61], v[174:177], v[210:213], v[26:29]
	v_mfma_f32_16x16x32_bf16 v[26:29], v[178:181], v[140:143], v[156:159]
	v_mfma_f32_16x16x32_bf16 v[46:49], v[182:185], v[202:205], v[26:29]
	v_mfma_f32_16x16x32_bf16 v[26:29], v[178:181], v[206:209], v[160:163]
	v_mfma_f32_16x16x32_bf16 v[10:13], v[222:225], v[206:209], v[10:13]
	v_mfma_f32_16x16x32_bf16 v[30:33], v[164:167], v[140:143], v[30:33]
	v_mfma_f32_16x16x32_bf16 v[42:45], v[182:185], v[210:213], v[26:29]
	v_mfma_f32_16x16x32_bf16 v[14:17], v[222:225], v[140:143], v[14:17]
	v_mfma_f32_16x16x32_bf16 v[26:29], v[136:139], v[210:213], v[10:13]
	v_mfma_f32_16x16x32_bf16 v[10:13], v[226:229], v[140:143], v[186:189]
	v_mfma_f32_16x16x32_bf16 v[62:65], v[174:177], v[202:205], v[30:33]
	v_mfma_f32_16x16x32_bf16 v[30:33], v[136:139], v[202:205], v[14:17]
	v_mfma_f32_16x16x32_bf16 v[14:17], v[230:233], v[202:205], v[10:13]
	v_mfma_f32_16x16x32_bf16 v[10:13], v[226:229], v[206:209], v[190:193]
	v_mfma_f32_16x16x32_bf16 v[10:13], v[230:233], v[210:213], v[10:13]
	s_setprio 0
	v_cmp_gt_u32_e32 vcc, s35, v134
	s_barrier
	s_and_saveexec_b64 s[12:13], vcc
	s_cbranch_execz .LBB0_233
	s_barrier

; #define STAGE(P, GP, ktrel) do { const GAS char* _g = (GP) + (ktrel) * (BK * 2); \
;     __builtin_amdgcn_global_load_lds((const GAS unsigned*)(_g + so0), (unsigned*)((char*)(P) + tid_ * 16), 16, 0, 0); \
;     __builtin_amdgcn_global_load_lds((const GAS unsigned*)(_g + so1), (unsigned*)((char*)(P) + tid_ * 16 + 8192), 16, 0, 0); } while (0)
; #define WAIT_V(n) asm volatile("s_waitcnt vmcnt(" #n ")" ::: "memory")
; #define WAIT_L(n) asm volatile("s_waitcnt lgkmcnt(" #n ")" ::: "memory")
; #define BAR __builtin_amdgcn_s_barrier()
; #define SCHED __builtin_amdgcn_sched_barrier(0)
; #define LDA(dst, b, h) for (int m = 0; m < 4; ++m) for (int k = 0; k < 2; ++k) \
;     dst[m][k] = *reinterpret_cast<const bf16x8*>((char*)SA(b, h) + lds_byte(wr * 64 + m * 16 + fr, k * 32 + fq * 8))
; #define LDB(dst, b, h) for (int n = 0; n < 2; ++n) for (int k = 0; k < 2; ++k) \
;     dst[n][k] = *reinterpret_cast<const bf16x8*>((char*)SB(b, h) + lds_byte(wc * 32 + n * 16 + fr, k * 32 + fq * 8))
; #define MMA(ai, bj, At_, Bt_) do { __builtin_amdgcn_s_setprio(1); \
;     for (int m = 0; m < 4; ++m) for (int n = 0; n < 2; ++n) for (int k = 0; k < 2; ++k) \
;       acc[ai][bj][m][n] = __builtin_amdgcn_mfma_f32_16x16x32_bf16(At_[m][k], Bt_[n][k], acc[ai][bj][m][n], 0, 0, 0); \
;     __builtin_amdgcn_s_setprio(0); } while (0)
; template <int K, int LD = K>
; __device__ __forceinline__ void gemm_main(const GAS bf16* A, const GAS bf16* Bt, int brow, int bcol, f32x4 (&acc)[2][2][4][2]) {
;     ...
;     LDB(B0, 0, 0); SCHED; LDA(At, 0, 0); STAGE(SA(1, 1), pA1, 1);
;     WAIT_L(8); BAR; WAIT_L(0); MMA(0, 0, At, B0); BAR; SCHED;
;     LDB(B1, 0, 1); STAGE(SB(0, 0), pB0, 2);
;     BAR; WAIT_L(0); MMA(0, 1, At, B1); BAR;
;     LDA(At, 0, 1); STAGE(SA(0, 0), pA0, 2);
;     BAR; WAIT_L(0); MMA(1, 0, At, B0); BAR; SCHED;
;     STAGE(SB(0, 1), pB1, 2);
;     WAIT_V(6); BAR; MMA(1, 1, At, B1); BAR;
.LBB0_346:
	ds_read_b128 v[162:165], v146
	ds_read_b128 v[166:169], v146 offset:1024
	ds_read_b128 v[174:177], v146 offset:2048
	ds_read_b128 v[178:181], v146 offset:3072
	v_lshl_add_u64 v[230:231], s[26:27], 0, v[130:131]
	v_readfirstlane_b32 s20, v143
	v_lshl_add_u64 v[214:215], v[230:231], 0, s[14:15]
	s_mov_b32 m0, s20
	v_lshl_add_u64 v[232:233], s[26:27], 0, v[132:133]
	v_readfirstlane_b32 s20, v142
	ds_read_b128 v[182:185], v138
	ds_read_b128 v[186:189], v138 offset:1024
	ds_read_b128 v[190:193], v137
	ds_read_b128 v[194:197], v137 offset:1024
	ds_read_b128 v[198:201], v136
	ds_read_b128 v[202:205], v136 offset:1024
	ds_read_b128 v[206:209], v135
	ds_read_b128 v[210:213], v135 offset:1024
	global_load_lds_dwordx4 v[214:215], off
	v_lshl_add_u64 v[214:215], v[232:233], 0, s[14:15]
	s_mov_b32 m0, s20
	s_nop 0
	global_load_lds_dwordx4 v[214:215], off
	s_waitcnt lgkmcnt(8)
	s_barrier
	s_waitcnt lgkmcnt(0)
	s_setprio 1
	s_waitcnt lgkmcnt(0)
	v_mfma_f32_16x16x32_bf16 v[126:129], v[182:185], v[162:165], v[126:129]
	v_mfma_f32_16x16x32_bf16 v[122:125], v[182:185], v[174:177], v[122:125]
	v_mfma_f32_16x16x32_bf16 v[118:121], v[190:193], v[162:165], v[118:121]
	v_mfma_f32_16x16x32_bf16 v[114:117], v[190:193], v[174:177], v[114:117]
	v_mfma_f32_16x16x32_bf16 v[110:113], v[198:201], v[162:165], v[110:113]
	v_mfma_f32_16x16x32_bf16 v[106:109], v[198:201], v[174:177], v[106:109]
	v_mfma_f32_16x16x32_bf16 v[102:105], v[206:209], v[162:165], v[102:105]
	v_mfma_f32_16x16x32_bf16 v[98:101], v[206:209], v[174:177], v[98:101]
	v_mfma_f32_16x16x32_bf16 v[126:129], v[186:189], v[166:169], v[126:129]
	v_mfma_f32_16x16x32_bf16 v[122:125], v[186:189], v[178:181], v[122:125]
	v_mfma_f32_16x16x32_bf16 v[118:121], v[194:197], v[166:169], v[118:121]
	v_mfma_f32_16x16x32_bf16 v[114:117], v[194:197], v[178:181], v[114:117]
	v_mfma_f32_16x16x32_bf16 v[110:113], v[202:205], v[166:169], v[110:113]
	v_mfma_f32_16x16x32_bf16 v[106:109], v[202:205], v[178:181], v[106:109]
	v_mfma_f32_16x16x32_bf16 v[102:105], v[210:213], v[166:169], v[102:105]
	v_mfma_f32_16x16x32_bf16 v[98:101], v[210:213], v[178:181], v[98:101]
	s_setprio 0
	s_barrier
	v_lshl_add_u64 v[234:235], s[36:37], 0, v[130:131]
	v_readfirstlane_b32 s20, v153
	v_lshl_add_u64 v[236:237], v[234:235], 0, s[22:23]
	s_mov_b32 m0, s20
	ds_read_b128 v[214:217], v141
	ds_read_b128 v[218:221], v141 offset:1024
	ds_read_b128 v[222:225], v141 offset:2048
	ds_read_b128 v[226:229], v141 offset:3072
	global_load_lds_dwordx4 v[236:237], off
	v_lshl_add_u64 v[236:237], s[36:37], 0, v[132:133]
	v_readfirstlane_b32 s20, v154
	v_lshl_add_u64 v[238:239], v[236:237], 0, s[22:23]
	s_mov_b32 m0, s20
	s_add_u32 s36, s36, 0x100
	global_load_lds_dwordx4 v[238:239], off
	s_waitcnt vmcnt(10)
	s_barrier
	s_waitcnt lgkmcnt(0)
	s_addc_u32 s37, s37, 0
	s_setprio 1
	s_waitcnt lgkmcnt(0)
	v_mfma_f32_16x16x32_bf16 v[94:97], v[182:185], v[214:217], v[94:97]
	v_mfma_f32_16x16x32_bf16 v[90:93], v[182:185], v[222:225], v[90:93]
	v_mfma_f32_16x16x32_bf16 v[86:89], v[190:193], v[214:217], v[86:89]
	v_mfma_f32_16x16x32_bf16 v[82:85], v[190:193], v[222:225], v[82:85]
	v_mfma_f32_16x16x32_bf16 v[78:81], v[198:201], v[214:217], v[78:81]
	v_mfma_f32_16x16x32_bf16 v[74:77], v[198:201], v[222:225], v[74:77]
	v_mfma_f32_16x16x32_bf16 v[70:73], v[206:209], v[214:217], v[70:73]
	v_mfma_f32_16x16x32_bf16 v[66:69], v[206:209], v[222:225], v[66:69]
	v_mfma_f32_16x16x32_bf16 v[94:97], v[186:189], v[218:221], v[94:97]
	v_mfma_f32_16x16x32_bf16 v[90:93], v[186:189], v[226:229], v[90:93]
	v_mfma_f32_16x16x32_bf16 v[86:89], v[194:197], v[218:221], v[86:89]
	v_mfma_f32_16x16x32_bf16 v[82:85], v[194:197], v[226:229], v[82:85]
	v_mfma_f32_16x16x32_bf16 v[78:81], v[202:205], v[218:221], v[78:81]
	v_mfma_f32_16x16x32_bf16 v[74:77], v[202:205], v[226:229], v[74:77]
	v_mfma_f32_16x16x32_bf16 v[70:73], v[210:213], v[218:221], v[70:73]
	v_mfma_f32_16x16x32_bf16 v[66:69], v[210:213], v[226:229], v[66:69]
	s_setprio 0
	v_lshl_add_u64 v[238:239], s[34:35], 0, v[130:131]
	v_readfirstlane_b32 s20, v147
	v_lshl_add_u64 v[240:241], v[238:239], 0, s[22:23]
	s_mov_b32 m0, s20
	s_barrier
	ds_read_b128 v[182:185], v138 offset:16384
	ds_read_b128 v[186:189], v138 offset:17408
	ds_read_b128 v[190:193], v137 offset:16384
	ds_read_b128 v[194:197], v137 offset:17408
	ds_read_b128 v[198:201], v136 offset:16384
	ds_read_b128 v[202:205], v136 offset:17408
	ds_read_b128 v[206:209], v135 offset:16384
	ds_read_b128 v[210:213], v135 offset:17408
	global_load_lds_dwordx4 v[240:241], off
	v_lshl_add_u64 v[240:241], s[34:35], 0, v[132:133]
	v_readfirstlane_b32 s20, v148
	v_lshl_add_u64 v[242:243], v[240:241], 0, s[22:23]
	s_mov_b32 m0, s20
	s_add_u32 s34, s34, 0x100
	global_load_lds_dwordx4 v[242:243], off
	s_barrier
	s_waitcnt lgkmcnt(0)
	s_addc_u32 s35, s35, 0
	s_setprio 1
	s_waitcnt lgkmcnt(0)
	v_mfma_f32_16x16x32_bf16 v[62:65], v[182:185], v[162:165], v[62:65]
	v_mfma_f32_16x16x32_bf16 v[58:61], v[182:185], v[174:177], v[58:61]
	v_mfma_f32_16x16x32_bf16 v[54:57], v[190:193], v[162:165], v[54:57]
	v_mfma_f32_16x16x32_bf16 v[50:53], v[190:193], v[174:177], v[50:53]
	v_mfma_f32_16x16x32_bf16 v[46:49], v[198:201], v[162:165], v[46:49]
	v_mfma_f32_16x16x32_bf16 v[42:45], v[198:201], v[174:177], v[42:45]
	v_mfma_f32_16x16x32_bf16 v[38:41], v[206:209], v[162:165], v[38:41]
	v_mfma_f32_16x16x32_bf16 v[34:37], v[206:209], v[174:177], v[34:37]
	v_mfma_f32_16x16x32_bf16 v[62:65], v[186:189], v[166:169], v[62:65]
	v_mfma_f32_16x16x32_bf16 v[58:61], v[186:189], v[178:181], v[58:61]
	v_mfma_f32_16x16x32_bf16 v[54:57], v[194:197], v[166:169], v[54:57]
	v_mfma_f32_16x16x32_bf16 v[50:53], v[194:197], v[178:181], v[50:53]
	v_mfma_f32_16x16x32_bf16 v[46:49], v[202:205], v[166:169], v[46:49]
	v_mfma_f32_16x16x32_bf16 v[42:45], v[202:205], v[178:181], v[42:45]
	v_mfma_f32_16x16x32_bf16 v[38:41], v[210:213], v[166:169], v[38:41]
	v_mfma_f32_16x16x32_bf16 v[34:37], v[210:213], v[178:181], v[34:37]
	s_setprio 0
	s_barrier
; #define STAGE(P, GP, ktrel) do { const GAS char* _g = (GP) + (ktrel) * (BK * 2); \
;     __builtin_amdgcn_global_load_lds((const GAS unsigned*)(_g + so0), (unsigned*)((char*)(P) + tid_ * 16), 16, 0, 0); \
;     __builtin_amdgcn_global_load_lds((const GAS unsigned*)(_g + so1), (unsigned*)((char*)(P) + tid_ * 16 + 8192), 16, 0, 0); } while (0)
; #define WAIT_V(n) asm volatile("s_waitcnt vmcnt(" #n ")" ::: "memory")
; #define WAIT_L(n) asm volatile("s_waitcnt lgkmcnt(" #n ")" ::: "memory")
; #define BAR __builtin_amdgcn_s_barrier()
; #define SCHED __builtin_amdgcn_sched_barrier(0)
; #define LDA(dst, b, h) for (int m = 0; m < 4; ++m) for (int k = 0; k < 2; ++k) \
;     dst[m][k] = *reinterpret_cast<const bf16x8*>((char*)SA(b, h) + lds_byte(wr * 64 + m * 16 + fr, k * 32 + fq * 8))
; #define LDB(dst, b, h) for (int n = 0; n < 2; ++n) for (int k = 0; k < 2; ++k) \
;     dst[n][k] = *reinterpret_cast<const bf16x8*>((char*)SB(b, h) + lds_byte(wc * 32 + n * 16 + fr, k * 32 + fq * 8))
; #define MMA(ai, bj, At_, Bt_) do { __builtin_amdgcn_s_setprio(1); \
;     for (int m = 0; m < 4; ++m) for (int n = 0; n < 2; ++n) for (int k = 0; k < 2; ++k) \
;       acc[ai][bj][m][n] = __builtin_amdgcn_mfma_f32_16x16x32_bf16(At_[m][k], Bt_[n][k], acc[ai][bj][m][n], 0, 0, 0); \
;     __builtin_amdgcn_s_setprio(0); } while (0)
; template <int K, int LD = K>
; __device__ __forceinline__ void gemm_main(const GAS bf16* A, const GAS bf16* Bt, int brow, int bcol, f32x4 (&acc)[2][2][4][2]) {
;     ...
;     WAIT_V(6); BAR; MMA(1, 1, At, B1); BAR;
;     LDB(B0, 1, 0); SCHED; LDA(At, 1, 0); STAGE(SA(0, 1), pA1, 2);
;     WAIT_L(8); BAR; WAIT_L(0); MMA(0, 0, At, B0); BAR; SCHED;
;     LDB(B1, 1, 1); STAGE(SB(1, 0), pB0, 3);
;     BAR; WAIT_L(0); MMA(0, 1, At, B1); BAR;
;     LDA(At, 1, 1); STAGE(SA(1, 0), pA0, 3);
;     BAR; WAIT_L(0); MMA(1, 0, At, B0); BAR; SCHED;
;     STAGE(SB(1, 1), pB1, 3);
;     WAIT_V(6); BAR; MMA(1, 1, At, B1); BAR;
	v_lshl_add_u64 v[242:243], s[28:29], 0, v[130:131]
	v_readfirstlane_b32 s20, v155
	v_lshl_add_u64 v[162:163], v[242:243], 0, s[22:23]
	s_mov_b32 m0, s20
	v_lshl_add_u64 v[244:245], s[28:29], 0, v[132:133]
	v_readfirstlane_b32 s20, v156
	global_load_lds_dwordx4 v[162:163], off
	v_lshl_add_u64 v[162:163], v[244:245], 0, s[22:23]
	s_mov_b32 m0, s20
	s_add_u32 s28, s28, 0x100
	global_load_lds_dwordx4 v[162:163], off
	s_waitcnt vmcnt(8)
	s_addc_u32 s29, s29, 0
	s_barrier
	s_setprio 1
	v_mfma_f32_16x16x32_bf16 v[30:33], v[182:185], v[214:217], v[30:33]
	v_mfma_f32_16x16x32_bf16 v[26:29], v[182:185], v[222:225], v[26:29]
	v_mfma_f32_16x16x32_bf16 v[22:25], v[190:193], v[214:217], v[22:25]
	v_mfma_f32_16x16x32_bf16 v[18:21], v[190:193], v[222:225], v[18:21]
	v_mfma_f32_16x16x32_bf16 v[14:17], v[198:201], v[214:217], v[14:17]
	v_mfma_f32_16x16x32_bf16 v[10:13], v[198:201], v[222:225], v[10:13]
	v_mfma_f32_16x16x32_bf16 v[6:9], v[206:209], v[214:217], v[6:9]
	v_mfma_f32_16x16x32_bf16 v[2:5], v[206:209], v[222:225], v[2:5]
	v_mfma_f32_16x16x32_bf16 v[30:33], v[186:189], v[218:221], v[30:33]
	v_mfma_f32_16x16x32_bf16 v[26:29], v[186:189], v[226:229], v[26:29]
	v_mfma_f32_16x16x32_bf16 v[22:25], v[194:197], v[218:221], v[22:25]
	v_mfma_f32_16x16x32_bf16 v[18:21], v[194:197], v[226:229], v[18:21]
	v_mfma_f32_16x16x32_bf16 v[14:17], v[202:205], v[218:221], v[14:17]
	v_mfma_f32_16x16x32_bf16 v[10:13], v[202:205], v[226:229], v[10:13]
	v_mfma_f32_16x16x32_bf16 v[6:9], v[210:213], v[218:221], v[6:9]
	v_mfma_f32_16x16x32_bf16 v[2:5], v[210:213], v[226:229], v[2:5]
	s_setprio 0
	s_barrier
	ds_read_b128 v[162:165], v140
	ds_read_b128 v[166:169], v140 offset:1024
	ds_read_b128 v[174:177], v140 offset:2048
	ds_read_b128 v[178:181], v140 offset:3072
	v_readfirstlane_b32 s20, v149
	v_lshl_add_u64 v[214:215], v[230:231], 0, s[22:23]
	s_mov_b32 m0, s20
	v_readfirstlane_b32 s20, v150
	ds_read_b128 v[182:185], v138 offset:32768
	ds_read_b128 v[186:189], v138 offset:33792
	ds_read_b128 v[190:193], v137 offset:32768
	ds_read_b128 v[194:197], v137 offset:33792
	ds_read_b128 v[198:201], v136 offset:32768
	ds_read_b128 v[202:205], v136 offset:33792
	ds_read_b128 v[206:209], v135 offset:32768
	ds_read_b128 v[210:213], v135 offset:33792
	global_load_lds_dwordx4 v[214:215], off
	v_lshl_add_u64 v[214:215], v[232:233], 0, s[22:23]
	s_mov_b32 m0, s20
	s_add_u32 s26, s26, 0x100
	global_load_lds_dwordx4 v[214:215], off
	s_waitcnt lgkmcnt(8)
	s_barrier
	s_waitcnt lgkmcnt(0)
	s_addc_u32 s27, s27, 0
	s_setprio 1
	s_waitcnt lgkmcnt(0)
	v_mfma_f32_16x16x32_bf16 v[126:129], v[182:185], v[162:165], v[126:129]
	v_mfma_f32_16x16x32_bf16 v[122:125], v[182:185], v[174:177], v[122:125]
	v_mfma_f32_16x16x32_bf16 v[118:121], v[190:193], v[162:165], v[118:121]
	v_mfma_f32_16x16x32_bf16 v[114:117], v[190:193], v[174:177], v[114:117]
	v_mfma_f32_16x16x32_bf16 v[110:113], v[198:201], v[162:165], v[110:113]
	v_mfma_f32_16x16x32_bf16 v[106:109], v[198:201], v[174:177], v[106:109]
	v_mfma_f32_16x16x32_bf16 v[102:105], v[206:209], v[162:165], v[102:105]
	v_mfma_f32_16x16x32_bf16 v[98:101], v[206:209], v[174:177], v[98:101]
	v_mfma_f32_16x16x32_bf16 v[126:129], v[186:189], v[166:169], v[126:129]
	v_mfma_f32_16x16x32_bf16 v[122:125], v[186:189], v[178:181], v[122:125]
	v_mfma_f32_16x16x32_bf16 v[118:121], v[194:197], v[166:169], v[118:121]
	v_mfma_f32_16x16x32_bf16 v[114:117], v[194:197], v[178:181], v[114:117]
	v_mfma_f32_16x16x32_bf16 v[110:113], v[202:205], v[166:169], v[110:113]
	v_mfma_f32_16x16x32_bf16 v[106:109], v[202:205], v[178:181], v[106:109]
	v_mfma_f32_16x16x32_bf16 v[102:105], v[210:213], v[166:169], v[102:105]
	v_mfma_f32_16x16x32_bf16 v[98:101], v[210:213], v[178:181], v[98:101]
	s_setprio 0
	s_barrier
	v_readfirstlane_b32 s20, v157
	v_lshl_add_u64 v[230:231], v[234:235], 0, s[24:25]
	s_mov_b32 m0, s20
	v_readfirstlane_b32 s20, v158
	ds_read_b128 v[214:217], v139
	ds_read_b128 v[218:221], v139 offset:1024
	ds_read_b128 v[222:225], v139 offset:2048
	ds_read_b128 v[226:229], v139 offset:3072
	global_load_lds_dwordx4 v[230:231], off
	v_lshl_add_u64 v[230:231], v[236:237], 0, s[24:25]
	s_mov_b32 m0, s20
	s_nop 0
	global_load_lds_dwordx4 v[230:231], off
	s_waitcnt vmcnt(10)
	s_barrier
	s_waitcnt lgkmcnt(0)
	s_setprio 1
	s_waitcnt lgkmcnt(0)
	v_mfma_f32_16x16x32_bf16 v[94:97], v[182:185], v[214:217], v[94:97]
	v_mfma_f32_16x16x32_bf16 v[90:93], v[182:185], v[222:225], v[90:93]
	v_mfma_f32_16x16x32_bf16 v[86:89], v[190:193], v[214:217], v[86:89]
	v_mfma_f32_16x16x32_bf16 v[82:85], v[190:193], v[222:225], v[82:85]
	v_mfma_f32_16x16x32_bf16 v[78:81], v[198:201], v[214:217], v[78:81]
	v_mfma_f32_16x16x32_bf16 v[74:77], v[198:201], v[222:225], v[74:77]
	v_mfma_f32_16x16x32_bf16 v[70:73], v[206:209], v[214:217], v[70:73]
	v_mfma_f32_16x16x32_bf16 v[66:69], v[206:209], v[222:225], v[66:69]
	v_mfma_f32_16x16x32_bf16 v[94:97], v[186:189], v[218:221], v[94:97]
	v_mfma_f32_16x16x32_bf16 v[90:93], v[186:189], v[226:229], v[90:93]
	v_mfma_f32_16x16x32_bf16 v[86:89], v[194:197], v[218:221], v[86:89]
	v_mfma_f32_16x16x32_bf16 v[82:85], v[194:197], v[226:229], v[82:85]
	v_mfma_f32_16x16x32_bf16 v[78:81], v[202:205], v[218:221], v[78:81]
	v_mfma_f32_16x16x32_bf16 v[74:77], v[202:205], v[226:229], v[74:77]
	v_mfma_f32_16x16x32_bf16 v[70:73], v[210:213], v[218:221], v[70:73]
	v_mfma_f32_16x16x32_bf16 v[66:69], v[210:213], v[226:229], v[66:69]
	s_setprio 0
	v_readfirstlane_b32 s20, v151
	v_lshl_add_u64 v[230:231], v[238:239], 0, s[24:25]
	s_mov_b32 m0, s20
	v_readfirstlane_b32 s20, v152
	s_barrier
; #define STAGE(P, GP, ktrel) do { const GAS char* _g = (GP) + (ktrel) * (BK * 2); \
;     __builtin_amdgcn_global_load_lds((const GAS unsigned*)(_g + so0), (unsigned*)((char*)(P) + tid_ * 16), 16, 0, 0); \
;     __builtin_amdgcn_global_load_lds((const GAS unsigned*)(_g + so1), (unsigned*)((char*)(P) + tid_ * 16 + 8192), 16, 0, 0); } while (0)
; #define WAIT_V(n) asm volatile("s_waitcnt vmcnt(" #n ")" ::: "memory")
; #define WAIT_L(n) asm volatile("s_waitcnt lgkmcnt(" #n ")" ::: "memory")
; #define BAR __builtin_amdgcn_s_barrier()
; #define SCHED __builtin_amdgcn_sched_barrier(0)
; #define LDA(dst, b, h) for (int m = 0; m < 4; ++m) for (int k = 0; k < 2; ++k) \
;     dst[m][k] = *reinterpret_cast<const bf16x8*>((char*)SA(b, h) + lds_byte(wr * 64 + m * 16 + fr, k * 32 + fq * 8))
; #define LDB(dst, b, h) for (int n = 0; n < 2; ++n) for (int k = 0; k < 2; ++k) \
;     dst[n][k] = *reinterpret_cast<const bf16x8*>((char*)SB(b, h) + lds_byte(wc * 32 + n * 16 + fr, k * 32 + fq * 8))
; #define MMA(ai, bj, At_, Bt_) do { __builtin_amdgcn_s_setprio(1); \
;     for (int m = 0; m < 4; ++m) for (int n = 0; n < 2; ++n) for (int k = 0; k < 2; ++k) \
;       acc[ai][bj][m][n] = __builtin_amdgcn_mfma_f32_16x16x32_bf16(At_[m][k], Bt_[n][k], acc[ai][bj][m][n], 0, 0, 0); \
;     __builtin_amdgcn_s_setprio(0); } while (0)
; template <int K, int LD = K>
; __device__ __forceinline__ void gemm_main(const GAS bf16* A, const GAS bf16* Bt, int brow, int bcol, f32x4 (&acc)[2][2][4][2]) {
;     ...
;     LDA(At, 1, 1); STAGE(SA(1, 0), pA0, 3);
;     BAR; WAIT_L(0); MMA(1, 0, At, B0); BAR; SCHED;
;     STAGE(SB(1, 1), pB1, 3);
;     WAIT_V(6); BAR; MMA(1, 1, At, B1); BAR;
;     pA0 += 4 * BK; pA1 += 4 * BK; pB0 += 4 * BK; pB1 += 4 * BK;
;     asm volatile("" : "+s"(pA0), "+s"(pA1), "+s"(pB0), "+s"(pB1));
;   }
;   { LDB(B0, 0, 0); LDA(At, 0, 0); STAGE(SA(1, 1), pA1, 1);
;     BAR; WAIT_L(0); MMA(0, 0, At, B0); BAR;
;     LDB(B1, 0, 1); BAR; WAIT_L(0); MMA(0, 1, At, B1); BAR;
;     LDA(At, 0, 1); WAIT_V(4); BAR; WAIT_L(0); MMA(1, 0, At, B0); MMA(1, 1, At, B1); BAR; }
	ds_read_b128 v[182:185], v138 offset:49152
	ds_read_b128 v[186:189], v138 offset:50176
	ds_read_b128 v[190:193], v137 offset:49152
	ds_read_b128 v[194:197], v137 offset:50176
	ds_read_b128 v[198:201], v136 offset:49152
	ds_read_b128 v[202:205], v136 offset:50176
	ds_read_b128 v[206:209], v135 offset:49152
	ds_read_b128 v[210:213], v135 offset:50176
	global_load_lds_dwordx4 v[230:231], off
	v_lshl_add_u64 v[230:231], v[240:241], 0, s[24:25]
	s_mov_b32 m0, s20
	s_nop 0
	global_load_lds_dwordx4 v[230:231], off
	s_barrier
	s_waitcnt lgkmcnt(0)
	s_setprio 1
	s_waitcnt lgkmcnt(0)
	v_mfma_f32_16x16x32_bf16 v[62:65], v[182:185], v[162:165], v[62:65]
	v_mfma_f32_16x16x32_bf16 v[58:61], v[182:185], v[174:177], v[58:61]
	v_mfma_f32_16x16x32_bf16 v[54:57], v[190:193], v[162:165], v[54:57]
	v_mfma_f32_16x16x32_bf16 v[50:53], v[190:193], v[174:177], v[50:53]
	v_mfma_f32_16x16x32_bf16 v[46:49], v[198:201], v[162:165], v[46:49]
	v_mfma_f32_16x16x32_bf16 v[42:45], v[198:201], v[174:177], v[42:45]
	v_mfma_f32_16x16x32_bf16 v[38:41], v[206:209], v[162:165], v[38:41]
	v_mfma_f32_16x16x32_bf16 v[34:37], v[206:209], v[174:177], v[34:37]
	v_mfma_f32_16x16x32_bf16 v[62:65], v[186:189], v[166:169], v[62:65]
	v_mfma_f32_16x16x32_bf16 v[58:61], v[186:189], v[178:181], v[58:61]
	v_mfma_f32_16x16x32_bf16 v[54:57], v[194:197], v[166:169], v[54:57]
	v_mfma_f32_16x16x32_bf16 v[50:53], v[194:197], v[178:181], v[50:53]
	v_mfma_f32_16x16x32_bf16 v[46:49], v[202:205], v[166:169], v[46:49]
	v_mfma_f32_16x16x32_bf16 v[42:45], v[202:205], v[178:181], v[42:45]
	v_mfma_f32_16x16x32_bf16 v[38:41], v[210:213], v[166:169], v[38:41]
	v_mfma_f32_16x16x32_bf16 v[34:37], v[210:213], v[178:181], v[34:37]
	s_setprio 0
	s_barrier
	v_readfirstlane_b32 s20, v159
	v_lshl_add_u64 v[162:163], v[242:243], 0, s[24:25]
	s_mov_b32 m0, s20
	v_readfirstlane_b32 s20, v160
	global_load_lds_dwordx4 v[162:163], off
	v_lshl_add_u64 v[162:163], v[244:245], 0, s[24:25]
	s_mov_b32 m0, s20
	s_nop 0
	global_load_lds_dwordx4 v[162:163], off
	s_waitcnt vmcnt(8)
	s_barrier
	s_setprio 1
	v_mfma_f32_16x16x32_bf16 v[30:33], v[182:185], v[214:217], v[30:33]
	v_mfma_f32_16x16x32_bf16 v[26:29], v[182:185], v[222:225], v[26:29]
	v_mfma_f32_16x16x32_bf16 v[22:25], v[190:193], v[214:217], v[22:25]
	v_mfma_f32_16x16x32_bf16 v[18:21], v[190:193], v[222:225], v[18:21]
	v_mfma_f32_16x16x32_bf16 v[14:17], v[198:201], v[214:217], v[14:17]
	v_mfma_f32_16x16x32_bf16 v[10:13], v[198:201], v[222:225], v[10:13]
	v_mfma_f32_16x16x32_bf16 v[6:9], v[206:209], v[214:217], v[6:9]
	v_mfma_f32_16x16x32_bf16 v[2:5], v[206:209], v[222:225], v[2:5]
	v_mfma_f32_16x16x32_bf16 v[30:33], v[186:189], v[218:221], v[30:33]
	v_mfma_f32_16x16x32_bf16 v[26:29], v[186:189], v[226:229], v[26:29]
	v_mfma_f32_16x16x32_bf16 v[22:25], v[194:197], v[218:221], v[22:25]
	v_mfma_f32_16x16x32_bf16 v[18:21], v[194:197], v[226:229], v[18:21]
	v_mfma_f32_16x16x32_bf16 v[14:17], v[202:205], v[218:221], v[14:17]
	v_mfma_f32_16x16x32_bf16 v[10:13], v[202:205], v[226:229], v[10:13]
	v_mfma_f32_16x16x32_bf16 v[6:9], v[210:213], v[218:221], v[6:9]
	v_mfma_f32_16x16x32_bf16 v[2:5], v[210:213], v[226:229], v[2:5]
	s_setprio 0
	s_add_i32 s5, s5, 2
	s_cmp_lt_u32 s5, 12
	s_barrier
	s_cbranch_scc1 .LBB0_346
	ds_read_b128 v[148:151], v146
	ds_read_b128 v[152:155], v146 offset:1024
	ds_read_b128 v[156:159], v146 offset:2048
	ds_read_b128 v[160:163], v146 offset:3072
	ds_read_b128 v[164:167], v138
	ds_read_b128 v[174:177], v138 offset:1024
	ds_read_b128 v[178:181], v137
	ds_read_b128 v[182:185], v137 offset:1024
	ds_read_b128 v[186:189], v136
	ds_read_b128 v[190:193], v136 offset:1024
	ds_read_b128 v[194:197], v135
	ds_read_b128 v[198:201], v135 offset:1024
	v_lshl_add_u64 v[146:147], s[26:27], 0, v[130:131]
	v_readfirstlane_b32 s5, v143
	v_lshl_add_u64 v[146:147], v[146:147], 0, s[14:15]
	s_mov_b32 m0, s5
	v_lshl_add_u64 v[132:133], s[26:27], 0, v[132:133]
	v_readfirstlane_b32 s5, v142
	global_load_lds_dwordx4 v[146:147], off
	v_lshl_add_u64 v[132:133], v[132:133], 0, s[14:15]
	s_mov_b32 m0, s5
	s_nop 0
	global_load_lds_dwordx4 v[132:133], off
	s_barrier
	s_waitcnt lgkmcnt(0)
	s_setprio 1
	s_waitcnt lgkmcnt(0)
	v_mfma_f32_16x16x32_bf16 v[126:129], v[164:167], v[148:151], v[126:129]
	v_mfma_f32_16x16x32_bf16 v[122:125], v[164:167], v[156:159], v[122:125]
	v_mfma_f32_16x16x32_bf16 v[110:113], v[186:189], v[148:151], v[110:113]
	v_mfma_f32_16x16x32_bf16 v[106:109], v[186:189], v[156:159], v[106:109]
	v_mfma_f32_16x16x32_bf16 v[126:129], v[174:177], v[152:155], v[126:129]
	v_mfma_f32_16x16x32_bf16 v[122:125], v[174:177], v[160:163], v[122:125]
	v_mfma_f32_16x16x32_bf16 v[118:121], v[178:181], v[148:151], v[118:121]
	v_mfma_f32_16x16x32_bf16 v[114:117], v[178:181], v[156:159], v[114:117]
	v_mfma_f32_16x16x32_bf16 v[110:113], v[190:193], v[152:155], v[110:113]
	v_mfma_f32_16x16x32_bf16 v[106:109], v[190:193], v[160:163], v[106:109]
	v_mfma_f32_16x16x32_bf16 v[102:105], v[194:197], v[148:151], v[102:105]
	v_mfma_f32_16x16x32_bf16 v[98:101], v[194:197], v[156:159], v[98:101]
	v_mfma_f32_16x16x32_bf16 v[202:205], v[182:185], v[152:155], v[118:121]
	v_mfma_f32_16x16x32_bf16 v[206:209], v[182:185], v[160:163], v[114:117]
	v_mfma_f32_16x16x32_bf16 v[210:213], v[198:201], v[152:155], v[102:105]
	v_mfma_f32_16x16x32_bf16 v[214:217], v[198:201], v[160:163], v[98:101]
	s_setprio 0
	s_barrier
	s_nop 1
	ds_read_b128 v[98:101], v141
	ds_read_b128 v[102:105], v141 offset:1024
	ds_read_b128 v[114:117], v141 offset:2048
	ds_read_b128 v[118:121], v141 offset:3072
	s_waitcnt vmcnt(8)
	s_barrier
; #define WAIT_V(n) asm volatile("s_waitcnt vmcnt(" #n ")" ::: "memory")
; #define WAIT_L(n) asm volatile("s_waitcnt lgkmcnt(" #n ")" ::: "memory")
; #define BAR __builtin_amdgcn_s_barrier()
; #define LDA(dst, b, h) for (int m = 0; m < 4; ++m) for (int k = 0; k < 2; ++k) \
;     dst[m][k] = *reinterpret_cast<const bf16x8*>((char*)SA(b, h) + lds_byte(wr * 64 + m * 16 + fr, k * 32 + fq * 8))
; #define LDB(dst, b, h) for (int n = 0; n < 2; ++n) for (int k = 0; k < 2; ++k) \
;     dst[n][k] = *reinterpret_cast<const bf16x8*>((char*)SB(b, h) + lds_byte(wc * 32 + n * 16 + fr, k * 32 + fq * 8))
; #define MMA(ai, bj, At_, Bt_) do { __builtin_amdgcn_s_setprio(1); \
;     for (int m = 0; m < 4; ++m) for (int n = 0; n < 2; ++n) for (int k = 0; k < 2; ++k) \
;       acc[ai][bj][m][n] = __builtin_amdgcn_mfma_f32_16x16x32_bf16(At_[m][k], Bt_[n][k], acc[ai][bj][m][n], 0, 0, 0); \
;     __builtin_amdgcn_s_setprio(0); } while (0)
; template <int K, int LD = K>
; __device__ __forceinline__ void gemm_main(const GAS bf16* A, const GAS bf16* Bt, int brow, int bcol, f32x4 (&acc)[2][2][4][2]) {
;     ...
;     LDA(At, 0, 1); WAIT_V(4); BAR; WAIT_L(0); MMA(1, 0, At, B0); MMA(1, 1, At, B1); BAR; }
;   { LDB(B0, 1, 0); LDA(At, 1, 0); WAIT_V(2); BAR; WAIT_L(0); MMA(0, 0, At, B0); BAR;
	s_waitcnt lgkmcnt(0)
	s_setprio 1
	s_waitcnt lgkmcnt(0)
	v_mfma_f32_16x16x32_bf16 v[94:97], v[164:167], v[98:101], v[94:97]
	v_mfma_f32_16x16x32_bf16 v[90:93], v[164:167], v[114:117], v[90:93]
	v_mfma_f32_16x16x32_bf16 v[78:81], v[186:189], v[98:101], v[78:81]
	v_mfma_f32_16x16x32_bf16 v[74:77], v[186:189], v[114:117], v[74:77]
	v_mfma_f32_16x16x32_bf16 v[94:97], v[174:177], v[102:105], v[94:97]
	v_mfma_f32_16x16x32_bf16 v[90:93], v[174:177], v[118:121], v[90:93]
	v_mfma_f32_16x16x32_bf16 v[86:89], v[178:181], v[98:101], v[86:89]
	v_mfma_f32_16x16x32_bf16 v[82:85], v[178:181], v[114:117], v[82:85]
	v_mfma_f32_16x16x32_bf16 v[78:81], v[190:193], v[102:105], v[78:81]
	v_mfma_f32_16x16x32_bf16 v[74:77], v[190:193], v[118:121], v[74:77]
	v_mfma_f32_16x16x32_bf16 v[70:73], v[194:197], v[98:101], v[70:73]
	v_mfma_f32_16x16x32_bf16 v[66:69], v[194:197], v[114:117], v[66:69]
	v_mfma_f32_16x16x32_bf16 v[164:167], v[182:185], v[102:105], v[86:89]
	v_mfma_f32_16x16x32_bf16 v[174:177], v[182:185], v[118:121], v[82:85]
	v_mfma_f32_16x16x32_bf16 v[178:181], v[198:201], v[102:105], v[70:73]
	v_mfma_f32_16x16x32_bf16 v[182:185], v[198:201], v[118:121], v[66:69]
	s_setprio 0
	s_barrier
	s_nop 1
	ds_read_b128 v[66:69], v138 offset:16384
	ds_read_b128 v[70:73], v138 offset:17408
	ds_read_b128 v[82:85], v137 offset:16384
	ds_read_b128 v[86:89], v137 offset:17408
	ds_read_b128 v[186:189], v136 offset:16384
	ds_read_b128 v[190:193], v136 offset:17408
	ds_read_b128 v[194:197], v135 offset:16384
	ds_read_b128 v[198:201], v135 offset:17408
	s_waitcnt vmcnt(4)
	s_barrier
	s_waitcnt lgkmcnt(0)
	s_setprio 1
	s_waitcnt lgkmcnt(0)
	v_mfma_f32_16x16x32_bf16 v[62:65], v[66:69], v[148:151], v[62:65]
	v_mfma_f32_16x16x32_bf16 v[58:61], v[66:69], v[156:159], v[58:61]
	v_mfma_f32_16x16x32_bf16 v[46:49], v[186:189], v[148:151], v[46:49]
	v_mfma_f32_16x16x32_bf16 v[42:45], v[186:189], v[156:159], v[42:45]
	v_mfma_f32_16x16x32_bf16 v[62:65], v[70:73], v[152:155], v[62:65]
	v_mfma_f32_16x16x32_bf16 v[58:61], v[70:73], v[160:163], v[58:61]
	v_mfma_f32_16x16x32_bf16 v[54:57], v[82:85], v[148:151], v[54:57]
	v_mfma_f32_16x16x32_bf16 v[50:53], v[82:85], v[156:159], v[50:53]
	v_mfma_f32_16x16x32_bf16 v[46:49], v[190:193], v[152:155], v[46:49]
	v_mfma_f32_16x16x32_bf16 v[42:45], v[190:193], v[160:163], v[42:45]
	v_mfma_f32_16x16x32_bf16 v[38:41], v[194:197], v[148:151], v[38:41]
	v_mfma_f32_16x16x32_bf16 v[34:37], v[194:197], v[156:159], v[34:37]
	v_mfma_f32_16x16x32_bf16 v[218:221], v[86:89], v[152:155], v[54:57]
	v_mfma_f32_16x16x32_bf16 v[222:225], v[86:89], v[160:163], v[50:53]
	v_mfma_f32_16x16x32_bf16 v[146:149], v[198:201], v[152:155], v[38:41]
	v_mfma_f32_16x16x32_bf16 v[150:153], v[198:201], v[160:163], v[34:37]
	s_setprio 0
	s_setprio 1
	v_mfma_f32_16x16x32_bf16 v[30:33], v[66:69], v[98:101], v[30:33]
	v_mfma_f32_16x16x32_bf16 v[26:29], v[66:69], v[114:117], v[26:29]
	v_mfma_f32_16x16x32_bf16 v[14:17], v[186:189], v[98:101], v[14:17]
	v_mfma_f32_16x16x32_bf16 v[10:13], v[186:189], v[114:117], v[10:13]
	v_mfma_f32_16x16x32_bf16 v[30:33], v[70:73], v[102:105], v[30:33]
	v_mfma_f32_16x16x32_bf16 v[26:29], v[70:73], v[118:121], v[26:29]
	v_mfma_f32_16x16x32_bf16 v[22:25], v[82:85], v[98:101], v[22:25]
	v_mfma_f32_16x16x32_bf16 v[18:21], v[82:85], v[114:117], v[18:21]
	v_mfma_f32_16x16x32_bf16 v[14:17], v[190:193], v[102:105], v[14:17]
	v_mfma_f32_16x16x32_bf16 v[10:13], v[190:193], v[118:121], v[10:13]
	v_mfma_f32_16x16x32_bf16 v[6:9], v[194:197], v[98:101], v[6:9]
	v_mfma_f32_16x16x32_bf16 v[2:5], v[194:197], v[114:117], v[2:5]
	v_mfma_f32_16x16x32_bf16 v[154:157], v[86:89], v[102:105], v[22:25]
	v_mfma_f32_16x16x32_bf16 v[158:161], v[86:89], v[118:121], v[18:21]
	v_mfma_f32_16x16x32_bf16 v[186:189], v[198:201], v[102:105], v[6:9]
	v_mfma_f32_16x16x32_bf16 v[190:193], v[198:201], v[118:121], v[2:5]
	s_setprio 0
	s_barrier
	s_nop 1
	ds_read_b128 v[2:5], v140
	ds_read_b128 v[6:9], v140 offset:1024
	ds_read_b128 v[194:197], v140 offset:2048
	ds_read_b128 v[140:143], v140 offset:3072
	ds_read_b128 v[18:21], v138 offset:32768
	ds_read_b128 v[22:25], v138 offset:33792
	ds_read_b128 v[34:37], v137 offset:32768
	ds_read_b128 v[38:41], v137 offset:33792
	ds_read_b128 v[50:53], v136 offset:32768
	ds_read_b128 v[54:57], v136 offset:33792
	ds_read_b128 v[198:201], v135 offset:32768
	ds_read_b128 v[226:229], v135 offset:33792
	s_waitcnt vmcnt(2)
	s_barrier
; #define WAIT_V(n) asm volatile("s_waitcnt vmcnt(" #n ")" ::: "memory")
; #define WAIT_L(n) asm volatile("s_waitcnt lgkmcnt(" #n ")" ::: "memory")
; #define BAR __builtin_amdgcn_s_barrier()
; #define LDA(dst, b, h) for (int m = 0; m < 4; ++m) for (int k = 0; k < 2; ++k) \
;     dst[m][k] = *reinterpret_cast<const bf16x8*>((char*)SA(b, h) + lds_byte(wr * 64 + m * 16 + fr, k * 32 + fq * 8))
; #define LDB(dst, b, h) for (int n = 0; n < 2; ++n) for (int k = 0; k < 2; ++k) \
;     dst[n][k] = *reinterpret_cast<const bf16x8*>((char*)SB(b, h) + lds_byte(wc * 32 + n * 16 + fr, k * 32 + fq * 8))
; #define MMA(ai, bj, At_, Bt_) do { __builtin_amdgcn_s_setprio(1); \
;     for (int m = 0; m < 4; ++m) for (int n = 0; n < 2; ++n) for (int k = 0; k < 2; ++k) \
;       acc[ai][bj][m][n] = __builtin_amdgcn_mfma_f32_16x16x32_bf16(At_[m][k], Bt_[n][k], acc[ai][bj][m][n], 0, 0, 0); \
;     __builtin_amdgcn_s_setprio(0); } while (0)
; template <int K, int LD = K>
; __device__ __forceinline__ void gemm_main(const GAS bf16* A, const GAS bf16* Bt, int brow, int bcol, f32x4 (&acc)[2][2][4][2]) {
;     ...
;   { LDB(B0, 1, 0); LDA(At, 1, 0); WAIT_V(2); BAR; WAIT_L(0); MMA(0, 0, At, B0); BAR;
;     LDB(B1, 1, 1); WAIT_V(0); BAR; WAIT_L(0); MMA(0, 1, At, B1); BAR;
;     LDA(At, 1, 1); BAR; WAIT_L(0); MMA(1, 0, At, B0); MMA(1, 1, At, B1); BAR; }
;   if (wr == 0) BAR;
	s_waitcnt lgkmcnt(0)
	s_setprio 1
	s_waitcnt lgkmcnt(0)
	v_mfma_f32_16x16x32_bf16 v[66:69], v[18:21], v[2:5], v[126:129]
	v_mfma_f32_16x16x32_bf16 v[114:117], v[22:25], v[6:9], v[66:69]
	v_mfma_f32_16x16x32_bf16 v[66:69], v[18:21], v[194:197], v[122:125]
	v_mfma_f32_16x16x32_bf16 v[118:121], v[22:25], v[140:143], v[66:69]
	v_mfma_f32_16x16x32_bf16 v[66:69], v[34:37], v[2:5], v[202:205]
	v_mfma_f32_16x16x32_bf16 v[102:105], v[38:41], v[6:9], v[66:69]
	v_mfma_f32_16x16x32_bf16 v[66:69], v[34:37], v[194:197], v[206:209]
	v_mfma_f32_16x16x32_bf16 v[98:101], v[38:41], v[140:143], v[66:69]
	v_mfma_f32_16x16x32_bf16 v[66:69], v[50:53], v[2:5], v[110:113]
	v_mfma_f32_16x16x32_bf16 v[82:85], v[54:57], v[6:9], v[66:69]
	v_mfma_f32_16x16x32_bf16 v[66:69], v[50:53], v[194:197], v[106:109]
	v_mfma_f32_16x16x32_bf16 v[86:89], v[54:57], v[140:143], v[66:69]
	v_mfma_f32_16x16x32_bf16 v[66:69], v[198:201], v[2:5], v[210:213]
	v_mfma_f32_16x16x32_bf16 v[70:73], v[226:229], v[6:9], v[66:69]
	v_mfma_f32_16x16x32_bf16 v[66:69], v[198:201], v[194:197], v[214:217]
	v_mfma_f32_16x16x32_bf16 v[66:69], v[226:229], v[140:143], v[66:69]
	s_setprio 0
	s_barrier
	ds_read_b128 v[202:205], v139
	ds_read_b128 v[206:209], v139 offset:1024
	ds_read_b128 v[210:213], v139 offset:2048
	ds_read_b128 v[214:217], v139 offset:3072
	s_waitcnt vmcnt(0)
	s_barrier
	s_waitcnt lgkmcnt(0)
	s_setprio 1
	s_waitcnt lgkmcnt(0)
	v_mfma_f32_16x16x32_bf16 v[94:97], v[18:21], v[202:205], v[94:97]
	v_mfma_f32_16x16x32_bf16 v[18:21], v[18:21], v[210:213], v[90:93]
	v_mfma_f32_16x16x32_bf16 v[126:129], v[22:25], v[214:217], v[18:21]
	v_mfma_f32_16x16x32_bf16 v[18:21], v[34:37], v[202:205], v[164:167]
	v_mfma_f32_16x16x32_bf16 v[106:109], v[38:41], v[206:209], v[18:21]
	v_mfma_f32_16x16x32_bf16 v[18:21], v[34:37], v[210:213], v[174:177]
	v_mfma_f32_16x16x32_bf16 v[110:113], v[38:41], v[214:217], v[18:21]
	v_mfma_f32_16x16x32_bf16 v[18:21], v[50:53], v[202:205], v[78:81]
	v_mfma_f32_16x16x32_bf16 v[90:93], v[54:57], v[206:209], v[18:21]
	v_mfma_f32_16x16x32_bf16 v[18:21], v[50:53], v[210:213], v[74:77]
	v_mfma_f32_16x16x32_bf16 v[122:125], v[22:25], v[206:209], v[94:97]
	v_mfma_f32_16x16x32_bf16 v[94:97], v[54:57], v[214:217], v[18:21]
	v_mfma_f32_16x16x32_bf16 v[18:21], v[198:201], v[202:205], v[178:181]
	v_mfma_f32_16x16x32_bf16 v[74:77], v[226:229], v[206:209], v[18:21]
	v_mfma_f32_16x16x32_bf16 v[18:21], v[198:201], v[210:213], v[182:185]
	v_mfma_f32_16x16x32_bf16 v[78:81], v[226:229], v[214:217], v[18:21]
	s_setprio 0
	s_barrier
	ds_read_b128 v[162:165], v138 offset:49152
	ds_read_b128 v[166:169], v138 offset:50176
	ds_read_b128 v[174:177], v137 offset:49152
	ds_read_b128 v[178:181], v137 offset:50176
	ds_read_b128 v[182:185], v136 offset:49152
	ds_read_b128 v[136:139], v136 offset:50176
	ds_read_b128 v[198:201], v135 offset:49152
	ds_read_b128 v[226:229], v135 offset:50176
	s_barrier
	s_waitcnt lgkmcnt(0)
	s_setprio 1
	s_waitcnt lgkmcnt(0)
	v_mfma_f32_16x16x32_bf16 v[18:21], v[162:165], v[2:5], v[62:65]
	v_mfma_f32_16x16x32_bf16 v[50:53], v[166:169], v[6:9], v[18:21]
	v_mfma_f32_16x16x32_bf16 v[18:21], v[162:165], v[194:197], v[58:61]
	v_mfma_f32_16x16x32_bf16 v[54:57], v[166:169], v[140:143], v[18:21]
	v_mfma_f32_16x16x32_bf16 v[18:21], v[174:177], v[2:5], v[218:221]
	v_mfma_f32_16x16x32_bf16 v[38:41], v[178:181], v[6:9], v[18:21]
	v_mfma_f32_16x16x32_bf16 v[18:21], v[174:177], v[194:197], v[222:225]
	v_mfma_f32_16x16x32_bf16 v[34:37], v[178:181], v[140:143], v[18:21]
	v_mfma_f32_16x16x32_bf16 v[18:21], v[182:185], v[2:5], v[46:49]
	v_mfma_f32_16x16x32_bf16 v[2:5], v[198:201], v[2:5], v[146:149]
	v_mfma_f32_16x16x32_bf16 v[18:21], v[136:139], v[6:9], v[18:21]
	v_mfma_f32_16x16x32_bf16 v[22:25], v[182:185], v[194:197], v[42:45]
	v_mfma_f32_16x16x32_bf16 v[6:9], v[226:229], v[6:9], v[2:5]
	v_mfma_f32_16x16x32_bf16 v[2:5], v[198:201], v[194:197], v[150:153]
	v_mfma_f32_16x16x32_bf16 v[22:25], v[136:139], v[140:143], v[22:25]
	v_mfma_f32_16x16x32_bf16 v[2:5], v[226:229], v[140:143], v[2:5]
	s_setprio 0
	s_setprio 1
	v_mfma_f32_16x16x32_bf16 v[26:29], v[162:165], v[210:213], v[26:29]
	v_mfma_f32_16x16x32_bf16 v[62:65], v[166:169], v[214:217], v[26:29]
	v_mfma_f32_16x16x32_bf16 v[26:29], v[174:177], v[202:205], v[154:157]
	v_mfma_f32_16x16x32_bf16 v[30:33], v[162:165], v[202:205], v[30:33]
	v_mfma_f32_16x16x32_bf16 v[42:45], v[178:181], v[206:209], v[26:29]
	v_mfma_f32_16x16x32_bf16 v[26:29], v[174:177], v[210:213], v[158:161]
	v_mfma_f32_16x16x32_bf16 v[14:17], v[182:185], v[202:205], v[14:17]
	v_mfma_f32_16x16x32_bf16 v[10:13], v[182:185], v[210:213], v[10:13]
	v_mfma_f32_16x16x32_bf16 v[58:61], v[166:169], v[206:209], v[30:33]
	v_mfma_f32_16x16x32_bf16 v[46:49], v[178:181], v[214:217], v[26:29]
	v_mfma_f32_16x16x32_bf16 v[26:29], v[136:139], v[206:209], v[14:17]
	v_mfma_f32_16x16x32_bf16 v[30:33], v[136:139], v[214:217], v[10:13]
	v_mfma_f32_16x16x32_bf16 v[10:13], v[198:201], v[202:205], v[186:189]
	v_mfma_f32_16x16x32_bf16 v[14:17], v[198:201], v[210:213], v[190:193]
	v_mfma_f32_16x16x32_bf16 v[10:13], v[226:229], v[206:209], v[10:13]
	v_mfma_f32_16x16x32_bf16 v[14:17], v[226:229], v[214:217], v[14:17]
	s_setprio 0
	v_cmp_gt_u32_e32 vcc, s48, v134
	s_barrier
	s_and_saveexec_b64 s[26:27], vcc
	s_cbranch_execz .LBB0_349
	s_barrier

; #define STAGE(P, GP, ktrel) do { const GAS char* _g = (GP) + (ktrel) * (BK * 2); \
;     __builtin_amdgcn_global_load_lds((const GAS unsigned*)(_g + so0), (unsigned*)((char*)(P) + tid_ * 16), 16, 0, 0); \
;     __builtin_amdgcn_global_load_lds((const GAS unsigned*)(_g + so1), (unsigned*)((char*)(P) + tid_ * 16 + 8192), 16, 0, 0); } while (0)
; #define WAIT_V(n) asm volatile("s_waitcnt vmcnt(" #n ")" ::: "memory")
; #define WAIT_L(n) asm volatile("s_waitcnt lgkmcnt(" #n ")" ::: "memory")
; #define BAR __builtin_amdgcn_s_barrier()
; #define SCHED __builtin_amdgcn_sched_barrier(0)
; #define LDA(dst, b, h) for (int m = 0; m < 4; ++m) for (int k = 0; k < 2; ++k) \
;     dst[m][k] = *reinterpret_cast<const bf16x8*>((char*)SA(b, h) + lds_byte(wr * 64 + m * 16 + fr, k * 32 + fq * 8))
; #define LDB(dst, b, h) for (int n = 0; n < 2; ++n) for (int k = 0; k < 2; ++k) \
;     dst[n][k] = *reinterpret_cast<const bf16x8*>((char*)SB(b, h) + lds_byte(wc * 32 + n * 16 + fr, k * 32 + fq * 8))
; #define MMA(ai, bj, At_, Bt_) do { __builtin_amdgcn_s_setprio(1); \
;     for (int m = 0; m < 4; ++m) for (int n = 0; n < 2; ++n) for (int k = 0; k < 2; ++k) \
;       acc[ai][bj][m][n] = __builtin_amdgcn_mfma_f32_16x16x32_bf16(At_[m][k], Bt_[n][k], acc[ai][bj][m][n], 0, 0, 0); \
;     __builtin_amdgcn_s_setprio(0); } while (0)
; template <int K, int LD = K>
; __device__ __forceinline__ void gemm_main(const GAS bf16* A, const GAS bf16* Bt, int brow, int bcol, f32x4 (&acc)[2][2][4][2]) {
;     ...
;     LDB(B0, 0, 0); SCHED; LDA(At, 0, 0); STAGE(SA(1, 1), pA1, 1);
;     WAIT_L(8); BAR; WAIT_L(0); MMA(0, 0, At, B0); BAR; SCHED;
;     LDB(B1, 0, 1); STAGE(SB(0, 0), pB0, 2);
;     BAR; WAIT_L(0); MMA(0, 1, At, B1); BAR;
;     LDA(At, 0, 1); STAGE(SA(0, 0), pA0, 2);
;     BAR; WAIT_L(0); MMA(1, 0, At, B0); BAR; SCHED;
;     STAGE(SB(0, 1), pB1, 2);
;     WAIT_V(6); BAR; MMA(1, 1, At, B1); BAR;
.LBB0_709:
	ds_read_b128 v[146:149], v143
	ds_read_b128 v[150:153], v143 offset:1024
	ds_read_b128 v[154:157], v143 offset:2048
	ds_read_b128 v[158:161], v143 offset:3072
	v_add_u32_e32 v230, 0x100, v141
	v_add_u32_e32 v144, 0xc000, v230
	v_lshl_add_u64 v[214:215], s[20:21], 0, v[130:131]
	v_readfirstlane_b32 s30, v144
	v_add_u32_e32 v145, 0xe000, v230
	v_lshl_add_u64 v[198:199], v[214:215], 0, s[6:7]
	s_mov_b32 m0, s30
	v_lshl_add_u64 v[216:217], s[20:21], 0, v[132:133]
	v_readfirstlane_b32 s30, v145
	ds_read_b128 v[162:165], v138
	ds_read_b128 v[166:169], v138 offset:1024
	ds_read_b128 v[174:177], v137
	ds_read_b128 v[178:181], v137 offset:1024
	ds_read_b128 v[182:185], v136
	ds_read_b128 v[186:189], v136 offset:1024
	ds_read_b128 v[190:193], v135
	ds_read_b128 v[194:197], v135 offset:1024
	global_load_lds_dwordx4 v[198:199], off
	v_lshl_add_u64 v[198:199], v[216:217], 0, s[6:7]
	s_mov_b32 m0, s30
	s_nop 0
	global_load_lds_dwordx4 v[198:199], off
	s_waitcnt lgkmcnt(8)
	s_barrier
	s_waitcnt lgkmcnt(0)
	s_setprio 1
	s_waitcnt lgkmcnt(0)
	v_mfma_f32_16x16x32_bf16 v[126:129], v[162:165], v[146:149], v[126:129]
	v_mfma_f32_16x16x32_bf16 v[122:125], v[162:165], v[154:157], v[122:125]
	v_mfma_f32_16x16x32_bf16 v[118:121], v[174:177], v[146:149], v[118:121]
	v_mfma_f32_16x16x32_bf16 v[114:117], v[174:177], v[154:157], v[114:117]
	v_mfma_f32_16x16x32_bf16 v[110:113], v[182:185], v[146:149], v[110:113]
	v_mfma_f32_16x16x32_bf16 v[106:109], v[182:185], v[154:157], v[106:109]
	v_mfma_f32_16x16x32_bf16 v[102:105], v[190:193], v[146:149], v[102:105]
	v_mfma_f32_16x16x32_bf16 v[98:101], v[190:193], v[154:157], v[98:101]
	v_mfma_f32_16x16x32_bf16 v[126:129], v[166:169], v[150:153], v[126:129]
	v_mfma_f32_16x16x32_bf16 v[122:125], v[166:169], v[158:161], v[122:125]
	v_mfma_f32_16x16x32_bf16 v[118:121], v[178:181], v[150:153], v[118:121]
	v_mfma_f32_16x16x32_bf16 v[114:117], v[178:181], v[158:161], v[114:117]
	v_mfma_f32_16x16x32_bf16 v[110:113], v[186:189], v[150:153], v[110:113]
	v_mfma_f32_16x16x32_bf16 v[106:109], v[186:189], v[158:161], v[106:109]
	v_mfma_f32_16x16x32_bf16 v[102:105], v[194:197], v[150:153], v[102:105]
	v_mfma_f32_16x16x32_bf16 v[98:101], v[194:197], v[158:161], v[98:101]
	s_setprio 0
	s_barrier
	v_add_u32_e32 v224, s47, v141
	v_lshl_add_u64 v[218:219], s[28:29], 0, v[130:131]
	v_readfirstlane_b32 s30, v224
	v_lshl_add_u64 v[220:221], v[218:219], 0, s[10:11]
	s_mov_b32 m0, s30
	v_add_u32_e32 v224, 0x2000, v224
	ds_read_b128 v[198:201], v142
	ds_read_b128 v[202:205], v142 offset:1024
	ds_read_b128 v[206:209], v142 offset:2048
	ds_read_b128 v[210:213], v142 offset:3072
	global_load_lds_dwordx4 v[220:221], off
	v_lshl_add_u64 v[220:221], s[28:29], 0, v[132:133]
	v_readfirstlane_b32 s30, v224
	v_lshl_add_u64 v[222:223], v[220:221], 0, s[10:11]
	s_mov_b32 m0, s30
	s_add_u32 s28, s28, 0x100
	global_load_lds_dwordx4 v[222:223], off
	s_waitcnt vmcnt(10)
	s_barrier
	s_waitcnt lgkmcnt(0)
	s_addc_u32 s29, s29, 0
	s_setprio 1
	s_waitcnt lgkmcnt(0)
	v_mfma_f32_16x16x32_bf16 v[94:97], v[162:165], v[198:201], v[94:97]
	v_mfma_f32_16x16x32_bf16 v[90:93], v[162:165], v[206:209], v[90:93]
	v_mfma_f32_16x16x32_bf16 v[86:89], v[174:177], v[198:201], v[86:89]
	v_mfma_f32_16x16x32_bf16 v[82:85], v[174:177], v[206:209], v[82:85]
	v_mfma_f32_16x16x32_bf16 v[78:81], v[182:185], v[198:201], v[78:81]
	v_mfma_f32_16x16x32_bf16 v[74:77], v[182:185], v[206:209], v[74:77]
	v_mfma_f32_16x16x32_bf16 v[70:73], v[190:193], v[198:201], v[70:73]
	v_mfma_f32_16x16x32_bf16 v[66:69], v[190:193], v[206:209], v[66:69]
	v_mfma_f32_16x16x32_bf16 v[94:97], v[166:169], v[202:205], v[94:97]
	v_mfma_f32_16x16x32_bf16 v[90:93], v[166:169], v[210:213], v[90:93]
	v_mfma_f32_16x16x32_bf16 v[86:89], v[178:181], v[202:205], v[86:89]
	v_mfma_f32_16x16x32_bf16 v[82:85], v[178:181], v[210:213], v[82:85]
	v_mfma_f32_16x16x32_bf16 v[78:81], v[186:189], v[202:205], v[78:81]
	v_mfma_f32_16x16x32_bf16 v[74:77], v[186:189], v[210:213], v[74:77]
	v_mfma_f32_16x16x32_bf16 v[70:73], v[194:197], v[202:205], v[70:73]
	v_mfma_f32_16x16x32_bf16 v[66:69], v[194:197], v[210:213], v[66:69]
	s_setprio 0
	v_lshl_add_u64 v[222:223], s[26:27], 0, v[130:131]
	v_readfirstlane_b32 s30, v230
	v_lshl_add_u64 v[224:225], v[222:223], 0, s[10:11]
	s_mov_b32 m0, s30
	v_add_u32_e32 v228, 0x2000, v230
	s_barrier
	ds_read_b128 v[162:165], v138 offset:16384
	ds_read_b128 v[166:169], v138 offset:17408
	ds_read_b128 v[174:177], v137 offset:16384
	ds_read_b128 v[178:181], v137 offset:17408
	ds_read_b128 v[182:185], v136 offset:16384
	ds_read_b128 v[186:189], v136 offset:17408
	ds_read_b128 v[190:193], v135 offset:16384
	ds_read_b128 v[194:197], v135 offset:17408
	global_load_lds_dwordx4 v[224:225], off
	v_lshl_add_u64 v[224:225], s[26:27], 0, v[132:133]
	v_readfirstlane_b32 s30, v228
	v_lshl_add_u64 v[226:227], v[224:225], 0, s[10:11]
	s_mov_b32 m0, s30
	s_add_u32 s26, s26, 0x100
	global_load_lds_dwordx4 v[226:227], off
	s_barrier
	s_waitcnt lgkmcnt(0)
	s_addc_u32 s27, s27, 0
	s_setprio 1
	s_waitcnt lgkmcnt(0)
	v_mfma_f32_16x16x32_bf16 v[62:65], v[162:165], v[146:149], v[62:65]
	v_mfma_f32_16x16x32_bf16 v[58:61], v[162:165], v[154:157], v[58:61]
	v_mfma_f32_16x16x32_bf16 v[54:57], v[174:177], v[146:149], v[54:57]
	v_mfma_f32_16x16x32_bf16 v[50:53], v[174:177], v[154:157], v[50:53]
	v_mfma_f32_16x16x32_bf16 v[46:49], v[182:185], v[146:149], v[46:49]
	v_mfma_f32_16x16x32_bf16 v[42:45], v[182:185], v[154:157], v[42:45]
	v_mfma_f32_16x16x32_bf16 v[38:41], v[190:193], v[146:149], v[38:41]
	v_mfma_f32_16x16x32_bf16 v[34:37], v[190:193], v[154:157], v[34:37]
	v_mfma_f32_16x16x32_bf16 v[62:65], v[166:169], v[150:153], v[62:65]
	v_mfma_f32_16x16x32_bf16 v[58:61], v[166:169], v[158:161], v[58:61]
	v_mfma_f32_16x16x32_bf16 v[54:57], v[178:181], v[150:153], v[54:57]
	v_mfma_f32_16x16x32_bf16 v[50:53], v[178:181], v[158:161], v[50:53]
	v_mfma_f32_16x16x32_bf16 v[46:49], v[186:189], v[150:153], v[46:49]
	v_mfma_f32_16x16x32_bf16 v[42:45], v[186:189], v[158:161], v[42:45]
	v_mfma_f32_16x16x32_bf16 v[38:41], v[194:197], v[150:153], v[38:41]
	v_mfma_f32_16x16x32_bf16 v[34:37], v[194:197], v[158:161], v[34:37]
	s_setprio 0
	s_barrier
; #define STAGE(P, GP, ktrel) do { const GAS char* _g = (GP) + (ktrel) * (BK * 2); \
;     __builtin_amdgcn_global_load_lds((const GAS unsigned*)(_g + so0), (unsigned*)((char*)(P) + tid_ * 16), 16, 0, 0); \
;     __builtin_amdgcn_global_load_lds((const GAS unsigned*)(_g + so1), (unsigned*)((char*)(P) + tid_ * 16 + 8192), 16, 0, 0); } while (0)
; #define WAIT_V(n) asm volatile("s_waitcnt vmcnt(" #n ")" ::: "memory")
; #define WAIT_L(n) asm volatile("s_waitcnt lgkmcnt(" #n ")" ::: "memory")
; #define BAR __builtin_amdgcn_s_barrier()
; #define SCHED __builtin_amdgcn_sched_barrier(0)
; #define LDA(dst, b, h) for (int m = 0; m < 4; ++m) for (int k = 0; k < 2; ++k) \
;     dst[m][k] = *reinterpret_cast<const bf16x8*>((char*)SA(b, h) + lds_byte(wr * 64 + m * 16 + fr, k * 32 + fq * 8))
; #define LDB(dst, b, h) for (int n = 0; n < 2; ++n) for (int k = 0; k < 2; ++k) \
;     dst[n][k] = *reinterpret_cast<const bf16x8*>((char*)SB(b, h) + lds_byte(wc * 32 + n * 16 + fr, k * 32 + fq * 8))
; #define MMA(ai, bj, At_, Bt_) do { __builtin_amdgcn_s_setprio(1); \
;     for (int m = 0; m < 4; ++m) for (int n = 0; n < 2; ++n) for (int k = 0; k < 2; ++k) \
;       acc[ai][bj][m][n] = __builtin_amdgcn_mfma_f32_16x16x32_bf16(At_[m][k], Bt_[n][k], acc[ai][bj][m][n], 0, 0, 0); \
;     __builtin_amdgcn_s_setprio(0); } while (0)
; template <int K, int LD = K>
; __device__ __forceinline__ void gemm_main(const GAS bf16* A, const GAS bf16* Bt, int brow, int bcol, f32x4 (&acc)[2][2][4][2]) {
;     ...
;     WAIT_V(6); BAR; MMA(1, 1, At, B1); BAR;
;     LDB(B0, 1, 0); SCHED; LDA(At, 1, 0); STAGE(SA(0, 1), pA1, 2);
;     WAIT_L(8); BAR; WAIT_L(0); MMA(0, 0, At, B0); BAR; SCHED;
;     LDB(B1, 1, 1); STAGE(SB(1, 0), pB0, 3);
;     BAR; WAIT_L(0); MMA(0, 1, At, B1); BAR;
;     LDA(At, 1, 1); STAGE(SA(1, 0), pA0, 3);
;     BAR; WAIT_L(0); MMA(1, 0, At, B0); BAR; SCHED;
;     STAGE(SB(1, 1), pB1, 3);
;     WAIT_V(6); BAR; MMA(1, 1, At, B1); BAR;
	v_add_u32_e32 v148, s48, v141
	v_lshl_add_u64 v[226:227], s[24:25], 0, v[130:131]
	v_readfirstlane_b32 s30, v148
	v_add_u32_e32 v148, 0x2000, v148
	v_lshl_add_u64 v[146:147], v[226:227], 0, s[10:11]
	s_mov_b32 m0, s30
	v_lshl_add_u64 v[228:229], s[24:25], 0, v[132:133]
	v_readfirstlane_b32 s30, v148
	global_load_lds_dwordx4 v[146:147], off
	v_lshl_add_u64 v[146:147], v[228:229], 0, s[10:11]
	s_mov_b32 m0, s30
	s_add_u32 s24, s24, 0x100
	global_load_lds_dwordx4 v[146:147], off
	s_waitcnt vmcnt(8)
	s_addc_u32 s25, s25, 0
	s_barrier
	s_setprio 1
	v_mfma_f32_16x16x32_bf16 v[30:33], v[162:165], v[198:201], v[30:33]
	v_mfma_f32_16x16x32_bf16 v[26:29], v[162:165], v[206:209], v[26:29]
	v_mfma_f32_16x16x32_bf16 v[22:25], v[174:177], v[198:201], v[22:25]
	v_mfma_f32_16x16x32_bf16 v[18:21], v[174:177], v[206:209], v[18:21]
	v_mfma_f32_16x16x32_bf16 v[14:17], v[182:185], v[198:201], v[14:17]
	v_mfma_f32_16x16x32_bf16 v[10:13], v[182:185], v[206:209], v[10:13]
	v_mfma_f32_16x16x32_bf16 v[6:9], v[190:193], v[198:201], v[6:9]
	v_mfma_f32_16x16x32_bf16 v[2:5], v[190:193], v[206:209], v[2:5]
	v_mfma_f32_16x16x32_bf16 v[30:33], v[166:169], v[202:205], v[30:33]
	v_mfma_f32_16x16x32_bf16 v[26:29], v[166:169], v[210:213], v[26:29]
	v_mfma_f32_16x16x32_bf16 v[22:25], v[178:181], v[202:205], v[22:25]
	v_mfma_f32_16x16x32_bf16 v[18:21], v[178:181], v[210:213], v[18:21]
	v_mfma_f32_16x16x32_bf16 v[14:17], v[186:189], v[202:205], v[14:17]
	v_mfma_f32_16x16x32_bf16 v[10:13], v[186:189], v[210:213], v[10:13]
	v_mfma_f32_16x16x32_bf16 v[6:9], v[194:197], v[202:205], v[6:9]
	v_mfma_f32_16x16x32_bf16 v[2:5], v[194:197], v[210:213], v[2:5]
	s_setprio 0
	s_barrier
	ds_read_b128 v[146:149], v140
	ds_read_b128 v[150:153], v140 offset:1024
	ds_read_b128 v[154:157], v140 offset:2048
	ds_read_b128 v[158:161], v140 offset:3072
	v_add_u32_e32 v200, 0x4000, v230
	v_lshl_add_u64 v[198:199], v[214:215], 0, s[10:11]
	v_readfirstlane_b32 s30, v200
	v_add_u32_e32 v200, 0x6000, v230
	s_mov_b32 m0, s30
	v_readfirstlane_b32 s30, v200
	ds_read_b128 v[162:165], v138 offset:32768
	ds_read_b128 v[166:169], v138 offset:33792
	ds_read_b128 v[174:177], v137 offset:32768
	ds_read_b128 v[178:181], v137 offset:33792
	ds_read_b128 v[182:185], v136 offset:32768
	ds_read_b128 v[186:189], v136 offset:33792
	ds_read_b128 v[190:193], v135 offset:32768
	ds_read_b128 v[194:197], v135 offset:33792
	global_load_lds_dwordx4 v[198:199], off
	v_lshl_add_u64 v[198:199], v[216:217], 0, s[10:11]
	s_mov_b32 m0, s30
	s_add_u32 s20, s20, 0x100
	global_load_lds_dwordx4 v[198:199], off
	s_waitcnt lgkmcnt(8)
	s_barrier
	s_waitcnt lgkmcnt(0)
	s_addc_u32 s21, s21, 0
	s_setprio 1
	s_waitcnt lgkmcnt(0)
	v_mfma_f32_16x16x32_bf16 v[126:129], v[162:165], v[146:149], v[126:129]
	v_mfma_f32_16x16x32_bf16 v[122:125], v[162:165], v[154:157], v[122:125]
	v_mfma_f32_16x16x32_bf16 v[118:121], v[174:177], v[146:149], v[118:121]
	v_mfma_f32_16x16x32_bf16 v[114:117], v[174:177], v[154:157], v[114:117]
	v_mfma_f32_16x16x32_bf16 v[110:113], v[182:185], v[146:149], v[110:113]
	v_mfma_f32_16x16x32_bf16 v[106:109], v[182:185], v[154:157], v[106:109]
	v_mfma_f32_16x16x32_bf16 v[102:105], v[190:193], v[146:149], v[102:105]
	v_mfma_f32_16x16x32_bf16 v[98:101], v[190:193], v[154:157], v[98:101]
	v_mfma_f32_16x16x32_bf16 v[126:129], v[166:169], v[150:153], v[126:129]
	v_mfma_f32_16x16x32_bf16 v[122:125], v[166:169], v[158:161], v[122:125]
	v_mfma_f32_16x16x32_bf16 v[118:121], v[178:181], v[150:153], v[118:121]
	v_mfma_f32_16x16x32_bf16 v[114:117], v[178:181], v[158:161], v[114:117]
	v_mfma_f32_16x16x32_bf16 v[110:113], v[186:189], v[150:153], v[110:113]
	v_mfma_f32_16x16x32_bf16 v[106:109], v[186:189], v[158:161], v[106:109]
	v_mfma_f32_16x16x32_bf16 v[102:105], v[194:197], v[150:153], v[102:105]
	v_mfma_f32_16x16x32_bf16 v[98:101], v[194:197], v[158:161], v[98:101]
	s_setprio 0
	s_barrier
	v_add_u32_e32 v216, s49, v141
	v_lshl_add_u64 v[214:215], v[218:219], 0, s[12:13]
	v_readfirstlane_b32 s30, v216
	v_add_u32_e32 v216, 0x2000, v216
	s_mov_b32 m0, s30
	v_readfirstlane_b32 s30, v216
	ds_read_b128 v[198:201], v139
	ds_read_b128 v[202:205], v139 offset:1024
	ds_read_b128 v[206:209], v139 offset:2048
	ds_read_b128 v[210:213], v139 offset:3072
	global_load_lds_dwordx4 v[214:215], off
	v_lshl_add_u64 v[214:215], v[220:221], 0, s[12:13]
	s_mov_b32 m0, s30
	s_nop 0
	global_load_lds_dwordx4 v[214:215], off
	s_waitcnt vmcnt(10)
	s_barrier
	s_waitcnt lgkmcnt(0)
	s_setprio 1
	s_waitcnt lgkmcnt(0)
	v_mfma_f32_16x16x32_bf16 v[94:97], v[162:165], v[198:201], v[94:97]
	v_mfma_f32_16x16x32_bf16 v[90:93], v[162:165], v[206:209], v[90:93]
	v_mfma_f32_16x16x32_bf16 v[86:89], v[174:177], v[198:201], v[86:89]
	v_mfma_f32_16x16x32_bf16 v[82:85], v[174:177], v[206:209], v[82:85]
	v_mfma_f32_16x16x32_bf16 v[78:81], v[182:185], v[198:201], v[78:81]
	v_mfma_f32_16x16x32_bf16 v[74:77], v[182:185], v[206:209], v[74:77]
	v_mfma_f32_16x16x32_bf16 v[70:73], v[190:193], v[198:201], v[70:73]
	v_mfma_f32_16x16x32_bf16 v[66:69], v[190:193], v[206:209], v[66:69]
	v_mfma_f32_16x16x32_bf16 v[94:97], v[166:169], v[202:205], v[94:97]
	v_mfma_f32_16x16x32_bf16 v[90:93], v[166:169], v[210:213], v[90:93]
	v_mfma_f32_16x16x32_bf16 v[86:89], v[178:181], v[202:205], v[86:89]
	v_mfma_f32_16x16x32_bf16 v[82:85], v[178:181], v[210:213], v[82:85]
	v_mfma_f32_16x16x32_bf16 v[78:81], v[186:189], v[202:205], v[78:81]
	v_mfma_f32_16x16x32_bf16 v[74:77], v[186:189], v[210:213], v[74:77]
	v_mfma_f32_16x16x32_bf16 v[70:73], v[194:197], v[202:205], v[70:73]
	v_mfma_f32_16x16x32_bf16 v[66:69], v[194:197], v[210:213], v[66:69]
	s_setprio 0
	v_add_u32_e32 v216, 0x8000, v230
	v_lshl_add_u64 v[214:215], v[222:223], 0, s[12:13]
	v_readfirstlane_b32 s30, v216
	v_add_u32_e32 v216, 0xa000, v230
	s_mov_b32 m0, s30
	v_readfirstlane_b32 s30, v216
	s_barrier
; #define STAGE(P, GP, ktrel) do { const GAS char* _g = (GP) + (ktrel) * (BK * 2); \
;     __builtin_amdgcn_global_load_lds((const GAS unsigned*)(_g + so0), (unsigned*)((char*)(P) + tid_ * 16), 16, 0, 0); \
;     __builtin_amdgcn_global_load_lds((const GAS unsigned*)(_g + so1), (unsigned*)((char*)(P) + tid_ * 16 + 8192), 16, 0, 0); } while (0)
; #define WAIT_V(n) asm volatile("s_waitcnt vmcnt(" #n ")" ::: "memory")
; #define WAIT_L(n) asm volatile("s_waitcnt lgkmcnt(" #n ")" ::: "memory")
; #define BAR __builtin_amdgcn_s_barrier()
; #define SCHED __builtin_amdgcn_sched_barrier(0)
; #define LDA(dst, b, h) for (int m = 0; m < 4; ++m) for (int k = 0; k < 2; ++k) \
;     dst[m][k] = *reinterpret_cast<const bf16x8*>((char*)SA(b, h) + lds_byte(wr * 64 + m * 16 + fr, k * 32 + fq * 8))
; #define LDB(dst, b, h) for (int n = 0; n < 2; ++n) for (int k = 0; k < 2; ++k) \
;     dst[n][k] = *reinterpret_cast<const bf16x8*>((char*)SB(b, h) + lds_byte(wc * 32 + n * 16 + fr, k * 32 + fq * 8))
; #define MMA(ai, bj, At_, Bt_) do { __builtin_amdgcn_s_setprio(1); \
;     for (int m = 0; m < 4; ++m) for (int n = 0; n < 2; ++n) for (int k = 0; k < 2; ++k) \
;       acc[ai][bj][m][n] = __builtin_amdgcn_mfma_f32_16x16x32_bf16(At_[m][k], Bt_[n][k], acc[ai][bj][m][n], 0, 0, 0); \
;     __builtin_amdgcn_s_setprio(0); } while (0)
; template <int K, int LD = K>
; __device__ __forceinline__ void gemm_main(const GAS bf16* A, const GAS bf16* Bt, int brow, int bcol, f32x4 (&acc)[2][2][4][2]) {
;     ...
;     LDA(At, 1, 1); STAGE(SA(1, 0), pA0, 3);
;     BAR; WAIT_L(0); MMA(1, 0, At, B0); BAR; SCHED;
;     STAGE(SB(1, 1), pB1, 3);
;     WAIT_V(6); BAR; MMA(1, 1, At, B1); BAR;
;     pA0 += 4 * BK; pA1 += 4 * BK; pB0 += 4 * BK; pB1 += 4 * BK;
;     asm volatile("" : "+s"(pA0), "+s"(pA1), "+s"(pB0), "+s"(pB1));
;   }
;   { LDB(B0, 0, 0); LDA(At, 0, 0); STAGE(SA(1, 1), pA1, 1);
;     BAR; WAIT_L(0); MMA(0, 0, At, B0); BAR;
;     LDB(B1, 0, 1); BAR; WAIT_L(0); MMA(0, 1, At, B1); BAR;
;     LDA(At, 0, 1); WAIT_V(4); BAR; WAIT_L(0); MMA(1, 0, At, B0); MMA(1, 1, At, B1); BAR; }
	ds_read_b128 v[162:165], v138 offset:49152
	ds_read_b128 v[166:169], v138 offset:50176
	ds_read_b128 v[174:177], v137 offset:49152
	ds_read_b128 v[178:181], v137 offset:50176
	ds_read_b128 v[182:185], v136 offset:49152
	ds_read_b128 v[186:189], v136 offset:50176
	ds_read_b128 v[190:193], v135 offset:49152
	ds_read_b128 v[194:197], v135 offset:50176
	global_load_lds_dwordx4 v[214:215], off
	v_lshl_add_u64 v[214:215], v[224:225], 0, s[12:13]
	s_mov_b32 m0, s30
	s_nop 0
	global_load_lds_dwordx4 v[214:215], off
	s_barrier
	s_waitcnt lgkmcnt(0)
	s_setprio 1
	s_waitcnt lgkmcnt(0)
	v_mfma_f32_16x16x32_bf16 v[62:65], v[162:165], v[146:149], v[62:65]
	v_mfma_f32_16x16x32_bf16 v[58:61], v[162:165], v[154:157], v[58:61]
	v_mfma_f32_16x16x32_bf16 v[54:57], v[174:177], v[146:149], v[54:57]
	v_mfma_f32_16x16x32_bf16 v[50:53], v[174:177], v[154:157], v[50:53]
	v_mfma_f32_16x16x32_bf16 v[46:49], v[182:185], v[146:149], v[46:49]
	v_mfma_f32_16x16x32_bf16 v[42:45], v[182:185], v[154:157], v[42:45]
	v_mfma_f32_16x16x32_bf16 v[38:41], v[190:193], v[146:149], v[38:41]
	v_mfma_f32_16x16x32_bf16 v[34:37], v[190:193], v[154:157], v[34:37]
	v_mfma_f32_16x16x32_bf16 v[62:65], v[166:169], v[150:153], v[62:65]
	v_mfma_f32_16x16x32_bf16 v[58:61], v[166:169], v[158:161], v[58:61]
	v_mfma_f32_16x16x32_bf16 v[54:57], v[178:181], v[150:153], v[54:57]
	v_mfma_f32_16x16x32_bf16 v[50:53], v[178:181], v[158:161], v[50:53]
	v_mfma_f32_16x16x32_bf16 v[46:49], v[186:189], v[150:153], v[46:49]
	v_mfma_f32_16x16x32_bf16 v[42:45], v[186:189], v[158:161], v[42:45]
	v_mfma_f32_16x16x32_bf16 v[38:41], v[194:197], v[150:153], v[38:41]
	v_mfma_f32_16x16x32_bf16 v[34:37], v[194:197], v[158:161], v[34:37]
	s_setprio 0
	s_barrier
	v_add_u32_e32 v148, s50, v141
	v_lshl_add_u64 v[146:147], v[226:227], 0, s[12:13]
	v_readfirstlane_b32 s30, v148
	v_add_u32_e32 v148, 0x2000, v148
	s_mov_b32 m0, s30
	v_readfirstlane_b32 s30, v148
	global_load_lds_dwordx4 v[146:147], off
	v_lshl_add_u64 v[146:147], v[228:229], 0, s[12:13]
	s_mov_b32 m0, s30
	s_nop 0
	global_load_lds_dwordx4 v[146:147], off
	s_waitcnt vmcnt(8)
	s_barrier
	s_setprio 1
	v_mfma_f32_16x16x32_bf16 v[30:33], v[162:165], v[198:201], v[30:33]
	v_mfma_f32_16x16x32_bf16 v[26:29], v[162:165], v[206:209], v[26:29]
	v_mfma_f32_16x16x32_bf16 v[22:25], v[174:177], v[198:201], v[22:25]
	v_mfma_f32_16x16x32_bf16 v[18:21], v[174:177], v[206:209], v[18:21]
	v_mfma_f32_16x16x32_bf16 v[14:17], v[182:185], v[198:201], v[14:17]
	v_mfma_f32_16x16x32_bf16 v[10:13], v[182:185], v[206:209], v[10:13]
	v_mfma_f32_16x16x32_bf16 v[6:9], v[190:193], v[198:201], v[6:9]
	v_mfma_f32_16x16x32_bf16 v[2:5], v[190:193], v[206:209], v[2:5]
	v_mfma_f32_16x16x32_bf16 v[30:33], v[166:169], v[202:205], v[30:33]
	v_mfma_f32_16x16x32_bf16 v[26:29], v[166:169], v[210:213], v[26:29]
	v_mfma_f32_16x16x32_bf16 v[22:25], v[178:181], v[202:205], v[22:25]
	v_mfma_f32_16x16x32_bf16 v[18:21], v[178:181], v[210:213], v[18:21]
	v_mfma_f32_16x16x32_bf16 v[14:17], v[186:189], v[202:205], v[14:17]
	v_mfma_f32_16x16x32_bf16 v[10:13], v[186:189], v[210:213], v[10:13]
	v_mfma_f32_16x16x32_bf16 v[6:9], v[194:197], v[202:205], v[6:9]
	v_mfma_f32_16x16x32_bf16 v[2:5], v[194:197], v[210:213], v[2:5]
	s_setprio 0
	s_add_i32 s17, s17, 2
	s_cmp_lt_u32 s17, 4
	s_barrier
	s_cbranch_scc1 .LBB0_709
	v_lshl_add_u64 v[198:199], s[20:21], 0, v[130:131]
	v_readfirstlane_b32 s17, v144
	v_lshl_add_u64 v[198:199], v[198:199], 0, s[6:7]
	s_mov_b32 m0, s17
	v_lshl_add_u64 v[132:133], s[20:21], 0, v[132:133]
	v_readfirstlane_b32 s17, v145
	ds_read_b128 v[146:149], v143
	ds_read_b128 v[150:153], v143 offset:1024
	ds_read_b128 v[154:157], v143 offset:2048
	ds_read_b128 v[158:161], v143 offset:3072
	ds_read_b128 v[162:165], v138
	ds_read_b128 v[166:169], v138 offset:1024
	ds_read_b128 v[174:177], v137
	ds_read_b128 v[178:181], v137 offset:1024
	ds_read_b128 v[182:185], v136
	ds_read_b128 v[186:189], v136 offset:1024
	ds_read_b128 v[190:193], v135
	ds_read_b128 v[194:197], v135 offset:1024
	global_load_lds_dwordx4 v[198:199], off
	v_lshl_add_u64 v[132:133], v[132:133], 0, s[6:7]
	s_mov_b32 m0, s17
	s_nop 0
	global_load_lds_dwordx4 v[132:133], off
	s_barrier
	s_waitcnt lgkmcnt(0)
	s_setprio 1
	s_waitcnt lgkmcnt(0)
	v_mfma_f32_16x16x32_bf16 v[126:129], v[162:165], v[146:149], v[126:129]
	v_mfma_f32_16x16x32_bf16 v[122:125], v[162:165], v[154:157], v[122:125]
	v_mfma_f32_16x16x32_bf16 v[110:113], v[182:185], v[146:149], v[110:113]
	v_mfma_f32_16x16x32_bf16 v[106:109], v[182:185], v[154:157], v[106:109]
	v_mfma_f32_16x16x32_bf16 v[126:129], v[166:169], v[150:153], v[126:129]
	v_mfma_f32_16x16x32_bf16 v[122:125], v[166:169], v[158:161], v[122:125]
	v_mfma_f32_16x16x32_bf16 v[118:121], v[174:177], v[146:149], v[118:121]
	v_mfma_f32_16x16x32_bf16 v[114:117], v[174:177], v[154:157], v[114:117]
	v_mfma_f32_16x16x32_bf16 v[110:113], v[186:189], v[150:153], v[110:113]
	v_mfma_f32_16x16x32_bf16 v[106:109], v[186:189], v[158:161], v[106:109]
	v_mfma_f32_16x16x32_bf16 v[102:105], v[190:193], v[146:149], v[102:105]
	v_mfma_f32_16x16x32_bf16 v[98:101], v[190:193], v[154:157], v[98:101]
	v_mfma_f32_16x16x32_bf16 v[198:201], v[178:181], v[150:153], v[118:121]
	v_mfma_f32_16x16x32_bf16 v[202:205], v[178:181], v[158:161], v[114:117]
	v_mfma_f32_16x16x32_bf16 v[206:209], v[194:197], v[150:153], v[102:105]
	v_mfma_f32_16x16x32_bf16 v[210:213], v[194:197], v[158:161], v[98:101]
	s_setprio 0
	s_barrier
	s_nop 1
	ds_read_b128 v[98:101], v142
	ds_read_b128 v[102:105], v142 offset:1024
	ds_read_b128 v[114:117], v142 offset:2048
	ds_read_b128 v[118:121], v142 offset:3072
	s_waitcnt vmcnt(8)
	s_barrier
; #define WAIT_V(n) asm volatile("s_waitcnt vmcnt(" #n ")" ::: "memory")
; #define WAIT_L(n) asm volatile("s_waitcnt lgkmcnt(" #n ")" ::: "memory")
; #define BAR __builtin_amdgcn_s_barrier()
; #define LDA(dst, b, h) for (int m = 0; m < 4; ++m) for (int k = 0; k < 2; ++k) \
;     dst[m][k] = *reinterpret_cast<const bf16x8*>((char*)SA(b, h) + lds_byte(wr * 64 + m * 16 + fr, k * 32 + fq * 8))
; #define LDB(dst, b, h) for (int n = 0; n < 2; ++n) for (int k = 0; k < 2; ++k) \
;     dst[n][k] = *reinterpret_cast<const bf16x8*>((char*)SB(b, h) + lds_byte(wc * 32 + n * 16 + fr, k * 32 + fq * 8))
; #define MMA(ai, bj, At_, Bt_) do { __builtin_amdgcn_s_setprio(1); \
;     for (int m = 0; m < 4; ++m) for (int n = 0; n < 2; ++n) for (int k = 0; k < 2; ++k) \
;       acc[ai][bj][m][n] = __builtin_amdgcn_mfma_f32_16x16x32_bf16(At_[m][k], Bt_[n][k], acc[ai][bj][m][n], 0, 0, 0); \
;     __builtin_amdgcn_s_setprio(0); } while (0)
; template <int K, int LD = K>
; __device__ __forceinline__ void gemm_main(const GAS bf16* A, const GAS bf16* Bt, int brow, int bcol, f32x4 (&acc)[2][2][4][2]) {
;     ...
;     LDB(B1, 0, 1); BAR; WAIT_L(0); MMA(0, 1, At, B1); BAR;
;     LDA(At, 0, 1); WAIT_V(4); BAR; WAIT_L(0); MMA(1, 0, At, B0); MMA(1, 1, At, B1); BAR; }
;   { LDB(B0, 1, 0); LDA(At, 1, 0); WAIT_V(2); BAR; WAIT_L(0); MMA(0, 0, At, B0); BAR;
	s_waitcnt lgkmcnt(0)
	s_setprio 1
	s_waitcnt lgkmcnt(0)
	v_mfma_f32_16x16x32_bf16 v[94:97], v[162:165], v[98:101], v[94:97]
	v_mfma_f32_16x16x32_bf16 v[90:93], v[162:165], v[114:117], v[90:93]
	v_mfma_f32_16x16x32_bf16 v[70:73], v[190:193], v[98:101], v[70:73]
	v_mfma_f32_16x16x32_bf16 v[66:69], v[190:193], v[114:117], v[66:69]
	v_mfma_f32_16x16x32_bf16 v[94:97], v[166:169], v[102:105], v[94:97]
	v_mfma_f32_16x16x32_bf16 v[90:93], v[166:169], v[118:121], v[90:93]
	v_mfma_f32_16x16x32_bf16 v[86:89], v[174:177], v[98:101], v[86:89]
	v_mfma_f32_16x16x32_bf16 v[82:85], v[174:177], v[114:117], v[82:85]
	v_mfma_f32_16x16x32_bf16 v[78:81], v[182:185], v[98:101], v[78:81]
	v_mfma_f32_16x16x32_bf16 v[74:77], v[182:185], v[114:117], v[74:77]
	v_mfma_f32_16x16x32_bf16 v[70:73], v[194:197], v[102:105], v[70:73]
	v_mfma_f32_16x16x32_bf16 v[66:69], v[194:197], v[118:121], v[66:69]
	v_mfma_f32_16x16x32_bf16 v[142:145], v[178:181], v[102:105], v[86:89]
	v_mfma_f32_16x16x32_bf16 v[162:165], v[178:181], v[118:121], v[82:85]
	v_mfma_f32_16x16x32_bf16 v[166:169], v[186:189], v[102:105], v[78:81]
	v_mfma_f32_16x16x32_bf16 v[174:177], v[186:189], v[118:121], v[74:77]
	s_setprio 0
	s_barrier
	s_nop 0
	ds_read_b128 v[74:77], v138 offset:16384
	ds_read_b128 v[78:81], v138 offset:17408
	ds_read_b128 v[82:85], v137 offset:16384
	ds_read_b128 v[86:89], v137 offset:17408
	ds_read_b128 v[178:181], v136 offset:16384
	ds_read_b128 v[182:185], v136 offset:17408
	ds_read_b128 v[186:189], v135 offset:16384
	ds_read_b128 v[190:193], v135 offset:17408
	s_waitcnt vmcnt(4)
	s_barrier
	s_waitcnt lgkmcnt(0)
	s_setprio 1
	s_waitcnt lgkmcnt(0)
	v_mfma_f32_16x16x32_bf16 v[62:65], v[74:77], v[146:149], v[62:65]
	v_mfma_f32_16x16x32_bf16 v[58:61], v[74:77], v[154:157], v[58:61]
	v_mfma_f32_16x16x32_bf16 v[54:57], v[82:85], v[146:149], v[54:57]
	v_mfma_f32_16x16x32_bf16 v[50:53], v[82:85], v[154:157], v[50:53]
	v_mfma_f32_16x16x32_bf16 v[38:41], v[186:189], v[146:149], v[38:41]
	v_mfma_f32_16x16x32_bf16 v[34:37], v[186:189], v[154:157], v[34:37]
	v_mfma_f32_16x16x32_bf16 v[62:65], v[78:81], v[150:153], v[62:65]
	v_mfma_f32_16x16x32_bf16 v[58:61], v[78:81], v[158:161], v[58:61]
	v_mfma_f32_16x16x32_bf16 v[54:57], v[86:89], v[150:153], v[54:57]
	v_mfma_f32_16x16x32_bf16 v[50:53], v[86:89], v[158:161], v[50:53]
	v_mfma_f32_16x16x32_bf16 v[46:49], v[178:181], v[146:149], v[46:49]
	v_mfma_f32_16x16x32_bf16 v[42:45], v[178:181], v[154:157], v[42:45]
	v_mfma_f32_16x16x32_bf16 v[38:41], v[190:193], v[150:153], v[38:41]
	v_mfma_f32_16x16x32_bf16 v[34:37], v[190:193], v[158:161], v[34:37]
	v_mfma_f32_16x16x32_bf16 v[194:197], v[182:185], v[150:153], v[46:49]
	v_mfma_f32_16x16x32_bf16 v[214:217], v[182:185], v[158:161], v[42:45]
	s_setprio 0
	s_setprio 1
	v_mfma_f32_16x16x32_bf16 v[22:25], v[82:85], v[98:101], v[22:25]
	v_mfma_f32_16x16x32_bf16 v[18:21], v[82:85], v[114:117], v[18:21]
	v_mfma_f32_16x16x32_bf16 v[14:17], v[178:181], v[98:101], v[14:17]
	v_mfma_f32_16x16x32_bf16 v[10:13], v[178:181], v[114:117], v[10:13]
	v_mfma_f32_16x16x32_bf16 v[30:33], v[74:77], v[98:101], v[30:33]
	v_mfma_f32_16x16x32_bf16 v[26:29], v[74:77], v[114:117], v[26:29]
	v_mfma_f32_16x16x32_bf16 v[22:25], v[86:89], v[102:105], v[22:25]
	v_mfma_f32_16x16x32_bf16 v[18:21], v[86:89], v[118:121], v[18:21]
	v_mfma_f32_16x16x32_bf16 v[14:17], v[182:185], v[102:105], v[14:17]
	v_mfma_f32_16x16x32_bf16 v[10:13], v[182:185], v[118:121], v[10:13]
	v_mfma_f32_16x16x32_bf16 v[6:9], v[186:189], v[98:101], v[6:9]
	v_mfma_f32_16x16x32_bf16 v[2:5], v[186:189], v[114:117], v[2:5]
	v_mfma_f32_16x16x32_bf16 v[146:149], v[78:81], v[102:105], v[30:33]
	v_mfma_f32_16x16x32_bf16 v[150:153], v[78:81], v[118:121], v[26:29]
	v_mfma_f32_16x16x32_bf16 v[154:157], v[190:193], v[102:105], v[6:9]
	v_mfma_f32_16x16x32_bf16 v[158:161], v[190:193], v[118:121], v[2:5]
	s_setprio 0
	s_barrier
	s_nop 1
	ds_read_b128 v[2:5], v140
	ds_read_b128 v[6:9], v140 offset:1024
	ds_read_b128 v[178:181], v140 offset:2048
	ds_read_b128 v[182:185], v140 offset:3072
	ds_read_b128 v[26:29], v138 offset:32768
	ds_read_b128 v[30:33], v138 offset:33792
	ds_read_b128 v[42:45], v137 offset:32768
	ds_read_b128 v[46:49], v137 offset:33792
	ds_read_b128 v[186:189], v136 offset:32768
	ds_read_b128 v[190:193], v136 offset:33792
	ds_read_b128 v[218:221], v135 offset:32768
	ds_read_b128 v[222:225], v135 offset:33792
	s_waitcnt vmcnt(2)
	s_barrier
; #define WAIT_V(n) asm volatile("s_waitcnt vmcnt(" #n ")" ::: "memory")
; #define WAIT_L(n) asm volatile("s_waitcnt lgkmcnt(" #n ")" ::: "memory")
; #define BAR __builtin_amdgcn_s_barrier()
; #define LDA(dst, b, h) for (int m = 0; m < 4; ++m) for (int k = 0; k < 2; ++k) \
;     dst[m][k] = *reinterpret_cast<const bf16x8*>((char*)SA(b, h) + lds_byte(wr * 64 + m * 16 + fr, k * 32 + fq * 8))
; #define LDB(dst, b, h) for (int n = 0; n < 2; ++n) for (int k = 0; k < 2; ++k) \
;     dst[n][k] = *reinterpret_cast<const bf16x8*>((char*)SB(b, h) + lds_byte(wc * 32 + n * 16 + fr, k * 32 + fq * 8))
; #define MMA(ai, bj, At_, Bt_) do { __builtin_amdgcn_s_setprio(1); \
;     for (int m = 0; m < 4; ++m) for (int n = 0; n < 2; ++n) for (int k = 0; k < 2; ++k) \
;       acc[ai][bj][m][n] = __builtin_amdgcn_mfma_f32_16x16x32_bf16(At_[m][k], Bt_[n][k], acc[ai][bj][m][n], 0, 0, 0); \
;     __builtin_amdgcn_s_setprio(0); } while (0)
; template <int K, int LD = K>
; __device__ __forceinline__ void gemm_main(const GAS bf16* A, const GAS bf16* Bt, int brow, int bcol, f32x4 (&acc)[2][2][4][2]) {
;     ...
;   { LDB(B0, 1, 0); LDA(At, 1, 0); WAIT_V(2); BAR; WAIT_L(0); MMA(0, 0, At, B0); BAR;
;     LDB(B1, 1, 1); WAIT_V(0); BAR; WAIT_L(0); MMA(0, 1, At, B1); BAR;
;     LDA(At, 1, 1); BAR; WAIT_L(0); MMA(1, 0, At, B0); MMA(1, 1, At, B1); BAR; }
;   if (wr == 0) BAR;
	s_waitcnt lgkmcnt(0)
	s_setprio 1
	s_waitcnt lgkmcnt(0)
	v_mfma_f32_16x16x32_bf16 v[74:77], v[26:29], v[2:5], v[126:129]
	v_mfma_f32_16x16x32_bf16 v[118:121], v[30:33], v[6:9], v[74:77]
	v_mfma_f32_16x16x32_bf16 v[74:77], v[26:29], v[178:181], v[122:125]
	v_mfma_f32_16x16x32_bf16 v[114:117], v[30:33], v[182:185], v[74:77]
	v_mfma_f32_16x16x32_bf16 v[74:77], v[42:45], v[2:5], v[198:201]
	v_mfma_f32_16x16x32_bf16 v[102:105], v[46:49], v[6:9], v[74:77]
	v_mfma_f32_16x16x32_bf16 v[74:77], v[42:45], v[178:181], v[202:205]
	v_mfma_f32_16x16x32_bf16 v[98:101], v[46:49], v[182:185], v[74:77]
	v_mfma_f32_16x16x32_bf16 v[74:77], v[186:189], v[2:5], v[110:113]
	v_mfma_f32_16x16x32_bf16 v[86:89], v[190:193], v[6:9], v[74:77]
	v_mfma_f32_16x16x32_bf16 v[74:77], v[186:189], v[178:181], v[106:109]
	v_mfma_f32_16x16x32_bf16 v[82:85], v[190:193], v[182:185], v[74:77]
	v_mfma_f32_16x16x32_bf16 v[74:77], v[218:221], v[2:5], v[206:209]
	v_mfma_f32_16x16x32_bf16 v[78:81], v[222:225], v[6:9], v[74:77]
	v_mfma_f32_16x16x32_bf16 v[74:77], v[218:221], v[178:181], v[210:213]
	v_mfma_f32_16x16x32_bf16 v[74:77], v[222:225], v[182:185], v[74:77]
	s_setprio 0
	s_barrier
	ds_read_b128 v[198:201], v139
	ds_read_b128 v[202:205], v139 offset:1024
	ds_read_b128 v[206:209], v139 offset:2048
	ds_read_b128 v[210:213], v139 offset:3072
	s_waitcnt vmcnt(0)
	s_barrier
	s_waitcnt lgkmcnt(0)
	s_setprio 1
	s_waitcnt lgkmcnt(0)
	v_mfma_f32_16x16x32_bf16 v[94:97], v[26:29], v[198:201], v[94:97]
	v_mfma_f32_16x16x32_bf16 v[26:29], v[26:29], v[206:209], v[90:93]
	v_mfma_f32_16x16x32_bf16 v[122:125], v[30:33], v[210:213], v[26:29]
	v_mfma_f32_16x16x32_bf16 v[26:29], v[42:45], v[198:201], v[142:145]
	v_mfma_f32_16x16x32_bf16 v[110:113], v[46:49], v[202:205], v[26:29]
	v_mfma_f32_16x16x32_bf16 v[26:29], v[42:45], v[206:209], v[162:165]
	v_mfma_f32_16x16x32_bf16 v[106:109], v[46:49], v[210:213], v[26:29]
	v_mfma_f32_16x16x32_bf16 v[26:29], v[186:189], v[198:201], v[166:169]
	v_mfma_f32_16x16x32_bf16 v[126:129], v[30:33], v[202:205], v[94:97]
	v_mfma_f32_16x16x32_bf16 v[94:97], v[190:193], v[202:205], v[26:29]
	v_mfma_f32_16x16x32_bf16 v[26:29], v[186:189], v[206:209], v[174:177]
	v_mfma_f32_16x16x32_bf16 v[90:93], v[190:193], v[210:213], v[26:29]
	v_mfma_f32_16x16x32_bf16 v[26:29], v[218:221], v[198:201], v[70:73]
	v_mfma_f32_16x16x32_bf16 v[70:73], v[222:225], v[202:205], v[26:29]
	v_mfma_f32_16x16x32_bf16 v[26:29], v[218:221], v[206:209], v[66:69]
	v_mfma_f32_16x16x32_bf16 v[66:69], v[222:225], v[210:213], v[26:29]
	s_setprio 0
	s_barrier
	ds_read_b128 v[140:143], v138 offset:49152
	ds_read_b128 v[162:165], v138 offset:50176
	ds_read_b128 v[166:169], v137 offset:49152
	ds_read_b128 v[174:177], v137 offset:50176
	ds_read_b128 v[186:189], v136 offset:49152
	ds_read_b128 v[136:139], v136 offset:50176
	ds_read_b128 v[190:193], v135 offset:49152
	ds_read_b128 v[218:221], v135 offset:50176
	s_barrier
	s_waitcnt lgkmcnt(0)
	s_setprio 1
	s_waitcnt lgkmcnt(0)
	v_mfma_f32_16x16x32_bf16 v[26:29], v[140:143], v[2:5], v[62:65]
	v_mfma_f32_16x16x32_bf16 v[62:65], v[162:165], v[6:9], v[26:29]
	v_mfma_f32_16x16x32_bf16 v[26:29], v[140:143], v[178:181], v[58:61]
	v_mfma_f32_16x16x32_bf16 v[58:61], v[162:165], v[182:185], v[26:29]
	v_mfma_f32_16x16x32_bf16 v[26:29], v[166:169], v[2:5], v[54:57]
	v_mfma_f32_16x16x32_bf16 v[46:49], v[174:177], v[6:9], v[26:29]
	v_mfma_f32_16x16x32_bf16 v[26:29], v[166:169], v[178:181], v[50:53]
	v_mfma_f32_16x16x32_bf16 v[42:45], v[174:177], v[182:185], v[26:29]
	v_mfma_f32_16x16x32_bf16 v[26:29], v[186:189], v[2:5], v[194:197]
	v_mfma_f32_16x16x32_bf16 v[2:5], v[190:193], v[2:5], v[38:41]
	v_mfma_f32_16x16x32_bf16 v[30:33], v[136:139], v[6:9], v[26:29]
	v_mfma_f32_16x16x32_bf16 v[26:29], v[186:189], v[178:181], v[214:217]
	v_mfma_f32_16x16x32_bf16 v[6:9], v[218:221], v[6:9], v[2:5]
	v_mfma_f32_16x16x32_bf16 v[2:5], v[190:193], v[178:181], v[34:37]
	v_mfma_f32_16x16x32_bf16 v[26:29], v[136:139], v[182:185], v[26:29]
	v_mfma_f32_16x16x32_bf16 v[2:5], v[218:221], v[182:185], v[2:5]
	s_setprio 0
	s_setprio 1
	v_mfma_f32_16x16x32_bf16 v[34:37], v[140:143], v[198:201], v[146:149]
	v_mfma_f32_16x16x32_bf16 v[54:57], v[162:165], v[202:205], v[34:37]
	v_mfma_f32_16x16x32_bf16 v[34:37], v[140:143], v[206:209], v[150:153]
	v_mfma_f32_16x16x32_bf16 v[18:21], v[166:169], v[206:209], v[18:21]
	v_mfma_f32_16x16x32_bf16 v[10:13], v[186:189], v[206:209], v[10:13]
	v_mfma_f32_16x16x32_bf16 v[50:53], v[162:165], v[210:213], v[34:37]
	v_mfma_f32_16x16x32_bf16 v[22:25], v[166:169], v[198:201], v[22:25]
	v_mfma_f32_16x16x32_bf16 v[34:37], v[174:177], v[210:213], v[18:21]
	v_mfma_f32_16x16x32_bf16 v[14:17], v[186:189], v[198:201], v[14:17]
	v_mfma_f32_16x16x32_bf16 v[18:21], v[136:139], v[210:213], v[10:13]
	v_mfma_f32_16x16x32_bf16 v[10:13], v[190:193], v[198:201], v[154:157]
	v_mfma_f32_16x16x32_bf16 v[38:41], v[174:177], v[202:205], v[22:25]
	v_mfma_f32_16x16x32_bf16 v[22:25], v[136:139], v[202:205], v[14:17]
	v_mfma_f32_16x16x32_bf16 v[14:17], v[218:221], v[202:205], v[10:13]
	v_mfma_f32_16x16x32_bf16 v[10:13], v[190:193], v[206:209], v[158:161]
	v_mfma_f32_16x16x32_bf16 v[10:13], v[218:221], v[210:213], v[10:13]
	s_setprio 0
	v_cmp_gt_u32_e32 vcc, s51, v134
	s_barrier
	s_and_saveexec_b64 s[20:21], vcc
	s_cbranch_execz .LBB0_712
	s_barrier

; #define STAGE(P, GP, ktrel) do { const GAS char* _g = (GP) + (ktrel) * (BK * 2); \
;     __builtin_amdgcn_global_load_lds((const GAS unsigned*)(_g + so0), (unsigned*)((char*)(P) + tid_ * 16), 16, 0, 0); \
;     __builtin_amdgcn_global_load_lds((const GAS unsigned*)(_g + so1), (unsigned*)((char*)(P) + tid_ * 16 + 8192), 16, 0, 0); } while (0)
; #define WAIT_L(n) asm volatile("s_waitcnt lgkmcnt(" #n ")" ::: "memory")
; #define BAR __builtin_amdgcn_s_barrier()
; #define SCHED __builtin_amdgcn_sched_barrier(0)
; #define LDA(dst, b, h) for (int m = 0; m < 4; ++m) for (int k = 0; k < 2; ++k) \
;     dst[m][k] = *reinterpret_cast<const bf16x8*>((char*)SA(b, h) + lds_byte(wr * 64 + m * 16 + fr, k * 32 + fq * 8))
; #define LDB(dst, b, h) for (int n = 0; n < 2; ++n) for (int k = 0; k < 2; ++k) \
;     dst[n][k] = *reinterpret_cast<const bf16x8*>((char*)SB(b, h) + lds_byte(wc * 32 + n * 16 + fr, k * 32 + fq * 8))
; #define MMA(ai, bj, At_, Bt_) do { __builtin_amdgcn_s_setprio(1); \
;     for (int m = 0; m < 4; ++m) for (int n = 0; n < 2; ++n) for (int k = 0; k < 2; ++k) \
;       acc[ai][bj][m][n] = __builtin_amdgcn_mfma_f32_16x16x32_bf16(At_[m][k], Bt_[n][k], acc[ai][bj][m][n], 0, 0, 0); \
;     __builtin_amdgcn_s_setprio(0); } while (0)
; template <int K, int LD = K>
; __device__ __forceinline__ void gemm_main(const GAS bf16* A, const GAS bf16* Bt, int brow, int bcol, f32x4 (&acc)[2][2][4][2]) {
;     ...
;   for (int t = 0; t < nt - 2; t += 2) {
;     LDB(B0, 0, 0); SCHED; LDA(At, 0, 0); STAGE(SA(1, 1), pA1, 1);
;     WAIT_L(8); BAR; WAIT_L(0); MMA(0, 0, At, B0); BAR; SCHED;
;     LDB(B1, 0, 1); STAGE(SB(0, 0), pB0, 2);
;     BAR; WAIT_L(0); MMA(0, 1, At, B1); BAR;
;     LDA(At, 0, 1); STAGE(SA(0, 0), pA0, 2);
;     BAR; WAIT_L(0); MMA(1, 0, At, B0); BAR; SCHED;
.LBB0_715:
	ds_read_b128 v[146:149], v143
	ds_read_b128 v[150:153], v143 offset:1024
	ds_read_b128 v[154:157], v143 offset:2048
	ds_read_b128 v[158:161], v143 offset:3072
	v_add_u32_e32 v230, 0x100, v141
	v_add_u32_e32 v144, 0xc000, v230
	v_lshl_add_u64 v[214:215], s[20:21], 0, v[130:131]
	v_readfirstlane_b32 s28, v144
	v_add_u32_e32 v145, 0xe000, v230
	v_lshl_add_u64 v[198:199], v[214:215], 0, s[6:7]
	s_mov_b32 m0, s28
	v_lshl_add_u64 v[216:217], s[20:21], 0, v[132:133]
	v_readfirstlane_b32 s28, v145
	ds_read_b128 v[162:165], v138
	ds_read_b128 v[166:169], v138 offset:1024
	ds_read_b128 v[174:177], v137
	ds_read_b128 v[178:181], v137 offset:1024
	ds_read_b128 v[182:185], v136
	ds_read_b128 v[186:189], v136 offset:1024
	ds_read_b128 v[190:193], v135
	ds_read_b128 v[194:197], v135 offset:1024
	global_load_lds_dwordx4 v[198:199], off
	v_lshl_add_u64 v[198:199], v[216:217], 0, s[6:7]
	s_mov_b32 m0, s28
	s_nop 0
	global_load_lds_dwordx4 v[198:199], off
	s_waitcnt lgkmcnt(8)
	s_barrier
	s_waitcnt lgkmcnt(0)
	s_setprio 1
	s_waitcnt lgkmcnt(0)
	v_mfma_f32_16x16x32_bf16 v[126:129], v[162:165], v[146:149], v[126:129]
	v_mfma_f32_16x16x32_bf16 v[122:125], v[162:165], v[154:157], v[122:125]
	v_mfma_f32_16x16x32_bf16 v[118:121], v[174:177], v[146:149], v[118:121]
	v_mfma_f32_16x16x32_bf16 v[114:117], v[174:177], v[154:157], v[114:117]
	v_mfma_f32_16x16x32_bf16 v[110:113], v[182:185], v[146:149], v[110:113]
	v_mfma_f32_16x16x32_bf16 v[106:109], v[182:185], v[154:157], v[106:109]
	v_mfma_f32_16x16x32_bf16 v[102:105], v[190:193], v[146:149], v[102:105]
	v_mfma_f32_16x16x32_bf16 v[98:101], v[190:193], v[154:157], v[98:101]
	v_mfma_f32_16x16x32_bf16 v[126:129], v[166:169], v[150:153], v[126:129]
	v_mfma_f32_16x16x32_bf16 v[122:125], v[166:169], v[158:161], v[122:125]
	v_mfma_f32_16x16x32_bf16 v[118:121], v[178:181], v[150:153], v[118:121]
	v_mfma_f32_16x16x32_bf16 v[114:117], v[178:181], v[158:161], v[114:117]
	v_mfma_f32_16x16x32_bf16 v[110:113], v[186:189], v[150:153], v[110:113]
	v_mfma_f32_16x16x32_bf16 v[106:109], v[186:189], v[158:161], v[106:109]
	v_mfma_f32_16x16x32_bf16 v[102:105], v[194:197], v[150:153], v[102:105]
	v_mfma_f32_16x16x32_bf16 v[98:101], v[194:197], v[158:161], v[98:101]
	s_setprio 0
	s_barrier
	v_add_u32_e32 v224, s47, v141
	v_lshl_add_u64 v[218:219], s[26:27], 0, v[130:131]
	v_readfirstlane_b32 s28, v224
	v_lshl_add_u64 v[220:221], v[218:219], 0, s[10:11]
	s_mov_b32 m0, s28
	v_add_u32_e32 v224, 0x2000, v224
	ds_read_b128 v[198:201], v142
	ds_read_b128 v[202:205], v142 offset:1024
	ds_read_b128 v[206:209], v142 offset:2048
	ds_read_b128 v[210:213], v142 offset:3072
	global_load_lds_dwordx4 v[220:221], off
	v_lshl_add_u64 v[220:221], s[26:27], 0, v[132:133]
	v_readfirstlane_b32 s28, v224
	v_lshl_add_u64 v[222:223], v[220:221], 0, s[10:11]
	s_mov_b32 m0, s28
	s_add_u32 s26, s26, 0x100
	global_load_lds_dwordx4 v[222:223], off
	s_waitcnt vmcnt(10)
	s_barrier
	s_waitcnt lgkmcnt(0)
	s_addc_u32 s27, s27, 0
	s_setprio 1
	s_waitcnt lgkmcnt(0)
	v_mfma_f32_16x16x32_bf16 v[94:97], v[162:165], v[198:201], v[94:97]
	v_mfma_f32_16x16x32_bf16 v[90:93], v[162:165], v[206:209], v[90:93]
	v_mfma_f32_16x16x32_bf16 v[86:89], v[174:177], v[198:201], v[86:89]
	v_mfma_f32_16x16x32_bf16 v[82:85], v[174:177], v[206:209], v[82:85]
	v_mfma_f32_16x16x32_bf16 v[78:81], v[182:185], v[198:201], v[78:81]
	v_mfma_f32_16x16x32_bf16 v[74:77], v[182:185], v[206:209], v[74:77]
	v_mfma_f32_16x16x32_bf16 v[70:73], v[190:193], v[198:201], v[70:73]
	v_mfma_f32_16x16x32_bf16 v[66:69], v[190:193], v[206:209], v[66:69]
	v_mfma_f32_16x16x32_bf16 v[94:97], v[166:169], v[202:205], v[94:97]
	v_mfma_f32_16x16x32_bf16 v[90:93], v[166:169], v[210:213], v[90:93]
	v_mfma_f32_16x16x32_bf16 v[86:89], v[178:181], v[202:205], v[86:89]
	v_mfma_f32_16x16x32_bf16 v[82:85], v[178:181], v[210:213], v[82:85]
	v_mfma_f32_16x16x32_bf16 v[78:81], v[186:189], v[202:205], v[78:81]
	v_mfma_f32_16x16x32_bf16 v[74:77], v[186:189], v[210:213], v[74:77]
	v_mfma_f32_16x16x32_bf16 v[70:73], v[194:197], v[202:205], v[70:73]
	v_mfma_f32_16x16x32_bf16 v[66:69], v[194:197], v[210:213], v[66:69]
	s_setprio 0
	v_lshl_add_u64 v[222:223], s[24:25], 0, v[130:131]
	v_readfirstlane_b32 s28, v230
	v_lshl_add_u64 v[224:225], v[222:223], 0, s[10:11]
	s_mov_b32 m0, s28
	v_add_u32_e32 v228, 0x2000, v230
	s_barrier
	ds_read_b128 v[162:165], v138 offset:16384
	ds_read_b128 v[166:169], v138 offset:17408
	ds_read_b128 v[174:177], v137 offset:16384
	ds_read_b128 v[178:181], v137 offset:17408
	ds_read_b128 v[182:185], v136 offset:16384
	ds_read_b128 v[186:189], v136 offset:17408
	ds_read_b128 v[190:193], v135 offset:16384
	ds_read_b128 v[194:197], v135 offset:17408
	global_load_lds_dwordx4 v[224:225], off
	v_lshl_add_u64 v[224:225], s[24:25], 0, v[132:133]
	v_readfirstlane_b32 s28, v228
	v_lshl_add_u64 v[226:227], v[224:225], 0, s[10:11]
	s_mov_b32 m0, s28
	s_add_u32 s24, s24, 0x100
	global_load_lds_dwordx4 v[226:227], off
	s_barrier
	s_waitcnt lgkmcnt(0)
	s_addc_u32 s25, s25, 0
	s_setprio 1
	s_waitcnt lgkmcnt(0)
	v_mfma_f32_16x16x32_bf16 v[62:65], v[162:165], v[146:149], v[62:65]
	v_mfma_f32_16x16x32_bf16 v[58:61], v[162:165], v[154:157], v[58:61]
	v_mfma_f32_16x16x32_bf16 v[54:57], v[174:177], v[146:149], v[54:57]
	v_mfma_f32_16x16x32_bf16 v[50:53], v[174:177], v[154:157], v[50:53]
	v_mfma_f32_16x16x32_bf16 v[46:49], v[182:185], v[146:149], v[46:49]
	v_mfma_f32_16x16x32_bf16 v[42:45], v[182:185], v[154:157], v[42:45]
	v_mfma_f32_16x16x32_bf16 v[38:41], v[190:193], v[146:149], v[38:41]
	v_mfma_f32_16x16x32_bf16 v[34:37], v[190:193], v[154:157], v[34:37]
	v_mfma_f32_16x16x32_bf16 v[62:65], v[166:169], v[150:153], v[62:65]
	v_mfma_f32_16x16x32_bf16 v[58:61], v[166:169], v[158:161], v[58:61]
	v_mfma_f32_16x16x32_bf16 v[54:57], v[178:181], v[150:153], v[54:57]
	v_mfma_f32_16x16x32_bf16 v[50:53], v[178:181], v[158:161], v[50:53]
	v_mfma_f32_16x16x32_bf16 v[46:49], v[186:189], v[150:153], v[46:49]
	v_mfma_f32_16x16x32_bf16 v[42:45], v[186:189], v[158:161], v[42:45]
	v_mfma_f32_16x16x32_bf16 v[38:41], v[194:197], v[150:153], v[38:41]
	v_mfma_f32_16x16x32_bf16 v[34:37], v[194:197], v[158:161], v[34:37]
	s_setprio 0
	s_barrier
; #define STAGE(P, GP, ktrel) do { const GAS char* _g = (GP) + (ktrel) * (BK * 2); \
;     __builtin_amdgcn_global_load_lds((const GAS unsigned*)(_g + so0), (unsigned*)((char*)(P) + tid_ * 16), 16, 0, 0); \
;     __builtin_amdgcn_global_load_lds((const GAS unsigned*)(_g + so1), (unsigned*)((char*)(P) + tid_ * 16 + 8192), 16, 0, 0); } while (0)
; #define WAIT_V(n) asm volatile("s_waitcnt vmcnt(" #n ")" ::: "memory")
; #define WAIT_L(n) asm volatile("s_waitcnt lgkmcnt(" #n ")" ::: "memory")
; #define BAR __builtin_amdgcn_s_barrier()
; #define SCHED __builtin_amdgcn_sched_barrier(0)
; #define LDA(dst, b, h) for (int m = 0; m < 4; ++m) for (int k = 0; k < 2; ++k) \
;     dst[m][k] = *reinterpret_cast<const bf16x8*>((char*)SA(b, h) + lds_byte(wr * 64 + m * 16 + fr, k * 32 + fq * 8))
; #define LDB(dst, b, h) for (int n = 0; n < 2; ++n) for (int k = 0; k < 2; ++k) \
;     dst[n][k] = *reinterpret_cast<const bf16x8*>((char*)SB(b, h) + lds_byte(wc * 32 + n * 16 + fr, k * 32 + fq * 8))
; #define MMA(ai, bj, At_, Bt_) do { __builtin_amdgcn_s_setprio(1); \
;     for (int m = 0; m < 4; ++m) for (int n = 0; n < 2; ++n) for (int k = 0; k < 2; ++k) \
;       acc[ai][bj][m][n] = __builtin_amdgcn_mfma_f32_16x16x32_bf16(At_[m][k], Bt_[n][k], acc[ai][bj][m][n], 0, 0, 0); \
;     __builtin_amdgcn_s_setprio(0); } while (0)
; template <int K, int LD = K>
; __device__ __forceinline__ void gemm_main(const GAS bf16* A, const GAS bf16* Bt, int brow, int bcol, f32x4 (&acc)[2][2][4][2]) {
;     ...
;     STAGE(SB(0, 1), pB1, 2);
;     WAIT_V(6); BAR; MMA(1, 1, At, B1); BAR;
;     LDB(B0, 1, 0); SCHED; LDA(At, 1, 0); STAGE(SA(0, 1), pA1, 2);
;     WAIT_L(8); BAR; WAIT_L(0); MMA(0, 0, At, B0); BAR; SCHED;
;     LDB(B1, 1, 1); STAGE(SB(1, 0), pB0, 3);
;     BAR; WAIT_L(0); MMA(0, 1, At, B1); BAR;
	v_add_u32_e32 v148, s48, v141
	v_lshl_add_u64 v[226:227], s[22:23], 0, v[130:131]
	v_readfirstlane_b32 s28, v148
	v_add_u32_e32 v148, 0x2000, v148
	v_lshl_add_u64 v[146:147], v[226:227], 0, s[10:11]
	s_mov_b32 m0, s28
	v_lshl_add_u64 v[228:229], s[22:23], 0, v[132:133]
	v_readfirstlane_b32 s28, v148
	global_load_lds_dwordx4 v[146:147], off
	v_lshl_add_u64 v[146:147], v[228:229], 0, s[10:11]
	s_mov_b32 m0, s28
	s_add_u32 s22, s22, 0x100
	global_load_lds_dwordx4 v[146:147], off
	s_waitcnt vmcnt(8)
	s_addc_u32 s23, s23, 0
	s_barrier
	s_setprio 1
	v_mfma_f32_16x16x32_bf16 v[30:33], v[162:165], v[198:201], v[30:33]
	v_mfma_f32_16x16x32_bf16 v[26:29], v[162:165], v[206:209], v[26:29]
	v_mfma_f32_16x16x32_bf16 v[22:25], v[174:177], v[198:201], v[22:25]
	v_mfma_f32_16x16x32_bf16 v[18:21], v[174:177], v[206:209], v[18:21]
	v_mfma_f32_16x16x32_bf16 v[14:17], v[182:185], v[198:201], v[14:17]
	v_mfma_f32_16x16x32_bf16 v[10:13], v[182:185], v[206:209], v[10:13]
	v_mfma_f32_16x16x32_bf16 v[6:9], v[190:193], v[198:201], v[6:9]
	v_mfma_f32_16x16x32_bf16 v[2:5], v[190:193], v[206:209], v[2:5]
	v_mfma_f32_16x16x32_bf16 v[30:33], v[166:169], v[202:205], v[30:33]
	v_mfma_f32_16x16x32_bf16 v[26:29], v[166:169], v[210:213], v[26:29]
	v_mfma_f32_16x16x32_bf16 v[22:25], v[178:181], v[202:205], v[22:25]
	v_mfma_f32_16x16x32_bf16 v[18:21], v[178:181], v[210:213], v[18:21]
	v_mfma_f32_16x16x32_bf16 v[14:17], v[186:189], v[202:205], v[14:17]
	v_mfma_f32_16x16x32_bf16 v[10:13], v[186:189], v[210:213], v[10:13]
	v_mfma_f32_16x16x32_bf16 v[6:9], v[194:197], v[202:205], v[6:9]
	v_mfma_f32_16x16x32_bf16 v[2:5], v[194:197], v[210:213], v[2:5]
	s_setprio 0
	s_barrier
	ds_read_b128 v[146:149], v140
	ds_read_b128 v[150:153], v140 offset:1024
	ds_read_b128 v[154:157], v140 offset:2048
	ds_read_b128 v[158:161], v140 offset:3072
	v_add_u32_e32 v200, 0x4000, v230
	v_lshl_add_u64 v[198:199], v[214:215], 0, s[10:11]
	v_readfirstlane_b32 s28, v200
	v_add_u32_e32 v200, 0x6000, v230
	s_mov_b32 m0, s28
	v_readfirstlane_b32 s28, v200
	ds_read_b128 v[162:165], v138 offset:32768
	ds_read_b128 v[166:169], v138 offset:33792
	ds_read_b128 v[174:177], v137 offset:32768
	ds_read_b128 v[178:181], v137 offset:33792
	ds_read_b128 v[182:185], v136 offset:32768
	ds_read_b128 v[186:189], v136 offset:33792
	ds_read_b128 v[190:193], v135 offset:32768
	ds_read_b128 v[194:197], v135 offset:33792
	global_load_lds_dwordx4 v[198:199], off
	v_lshl_add_u64 v[198:199], v[216:217], 0, s[10:11]
	s_mov_b32 m0, s28
	s_add_u32 s20, s20, 0x100
	global_load_lds_dwordx4 v[198:199], off
	s_waitcnt lgkmcnt(8)
	s_barrier
	s_waitcnt lgkmcnt(0)
	s_addc_u32 s21, s21, 0
	s_setprio 1
	s_waitcnt lgkmcnt(0)
	v_mfma_f32_16x16x32_bf16 v[126:129], v[162:165], v[146:149], v[126:129]
	v_mfma_f32_16x16x32_bf16 v[122:125], v[162:165], v[154:157], v[122:125]
	v_mfma_f32_16x16x32_bf16 v[118:121], v[174:177], v[146:149], v[118:121]
	v_mfma_f32_16x16x32_bf16 v[114:117], v[174:177], v[154:157], v[114:117]
	v_mfma_f32_16x16x32_bf16 v[110:113], v[182:185], v[146:149], v[110:113]
	v_mfma_f32_16x16x32_bf16 v[106:109], v[182:185], v[154:157], v[106:109]
	v_mfma_f32_16x16x32_bf16 v[102:105], v[190:193], v[146:149], v[102:105]
	v_mfma_f32_16x16x32_bf16 v[98:101], v[190:193], v[154:157], v[98:101]
	v_mfma_f32_16x16x32_bf16 v[126:129], v[166:169], v[150:153], v[126:129]
	v_mfma_f32_16x16x32_bf16 v[122:125], v[166:169], v[158:161], v[122:125]
	v_mfma_f32_16x16x32_bf16 v[118:121], v[178:181], v[150:153], v[118:121]
	v_mfma_f32_16x16x32_bf16 v[114:117], v[178:181], v[158:161], v[114:117]
	v_mfma_f32_16x16x32_bf16 v[110:113], v[186:189], v[150:153], v[110:113]
	v_mfma_f32_16x16x32_bf16 v[106:109], v[186:189], v[158:161], v[106:109]
	v_mfma_f32_16x16x32_bf16 v[102:105], v[194:197], v[150:153], v[102:105]
	v_mfma_f32_16x16x32_bf16 v[98:101], v[194:197], v[158:161], v[98:101]
	s_setprio 0
	s_barrier
	v_add_u32_e32 v216, s49, v141
	v_lshl_add_u64 v[214:215], v[218:219], 0, s[12:13]
	v_readfirstlane_b32 s28, v216
	v_add_u32_e32 v216, 0x2000, v216
	s_mov_b32 m0, s28
	v_readfirstlane_b32 s28, v216
	ds_read_b128 v[198:201], v139
	ds_read_b128 v[202:205], v139 offset:1024
	ds_read_b128 v[206:209], v139 offset:2048
	ds_read_b128 v[210:213], v139 offset:3072
	global_load_lds_dwordx4 v[214:215], off
	v_lshl_add_u64 v[214:215], v[220:221], 0, s[12:13]
	s_mov_b32 m0, s28
	s_nop 0
	global_load_lds_dwordx4 v[214:215], off
	s_waitcnt vmcnt(10)
	s_barrier
	s_waitcnt lgkmcnt(0)
	s_setprio 1
	s_waitcnt lgkmcnt(0)
	v_mfma_f32_16x16x32_bf16 v[94:97], v[162:165], v[198:201], v[94:97]
	v_mfma_f32_16x16x32_bf16 v[90:93], v[162:165], v[206:209], v[90:93]
	v_mfma_f32_16x16x32_bf16 v[86:89], v[174:177], v[198:201], v[86:89]
	v_mfma_f32_16x16x32_bf16 v[82:85], v[174:177], v[206:209], v[82:85]
	v_mfma_f32_16x16x32_bf16 v[78:81], v[182:185], v[198:201], v[78:81]
	v_mfma_f32_16x16x32_bf16 v[74:77], v[182:185], v[206:209], v[74:77]
	v_mfma_f32_16x16x32_bf16 v[70:73], v[190:193], v[198:201], v[70:73]
	v_mfma_f32_16x16x32_bf16 v[66:69], v[190:193], v[206:209], v[66:69]
	v_mfma_f32_16x16x32_bf16 v[94:97], v[166:169], v[202:205], v[94:97]
	v_mfma_f32_16x16x32_bf16 v[90:93], v[166:169], v[210:213], v[90:93]
	v_mfma_f32_16x16x32_bf16 v[86:89], v[178:181], v[202:205], v[86:89]
	v_mfma_f32_16x16x32_bf16 v[82:85], v[178:181], v[210:213], v[82:85]
	v_mfma_f32_16x16x32_bf16 v[78:81], v[186:189], v[202:205], v[78:81]
	v_mfma_f32_16x16x32_bf16 v[74:77], v[186:189], v[210:213], v[74:77]
	v_mfma_f32_16x16x32_bf16 v[70:73], v[194:197], v[202:205], v[70:73]
	v_mfma_f32_16x16x32_bf16 v[66:69], v[194:197], v[210:213], v[66:69]
	s_setprio 0
	v_add_u32_e32 v216, 0x8000, v230
	v_lshl_add_u64 v[214:215], v[222:223], 0, s[12:13]
	v_readfirstlane_b32 s28, v216
	v_add_u32_e32 v216, 0xa000, v230
	s_mov_b32 m0, s28
	v_readfirstlane_b32 s28, v216
	s_barrier
; #define STAGE(P, GP, ktrel) do { const GAS char* _g = (GP) + (ktrel) * (BK * 2); \
;     __builtin_amdgcn_global_load_lds((const GAS unsigned*)(_g + so0), (unsigned*)((char*)(P) + tid_ * 16), 16, 0, 0); \
;     __builtin_amdgcn_global_load_lds((const GAS unsigned*)(_g + so1), (unsigned*)((char*)(P) + tid_ * 16 + 8192), 16, 0, 0); } while (0)
; #define WAIT_V(n) asm volatile("s_waitcnt vmcnt(" #n ")" ::: "memory")
; #define WAIT_L(n) asm volatile("s_waitcnt lgkmcnt(" #n ")" ::: "memory")
; #define BAR __builtin_amdgcn_s_barrier()
; #define SCHED __builtin_amdgcn_sched_barrier(0)
; #define LDA(dst, b, h) for (int m = 0; m < 4; ++m) for (int k = 0; k < 2; ++k) \
;     dst[m][k] = *reinterpret_cast<const bf16x8*>((char*)SA(b, h) + lds_byte(wr * 64 + m * 16 + fr, k * 32 + fq * 8))
; #define LDB(dst, b, h) for (int n = 0; n < 2; ++n) for (int k = 0; k < 2; ++k) \
;     dst[n][k] = *reinterpret_cast<const bf16x8*>((char*)SB(b, h) + lds_byte(wc * 32 + n * 16 + fr, k * 32 + fq * 8))
; #define MMA(ai, bj, At_, Bt_) do { __builtin_amdgcn_s_setprio(1); \
;     for (int m = 0; m < 4; ++m) for (int n = 0; n < 2; ++n) for (int k = 0; k < 2; ++k) \
;       acc[ai][bj][m][n] = __builtin_amdgcn_mfma_f32_16x16x32_bf16(At_[m][k], Bt_[n][k], acc[ai][bj][m][n], 0, 0, 0); \
;     __builtin_amdgcn_s_setprio(0); } while (0)
; template <int K, int LD = K>
; __device__ __forceinline__ void gemm_main(const GAS bf16* A, const GAS bf16* Bt, int brow, int bcol, f32x4 (&acc)[2][2][4][2]) {
;     ...
;     LDA(At, 1, 1); STAGE(SA(1, 0), pA0, 3);
;     BAR; WAIT_L(0); MMA(1, 0, At, B0); BAR; SCHED;
;     STAGE(SB(1, 1), pB1, 3);
;     WAIT_V(6); BAR; MMA(1, 1, At, B1); BAR;
;     pA0 += 4 * BK; pA1 += 4 * BK; pB0 += 4 * BK; pB1 += 4 * BK;
;     asm volatile("" : "+s"(pA0), "+s"(pA1), "+s"(pB0), "+s"(pB1));
;   }
;   { LDB(B0, 0, 0); LDA(At, 0, 0); STAGE(SA(1, 1), pA1, 1);
;     BAR; WAIT_L(0); MMA(0, 0, At, B0); BAR;
;     LDB(B1, 0, 1); BAR; WAIT_L(0); MMA(0, 1, At, B1); BAR;
;     LDA(At, 0, 1); WAIT_V(4); BAR; WAIT_L(0); MMA(1, 0, At, B0); MMA(1, 1, At, B1); BAR; }
	ds_read_b128 v[162:165], v138 offset:49152
	ds_read_b128 v[166:169], v138 offset:50176
	ds_read_b128 v[174:177], v137 offset:49152
	ds_read_b128 v[178:181], v137 offset:50176
	ds_read_b128 v[182:185], v136 offset:49152
	ds_read_b128 v[186:189], v136 offset:50176
	ds_read_b128 v[190:193], v135 offset:49152
	ds_read_b128 v[194:197], v135 offset:50176
	global_load_lds_dwordx4 v[214:215], off
	v_lshl_add_u64 v[214:215], v[224:225], 0, s[12:13]
	s_mov_b32 m0, s28
	s_nop 0
	global_load_lds_dwordx4 v[214:215], off
	s_barrier
	s_waitcnt lgkmcnt(0)
	s_setprio 1
	s_waitcnt lgkmcnt(0)
	v_mfma_f32_16x16x32_bf16 v[62:65], v[162:165], v[146:149], v[62:65]
	v_mfma_f32_16x16x32_bf16 v[58:61], v[162:165], v[154:157], v[58:61]
	v_mfma_f32_16x16x32_bf16 v[54:57], v[174:177], v[146:149], v[54:57]
	v_mfma_f32_16x16x32_bf16 v[50:53], v[174:177], v[154:157], v[50:53]
	v_mfma_f32_16x16x32_bf16 v[46:49], v[182:185], v[146:149], v[46:49]
	v_mfma_f32_16x16x32_bf16 v[42:45], v[182:185], v[154:157], v[42:45]
	v_mfma_f32_16x16x32_bf16 v[38:41], v[190:193], v[146:149], v[38:41]
	v_mfma_f32_16x16x32_bf16 v[34:37], v[190:193], v[154:157], v[34:37]
	v_mfma_f32_16x16x32_bf16 v[62:65], v[166:169], v[150:153], v[62:65]
	v_mfma_f32_16x16x32_bf16 v[58:61], v[166:169], v[158:161], v[58:61]
	v_mfma_f32_16x16x32_bf16 v[54:57], v[178:181], v[150:153], v[54:57]
	v_mfma_f32_16x16x32_bf16 v[50:53], v[178:181], v[158:161], v[50:53]
	v_mfma_f32_16x16x32_bf16 v[46:49], v[186:189], v[150:153], v[46:49]
	v_mfma_f32_16x16x32_bf16 v[42:45], v[186:189], v[158:161], v[42:45]
	v_mfma_f32_16x16x32_bf16 v[38:41], v[194:197], v[150:153], v[38:41]
	v_mfma_f32_16x16x32_bf16 v[34:37], v[194:197], v[158:161], v[34:37]
	s_setprio 0
	s_barrier
	v_add_u32_e32 v148, s50, v141
	v_lshl_add_u64 v[146:147], v[226:227], 0, s[12:13]
	v_readfirstlane_b32 s28, v148
	v_add_u32_e32 v148, 0x2000, v148
	s_mov_b32 m0, s28
	v_readfirstlane_b32 s28, v148
	global_load_lds_dwordx4 v[146:147], off
	v_lshl_add_u64 v[146:147], v[228:229], 0, s[12:13]
	s_mov_b32 m0, s28
	s_nop 0
	global_load_lds_dwordx4 v[146:147], off
	s_waitcnt vmcnt(8)
	s_barrier
	s_setprio 1
	v_mfma_f32_16x16x32_bf16 v[30:33], v[162:165], v[198:201], v[30:33]
	v_mfma_f32_16x16x32_bf16 v[26:29], v[162:165], v[206:209], v[26:29]
	v_mfma_f32_16x16x32_bf16 v[22:25], v[174:177], v[198:201], v[22:25]
	v_mfma_f32_16x16x32_bf16 v[18:21], v[174:177], v[206:209], v[18:21]
	v_mfma_f32_16x16x32_bf16 v[14:17], v[182:185], v[198:201], v[14:17]
	v_mfma_f32_16x16x32_bf16 v[10:13], v[182:185], v[206:209], v[10:13]
	v_mfma_f32_16x16x32_bf16 v[6:9], v[190:193], v[198:201], v[6:9]
	v_mfma_f32_16x16x32_bf16 v[2:5], v[190:193], v[206:209], v[2:5]
	v_mfma_f32_16x16x32_bf16 v[30:33], v[166:169], v[202:205], v[30:33]
	v_mfma_f32_16x16x32_bf16 v[26:29], v[166:169], v[210:213], v[26:29]
	v_mfma_f32_16x16x32_bf16 v[22:25], v[178:181], v[202:205], v[22:25]
	v_mfma_f32_16x16x32_bf16 v[18:21], v[178:181], v[210:213], v[18:21]
	v_mfma_f32_16x16x32_bf16 v[14:17], v[186:189], v[202:205], v[14:17]
	v_mfma_f32_16x16x32_bf16 v[10:13], v[186:189], v[210:213], v[10:13]
	v_mfma_f32_16x16x32_bf16 v[6:9], v[194:197], v[202:205], v[6:9]
	v_mfma_f32_16x16x32_bf16 v[2:5], v[194:197], v[210:213], v[2:5]
	s_setprio 0
	s_add_i32 s17, s17, 2
	s_cmp_lt_u32 s17, 4
	s_barrier
	s_cbranch_scc1 .LBB0_715
	v_lshl_add_u64 v[198:199], s[20:21], 0, v[130:131]
	v_readfirstlane_b32 s17, v144
	v_lshl_add_u64 v[198:199], v[198:199], 0, s[6:7]
	s_mov_b32 m0, s17
	v_lshl_add_u64 v[132:133], s[20:21], 0, v[132:133]
	v_readfirstlane_b32 s17, v145
	ds_read_b128 v[146:149], v143
	ds_read_b128 v[150:153], v143 offset:1024
	ds_read_b128 v[154:157], v143 offset:2048
	ds_read_b128 v[158:161], v143 offset:3072
	ds_read_b128 v[162:165], v138
	ds_read_b128 v[166:169], v138 offset:1024
	ds_read_b128 v[174:177], v137
	ds_read_b128 v[178:181], v137 offset:1024
	ds_read_b128 v[182:185], v136
	ds_read_b128 v[186:189], v136 offset:1024
	ds_read_b128 v[190:193], v135
	ds_read_b128 v[194:197], v135 offset:1024
	global_load_lds_dwordx4 v[198:199], off
	v_lshl_add_u64 v[132:133], v[132:133], 0, s[6:7]
	s_mov_b32 m0, s17
	s_nop 0
	global_load_lds_dwordx4 v[132:133], off
	s_barrier
	s_waitcnt lgkmcnt(0)
	s_setprio 1
	s_waitcnt lgkmcnt(0)
	v_mfma_f32_16x16x32_bf16 v[126:129], v[162:165], v[146:149], v[126:129]
	v_mfma_f32_16x16x32_bf16 v[122:125], v[162:165], v[154:157], v[122:125]
	v_mfma_f32_16x16x32_bf16 v[110:113], v[182:185], v[146:149], v[110:113]
	v_mfma_f32_16x16x32_bf16 v[106:109], v[182:185], v[154:157], v[106:109]
	v_mfma_f32_16x16x32_bf16 v[126:129], v[166:169], v[150:153], v[126:129]
	v_mfma_f32_16x16x32_bf16 v[122:125], v[166:169], v[158:161], v[122:125]
	v_mfma_f32_16x16x32_bf16 v[118:121], v[174:177], v[146:149], v[118:121]
	v_mfma_f32_16x16x32_bf16 v[114:117], v[174:177], v[154:157], v[114:117]
	v_mfma_f32_16x16x32_bf16 v[110:113], v[186:189], v[150:153], v[110:113]
	v_mfma_f32_16x16x32_bf16 v[106:109], v[186:189], v[158:161], v[106:109]
	v_mfma_f32_16x16x32_bf16 v[102:105], v[190:193], v[146:149], v[102:105]
	v_mfma_f32_16x16x32_bf16 v[98:101], v[190:193], v[154:157], v[98:101]
	v_mfma_f32_16x16x32_bf16 v[198:201], v[178:181], v[150:153], v[118:121]
	v_mfma_f32_16x16x32_bf16 v[202:205], v[178:181], v[158:161], v[114:117]
	v_mfma_f32_16x16x32_bf16 v[206:209], v[194:197], v[150:153], v[102:105]
	v_mfma_f32_16x16x32_bf16 v[210:213], v[194:197], v[158:161], v[98:101]
	s_setprio 0
	s_barrier
	s_nop 1
	ds_read_b128 v[98:101], v142
	ds_read_b128 v[102:105], v142 offset:1024
	ds_read_b128 v[114:117], v142 offset:2048
	ds_read_b128 v[118:121], v142 offset:3072
	s_waitcnt vmcnt(8)
	s_barrier
; #define WAIT_V(n) asm volatile("s_waitcnt vmcnt(" #n ")" ::: "memory")
; #define WAIT_L(n) asm volatile("s_waitcnt lgkmcnt(" #n ")" ::: "memory")
; #define BAR __builtin_amdgcn_s_barrier()
; #define LDA(dst, b, h) for (int m = 0; m < 4; ++m) for (int k = 0; k < 2; ++k) \
;     dst[m][k] = *reinterpret_cast<const bf16x8*>((char*)SA(b, h) + lds_byte(wr * 64 + m * 16 + fr, k * 32 + fq * 8))
; #define LDB(dst, b, h) for (int n = 0; n < 2; ++n) for (int k = 0; k < 2; ++k) \
;     dst[n][k] = *reinterpret_cast<const bf16x8*>((char*)SB(b, h) + lds_byte(wc * 32 + n * 16 + fr, k * 32 + fq * 8))
; #define MMA(ai, bj, At_, Bt_) do { __builtin_amdgcn_s_setprio(1); \
;     for (int m = 0; m < 4; ++m) for (int n = 0; n < 2; ++n) for (int k = 0; k < 2; ++k) \
;       acc[ai][bj][m][n] = __builtin_amdgcn_mfma_f32_16x16x32_bf16(At_[m][k], Bt_[n][k], acc[ai][bj][m][n], 0, 0, 0); \
;     __builtin_amdgcn_s_setprio(0); } while (0)
; template <int K, int LD = K>
; __device__ __forceinline__ void gemm_main(const GAS bf16* A, const GAS bf16* Bt, int brow, int bcol, f32x4 (&acc)[2][2][4][2]) {
;     ...
;     LDB(B1, 0, 1); BAR; WAIT_L(0); MMA(0, 1, At, B1); BAR;
;     LDA(At, 0, 1); WAIT_V(4); BAR; WAIT_L(0); MMA(1, 0, At, B0); MMA(1, 1, At, B1); BAR; }
;   { LDB(B0, 1, 0); LDA(At, 1, 0); WAIT_V(2); BAR; WAIT_L(0); MMA(0, 0, At, B0); BAR;
	s_waitcnt lgkmcnt(0)
	s_setprio 1
	s_waitcnt lgkmcnt(0)
	v_mfma_f32_16x16x32_bf16 v[94:97], v[162:165], v[98:101], v[94:97]
	v_mfma_f32_16x16x32_bf16 v[90:93], v[162:165], v[114:117], v[90:93]
	v_mfma_f32_16x16x32_bf16 v[78:81], v[182:185], v[98:101], v[78:81]
	v_mfma_f32_16x16x32_bf16 v[74:77], v[182:185], v[114:117], v[74:77]
	v_mfma_f32_16x16x32_bf16 v[94:97], v[166:169], v[102:105], v[94:97]
	v_mfma_f32_16x16x32_bf16 v[90:93], v[166:169], v[118:121], v[90:93]
	v_mfma_f32_16x16x32_bf16 v[86:89], v[174:177], v[98:101], v[86:89]
	v_mfma_f32_16x16x32_bf16 v[82:85], v[174:177], v[114:117], v[82:85]
	v_mfma_f32_16x16x32_bf16 v[78:81], v[186:189], v[102:105], v[78:81]
	v_mfma_f32_16x16x32_bf16 v[74:77], v[186:189], v[118:121], v[74:77]
	v_mfma_f32_16x16x32_bf16 v[70:73], v[190:193], v[98:101], v[70:73]
	v_mfma_f32_16x16x32_bf16 v[66:69], v[190:193], v[114:117], v[66:69]
	v_mfma_f32_16x16x32_bf16 v[142:145], v[178:181], v[102:105], v[86:89]
	v_mfma_f32_16x16x32_bf16 v[162:165], v[178:181], v[118:121], v[82:85]
	v_mfma_f32_16x16x32_bf16 v[166:169], v[194:197], v[102:105], v[70:73]
	v_mfma_f32_16x16x32_bf16 v[174:177], v[194:197], v[118:121], v[66:69]
	s_setprio 0
	s_barrier
	s_nop 1
	ds_read_b128 v[66:69], v138 offset:16384
	ds_read_b128 v[70:73], v138 offset:17408
	ds_read_b128 v[82:85], v137 offset:16384
	ds_read_b128 v[86:89], v137 offset:17408
	ds_read_b128 v[178:181], v136 offset:16384
	ds_read_b128 v[182:185], v136 offset:17408
	ds_read_b128 v[186:189], v135 offset:16384
	ds_read_b128 v[190:193], v135 offset:17408
	s_waitcnt vmcnt(4)
	s_barrier
	s_waitcnt lgkmcnt(0)
	s_setprio 1
	s_waitcnt lgkmcnt(0)
	v_mfma_f32_16x16x32_bf16 v[62:65], v[66:69], v[146:149], v[62:65]
	v_mfma_f32_16x16x32_bf16 v[54:57], v[82:85], v[146:149], v[54:57]
	v_mfma_f32_16x16x32_bf16 v[46:49], v[178:181], v[146:149], v[46:49]
	v_mfma_f32_16x16x32_bf16 v[38:41], v[186:189], v[146:149], v[38:41]
	v_mfma_f32_16x16x32_bf16 v[62:65], v[70:73], v[150:153], v[62:65]
	v_mfma_f32_16x16x32_bf16 v[58:61], v[66:69], v[154:157], v[58:61]
	v_mfma_f32_16x16x32_bf16 v[54:57], v[86:89], v[150:153], v[54:57]
	v_mfma_f32_16x16x32_bf16 v[50:53], v[82:85], v[154:157], v[50:53]
	v_mfma_f32_16x16x32_bf16 v[46:49], v[182:185], v[150:153], v[46:49]
	v_mfma_f32_16x16x32_bf16 v[42:45], v[178:181], v[154:157], v[42:45]
	v_mfma_f32_16x16x32_bf16 v[38:41], v[190:193], v[150:153], v[38:41]
	v_mfma_f32_16x16x32_bf16 v[34:37], v[186:189], v[154:157], v[34:37]
	v_mfma_f32_16x16x32_bf16 v[194:197], v[70:73], v[158:161], v[58:61]
	v_mfma_f32_16x16x32_bf16 v[214:217], v[86:89], v[158:161], v[50:53]
	v_mfma_f32_16x16x32_bf16 v[218:221], v[182:185], v[158:161], v[42:45]
	v_mfma_f32_16x16x32_bf16 v[146:149], v[190:193], v[158:161], v[34:37]
	s_setprio 0
	s_setprio 1
	v_mfma_f32_16x16x32_bf16 v[30:33], v[66:69], v[98:101], v[30:33]
	v_mfma_f32_16x16x32_bf16 v[22:25], v[82:85], v[98:101], v[22:25]
	v_mfma_f32_16x16x32_bf16 v[14:17], v[178:181], v[98:101], v[14:17]
	v_mfma_f32_16x16x32_bf16 v[6:9], v[186:189], v[98:101], v[6:9]
	v_mfma_f32_16x16x32_bf16 v[30:33], v[70:73], v[102:105], v[30:33]
	v_mfma_f32_16x16x32_bf16 v[26:29], v[66:69], v[114:117], v[26:29]
	v_mfma_f32_16x16x32_bf16 v[22:25], v[86:89], v[102:105], v[22:25]
	v_mfma_f32_16x16x32_bf16 v[18:21], v[82:85], v[114:117], v[18:21]
	v_mfma_f32_16x16x32_bf16 v[14:17], v[182:185], v[102:105], v[14:17]
	v_mfma_f32_16x16x32_bf16 v[10:13], v[178:181], v[114:117], v[10:13]
	v_mfma_f32_16x16x32_bf16 v[6:9], v[190:193], v[102:105], v[6:9]
	v_mfma_f32_16x16x32_bf16 v[2:5], v[186:189], v[114:117], v[2:5]
	v_mfma_f32_16x16x32_bf16 v[150:153], v[70:73], v[118:121], v[26:29]
	v_mfma_f32_16x16x32_bf16 v[154:157], v[86:89], v[118:121], v[18:21]
	v_mfma_f32_16x16x32_bf16 v[158:161], v[182:185], v[118:121], v[10:13]
	v_mfma_f32_16x16x32_bf16 v[178:181], v[190:193], v[118:121], v[2:5]
	s_setprio 0
	s_barrier
	s_nop 1
	ds_read_b128 v[2:5], v140
	ds_read_b128 v[10:13], v140 offset:1024
	ds_read_b128 v[182:185], v140 offset:2048
	ds_read_b128 v[186:189], v140 offset:3072
	ds_read_b128 v[18:21], v138 offset:32768
	ds_read_b128 v[26:29], v138 offset:33792
	ds_read_b128 v[34:37], v137 offset:32768
	ds_read_b128 v[42:45], v137 offset:33792
	ds_read_b128 v[50:53], v136 offset:32768
	ds_read_b128 v[58:61], v136 offset:33792
	ds_read_b128 v[190:193], v135 offset:32768
	ds_read_b128 v[222:225], v135 offset:33792
	s_waitcnt vmcnt(2)
	s_barrier
; #define WAIT_V(n) asm volatile("s_waitcnt vmcnt(" #n ")" ::: "memory")
; #define WAIT_L(n) asm volatile("s_waitcnt lgkmcnt(" #n ")" ::: "memory")
; #define BAR __builtin_amdgcn_s_barrier()
; #define LDA(dst, b, h) for (int m = 0; m < 4; ++m) for (int k = 0; k < 2; ++k) \
;     dst[m][k] = *reinterpret_cast<const bf16x8*>((char*)SA(b, h) + lds_byte(wr * 64 + m * 16 + fr, k * 32 + fq * 8))
; #define LDB(dst, b, h) for (int n = 0; n < 2; ++n) for (int k = 0; k < 2; ++k) \
;     dst[n][k] = *reinterpret_cast<const bf16x8*>((char*)SB(b, h) + lds_byte(wc * 32 + n * 16 + fr, k * 32 + fq * 8))
; #define MMA(ai, bj, At_, Bt_) do { __builtin_amdgcn_s_setprio(1); \
;     for (int m = 0; m < 4; ++m) for (int n = 0; n < 2; ++n) for (int k = 0; k < 2; ++k) \
;       acc[ai][bj][m][n] = __builtin_amdgcn_mfma_f32_16x16x32_bf16(At_[m][k], Bt_[n][k], acc[ai][bj][m][n], 0, 0, 0); \
;     __builtin_amdgcn_s_setprio(0); } while (0)
; template <int K, int LD = K>
; __device__ __forceinline__ void gemm_main(const GAS bf16* A, const GAS bf16* Bt, int brow, int bcol, f32x4 (&acc)[2][2][4][2]) {
;     ...
;   { LDB(B0, 1, 0); LDA(At, 1, 0); WAIT_V(2); BAR; WAIT_L(0); MMA(0, 0, At, B0); BAR;
;     LDB(B1, 1, 1); WAIT_V(0); BAR; WAIT_L(0); MMA(0, 1, At, B1); BAR;
;     LDA(At, 1, 1); BAR; WAIT_L(0); MMA(1, 0, At, B0); MMA(1, 1, At, B1); BAR; }
;   if (wr == 0) BAR;
	s_waitcnt lgkmcnt(0)
	s_setprio 1
	s_waitcnt lgkmcnt(0)
	v_mfma_f32_16x16x32_bf16 v[66:69], v[18:21], v[2:5], v[126:129]
	v_mfma_f32_16x16x32_bf16 v[118:121], v[26:29], v[10:13], v[66:69]
	v_mfma_f32_16x16x32_bf16 v[66:69], v[18:21], v[182:185], v[122:125]
	v_mfma_f32_16x16x32_bf16 v[114:117], v[26:29], v[186:189], v[66:69]
	v_mfma_f32_16x16x32_bf16 v[66:69], v[34:37], v[2:5], v[198:201]
	v_mfma_f32_16x16x32_bf16 v[102:105], v[42:45], v[10:13], v[66:69]
	v_mfma_f32_16x16x32_bf16 v[66:69], v[34:37], v[182:185], v[202:205]
	v_mfma_f32_16x16x32_bf16 v[98:101], v[42:45], v[186:189], v[66:69]
	v_mfma_f32_16x16x32_bf16 v[66:69], v[50:53], v[2:5], v[110:113]
	v_mfma_f32_16x16x32_bf16 v[86:89], v[58:61], v[10:13], v[66:69]
	v_mfma_f32_16x16x32_bf16 v[66:69], v[50:53], v[182:185], v[106:109]
	v_mfma_f32_16x16x32_bf16 v[82:85], v[58:61], v[186:189], v[66:69]
	v_mfma_f32_16x16x32_bf16 v[66:69], v[190:193], v[2:5], v[206:209]
	v_mfma_f32_16x16x32_bf16 v[70:73], v[222:225], v[10:13], v[66:69]
	v_mfma_f32_16x16x32_bf16 v[66:69], v[190:193], v[182:185], v[210:213]
	v_mfma_f32_16x16x32_bf16 v[66:69], v[222:225], v[186:189], v[66:69]
	s_setprio 0
	s_barrier
	ds_read_b128 v[198:201], v139
	ds_read_b128 v[202:205], v139 offset:1024
	ds_read_b128 v[206:209], v139 offset:2048
	ds_read_b128 v[210:213], v139 offset:3072
	s_waitcnt vmcnt(0)
	s_barrier
	s_waitcnt lgkmcnt(0)
	s_setprio 1
	s_waitcnt lgkmcnt(0)
	v_mfma_f32_16x16x32_bf16 v[94:97], v[18:21], v[198:201], v[94:97]
	v_mfma_f32_16x16x32_bf16 v[18:21], v[18:21], v[206:209], v[90:93]
	v_mfma_f32_16x16x32_bf16 v[122:125], v[26:29], v[210:213], v[18:21]
	v_mfma_f32_16x16x32_bf16 v[18:21], v[34:37], v[198:201], v[142:145]
	v_mfma_f32_16x16x32_bf16 v[110:113], v[42:45], v[202:205], v[18:21]
	v_mfma_f32_16x16x32_bf16 v[18:21], v[34:37], v[206:209], v[162:165]
	v_mfma_f32_16x16x32_bf16 v[106:109], v[42:45], v[210:213], v[18:21]
	v_mfma_f32_16x16x32_bf16 v[18:21], v[50:53], v[198:201], v[78:81]
	v_mfma_f32_16x16x32_bf16 v[126:129], v[26:29], v[202:205], v[94:97]
	v_mfma_f32_16x16x32_bf16 v[94:97], v[58:61], v[202:205], v[18:21]
	v_mfma_f32_16x16x32_bf16 v[18:21], v[50:53], v[206:209], v[74:77]
	v_mfma_f32_16x16x32_bf16 v[90:93], v[58:61], v[210:213], v[18:21]
	v_mfma_f32_16x16x32_bf16 v[18:21], v[190:193], v[198:201], v[166:169]
	v_mfma_f32_16x16x32_bf16 v[78:81], v[222:225], v[202:205], v[18:21]
	v_mfma_f32_16x16x32_bf16 v[18:21], v[190:193], v[206:209], v[174:177]
	v_mfma_f32_16x16x32_bf16 v[74:77], v[222:225], v[210:213], v[18:21]
	s_setprio 0
	s_barrier
	ds_read_b128 v[140:143], v138 offset:49152
	ds_read_b128 v[162:165], v138 offset:50176
	ds_read_b128 v[166:169], v137 offset:49152
	ds_read_b128 v[174:177], v137 offset:50176
	ds_read_b128 v[190:193], v136 offset:49152
	ds_read_b128 v[136:139], v136 offset:50176
	ds_read_b128 v[222:225], v135 offset:49152
	ds_read_b128 v[226:229], v135 offset:50176
	s_barrier
	s_waitcnt lgkmcnt(0)
	s_setprio 1
	s_waitcnt lgkmcnt(0)
	v_mfma_f32_16x16x32_bf16 v[18:21], v[140:143], v[2:5], v[62:65]
	v_mfma_f32_16x16x32_bf16 v[58:61], v[162:165], v[10:13], v[18:21]
	v_mfma_f32_16x16x32_bf16 v[18:21], v[140:143], v[182:185], v[194:197]
	v_mfma_f32_16x16x32_bf16 v[50:53], v[162:165], v[186:189], v[18:21]
	v_mfma_f32_16x16x32_bf16 v[18:21], v[166:169], v[2:5], v[54:57]
	v_mfma_f32_16x16x32_bf16 v[42:45], v[174:177], v[10:13], v[18:21]
	v_mfma_f32_16x16x32_bf16 v[18:21], v[166:169], v[182:185], v[214:217]
	v_mfma_f32_16x16x32_bf16 v[34:37], v[174:177], v[186:189], v[18:21]
	v_mfma_f32_16x16x32_bf16 v[18:21], v[190:193], v[2:5], v[46:49]
	v_mfma_f32_16x16x32_bf16 v[2:5], v[222:225], v[2:5], v[38:41]
	v_mfma_f32_16x16x32_bf16 v[26:29], v[136:139], v[10:13], v[18:21]
	v_mfma_f32_16x16x32_bf16 v[18:21], v[190:193], v[182:185], v[218:221]
	v_mfma_f32_16x16x32_bf16 v[10:13], v[226:229], v[10:13], v[2:5]
	v_mfma_f32_16x16x32_bf16 v[2:5], v[222:225], v[182:185], v[146:149]
	v_mfma_f32_16x16x32_bf16 v[18:21], v[136:139], v[186:189], v[18:21]
	v_mfma_f32_16x16x32_bf16 v[2:5], v[226:229], v[186:189], v[2:5]
	s_setprio 0
	s_setprio 1
	v_mfma_f32_16x16x32_bf16 v[30:33], v[140:143], v[198:201], v[30:33]
	v_mfma_f32_16x16x32_bf16 v[62:65], v[162:165], v[202:205], v[30:33]
	v_mfma_f32_16x16x32_bf16 v[30:33], v[140:143], v[206:209], v[150:153]
	v_mfma_f32_16x16x32_bf16 v[22:25], v[166:169], v[198:201], v[22:25]
	v_mfma_f32_16x16x32_bf16 v[14:17], v[190:193], v[198:201], v[14:17]
	v_mfma_f32_16x16x32_bf16 v[54:57], v[162:165], v[210:213], v[30:33]
	v_mfma_f32_16x16x32_bf16 v[46:49], v[174:177], v[202:205], v[22:25]
	v_mfma_f32_16x16x32_bf16 v[22:25], v[166:169], v[206:209], v[154:157]
	v_mfma_f32_16x16x32_bf16 v[30:33], v[136:139], v[202:205], v[14:17]
	v_mfma_f32_16x16x32_bf16 v[14:17], v[190:193], v[206:209], v[158:161]
	v_mfma_f32_16x16x32_bf16 v[6:9], v[222:225], v[198:201], v[6:9]
	v_mfma_f32_16x16x32_bf16 v[38:41], v[174:177], v[210:213], v[22:25]
	v_mfma_f32_16x16x32_bf16 v[22:25], v[136:139], v[210:213], v[14:17]
	v_mfma_f32_16x16x32_bf16 v[14:17], v[226:229], v[202:205], v[6:9]
	v_mfma_f32_16x16x32_bf16 v[6:9], v[222:225], v[206:209], v[178:181]
	v_mfma_f32_16x16x32_bf16 v[6:9], v[226:229], v[210:213], v[6:9]
	s_setprio 0
	v_cmp_gt_u32_e32 vcc, s51, v134
	s_barrier
	s_and_saveexec_b64 s[20:21], vcc
	s_cbranch_execz .LBB0_718
	s_barrier

; #define STAGE(P, GP, ktrel) do { const GAS char* _g = (GP) + (ktrel) * (BK * 2); \
;     __builtin_amdgcn_global_load_lds((const GAS unsigned*)(_g + so0), (unsigned*)((char*)(P) + tid_ * 16), 16, 0, 0); \
;     __builtin_amdgcn_global_load_lds((const GAS unsigned*)(_g + so1), (unsigned*)((char*)(P) + tid_ * 16 + 8192), 16, 0, 0); } while (0)
; #define WAIT_L(n) asm volatile("s_waitcnt lgkmcnt(" #n ")" ::: "memory")
; #define BAR __builtin_amdgcn_s_barrier()
; #define SCHED __builtin_amdgcn_sched_barrier(0)
; #define LDA(dst, b, h) for (int m = 0; m < 4; ++m) for (int k = 0; k < 2; ++k) \
;     dst[m][k] = *reinterpret_cast<const bf16x8*>((char*)SA(b, h) + lds_byte(wr * 64 + m * 16 + fr, k * 32 + fq * 8))
; #define LDB(dst, b, h) for (int n = 0; n < 2; ++n) for (int k = 0; k < 2; ++k) \
;     dst[n][k] = *reinterpret_cast<const bf16x8*>((char*)SB(b, h) + lds_byte(wc * 32 + n * 16 + fr, k * 32 + fq * 8))
; #define MMA(ai, bj, At_, Bt_) do { __builtin_amdgcn_s_setprio(1); \
;     for (int m = 0; m < 4; ++m) for (int n = 0; n < 2; ++n) for (int k = 0; k < 2; ++k) \
;       acc[ai][bj][m][n] = __builtin_amdgcn_mfma_f32_16x16x32_bf16(At_[m][k], Bt_[n][k], acc[ai][bj][m][n], 0, 0, 0); \
;     __builtin_amdgcn_s_setprio(0); } while (0)
; template <int K, int LD = K>
; __device__ __forceinline__ void gemm_main(const GAS bf16* A, const GAS bf16* Bt, int brow, int bcol, f32x4 (&acc)[2][2][4][2]) {
;     ...
;   for (int t = 0; t < nt - 2; t += 2) {
;     LDB(B0, 0, 0); SCHED; LDA(At, 0, 0); STAGE(SA(1, 1), pA1, 1);
;     WAIT_L(8); BAR; WAIT_L(0); MMA(0, 0, At, B0); BAR; SCHED;
;     LDB(B1, 0, 1); STAGE(SB(0, 0), pB0, 2);
;     BAR; WAIT_L(0); MMA(0, 1, At, B1); BAR;
;     LDA(At, 0, 1); STAGE(SA(0, 0), pA0, 2);
;     BAR; WAIT_L(0); MMA(1, 0, At, B0); BAR; SCHED;
.LBB0_767:
	ds_read_b128 v[160:163], v144
	ds_read_b128 v[164:167], v144 offset:1024
	ds_read_b128 v[174:177], v144 offset:2048
	ds_read_b128 v[178:181], v144 offset:3072
	v_lshl_add_u64 v[168:169], s[10:11], 0, v[130:131]
	v_readfirstlane_b32 s22, v143
	v_lshl_add_u64 v[214:215], v[168:169], 0, s[4:5]
	s_mov_b32 m0, s22
	v_lshl_add_u64 v[230:231], s[10:11], 0, v[132:133]
	v_readfirstlane_b32 s22, v142
	ds_read_b128 v[182:185], v138
	ds_read_b128 v[186:189], v138 offset:1024
	ds_read_b128 v[190:193], v137
	ds_read_b128 v[194:197], v137 offset:1024
	ds_read_b128 v[198:201], v136
	ds_read_b128 v[202:205], v136 offset:1024
	ds_read_b128 v[206:209], v135
	ds_read_b128 v[210:213], v135 offset:1024
	global_load_lds_dwordx4 v[214:215], off
	v_lshl_add_u64 v[214:215], v[230:231], 0, s[4:5]
	s_mov_b32 m0, s22
	s_nop 0
	global_load_lds_dwordx4 v[214:215], off
	s_waitcnt lgkmcnt(8)
	s_barrier
	s_waitcnt lgkmcnt(0)
	s_setprio 1
	s_waitcnt lgkmcnt(0)
	v_mfma_f32_16x16x32_bf16 v[126:129], v[182:185], v[160:163], v[126:129]
	v_mfma_f32_16x16x32_bf16 v[122:125], v[182:185], v[174:177], v[122:125]
	v_mfma_f32_16x16x32_bf16 v[118:121], v[190:193], v[160:163], v[118:121]
	v_mfma_f32_16x16x32_bf16 v[114:117], v[190:193], v[174:177], v[114:117]
	v_mfma_f32_16x16x32_bf16 v[110:113], v[198:201], v[160:163], v[110:113]
	v_mfma_f32_16x16x32_bf16 v[106:109], v[198:201], v[174:177], v[106:109]
	v_mfma_f32_16x16x32_bf16 v[102:105], v[206:209], v[160:163], v[102:105]
	v_mfma_f32_16x16x32_bf16 v[98:101], v[206:209], v[174:177], v[98:101]
	v_mfma_f32_16x16x32_bf16 v[126:129], v[186:189], v[164:167], v[126:129]
	v_mfma_f32_16x16x32_bf16 v[122:125], v[186:189], v[178:181], v[122:125]
	v_mfma_f32_16x16x32_bf16 v[118:121], v[194:197], v[164:167], v[118:121]
	v_mfma_f32_16x16x32_bf16 v[114:117], v[194:197], v[178:181], v[114:117]
	v_mfma_f32_16x16x32_bf16 v[110:113], v[202:205], v[164:167], v[110:113]
	v_mfma_f32_16x16x32_bf16 v[106:109], v[202:205], v[178:181], v[106:109]
	v_mfma_f32_16x16x32_bf16 v[102:105], v[210:213], v[164:167], v[102:105]
	v_mfma_f32_16x16x32_bf16 v[98:101], v[210:213], v[178:181], v[98:101]
	s_setprio 0
	s_barrier
	v_lshl_add_u64 v[232:233], s[20:21], 0, v[130:131]
	v_readfirstlane_b32 s22, v151
	v_lshl_add_u64 v[234:235], v[232:233], 0, s[6:7]
	s_mov_b32 m0, s22
	ds_read_b128 v[214:217], v141
	ds_read_b128 v[218:221], v141 offset:1024
	ds_read_b128 v[222:225], v141 offset:2048
	ds_read_b128 v[226:229], v141 offset:3072
	global_load_lds_dwordx4 v[234:235], off
	v_lshl_add_u64 v[234:235], s[20:21], 0, v[132:133]
	v_readfirstlane_b32 s22, v152
	v_lshl_add_u64 v[236:237], v[234:235], 0, s[6:7]
	s_mov_b32 m0, s22
	s_add_u32 s20, s20, 0x100
	global_load_lds_dwordx4 v[236:237], off
	s_waitcnt vmcnt(10)
	s_barrier
	s_waitcnt lgkmcnt(0)
	s_addc_u32 s21, s21, 0
	s_setprio 1
	s_waitcnt lgkmcnt(0)
	v_mfma_f32_16x16x32_bf16 v[94:97], v[182:185], v[214:217], v[94:97]
	v_mfma_f32_16x16x32_bf16 v[90:93], v[182:185], v[222:225], v[90:93]
	v_mfma_f32_16x16x32_bf16 v[86:89], v[190:193], v[214:217], v[86:89]
	v_mfma_f32_16x16x32_bf16 v[82:85], v[190:193], v[222:225], v[82:85]
	v_mfma_f32_16x16x32_bf16 v[78:81], v[198:201], v[214:217], v[78:81]
	v_mfma_f32_16x16x32_bf16 v[74:77], v[198:201], v[222:225], v[74:77]
	v_mfma_f32_16x16x32_bf16 v[70:73], v[206:209], v[214:217], v[70:73]
	v_mfma_f32_16x16x32_bf16 v[66:69], v[206:209], v[222:225], v[66:69]
	v_mfma_f32_16x16x32_bf16 v[94:97], v[186:189], v[218:221], v[94:97]
	v_mfma_f32_16x16x32_bf16 v[90:93], v[186:189], v[226:229], v[90:93]
	v_mfma_f32_16x16x32_bf16 v[86:89], v[194:197], v[218:221], v[86:89]
	v_mfma_f32_16x16x32_bf16 v[82:85], v[194:197], v[226:229], v[82:85]
	v_mfma_f32_16x16x32_bf16 v[78:81], v[202:205], v[218:221], v[78:81]
	v_mfma_f32_16x16x32_bf16 v[74:77], v[202:205], v[226:229], v[74:77]
	v_mfma_f32_16x16x32_bf16 v[70:73], v[210:213], v[218:221], v[70:73]
	v_mfma_f32_16x16x32_bf16 v[66:69], v[210:213], v[226:229], v[66:69]
	s_setprio 0
	v_lshl_add_u64 v[236:237], s[18:19], 0, v[130:131]
	v_readfirstlane_b32 s22, v145
	v_lshl_add_u64 v[238:239], v[236:237], 0, s[6:7]
	s_mov_b32 m0, s22
	s_barrier
	ds_read_b128 v[182:185], v138 offset:16384
	ds_read_b128 v[186:189], v138 offset:17408
	ds_read_b128 v[190:193], v137 offset:16384
	ds_read_b128 v[194:197], v137 offset:17408
	ds_read_b128 v[198:201], v136 offset:16384
	ds_read_b128 v[202:205], v136 offset:17408
	ds_read_b128 v[206:209], v135 offset:16384
	ds_read_b128 v[210:213], v135 offset:17408
	global_load_lds_dwordx4 v[238:239], off
	v_lshl_add_u64 v[238:239], s[18:19], 0, v[132:133]
	v_readfirstlane_b32 s22, v146
	v_lshl_add_u64 v[240:241], v[238:239], 0, s[6:7]
	s_mov_b32 m0, s22
	s_add_u32 s18, s18, 0x100
	global_load_lds_dwordx4 v[240:241], off
	s_barrier
	s_waitcnt lgkmcnt(0)
	s_addc_u32 s19, s19, 0
	s_setprio 1
	s_waitcnt lgkmcnt(0)
	v_mfma_f32_16x16x32_bf16 v[62:65], v[182:185], v[160:163], v[62:65]
	v_mfma_f32_16x16x32_bf16 v[58:61], v[182:185], v[174:177], v[58:61]
	v_mfma_f32_16x16x32_bf16 v[54:57], v[190:193], v[160:163], v[54:57]
	v_mfma_f32_16x16x32_bf16 v[50:53], v[190:193], v[174:177], v[50:53]
	v_mfma_f32_16x16x32_bf16 v[46:49], v[198:201], v[160:163], v[46:49]
	v_mfma_f32_16x16x32_bf16 v[42:45], v[198:201], v[174:177], v[42:45]
	v_mfma_f32_16x16x32_bf16 v[38:41], v[206:209], v[160:163], v[38:41]
	v_mfma_f32_16x16x32_bf16 v[34:37], v[206:209], v[174:177], v[34:37]
	v_mfma_f32_16x16x32_bf16 v[62:65], v[186:189], v[164:167], v[62:65]
	v_mfma_f32_16x16x32_bf16 v[58:61], v[186:189], v[178:181], v[58:61]
	v_mfma_f32_16x16x32_bf16 v[54:57], v[194:197], v[164:167], v[54:57]
	v_mfma_f32_16x16x32_bf16 v[50:53], v[194:197], v[178:181], v[50:53]
	v_mfma_f32_16x16x32_bf16 v[46:49], v[202:205], v[164:167], v[46:49]
	v_mfma_f32_16x16x32_bf16 v[42:45], v[202:205], v[178:181], v[42:45]
	v_mfma_f32_16x16x32_bf16 v[38:41], v[210:213], v[164:167], v[38:41]
	v_mfma_f32_16x16x32_bf16 v[34:37], v[210:213], v[178:181], v[34:37]
	s_setprio 0
	s_barrier
; #define STAGE(P, GP, ktrel) do { const GAS char* _g = (GP) + (ktrel) * (BK * 2); \
;     __builtin_amdgcn_global_load_lds((const GAS unsigned*)(_g + so0), (unsigned*)((char*)(P) + tid_ * 16), 16, 0, 0); \
;     __builtin_amdgcn_global_load_lds((const GAS unsigned*)(_g + so1), (unsigned*)((char*)(P) + tid_ * 16 + 8192), 16, 0, 0); } while (0)
; #define WAIT_V(n) asm volatile("s_waitcnt vmcnt(" #n ")" ::: "memory")
; #define WAIT_L(n) asm volatile("s_waitcnt lgkmcnt(" #n ")" ::: "memory")
; #define BAR __builtin_amdgcn_s_barrier()
; #define SCHED __builtin_amdgcn_sched_barrier(0)
; #define LDA(dst, b, h) for (int m = 0; m < 4; ++m) for (int k = 0; k < 2; ++k) \
;     dst[m][k] = *reinterpret_cast<const bf16x8*>((char*)SA(b, h) + lds_byte(wr * 64 + m * 16 + fr, k * 32 + fq * 8))
; #define LDB(dst, b, h) for (int n = 0; n < 2; ++n) for (int k = 0; k < 2; ++k) \
;     dst[n][k] = *reinterpret_cast<const bf16x8*>((char*)SB(b, h) + lds_byte(wc * 32 + n * 16 + fr, k * 32 + fq * 8))
; #define MMA(ai, bj, At_, Bt_) do { __builtin_amdgcn_s_setprio(1); \
;     for (int m = 0; m < 4; ++m) for (int n = 0; n < 2; ++n) for (int k = 0; k < 2; ++k) \
;       acc[ai][bj][m][n] = __builtin_amdgcn_mfma_f32_16x16x32_bf16(At_[m][k], Bt_[n][k], acc[ai][bj][m][n], 0, 0, 0); \
;     __builtin_amdgcn_s_setprio(0); } while (0)
; template <int K, int LD = K>
; __device__ __forceinline__ void gemm_main(const GAS bf16* A, const GAS bf16* Bt, int brow, int bcol, f32x4 (&acc)[2][2][4][2]) {
;     ...
;     STAGE(SB(0, 1), pB1, 2);
;     WAIT_V(6); BAR; MMA(1, 1, At, B1); BAR;
;     LDB(B0, 1, 0); SCHED; LDA(At, 1, 0); STAGE(SA(0, 1), pA1, 2);
;     WAIT_L(8); BAR; WAIT_L(0); MMA(0, 0, At, B0); BAR; SCHED;
;     LDB(B1, 1, 1); STAGE(SB(1, 0), pB0, 3);
;     BAR; WAIT_L(0); MMA(0, 1, At, B1); BAR;
	v_lshl_add_u64 v[240:241], s[16:17], 0, v[130:131]
	v_readfirstlane_b32 s22, v153
	v_lshl_add_u64 v[160:161], v[240:241], 0, s[6:7]
	s_mov_b32 m0, s22
	v_lshl_add_u64 v[242:243], s[16:17], 0, v[132:133]
	v_readfirstlane_b32 s22, v154
	global_load_lds_dwordx4 v[160:161], off
	v_lshl_add_u64 v[160:161], v[242:243], 0, s[6:7]
	s_mov_b32 m0, s22
	s_add_u32 s16, s16, 0x100
	global_load_lds_dwordx4 v[160:161], off
	s_waitcnt vmcnt(8)
	s_addc_u32 s17, s17, 0
	s_barrier
	s_setprio 1
	v_mfma_f32_16x16x32_bf16 v[30:33], v[182:185], v[214:217], v[30:33]
	v_mfma_f32_16x16x32_bf16 v[26:29], v[182:185], v[222:225], v[26:29]
	v_mfma_f32_16x16x32_bf16 v[22:25], v[190:193], v[214:217], v[22:25]
	v_mfma_f32_16x16x32_bf16 v[18:21], v[190:193], v[222:225], v[18:21]
	v_mfma_f32_16x16x32_bf16 v[14:17], v[198:201], v[214:217], v[14:17]
	v_mfma_f32_16x16x32_bf16 v[10:13], v[198:201], v[222:225], v[10:13]
	v_mfma_f32_16x16x32_bf16 v[6:9], v[206:209], v[214:217], v[6:9]
	v_mfma_f32_16x16x32_bf16 v[2:5], v[206:209], v[222:225], v[2:5]
	v_mfma_f32_16x16x32_bf16 v[30:33], v[186:189], v[218:221], v[30:33]
	v_mfma_f32_16x16x32_bf16 v[26:29], v[186:189], v[226:229], v[26:29]
	v_mfma_f32_16x16x32_bf16 v[22:25], v[194:197], v[218:221], v[22:25]
	v_mfma_f32_16x16x32_bf16 v[18:21], v[194:197], v[226:229], v[18:21]
	v_mfma_f32_16x16x32_bf16 v[14:17], v[202:205], v[218:221], v[14:17]
	v_mfma_f32_16x16x32_bf16 v[10:13], v[202:205], v[226:229], v[10:13]
	v_mfma_f32_16x16x32_bf16 v[6:9], v[210:213], v[218:221], v[6:9]
	v_mfma_f32_16x16x32_bf16 v[2:5], v[210:213], v[226:229], v[2:5]
	s_setprio 0
	s_barrier
	ds_read_b128 v[160:163], v140
	ds_read_b128 v[164:167], v140 offset:1024
	ds_read_b128 v[174:177], v140 offset:2048
	ds_read_b128 v[178:181], v140 offset:3072
	v_readfirstlane_b32 s22, v147
	v_lshl_add_u64 v[168:169], v[168:169], 0, s[6:7]
	s_mov_b32 m0, s22
	v_readfirstlane_b32 s22, v148
	ds_read_b128 v[182:185], v138 offset:32768
	ds_read_b128 v[186:189], v138 offset:33792
	ds_read_b128 v[190:193], v137 offset:32768
	ds_read_b128 v[194:197], v137 offset:33792
	ds_read_b128 v[198:201], v136 offset:32768
	ds_read_b128 v[202:205], v136 offset:33792
	ds_read_b128 v[206:209], v135 offset:32768
	ds_read_b128 v[210:213], v135 offset:33792
	global_load_lds_dwordx4 v[168:169], off
	v_lshl_add_u64 v[168:169], v[230:231], 0, s[6:7]
	s_mov_b32 m0, s22
	s_add_u32 s10, s10, 0x100
	global_load_lds_dwordx4 v[168:169], off
	s_waitcnt lgkmcnt(8)
	s_barrier
	s_waitcnt lgkmcnt(0)
	s_addc_u32 s11, s11, 0
	s_setprio 1
	s_waitcnt lgkmcnt(0)
	v_mfma_f32_16x16x32_bf16 v[126:129], v[182:185], v[160:163], v[126:129]
	v_mfma_f32_16x16x32_bf16 v[122:125], v[182:185], v[174:177], v[122:125]
	v_mfma_f32_16x16x32_bf16 v[118:121], v[190:193], v[160:163], v[118:121]
	v_mfma_f32_16x16x32_bf16 v[114:117], v[190:193], v[174:177], v[114:117]
	v_mfma_f32_16x16x32_bf16 v[110:113], v[198:201], v[160:163], v[110:113]
	v_mfma_f32_16x16x32_bf16 v[106:109], v[198:201], v[174:177], v[106:109]
	v_mfma_f32_16x16x32_bf16 v[102:105], v[206:209], v[160:163], v[102:105]
	v_mfma_f32_16x16x32_bf16 v[98:101], v[206:209], v[174:177], v[98:101]
	v_mfma_f32_16x16x32_bf16 v[126:129], v[186:189], v[164:167], v[126:129]
	v_mfma_f32_16x16x32_bf16 v[122:125], v[186:189], v[178:181], v[122:125]
	v_mfma_f32_16x16x32_bf16 v[118:121], v[194:197], v[164:167], v[118:121]
	v_mfma_f32_16x16x32_bf16 v[114:117], v[194:197], v[178:181], v[114:117]
	v_mfma_f32_16x16x32_bf16 v[110:113], v[202:205], v[164:167], v[110:113]
	v_mfma_f32_16x16x32_bf16 v[106:109], v[202:205], v[178:181], v[106:109]
	v_mfma_f32_16x16x32_bf16 v[102:105], v[210:213], v[164:167], v[102:105]
	v_mfma_f32_16x16x32_bf16 v[98:101], v[210:213], v[178:181], v[98:101]
	s_setprio 0
	s_barrier
	v_readfirstlane_b32 s22, v155
	v_lshl_add_u64 v[168:169], v[232:233], 0, s[8:9]
	s_mov_b32 m0, s22
	v_readfirstlane_b32 s22, v156
	ds_read_b128 v[214:217], v139
	ds_read_b128 v[218:221], v139 offset:1024
	ds_read_b128 v[222:225], v139 offset:2048
	ds_read_b128 v[226:229], v139 offset:3072
	global_load_lds_dwordx4 v[168:169], off
	v_lshl_add_u64 v[168:169], v[234:235], 0, s[8:9]
	s_mov_b32 m0, s22
	s_nop 0
	global_load_lds_dwordx4 v[168:169], off
	s_waitcnt vmcnt(10)
	s_barrier
	s_waitcnt lgkmcnt(0)
	s_setprio 1
	s_waitcnt lgkmcnt(0)
	v_mfma_f32_16x16x32_bf16 v[94:97], v[182:185], v[214:217], v[94:97]
	v_mfma_f32_16x16x32_bf16 v[90:93], v[182:185], v[222:225], v[90:93]
	v_mfma_f32_16x16x32_bf16 v[86:89], v[190:193], v[214:217], v[86:89]
	v_mfma_f32_16x16x32_bf16 v[82:85], v[190:193], v[222:225], v[82:85]
	v_mfma_f32_16x16x32_bf16 v[78:81], v[198:201], v[214:217], v[78:81]
	v_mfma_f32_16x16x32_bf16 v[74:77], v[198:201], v[222:225], v[74:77]
	v_mfma_f32_16x16x32_bf16 v[70:73], v[206:209], v[214:217], v[70:73]
	v_mfma_f32_16x16x32_bf16 v[66:69], v[206:209], v[222:225], v[66:69]
	v_mfma_f32_16x16x32_bf16 v[94:97], v[186:189], v[218:221], v[94:97]
	v_mfma_f32_16x16x32_bf16 v[90:93], v[186:189], v[226:229], v[90:93]
	v_mfma_f32_16x16x32_bf16 v[86:89], v[194:197], v[218:221], v[86:89]
	v_mfma_f32_16x16x32_bf16 v[82:85], v[194:197], v[226:229], v[82:85]
	v_mfma_f32_16x16x32_bf16 v[78:81], v[202:205], v[218:221], v[78:81]
	v_mfma_f32_16x16x32_bf16 v[74:77], v[202:205], v[226:229], v[74:77]
	v_mfma_f32_16x16x32_bf16 v[70:73], v[210:213], v[218:221], v[70:73]
	v_mfma_f32_16x16x32_bf16 v[66:69], v[210:213], v[226:229], v[66:69]
	s_setprio 0
	v_readfirstlane_b32 s22, v149
	v_lshl_add_u64 v[168:169], v[236:237], 0, s[8:9]
	s_mov_b32 m0, s22
	v_readfirstlane_b32 s22, v150
	s_barrier
; #define STAGE(P, GP, ktrel) do { const GAS char* _g = (GP) + (ktrel) * (BK * 2); \
;     __builtin_amdgcn_global_load_lds((const GAS unsigned*)(_g + so0), (unsigned*)((char*)(P) + tid_ * 16), 16, 0, 0); \
;     __builtin_amdgcn_global_load_lds((const GAS unsigned*)(_g + so1), (unsigned*)((char*)(P) + tid_ * 16 + 8192), 16, 0, 0); } while (0)
; #define WAIT_V(n) asm volatile("s_waitcnt vmcnt(" #n ")" ::: "memory")
; #define WAIT_L(n) asm volatile("s_waitcnt lgkmcnt(" #n ")" ::: "memory")
; #define BAR __builtin_amdgcn_s_barrier()
; #define SCHED __builtin_amdgcn_sched_barrier(0)
; #define LDA(dst, b, h) for (int m = 0; m < 4; ++m) for (int k = 0; k < 2; ++k) \
;     dst[m][k] = *reinterpret_cast<const bf16x8*>((char*)SA(b, h) + lds_byte(wr * 64 + m * 16 + fr, k * 32 + fq * 8))
; #define LDB(dst, b, h) for (int n = 0; n < 2; ++n) for (int k = 0; k < 2; ++k) \
;     dst[n][k] = *reinterpret_cast<const bf16x8*>((char*)SB(b, h) + lds_byte(wc * 32 + n * 16 + fr, k * 32 + fq * 8))
; #define MMA(ai, bj, At_, Bt_) do { __builtin_amdgcn_s_setprio(1); \
;     for (int m = 0; m < 4; ++m) for (int n = 0; n < 2; ++n) for (int k = 0; k < 2; ++k) \
;       acc[ai][bj][m][n] = __builtin_amdgcn_mfma_f32_16x16x32_bf16(At_[m][k], Bt_[n][k], acc[ai][bj][m][n], 0, 0, 0); \
;     __builtin_amdgcn_s_setprio(0); } while (0)
; template <int K, int LD = K>
; __device__ __forceinline__ void gemm_main(const GAS bf16* A, const GAS bf16* Bt, int brow, int bcol, f32x4 (&acc)[2][2][4][2]) {
;     ...
;     LDA(At, 1, 1); STAGE(SA(1, 0), pA0, 3);
;     BAR; WAIT_L(0); MMA(1, 0, At, B0); BAR; SCHED;
;     STAGE(SB(1, 1), pB1, 3);
;     WAIT_V(6); BAR; MMA(1, 1, At, B1); BAR;
;     pA0 += 4 * BK; pA1 += 4 * BK; pB0 += 4 * BK; pB1 += 4 * BK;
;     asm volatile("" : "+s"(pA0), "+s"(pA1), "+s"(pB0), "+s"(pB1));
;   }
;   { LDB(B0, 0, 0); LDA(At, 0, 0); STAGE(SA(1, 1), pA1, 1);
;     BAR; WAIT_L(0); MMA(0, 0, At, B0); BAR;
;     LDB(B1, 0, 1); BAR; WAIT_L(0); MMA(0, 1, At, B1); BAR;
;     LDA(At, 0, 1); WAIT_V(4); BAR; WAIT_L(0); MMA(1, 0, At, B0); MMA(1, 1, At, B1); BAR; }
	ds_read_b128 v[182:185], v138 offset:49152
	ds_read_b128 v[186:189], v138 offset:50176
	ds_read_b128 v[190:193], v137 offset:49152
	ds_read_b128 v[194:197], v137 offset:50176
	ds_read_b128 v[198:201], v136 offset:49152
	ds_read_b128 v[202:205], v136 offset:50176
	ds_read_b128 v[206:209], v135 offset:49152
	ds_read_b128 v[210:213], v135 offset:50176
	global_load_lds_dwordx4 v[168:169], off
	v_lshl_add_u64 v[168:169], v[238:239], 0, s[8:9]
	s_mov_b32 m0, s22
	s_nop 0
	global_load_lds_dwordx4 v[168:169], off
	s_barrier
	s_waitcnt lgkmcnt(0)
	s_setprio 1
	s_waitcnt lgkmcnt(0)
	v_mfma_f32_16x16x32_bf16 v[62:65], v[182:185], v[160:163], v[62:65]
	v_mfma_f32_16x16x32_bf16 v[58:61], v[182:185], v[174:177], v[58:61]
	v_mfma_f32_16x16x32_bf16 v[54:57], v[190:193], v[160:163], v[54:57]
	v_mfma_f32_16x16x32_bf16 v[50:53], v[190:193], v[174:177], v[50:53]
	v_mfma_f32_16x16x32_bf16 v[46:49], v[198:201], v[160:163], v[46:49]
	v_mfma_f32_16x16x32_bf16 v[42:45], v[198:201], v[174:177], v[42:45]
	v_mfma_f32_16x16x32_bf16 v[38:41], v[206:209], v[160:163], v[38:41]
	v_mfma_f32_16x16x32_bf16 v[34:37], v[206:209], v[174:177], v[34:37]
	v_mfma_f32_16x16x32_bf16 v[62:65], v[186:189], v[164:167], v[62:65]
	v_mfma_f32_16x16x32_bf16 v[58:61], v[186:189], v[178:181], v[58:61]
	v_mfma_f32_16x16x32_bf16 v[54:57], v[194:197], v[164:167], v[54:57]
	v_mfma_f32_16x16x32_bf16 v[50:53], v[194:197], v[178:181], v[50:53]
	v_mfma_f32_16x16x32_bf16 v[46:49], v[202:205], v[164:167], v[46:49]
	v_mfma_f32_16x16x32_bf16 v[42:45], v[202:205], v[178:181], v[42:45]
	v_mfma_f32_16x16x32_bf16 v[38:41], v[210:213], v[164:167], v[38:41]
	v_mfma_f32_16x16x32_bf16 v[34:37], v[210:213], v[178:181], v[34:37]
	s_setprio 0
	s_barrier
	v_readfirstlane_b32 s22, v157
	v_lshl_add_u64 v[160:161], v[240:241], 0, s[8:9]
	s_mov_b32 m0, s22
	v_readfirstlane_b32 s22, v158
	global_load_lds_dwordx4 v[160:161], off
	v_lshl_add_u64 v[160:161], v[242:243], 0, s[8:9]
	s_mov_b32 m0, s22
	s_nop 0
	global_load_lds_dwordx4 v[160:161], off
	s_waitcnt vmcnt(8)
	s_barrier
	s_setprio 1
	v_mfma_f32_16x16x32_bf16 v[30:33], v[182:185], v[214:217], v[30:33]
	v_mfma_f32_16x16x32_bf16 v[26:29], v[182:185], v[222:225], v[26:29]
	v_mfma_f32_16x16x32_bf16 v[22:25], v[190:193], v[214:217], v[22:25]
	v_mfma_f32_16x16x32_bf16 v[18:21], v[190:193], v[222:225], v[18:21]
	v_mfma_f32_16x16x32_bf16 v[14:17], v[198:201], v[214:217], v[14:17]
	v_mfma_f32_16x16x32_bf16 v[10:13], v[198:201], v[222:225], v[10:13]
	v_mfma_f32_16x16x32_bf16 v[6:9], v[206:209], v[214:217], v[6:9]
	v_mfma_f32_16x16x32_bf16 v[2:5], v[206:209], v[222:225], v[2:5]
	v_mfma_f32_16x16x32_bf16 v[30:33], v[186:189], v[218:221], v[30:33]
	v_mfma_f32_16x16x32_bf16 v[26:29], v[186:189], v[226:229], v[26:29]
	v_mfma_f32_16x16x32_bf16 v[22:25], v[194:197], v[218:221], v[22:25]
	v_mfma_f32_16x16x32_bf16 v[18:21], v[194:197], v[226:229], v[18:21]
	v_mfma_f32_16x16x32_bf16 v[14:17], v[202:205], v[218:221], v[14:17]
	v_mfma_f32_16x16x32_bf16 v[10:13], v[202:205], v[226:229], v[10:13]
	v_mfma_f32_16x16x32_bf16 v[6:9], v[210:213], v[218:221], v[6:9]
	v_mfma_f32_16x16x32_bf16 v[2:5], v[210:213], v[226:229], v[2:5]
	s_setprio 0
	s_add_i32 s15, s15, 2
	s_cmp_lt_u32 s15, 12
	s_barrier
	s_cbranch_scc1 .LBB0_767
	ds_read_b128 v[146:149], v144
	ds_read_b128 v[150:153], v144 offset:1024
	ds_read_b128 v[154:157], v144 offset:2048
	ds_read_b128 v[158:161], v144 offset:3072
	ds_read_b128 v[162:165], v138
	ds_read_b128 v[166:169], v138 offset:1024
	ds_read_b128 v[174:177], v137
	ds_read_b128 v[178:181], v137 offset:1024
	ds_read_b128 v[182:185], v136
	ds_read_b128 v[186:189], v136 offset:1024
	ds_read_b128 v[190:193], v135
	ds_read_b128 v[194:197], v135 offset:1024
	v_lshl_add_u64 v[144:145], s[10:11], 0, v[130:131]
	v_readfirstlane_b32 s15, v143
	v_lshl_add_u64 v[144:145], v[144:145], 0, s[4:5]
	s_mov_b32 m0, s15
	v_lshl_add_u64 v[132:133], s[10:11], 0, v[132:133]
	v_readfirstlane_b32 s10, v142
	global_load_lds_dwordx4 v[144:145], off
	v_lshl_add_u64 v[132:133], v[132:133], 0, s[4:5]
	s_mov_b32 m0, s10
	s_nop 0
	global_load_lds_dwordx4 v[132:133], off
	s_barrier
	s_waitcnt lgkmcnt(0)
	s_setprio 1
	s_waitcnt lgkmcnt(0)
	v_mfma_f32_16x16x32_bf16 v[126:129], v[162:165], v[146:149], v[126:129]
	v_mfma_f32_16x16x32_bf16 v[122:125], v[162:165], v[154:157], v[122:125]
	v_mfma_f32_16x16x32_bf16 v[110:113], v[182:185], v[146:149], v[110:113]
	v_mfma_f32_16x16x32_bf16 v[106:109], v[182:185], v[154:157], v[106:109]
	v_mfma_f32_16x16x32_bf16 v[126:129], v[166:169], v[150:153], v[126:129]
	v_mfma_f32_16x16x32_bf16 v[122:125], v[166:169], v[158:161], v[122:125]
	v_mfma_f32_16x16x32_bf16 v[118:121], v[174:177], v[146:149], v[118:121]
	v_mfma_f32_16x16x32_bf16 v[114:117], v[174:177], v[154:157], v[114:117]
	v_mfma_f32_16x16x32_bf16 v[110:113], v[186:189], v[150:153], v[110:113]
	v_mfma_f32_16x16x32_bf16 v[106:109], v[186:189], v[158:161], v[106:109]
	v_mfma_f32_16x16x32_bf16 v[102:105], v[190:193], v[146:149], v[102:105]
	v_mfma_f32_16x16x32_bf16 v[98:101], v[190:193], v[154:157], v[98:101]
	v_mfma_f32_16x16x32_bf16 v[142:145], v[178:181], v[150:153], v[118:121]
	v_mfma_f32_16x16x32_bf16 v[198:201], v[178:181], v[158:161], v[114:117]
	v_mfma_f32_16x16x32_bf16 v[202:205], v[194:197], v[150:153], v[102:105]
	v_mfma_f32_16x16x32_bf16 v[206:209], v[194:197], v[158:161], v[98:101]
	s_setprio 0
	s_barrier
	s_nop 1
	ds_read_b128 v[98:101], v141
	ds_read_b128 v[102:105], v141 offset:1024
	ds_read_b128 v[114:117], v141 offset:2048
	ds_read_b128 v[118:121], v141 offset:3072
	s_waitcnt vmcnt(8)
	s_barrier
; #define WAIT_V(n) asm volatile("s_waitcnt vmcnt(" #n ")" ::: "memory")
; #define WAIT_L(n) asm volatile("s_waitcnt lgkmcnt(" #n ")" ::: "memory")
; #define BAR __builtin_amdgcn_s_barrier()
; #define LDA(dst, b, h) for (int m = 0; m < 4; ++m) for (int k = 0; k < 2; ++k) \
;     dst[m][k] = *reinterpret_cast<const bf16x8*>((char*)SA(b, h) + lds_byte(wr * 64 + m * 16 + fr, k * 32 + fq * 8))
; #define LDB(dst, b, h) for (int n = 0; n < 2; ++n) for (int k = 0; k < 2; ++k) \
;     dst[n][k] = *reinterpret_cast<const bf16x8*>((char*)SB(b, h) + lds_byte(wc * 32 + n * 16 + fr, k * 32 + fq * 8))
; #define MMA(ai, bj, At_, Bt_) do { __builtin_amdgcn_s_setprio(1); \
;     for (int m = 0; m < 4; ++m) for (int n = 0; n < 2; ++n) for (int k = 0; k < 2; ++k) \
;       acc[ai][bj][m][n] = __builtin_amdgcn_mfma_f32_16x16x32_bf16(At_[m][k], Bt_[n][k], acc[ai][bj][m][n], 0, 0, 0); \
;     __builtin_amdgcn_s_setprio(0); } while (0)
; template <int K, int LD = K>
; __device__ __forceinline__ void gemm_main(const GAS bf16* A, const GAS bf16* Bt, int brow, int bcol, f32x4 (&acc)[2][2][4][2]) {
;     ...
;     LDB(B1, 0, 1); BAR; WAIT_L(0); MMA(0, 1, At, B1); BAR;
;     LDA(At, 0, 1); WAIT_V(4); BAR; WAIT_L(0); MMA(1, 0, At, B0); MMA(1, 1, At, B1); BAR; }
;   { LDB(B0, 1, 0); LDA(At, 1, 0); WAIT_V(2); BAR; WAIT_L(0); MMA(0, 0, At, B0); BAR;
	s_waitcnt lgkmcnt(0)
	s_setprio 1
	s_waitcnt lgkmcnt(0)
	v_mfma_f32_16x16x32_bf16 v[94:97], v[162:165], v[98:101], v[94:97]
	v_mfma_f32_16x16x32_bf16 v[90:93], v[162:165], v[114:117], v[90:93]
	v_mfma_f32_16x16x32_bf16 v[78:81], v[182:185], v[98:101], v[78:81]
	v_mfma_f32_16x16x32_bf16 v[74:77], v[182:185], v[114:117], v[74:77]
	v_mfma_f32_16x16x32_bf16 v[94:97], v[166:169], v[102:105], v[94:97]
	v_mfma_f32_16x16x32_bf16 v[90:93], v[166:169], v[118:121], v[90:93]
	v_mfma_f32_16x16x32_bf16 v[86:89], v[174:177], v[98:101], v[86:89]
	v_mfma_f32_16x16x32_bf16 v[82:85], v[174:177], v[114:117], v[82:85]
	v_mfma_f32_16x16x32_bf16 v[78:81], v[186:189], v[102:105], v[78:81]
	v_mfma_f32_16x16x32_bf16 v[74:77], v[186:189], v[118:121], v[74:77]
	v_mfma_f32_16x16x32_bf16 v[70:73], v[190:193], v[98:101], v[70:73]
	v_mfma_f32_16x16x32_bf16 v[66:69], v[190:193], v[114:117], v[66:69]
	v_mfma_f32_16x16x32_bf16 v[162:165], v[178:181], v[102:105], v[86:89]
	v_mfma_f32_16x16x32_bf16 v[166:169], v[178:181], v[118:121], v[82:85]
	v_mfma_f32_16x16x32_bf16 v[174:177], v[194:197], v[102:105], v[70:73]
	v_mfma_f32_16x16x32_bf16 v[178:181], v[194:197], v[118:121], v[66:69]
	s_setprio 0
	s_barrier
	s_nop 1
	ds_read_b128 v[66:69], v138 offset:16384
	ds_read_b128 v[70:73], v138 offset:17408
	ds_read_b128 v[82:85], v137 offset:16384
	ds_read_b128 v[86:89], v137 offset:17408
	ds_read_b128 v[182:185], v136 offset:16384
	ds_read_b128 v[186:189], v136 offset:17408
	ds_read_b128 v[190:193], v135 offset:16384
	ds_read_b128 v[194:197], v135 offset:17408
	s_waitcnt vmcnt(4)
	s_barrier
	s_waitcnt lgkmcnt(0)
	s_setprio 1
	s_waitcnt lgkmcnt(0)
	v_mfma_f32_16x16x32_bf16 v[62:65], v[66:69], v[146:149], v[62:65]
	v_mfma_f32_16x16x32_bf16 v[58:61], v[66:69], v[154:157], v[58:61]
	v_mfma_f32_16x16x32_bf16 v[46:49], v[182:185], v[146:149], v[46:49]
	v_mfma_f32_16x16x32_bf16 v[42:45], v[182:185], v[154:157], v[42:45]
	v_mfma_f32_16x16x32_bf16 v[62:65], v[70:73], v[150:153], v[62:65]
	v_mfma_f32_16x16x32_bf16 v[58:61], v[70:73], v[158:161], v[58:61]
	v_mfma_f32_16x16x32_bf16 v[54:57], v[82:85], v[146:149], v[54:57]
	v_mfma_f32_16x16x32_bf16 v[50:53], v[82:85], v[154:157], v[50:53]
	v_mfma_f32_16x16x32_bf16 v[46:49], v[186:189], v[150:153], v[46:49]
	v_mfma_f32_16x16x32_bf16 v[42:45], v[186:189], v[158:161], v[42:45]
	v_mfma_f32_16x16x32_bf16 v[38:41], v[190:193], v[146:149], v[38:41]
	v_mfma_f32_16x16x32_bf16 v[34:37], v[190:193], v[154:157], v[34:37]
	v_mfma_f32_16x16x32_bf16 v[210:213], v[86:89], v[150:153], v[54:57]
	v_mfma_f32_16x16x32_bf16 v[214:217], v[86:89], v[158:161], v[50:53]
	v_mfma_f32_16x16x32_bf16 v[146:149], v[194:197], v[150:153], v[38:41]
	v_mfma_f32_16x16x32_bf16 v[150:153], v[194:197], v[158:161], v[34:37]
	s_setprio 0
	s_setprio 1
	v_mfma_f32_16x16x32_bf16 v[30:33], v[66:69], v[98:101], v[30:33]
	v_mfma_f32_16x16x32_bf16 v[26:29], v[66:69], v[114:117], v[26:29]
	v_mfma_f32_16x16x32_bf16 v[14:17], v[182:185], v[98:101], v[14:17]
	v_mfma_f32_16x16x32_bf16 v[10:13], v[182:185], v[114:117], v[10:13]
	v_mfma_f32_16x16x32_bf16 v[30:33], v[70:73], v[102:105], v[30:33]
	v_mfma_f32_16x16x32_bf16 v[26:29], v[70:73], v[118:121], v[26:29]
	v_mfma_f32_16x16x32_bf16 v[22:25], v[82:85], v[98:101], v[22:25]
	v_mfma_f32_16x16x32_bf16 v[18:21], v[82:85], v[114:117], v[18:21]
	v_mfma_f32_16x16x32_bf16 v[14:17], v[186:189], v[102:105], v[14:17]
	v_mfma_f32_16x16x32_bf16 v[10:13], v[186:189], v[118:121], v[10:13]
	v_mfma_f32_16x16x32_bf16 v[6:9], v[190:193], v[98:101], v[6:9]
	v_mfma_f32_16x16x32_bf16 v[2:5], v[190:193], v[114:117], v[2:5]
	v_mfma_f32_16x16x32_bf16 v[154:157], v[86:89], v[102:105], v[22:25]
	v_mfma_f32_16x16x32_bf16 v[158:161], v[86:89], v[118:121], v[18:21]
	v_mfma_f32_16x16x32_bf16 v[182:185], v[194:197], v[102:105], v[6:9]
	v_mfma_f32_16x16x32_bf16 v[186:189], v[194:197], v[118:121], v[2:5]
	s_setprio 0
	s_barrier
	s_nop 1
	ds_read_b128 v[2:5], v140
	ds_read_b128 v[6:9], v140 offset:1024
	ds_read_b128 v[190:193], v140 offset:2048
	ds_read_b128 v[194:197], v140 offset:3072
	ds_read_b128 v[18:21], v138 offset:32768
	ds_read_b128 v[22:25], v138 offset:33792
	ds_read_b128 v[34:37], v137 offset:32768
	ds_read_b128 v[38:41], v137 offset:33792
	ds_read_b128 v[50:53], v136 offset:32768
	ds_read_b128 v[54:57], v136 offset:33792
	ds_read_b128 v[218:221], v135 offset:32768
	ds_read_b128 v[222:225], v135 offset:33792
	s_waitcnt vmcnt(2)
	s_barrier
; #define WAIT_V(n) asm volatile("s_waitcnt vmcnt(" #n ")" ::: "memory")
; #define WAIT_L(n) asm volatile("s_waitcnt lgkmcnt(" #n ")" ::: "memory")
; #define BAR __builtin_amdgcn_s_barrier()
; #define LDA(dst, b, h) for (int m = 0; m < 4; ++m) for (int k = 0; k < 2; ++k) \
;     dst[m][k] = *reinterpret_cast<const bf16x8*>((char*)SA(b, h) + lds_byte(wr * 64 + m * 16 + fr, k * 32 + fq * 8))
; #define LDB(dst, b, h) for (int n = 0; n < 2; ++n) for (int k = 0; k < 2; ++k) \
;     dst[n][k] = *reinterpret_cast<const bf16x8*>((char*)SB(b, h) + lds_byte(wc * 32 + n * 16 + fr, k * 32 + fq * 8))
; #define MMA(ai, bj, At_, Bt_) do { __builtin_amdgcn_s_setprio(1); \
;     for (int m = 0; m < 4; ++m) for (int n = 0; n < 2; ++n) for (int k = 0; k < 2; ++k) \
;       acc[ai][bj][m][n] = __builtin_amdgcn_mfma_f32_16x16x32_bf16(At_[m][k], Bt_[n][k], acc[ai][bj][m][n], 0, 0, 0); \
;     __builtin_amdgcn_s_setprio(0); } while (0)
; template <int K, int LD = K>
; __device__ __forceinline__ void gemm_main(const GAS bf16* A, const GAS bf16* Bt, int brow, int bcol, f32x4 (&acc)[2][2][4][2]) {
;     ...
;   { LDB(B0, 1, 0); LDA(At, 1, 0); WAIT_V(2); BAR; WAIT_L(0); MMA(0, 0, At, B0); BAR;
;     LDB(B1, 1, 1); WAIT_V(0); BAR; WAIT_L(0); MMA(0, 1, At, B1); BAR;
;     LDA(At, 1, 1); BAR; WAIT_L(0); MMA(1, 0, At, B0); MMA(1, 1, At, B1); BAR; }
;   if (wr == 0) BAR;
	s_waitcnt lgkmcnt(0)
	s_setprio 1
	s_waitcnt lgkmcnt(0)
	v_mfma_f32_16x16x32_bf16 v[66:69], v[18:21], v[2:5], v[126:129]
	v_mfma_f32_16x16x32_bf16 v[118:121], v[22:25], v[6:9], v[66:69]
	v_mfma_f32_16x16x32_bf16 v[66:69], v[18:21], v[190:193], v[122:125]
	v_mfma_f32_16x16x32_bf16 v[114:117], v[22:25], v[194:197], v[66:69]
	v_mfma_f32_16x16x32_bf16 v[66:69], v[34:37], v[2:5], v[142:145]
	v_mfma_f32_16x16x32_bf16 v[102:105], v[38:41], v[6:9], v[66:69]
	v_mfma_f32_16x16x32_bf16 v[66:69], v[34:37], v[190:193], v[198:201]
	v_mfma_f32_16x16x32_bf16 v[98:101], v[38:41], v[194:197], v[66:69]
	v_mfma_f32_16x16x32_bf16 v[66:69], v[50:53], v[2:5], v[110:113]
	v_mfma_f32_16x16x32_bf16 v[86:89], v[54:57], v[6:9], v[66:69]
	v_mfma_f32_16x16x32_bf16 v[66:69], v[50:53], v[190:193], v[106:109]
	v_mfma_f32_16x16x32_bf16 v[82:85], v[54:57], v[194:197], v[66:69]
	v_mfma_f32_16x16x32_bf16 v[66:69], v[218:221], v[2:5], v[202:205]
	v_mfma_f32_16x16x32_bf16 v[70:73], v[222:225], v[6:9], v[66:69]
	v_mfma_f32_16x16x32_bf16 v[66:69], v[218:221], v[190:193], v[206:209]
	v_mfma_f32_16x16x32_bf16 v[66:69], v[222:225], v[194:197], v[66:69]
	s_setprio 0
	s_barrier
	ds_read_b128 v[140:143], v139
	ds_read_b128 v[198:201], v139 offset:1024
	ds_read_b128 v[202:205], v139 offset:2048
	ds_read_b128 v[206:209], v139 offset:3072
	s_waitcnt vmcnt(0)
	s_barrier
	s_waitcnt lgkmcnt(0)
	s_setprio 1
	s_waitcnt lgkmcnt(0)
	v_mfma_f32_16x16x32_bf16 v[94:97], v[18:21], v[140:143], v[94:97]
	v_mfma_f32_16x16x32_bf16 v[18:21], v[18:21], v[202:205], v[90:93]
	v_mfma_f32_16x16x32_bf16 v[122:125], v[22:25], v[206:209], v[18:21]
	v_mfma_f32_16x16x32_bf16 v[18:21], v[34:37], v[140:143], v[162:165]
	v_mfma_f32_16x16x32_bf16 v[110:113], v[38:41], v[198:201], v[18:21]
	v_mfma_f32_16x16x32_bf16 v[18:21], v[34:37], v[202:205], v[166:169]
	v_mfma_f32_16x16x32_bf16 v[106:109], v[38:41], v[206:209], v[18:21]
	v_mfma_f32_16x16x32_bf16 v[18:21], v[50:53], v[140:143], v[78:81]
	v_mfma_f32_16x16x32_bf16 v[126:129], v[22:25], v[198:201], v[94:97]
	v_mfma_f32_16x16x32_bf16 v[94:97], v[54:57], v[198:201], v[18:21]
	v_mfma_f32_16x16x32_bf16 v[18:21], v[50:53], v[202:205], v[74:77]
	v_mfma_f32_16x16x32_bf16 v[90:93], v[54:57], v[206:209], v[18:21]
	v_mfma_f32_16x16x32_bf16 v[18:21], v[218:221], v[140:143], v[174:177]
	v_mfma_f32_16x16x32_bf16 v[78:81], v[222:225], v[198:201], v[18:21]
	v_mfma_f32_16x16x32_bf16 v[18:21], v[218:221], v[202:205], v[178:181]
	v_mfma_f32_16x16x32_bf16 v[74:77], v[222:225], v[206:209], v[18:21]
	s_setprio 0
	s_barrier
	ds_read_b128 v[162:165], v138 offset:49152
	ds_read_b128 v[166:169], v138 offset:50176
	ds_read_b128 v[174:177], v137 offset:49152
	ds_read_b128 v[178:181], v137 offset:50176
	ds_read_b128 v[218:221], v136 offset:49152
	ds_read_b128 v[136:139], v136 offset:50176
	ds_read_b128 v[222:225], v135 offset:49152
	ds_read_b128 v[226:229], v135 offset:50176
	s_barrier
	s_waitcnt lgkmcnt(0)
	s_setprio 1
	s_waitcnt lgkmcnt(0)
	v_mfma_f32_16x16x32_bf16 v[18:21], v[162:165], v[2:5], v[62:65]
	v_mfma_f32_16x16x32_bf16 v[54:57], v[166:169], v[6:9], v[18:21]
	v_mfma_f32_16x16x32_bf16 v[18:21], v[162:165], v[190:193], v[58:61]
	v_mfma_f32_16x16x32_bf16 v[50:53], v[166:169], v[194:197], v[18:21]
	v_mfma_f32_16x16x32_bf16 v[18:21], v[174:177], v[2:5], v[210:213]
	v_mfma_f32_16x16x32_bf16 v[38:41], v[178:181], v[6:9], v[18:21]
	v_mfma_f32_16x16x32_bf16 v[18:21], v[174:177], v[190:193], v[214:217]
	v_mfma_f32_16x16x32_bf16 v[34:37], v[178:181], v[194:197], v[18:21]
	v_mfma_f32_16x16x32_bf16 v[18:21], v[218:221], v[2:5], v[46:49]
	v_mfma_f32_16x16x32_bf16 v[2:5], v[222:225], v[2:5], v[146:149]
	v_mfma_f32_16x16x32_bf16 v[22:25], v[136:139], v[6:9], v[18:21]
	v_mfma_f32_16x16x32_bf16 v[18:21], v[218:221], v[190:193], v[42:45]
	v_mfma_f32_16x16x32_bf16 v[6:9], v[226:229], v[6:9], v[2:5]
	v_mfma_f32_16x16x32_bf16 v[2:5], v[222:225], v[190:193], v[150:153]
	v_mfma_f32_16x16x32_bf16 v[18:21], v[136:139], v[194:197], v[18:21]
	v_mfma_f32_16x16x32_bf16 v[2:5], v[226:229], v[194:197], v[2:5]
	s_setprio 0
	s_setprio 1
	v_mfma_f32_16x16x32_bf16 v[26:29], v[162:165], v[202:205], v[26:29]
	v_mfma_f32_16x16x32_bf16 v[58:61], v[166:169], v[206:209], v[26:29]
	v_mfma_f32_16x16x32_bf16 v[26:29], v[174:177], v[140:143], v[154:157]
	v_mfma_f32_16x16x32_bf16 v[46:49], v[178:181], v[198:201], v[26:29]
	v_mfma_f32_16x16x32_bf16 v[26:29], v[174:177], v[202:205], v[158:161]
	v_mfma_f32_16x16x32_bf16 v[10:13], v[218:221], v[202:205], v[10:13]
	v_mfma_f32_16x16x32_bf16 v[30:33], v[162:165], v[140:143], v[30:33]
	v_mfma_f32_16x16x32_bf16 v[42:45], v[178:181], v[206:209], v[26:29]
	v_mfma_f32_16x16x32_bf16 v[14:17], v[218:221], v[140:143], v[14:17]
	v_mfma_f32_16x16x32_bf16 v[26:29], v[136:139], v[206:209], v[10:13]
	v_mfma_f32_16x16x32_bf16 v[10:13], v[222:225], v[140:143], v[182:185]
	v_mfma_f32_16x16x32_bf16 v[62:65], v[166:169], v[198:201], v[30:33]
	v_mfma_f32_16x16x32_bf16 v[30:33], v[136:139], v[198:201], v[14:17]
	v_mfma_f32_16x16x32_bf16 v[14:17], v[226:229], v[198:201], v[10:13]
	v_mfma_f32_16x16x32_bf16 v[10:13], v[222:225], v[202:205], v[186:189]
	v_mfma_f32_16x16x32_bf16 v[10:13], v[226:229], v[206:209], v[10:13]
	s_setprio 0
	v_cmp_gt_u32_e32 vcc, s34, v134
	s_barrier
	s_and_saveexec_b64 s[10:11], vcc
	s_cbranch_execz .LBB0_770
	s_barrier

; #define STAGE(P, GP, ktrel) do { const GAS char* _g = (GP) + (ktrel) * (BK * 2); \
;     __builtin_amdgcn_global_load_lds((const GAS unsigned*)(_g + so0), (unsigned*)((char*)(P) + tid_ * 16), 16, 0, 0); \
;     __builtin_amdgcn_global_load_lds((const GAS unsigned*)(_g + so1), (unsigned*)((char*)(P) + tid_ * 16 + 8192), 16, 0, 0); } while (0)
; #define WAIT_L(n) asm volatile("s_waitcnt lgkmcnt(" #n ")" ::: "memory")
; #define BAR __builtin_amdgcn_s_barrier()
; #define SCHED __builtin_amdgcn_sched_barrier(0)
; #define LDA(dst, b, h) for (int m = 0; m < 4; ++m) for (int k = 0; k < 2; ++k) \
;     dst[m][k] = *reinterpret_cast<const bf16x8*>((char*)SA(b, h) + lds_byte(wr * 64 + m * 16 + fr, k * 32 + fq * 8))
; #define LDB(dst, b, h) for (int n = 0; n < 2; ++n) for (int k = 0; k < 2; ++k) \
;     dst[n][k] = *reinterpret_cast<const bf16x8*>((char*)SB(b, h) + lds_byte(wc * 32 + n * 16 + fr, k * 32 + fq * 8))
; #define MMA(ai, bj, At_, Bt_) do { __builtin_amdgcn_s_setprio(1); \
;     for (int m = 0; m < 4; ++m) for (int n = 0; n < 2; ++n) for (int k = 0; k < 2; ++k) \
;       acc[ai][bj][m][n] = __builtin_amdgcn_mfma_f32_16x16x32_bf16(At_[m][k], Bt_[n][k], acc[ai][bj][m][n], 0, 0, 0); \
;     __builtin_amdgcn_s_setprio(0); } while (0)
; template <int K, int LD = K>
; __device__ __forceinline__ void gemm_main(const GAS bf16* A, const GAS bf16* Bt, int brow, int bcol, f32x4 (&acc)[2][2][4][2]) {
;     ...
;   for (int t = 0; t < nt - 2; t += 2) {
;     LDB(B0, 0, 0); SCHED; LDA(At, 0, 0); STAGE(SA(1, 1), pA1, 1);
;     WAIT_L(8); BAR; WAIT_L(0); MMA(0, 0, At, B0); BAR; SCHED;
;     LDB(B1, 0, 1); STAGE(SB(0, 0), pB0, 2);
;     BAR; WAIT_L(0); MMA(0, 1, At, B1); BAR;
;     LDA(At, 0, 1); STAGE(SA(0, 0), pA0, 2);
;     BAR; WAIT_L(0); MMA(1, 0, At, B0); BAR; SCHED;
.LBB0_884:
	ds_read_b128 v[160:163], v145
	ds_read_b128 v[164:167], v145 offset:1024
	ds_read_b128 v[174:177], v145 offset:2048
	ds_read_b128 v[178:181], v145 offset:3072
	v_lshl_add_u64 v[168:169], s[12:13], 0, v[130:131]
	v_readfirstlane_b32 s22, v144
	v_lshl_add_u64 v[214:215], v[168:169], 0, s[6:7]
	s_mov_b32 m0, s22
	v_lshl_add_u64 v[230:231], s[12:13], 0, v[132:133]
	v_readfirstlane_b32 s22, v143
	ds_read_b128 v[182:185], v139
	ds_read_b128 v[186:189], v139 offset:1024
	ds_read_b128 v[190:193], v138
	ds_read_b128 v[194:197], v138 offset:1024
	ds_read_b128 v[198:201], v137
	ds_read_b128 v[202:205], v137 offset:1024
	ds_read_b128 v[206:209], v136
	ds_read_b128 v[210:213], v136 offset:1024
	global_load_lds_dwordx4 v[214:215], off
	v_lshl_add_u64 v[214:215], v[230:231], 0, s[6:7]
	s_mov_b32 m0, s22
	s_nop 0
	global_load_lds_dwordx4 v[214:215], off
	s_waitcnt lgkmcnt(8)
	s_barrier
	s_waitcnt lgkmcnt(0)
	s_setprio 1
	s_waitcnt lgkmcnt(0)
	v_mfma_f32_16x16x32_bf16 v[126:129], v[182:185], v[160:163], v[126:129]
	v_mfma_f32_16x16x32_bf16 v[122:125], v[182:185], v[174:177], v[122:125]
	v_mfma_f32_16x16x32_bf16 v[118:121], v[190:193], v[160:163], v[118:121]
	v_mfma_f32_16x16x32_bf16 v[114:117], v[190:193], v[174:177], v[114:117]
	v_mfma_f32_16x16x32_bf16 v[110:113], v[198:201], v[160:163], v[110:113]
	v_mfma_f32_16x16x32_bf16 v[106:109], v[198:201], v[174:177], v[106:109]
	v_mfma_f32_16x16x32_bf16 v[102:105], v[206:209], v[160:163], v[102:105]
	v_mfma_f32_16x16x32_bf16 v[98:101], v[206:209], v[174:177], v[98:101]
	v_mfma_f32_16x16x32_bf16 v[126:129], v[186:189], v[164:167], v[126:129]
	v_mfma_f32_16x16x32_bf16 v[122:125], v[186:189], v[178:181], v[122:125]
	v_mfma_f32_16x16x32_bf16 v[118:121], v[194:197], v[164:167], v[118:121]
	v_mfma_f32_16x16x32_bf16 v[114:117], v[194:197], v[178:181], v[114:117]
	v_mfma_f32_16x16x32_bf16 v[110:113], v[202:205], v[164:167], v[110:113]
	v_mfma_f32_16x16x32_bf16 v[106:109], v[202:205], v[178:181], v[106:109]
	v_mfma_f32_16x16x32_bf16 v[102:105], v[210:213], v[164:167], v[102:105]
	v_mfma_f32_16x16x32_bf16 v[98:101], v[210:213], v[178:181], v[98:101]
	s_setprio 0
	s_barrier
	v_lshl_add_u64 v[232:233], s[20:21], 0, v[130:131]
	v_readfirstlane_b32 s22, v152
	v_lshl_add_u64 v[234:235], v[232:233], 0, s[8:9]
	s_mov_b32 m0, s22
	ds_read_b128 v[214:217], v142
	ds_read_b128 v[218:221], v142 offset:1024
	ds_read_b128 v[222:225], v142 offset:2048
	ds_read_b128 v[226:229], v142 offset:3072
	global_load_lds_dwordx4 v[234:235], off
	v_lshl_add_u64 v[234:235], s[20:21], 0, v[132:133]
	v_readfirstlane_b32 s22, v153
	v_lshl_add_u64 v[236:237], v[234:235], 0, s[8:9]
	s_mov_b32 m0, s22
	s_add_u32 s20, s20, 0x100
	global_load_lds_dwordx4 v[236:237], off
	s_waitcnt vmcnt(10)
	s_barrier
	s_waitcnt lgkmcnt(0)
	s_addc_u32 s21, s21, 0
	s_setprio 1
	s_waitcnt lgkmcnt(0)
	v_mfma_f32_16x16x32_bf16 v[94:97], v[182:185], v[214:217], v[94:97]
	v_mfma_f32_16x16x32_bf16 v[90:93], v[182:185], v[222:225], v[90:93]
	v_mfma_f32_16x16x32_bf16 v[86:89], v[190:193], v[214:217], v[86:89]
	v_mfma_f32_16x16x32_bf16 v[82:85], v[190:193], v[222:225], v[82:85]
	v_mfma_f32_16x16x32_bf16 v[78:81], v[198:201], v[214:217], v[78:81]
	v_mfma_f32_16x16x32_bf16 v[74:77], v[198:201], v[222:225], v[74:77]
	v_mfma_f32_16x16x32_bf16 v[70:73], v[206:209], v[214:217], v[70:73]
	v_mfma_f32_16x16x32_bf16 v[66:69], v[206:209], v[222:225], v[66:69]
	v_mfma_f32_16x16x32_bf16 v[94:97], v[186:189], v[218:221], v[94:97]
	v_mfma_f32_16x16x32_bf16 v[90:93], v[186:189], v[226:229], v[90:93]
	v_mfma_f32_16x16x32_bf16 v[86:89], v[194:197], v[218:221], v[86:89]
	v_mfma_f32_16x16x32_bf16 v[82:85], v[194:197], v[226:229], v[82:85]
	v_mfma_f32_16x16x32_bf16 v[78:81], v[202:205], v[218:221], v[78:81]
	v_mfma_f32_16x16x32_bf16 v[74:77], v[202:205], v[226:229], v[74:77]
	v_mfma_f32_16x16x32_bf16 v[70:73], v[210:213], v[218:221], v[70:73]
	v_mfma_f32_16x16x32_bf16 v[66:69], v[210:213], v[226:229], v[66:69]
	s_setprio 0
	v_lshl_add_u64 v[236:237], s[18:19], 0, v[130:131]
	v_readfirstlane_b32 s22, v146
	v_lshl_add_u64 v[238:239], v[236:237], 0, s[8:9]
	s_mov_b32 m0, s22
	s_barrier
	ds_read_b128 v[182:185], v139 offset:16384
	ds_read_b128 v[186:189], v139 offset:17408
	ds_read_b128 v[190:193], v138 offset:16384
	ds_read_b128 v[194:197], v138 offset:17408
	ds_read_b128 v[198:201], v137 offset:16384
	ds_read_b128 v[202:205], v137 offset:17408
	ds_read_b128 v[206:209], v136 offset:16384
	ds_read_b128 v[210:213], v136 offset:17408
	global_load_lds_dwordx4 v[238:239], off
	v_lshl_add_u64 v[238:239], s[18:19], 0, v[132:133]
	v_readfirstlane_b32 s22, v147
	v_lshl_add_u64 v[240:241], v[238:239], 0, s[8:9]
	s_mov_b32 m0, s22
	s_add_u32 s18, s18, 0x100
	global_load_lds_dwordx4 v[240:241], off
	s_barrier
	s_waitcnt lgkmcnt(0)
	s_addc_u32 s19, s19, 0
	s_setprio 1
	s_waitcnt lgkmcnt(0)
	v_mfma_f32_16x16x32_bf16 v[62:65], v[182:185], v[160:163], v[62:65]
	v_mfma_f32_16x16x32_bf16 v[58:61], v[182:185], v[174:177], v[58:61]
	v_mfma_f32_16x16x32_bf16 v[54:57], v[190:193], v[160:163], v[54:57]
	v_mfma_f32_16x16x32_bf16 v[50:53], v[190:193], v[174:177], v[50:53]
	v_mfma_f32_16x16x32_bf16 v[46:49], v[198:201], v[160:163], v[46:49]
	v_mfma_f32_16x16x32_bf16 v[42:45], v[198:201], v[174:177], v[42:45]
	v_mfma_f32_16x16x32_bf16 v[38:41], v[206:209], v[160:163], v[38:41]
	v_mfma_f32_16x16x32_bf16 v[34:37], v[206:209], v[174:177], v[34:37]
	v_mfma_f32_16x16x32_bf16 v[62:65], v[186:189], v[164:167], v[62:65]
	v_mfma_f32_16x16x32_bf16 v[58:61], v[186:189], v[178:181], v[58:61]
	v_mfma_f32_16x16x32_bf16 v[54:57], v[194:197], v[164:167], v[54:57]
	v_mfma_f32_16x16x32_bf16 v[50:53], v[194:197], v[178:181], v[50:53]
	v_mfma_f32_16x16x32_bf16 v[46:49], v[202:205], v[164:167], v[46:49]
	v_mfma_f32_16x16x32_bf16 v[42:45], v[202:205], v[178:181], v[42:45]
	v_mfma_f32_16x16x32_bf16 v[38:41], v[210:213], v[164:167], v[38:41]
	v_mfma_f32_16x16x32_bf16 v[34:37], v[210:213], v[178:181], v[34:37]
	s_setprio 0
	s_barrier
; #define STAGE(P, GP, ktrel) do { const GAS char* _g = (GP) + (ktrel) * (BK * 2); \
;     __builtin_amdgcn_global_load_lds((const GAS unsigned*)(_g + so0), (unsigned*)((char*)(P) + tid_ * 16), 16, 0, 0); \
;     __builtin_amdgcn_global_load_lds((const GAS unsigned*)(_g + so1), (unsigned*)((char*)(P) + tid_ * 16 + 8192), 16, 0, 0); } while (0)
; #define WAIT_V(n) asm volatile("s_waitcnt vmcnt(" #n ")" ::: "memory")
; #define WAIT_L(n) asm volatile("s_waitcnt lgkmcnt(" #n ")" ::: "memory")
; #define BAR __builtin_amdgcn_s_barrier()
; #define SCHED __builtin_amdgcn_sched_barrier(0)
; #define LDA(dst, b, h) for (int m = 0; m < 4; ++m) for (int k = 0; k < 2; ++k) \
;     dst[m][k] = *reinterpret_cast<const bf16x8*>((char*)SA(b, h) + lds_byte(wr * 64 + m * 16 + fr, k * 32 + fq * 8))
; #define LDB(dst, b, h) for (int n = 0; n < 2; ++n) for (int k = 0; k < 2; ++k) \
;     dst[n][k] = *reinterpret_cast<const bf16x8*>((char*)SB(b, h) + lds_byte(wc * 32 + n * 16 + fr, k * 32 + fq * 8))
; #define MMA(ai, bj, At_, Bt_) do { __builtin_amdgcn_s_setprio(1); \
;     for (int m = 0; m < 4; ++m) for (int n = 0; n < 2; ++n) for (int k = 0; k < 2; ++k) \
;       acc[ai][bj][m][n] = __builtin_amdgcn_mfma_f32_16x16x32_bf16(At_[m][k], Bt_[n][k], acc[ai][bj][m][n], 0, 0, 0); \
;     __builtin_amdgcn_s_setprio(0); } while (0)
; template <int K, int LD = K>
; __device__ __forceinline__ void gemm_main(const GAS bf16* A, const GAS bf16* Bt, int brow, int bcol, f32x4 (&acc)[2][2][4][2]) {
;     ...
;     STAGE(SB(0, 1), pB1, 2);
;     WAIT_V(6); BAR; MMA(1, 1, At, B1); BAR;
;     LDB(B0, 1, 0); SCHED; LDA(At, 1, 0); STAGE(SA(0, 1), pA1, 2);
;     WAIT_L(8); BAR; WAIT_L(0); MMA(0, 0, At, B0); BAR; SCHED;
;     LDB(B1, 1, 1); STAGE(SB(1, 0), pB0, 3);
;     BAR; WAIT_L(0); MMA(0, 1, At, B1); BAR;
	v_lshl_add_u64 v[240:241], s[16:17], 0, v[130:131]
	v_readfirstlane_b32 s22, v154
	v_lshl_add_u64 v[160:161], v[240:241], 0, s[8:9]
	s_mov_b32 m0, s22
	v_lshl_add_u64 v[242:243], s[16:17], 0, v[132:133]
	v_readfirstlane_b32 s22, v155
	global_load_lds_dwordx4 v[160:161], off
	v_lshl_add_u64 v[160:161], v[242:243], 0, s[8:9]
	s_mov_b32 m0, s22
	s_add_u32 s16, s16, 0x100
	global_load_lds_dwordx4 v[160:161], off
	s_waitcnt vmcnt(8)
	s_addc_u32 s17, s17, 0
	s_barrier
	s_setprio 1
	v_mfma_f32_16x16x32_bf16 v[30:33], v[182:185], v[214:217], v[30:33]
	v_mfma_f32_16x16x32_bf16 v[26:29], v[182:185], v[222:225], v[26:29]
	v_mfma_f32_16x16x32_bf16 v[22:25], v[190:193], v[214:217], v[22:25]
	v_mfma_f32_16x16x32_bf16 v[18:21], v[190:193], v[222:225], v[18:21]
	v_mfma_f32_16x16x32_bf16 v[14:17], v[198:201], v[214:217], v[14:17]
	v_mfma_f32_16x16x32_bf16 v[10:13], v[198:201], v[222:225], v[10:13]
	v_mfma_f32_16x16x32_bf16 v[6:9], v[206:209], v[214:217], v[6:9]
	v_mfma_f32_16x16x32_bf16 v[2:5], v[206:209], v[222:225], v[2:5]
	v_mfma_f32_16x16x32_bf16 v[30:33], v[186:189], v[218:221], v[30:33]
	v_mfma_f32_16x16x32_bf16 v[26:29], v[186:189], v[226:229], v[26:29]
	v_mfma_f32_16x16x32_bf16 v[22:25], v[194:197], v[218:221], v[22:25]
	v_mfma_f32_16x16x32_bf16 v[18:21], v[194:197], v[226:229], v[18:21]
	v_mfma_f32_16x16x32_bf16 v[14:17], v[202:205], v[218:221], v[14:17]
	v_mfma_f32_16x16x32_bf16 v[10:13], v[202:205], v[226:229], v[10:13]
	v_mfma_f32_16x16x32_bf16 v[6:9], v[210:213], v[218:221], v[6:9]
	v_mfma_f32_16x16x32_bf16 v[2:5], v[210:213], v[226:229], v[2:5]
	s_setprio 0
	s_barrier
	ds_read_b128 v[160:163], v141
	ds_read_b128 v[164:167], v141 offset:1024
	ds_read_b128 v[174:177], v141 offset:2048
	ds_read_b128 v[178:181], v141 offset:3072
	v_readfirstlane_b32 s22, v148
	v_lshl_add_u64 v[168:169], v[168:169], 0, s[8:9]
	s_mov_b32 m0, s22
	v_readfirstlane_b32 s22, v149
	ds_read_b128 v[182:185], v139 offset:32768
	ds_read_b128 v[186:189], v139 offset:33792
	ds_read_b128 v[190:193], v138 offset:32768
	ds_read_b128 v[194:197], v138 offset:33792
	ds_read_b128 v[198:201], v137 offset:32768
	ds_read_b128 v[202:205], v137 offset:33792
	ds_read_b128 v[206:209], v136 offset:32768
	ds_read_b128 v[210:213], v136 offset:33792
	global_load_lds_dwordx4 v[168:169], off
	v_lshl_add_u64 v[168:169], v[230:231], 0, s[8:9]
	s_mov_b32 m0, s22
	s_add_u32 s12, s12, 0x100
	global_load_lds_dwordx4 v[168:169], off
	s_waitcnt lgkmcnt(8)
	s_barrier
	s_waitcnt lgkmcnt(0)
	s_addc_u32 s13, s13, 0
	s_setprio 1
	s_waitcnt lgkmcnt(0)
	v_mfma_f32_16x16x32_bf16 v[126:129], v[182:185], v[160:163], v[126:129]
	v_mfma_f32_16x16x32_bf16 v[122:125], v[182:185], v[174:177], v[122:125]
	v_mfma_f32_16x16x32_bf16 v[118:121], v[190:193], v[160:163], v[118:121]
	v_mfma_f32_16x16x32_bf16 v[114:117], v[190:193], v[174:177], v[114:117]
	v_mfma_f32_16x16x32_bf16 v[110:113], v[198:201], v[160:163], v[110:113]
	v_mfma_f32_16x16x32_bf16 v[106:109], v[198:201], v[174:177], v[106:109]
	v_mfma_f32_16x16x32_bf16 v[102:105], v[206:209], v[160:163], v[102:105]
	v_mfma_f32_16x16x32_bf16 v[98:101], v[206:209], v[174:177], v[98:101]
	v_mfma_f32_16x16x32_bf16 v[126:129], v[186:189], v[164:167], v[126:129]
	v_mfma_f32_16x16x32_bf16 v[122:125], v[186:189], v[178:181], v[122:125]
	v_mfma_f32_16x16x32_bf16 v[118:121], v[194:197], v[164:167], v[118:121]
	v_mfma_f32_16x16x32_bf16 v[114:117], v[194:197], v[178:181], v[114:117]
	v_mfma_f32_16x16x32_bf16 v[110:113], v[202:205], v[164:167], v[110:113]
	v_mfma_f32_16x16x32_bf16 v[106:109], v[202:205], v[178:181], v[106:109]
	v_mfma_f32_16x16x32_bf16 v[102:105], v[210:213], v[164:167], v[102:105]
	v_mfma_f32_16x16x32_bf16 v[98:101], v[210:213], v[178:181], v[98:101]
	s_setprio 0
	s_barrier
	v_readfirstlane_b32 s22, v156
	v_lshl_add_u64 v[168:169], v[232:233], 0, s[10:11]
	s_mov_b32 m0, s22
	v_readfirstlane_b32 s22, v157
	ds_read_b128 v[214:217], v140
	ds_read_b128 v[218:221], v140 offset:1024
	ds_read_b128 v[222:225], v140 offset:2048
	ds_read_b128 v[226:229], v140 offset:3072
	global_load_lds_dwordx4 v[168:169], off
	v_lshl_add_u64 v[168:169], v[234:235], 0, s[10:11]
	s_mov_b32 m0, s22
	s_nop 0
	global_load_lds_dwordx4 v[168:169], off
	s_waitcnt vmcnt(10)
	s_barrier
	s_waitcnt lgkmcnt(0)
	s_setprio 1
	s_waitcnt lgkmcnt(0)
	v_mfma_f32_16x16x32_bf16 v[94:97], v[182:185], v[214:217], v[94:97]
	v_mfma_f32_16x16x32_bf16 v[90:93], v[182:185], v[222:225], v[90:93]
	v_mfma_f32_16x16x32_bf16 v[86:89], v[190:193], v[214:217], v[86:89]
	v_mfma_f32_16x16x32_bf16 v[82:85], v[190:193], v[222:225], v[82:85]
	v_mfma_f32_16x16x32_bf16 v[78:81], v[198:201], v[214:217], v[78:81]
	v_mfma_f32_16x16x32_bf16 v[74:77], v[198:201], v[222:225], v[74:77]
	v_mfma_f32_16x16x32_bf16 v[70:73], v[206:209], v[214:217], v[70:73]
	v_mfma_f32_16x16x32_bf16 v[66:69], v[206:209], v[222:225], v[66:69]
	v_mfma_f32_16x16x32_bf16 v[94:97], v[186:189], v[218:221], v[94:97]
	v_mfma_f32_16x16x32_bf16 v[90:93], v[186:189], v[226:229], v[90:93]
	v_mfma_f32_16x16x32_bf16 v[86:89], v[194:197], v[218:221], v[86:89]
	v_mfma_f32_16x16x32_bf16 v[82:85], v[194:197], v[226:229], v[82:85]
	v_mfma_f32_16x16x32_bf16 v[78:81], v[202:205], v[218:221], v[78:81]
	v_mfma_f32_16x16x32_bf16 v[74:77], v[202:205], v[226:229], v[74:77]
	v_mfma_f32_16x16x32_bf16 v[70:73], v[210:213], v[218:221], v[70:73]
	v_mfma_f32_16x16x32_bf16 v[66:69], v[210:213], v[226:229], v[66:69]
	s_setprio 0
	v_readfirstlane_b32 s22, v150
	v_lshl_add_u64 v[168:169], v[236:237], 0, s[10:11]
	s_mov_b32 m0, s22
	v_readfirstlane_b32 s22, v151
	s_barrier
; #define STAGE(P, GP, ktrel) do { const GAS char* _g = (GP) + (ktrel) * (BK * 2); \
;     __builtin_amdgcn_global_load_lds((const GAS unsigned*)(_g + so0), (unsigned*)((char*)(P) + tid_ * 16), 16, 0, 0); \
;     __builtin_amdgcn_global_load_lds((const GAS unsigned*)(_g + so1), (unsigned*)((char*)(P) + tid_ * 16 + 8192), 16, 0, 0); } while (0)
; #define WAIT_V(n) asm volatile("s_waitcnt vmcnt(" #n ")" ::: "memory")
; #define WAIT_L(n) asm volatile("s_waitcnt lgkmcnt(" #n ")" ::: "memory")
; #define BAR __builtin_amdgcn_s_barrier()
; #define SCHED __builtin_amdgcn_sched_barrier(0)
; #define LDA(dst, b, h) for (int m = 0; m < 4; ++m) for (int k = 0; k < 2; ++k) \
;     dst[m][k] = *reinterpret_cast<const bf16x8*>((char*)SA(b, h) + lds_byte(wr * 64 + m * 16 + fr, k * 32 + fq * 8))
; #define LDB(dst, b, h) for (int n = 0; n < 2; ++n) for (int k = 0; k < 2; ++k) \
;     dst[n][k] = *reinterpret_cast<const bf16x8*>((char*)SB(b, h) + lds_byte(wc * 32 + n * 16 + fr, k * 32 + fq * 8))
; #define MMA(ai, bj, At_, Bt_) do { __builtin_amdgcn_s_setprio(1); \
;     for (int m = 0; m < 4; ++m) for (int n = 0; n < 2; ++n) for (int k = 0; k < 2; ++k) \
;       acc[ai][bj][m][n] = __builtin_amdgcn_mfma_f32_16x16x32_bf16(At_[m][k], Bt_[n][k], acc[ai][bj][m][n], 0, 0, 0); \
;     __builtin_amdgcn_s_setprio(0); } while (0)
; template <int K, int LD = K>
; __device__ __forceinline__ void gemm_main(const GAS bf16* A, const GAS bf16* Bt, int brow, int bcol, f32x4 (&acc)[2][2][4][2]) {
;     ...
;     LDA(At, 1, 1); STAGE(SA(1, 0), pA0, 3);
;     BAR; WAIT_L(0); MMA(1, 0, At, B0); BAR; SCHED;
;     STAGE(SB(1, 1), pB1, 3);
;     WAIT_V(6); BAR; MMA(1, 1, At, B1); BAR;
;     pA0 += 4 * BK; pA1 += 4 * BK; pB0 += 4 * BK; pB1 += 4 * BK;
;     asm volatile("" : "+s"(pA0), "+s"(pA1), "+s"(pB0), "+s"(pB1));
;   }
;   { LDB(B0, 0, 0); LDA(At, 0, 0); STAGE(SA(1, 1), pA1, 1);
;     BAR; WAIT_L(0); MMA(0, 0, At, B0); BAR;
;     LDB(B1, 0, 1); BAR; WAIT_L(0); MMA(0, 1, At, B1); BAR;
;     LDA(At, 0, 1); WAIT_V(4); BAR; WAIT_L(0); MMA(1, 0, At, B0); MMA(1, 1, At, B1); BAR; }
	ds_read_b128 v[182:185], v139 offset:49152
	ds_read_b128 v[186:189], v139 offset:50176
	ds_read_b128 v[190:193], v138 offset:49152
	ds_read_b128 v[194:197], v138 offset:50176
	ds_read_b128 v[198:201], v137 offset:49152
	ds_read_b128 v[202:205], v137 offset:50176
	ds_read_b128 v[206:209], v136 offset:49152
	ds_read_b128 v[210:213], v136 offset:50176
	global_load_lds_dwordx4 v[168:169], off
	v_lshl_add_u64 v[168:169], v[238:239], 0, s[10:11]
	s_mov_b32 m0, s22
	s_nop 0
	global_load_lds_dwordx4 v[168:169], off
	s_barrier
	s_waitcnt lgkmcnt(0)
	s_setprio 1
	s_waitcnt lgkmcnt(0)
	v_mfma_f32_16x16x32_bf16 v[62:65], v[182:185], v[160:163], v[62:65]
	v_mfma_f32_16x16x32_bf16 v[58:61], v[182:185], v[174:177], v[58:61]
	v_mfma_f32_16x16x32_bf16 v[54:57], v[190:193], v[160:163], v[54:57]
	v_mfma_f32_16x16x32_bf16 v[50:53], v[190:193], v[174:177], v[50:53]
	v_mfma_f32_16x16x32_bf16 v[46:49], v[198:201], v[160:163], v[46:49]
	v_mfma_f32_16x16x32_bf16 v[42:45], v[198:201], v[174:177], v[42:45]
	v_mfma_f32_16x16x32_bf16 v[38:41], v[206:209], v[160:163], v[38:41]
	v_mfma_f32_16x16x32_bf16 v[34:37], v[206:209], v[174:177], v[34:37]
	v_mfma_f32_16x16x32_bf16 v[62:65], v[186:189], v[164:167], v[62:65]
	v_mfma_f32_16x16x32_bf16 v[58:61], v[186:189], v[178:181], v[58:61]
	v_mfma_f32_16x16x32_bf16 v[54:57], v[194:197], v[164:167], v[54:57]
	v_mfma_f32_16x16x32_bf16 v[50:53], v[194:197], v[178:181], v[50:53]
	v_mfma_f32_16x16x32_bf16 v[46:49], v[202:205], v[164:167], v[46:49]
	v_mfma_f32_16x16x32_bf16 v[42:45], v[202:205], v[178:181], v[42:45]
	v_mfma_f32_16x16x32_bf16 v[38:41], v[210:213], v[164:167], v[38:41]
	v_mfma_f32_16x16x32_bf16 v[34:37], v[210:213], v[178:181], v[34:37]
	s_setprio 0
	s_barrier
	v_readfirstlane_b32 s22, v158
	v_lshl_add_u64 v[160:161], v[240:241], 0, s[10:11]
	s_mov_b32 m0, s22
	v_readfirstlane_b32 s22, v159
	global_load_lds_dwordx4 v[160:161], off
	v_lshl_add_u64 v[160:161], v[242:243], 0, s[10:11]
	s_mov_b32 m0, s22
	s_nop 0
	global_load_lds_dwordx4 v[160:161], off
	s_waitcnt vmcnt(8)
	s_barrier
	s_setprio 1
	v_mfma_f32_16x16x32_bf16 v[30:33], v[182:185], v[214:217], v[30:33]
	v_mfma_f32_16x16x32_bf16 v[26:29], v[182:185], v[222:225], v[26:29]
	v_mfma_f32_16x16x32_bf16 v[22:25], v[190:193], v[214:217], v[22:25]
	v_mfma_f32_16x16x32_bf16 v[18:21], v[190:193], v[222:225], v[18:21]
	v_mfma_f32_16x16x32_bf16 v[14:17], v[198:201], v[214:217], v[14:17]
	v_mfma_f32_16x16x32_bf16 v[10:13], v[198:201], v[222:225], v[10:13]
	v_mfma_f32_16x16x32_bf16 v[6:9], v[206:209], v[214:217], v[6:9]
	v_mfma_f32_16x16x32_bf16 v[2:5], v[206:209], v[222:225], v[2:5]
	v_mfma_f32_16x16x32_bf16 v[30:33], v[186:189], v[218:221], v[30:33]
	v_mfma_f32_16x16x32_bf16 v[26:29], v[186:189], v[226:229], v[26:29]
	v_mfma_f32_16x16x32_bf16 v[22:25], v[194:197], v[218:221], v[22:25]
	v_mfma_f32_16x16x32_bf16 v[18:21], v[194:197], v[226:229], v[18:21]
	v_mfma_f32_16x16x32_bf16 v[14:17], v[202:205], v[218:221], v[14:17]
	v_mfma_f32_16x16x32_bf16 v[10:13], v[202:205], v[226:229], v[10:13]
	v_mfma_f32_16x16x32_bf16 v[6:9], v[210:213], v[218:221], v[6:9]
	v_mfma_f32_16x16x32_bf16 v[2:5], v[210:213], v[226:229], v[2:5]
	s_setprio 0
	s_add_i32 s15, s15, 2
	s_cmp_lt_u32 s15, 12
	s_barrier
	s_cbranch_scc1 .LBB0_884
	v_lshl_add_u64 v[198:199], s[12:13], 0, v[130:131]
	v_readfirstlane_b32 s15, v144
	v_lshl_add_u64 v[198:199], v[198:199], 0, s[6:7]
	s_mov_b32 m0, s15
	v_lshl_add_u64 v[132:133], s[12:13], 0, v[132:133]
	v_readfirstlane_b32 s12, v143
	ds_read_b128 v[146:149], v145
	ds_read_b128 v[150:153], v145 offset:1024
	ds_read_b128 v[154:157], v145 offset:2048
	ds_read_b128 v[158:161], v145 offset:3072
	ds_read_b128 v[162:165], v139
	ds_read_b128 v[166:169], v139 offset:1024
	ds_read_b128 v[174:177], v138
	ds_read_b128 v[178:181], v138 offset:1024
	ds_read_b128 v[182:185], v137
	ds_read_b128 v[186:189], v137 offset:1024
	ds_read_b128 v[190:193], v136
	ds_read_b128 v[194:197], v136 offset:1024
	global_load_lds_dwordx4 v[198:199], off
	v_lshl_add_u64 v[132:133], v[132:133], 0, s[6:7]
	s_mov_b32 m0, s12
	s_nop 0
	global_load_lds_dwordx4 v[132:133], off
	s_barrier
	s_waitcnt lgkmcnt(0)
	s_setprio 1
	s_waitcnt lgkmcnt(0)
	v_mfma_f32_16x16x32_bf16 v[126:129], v[162:165], v[146:149], v[126:129]
	v_mfma_f32_16x16x32_bf16 v[122:125], v[162:165], v[154:157], v[122:125]
	v_mfma_f32_16x16x32_bf16 v[110:113], v[182:185], v[146:149], v[110:113]
	v_mfma_f32_16x16x32_bf16 v[106:109], v[182:185], v[154:157], v[106:109]
	v_mfma_f32_16x16x32_bf16 v[126:129], v[166:169], v[150:153], v[126:129]
	v_mfma_f32_16x16x32_bf16 v[122:125], v[166:169], v[158:161], v[122:125]
	v_mfma_f32_16x16x32_bf16 v[118:121], v[174:177], v[146:149], v[118:121]
	v_mfma_f32_16x16x32_bf16 v[114:117], v[174:177], v[154:157], v[114:117]
	v_mfma_f32_16x16x32_bf16 v[110:113], v[186:189], v[150:153], v[110:113]
	v_mfma_f32_16x16x32_bf16 v[106:109], v[186:189], v[158:161], v[106:109]
	v_mfma_f32_16x16x32_bf16 v[102:105], v[190:193], v[146:149], v[102:105]
	v_mfma_f32_16x16x32_bf16 v[98:101], v[190:193], v[154:157], v[98:101]
	v_mfma_f32_16x16x32_bf16 v[198:201], v[178:181], v[150:153], v[118:121]
	v_mfma_f32_16x16x32_bf16 v[202:205], v[178:181], v[158:161], v[114:117]
	v_mfma_f32_16x16x32_bf16 v[206:209], v[194:197], v[150:153], v[102:105]
	v_mfma_f32_16x16x32_bf16 v[210:213], v[194:197], v[158:161], v[98:101]
	s_setprio 0
	s_barrier
	s_nop 1
	ds_read_b128 v[98:101], v142
	ds_read_b128 v[102:105], v142 offset:1024
	ds_read_b128 v[114:117], v142 offset:2048
	ds_read_b128 v[118:121], v142 offset:3072
	s_waitcnt vmcnt(8)
	s_barrier
; #define WAIT_V(n) asm volatile("s_waitcnt vmcnt(" #n ")" ::: "memory")
; #define WAIT_L(n) asm volatile("s_waitcnt lgkmcnt(" #n ")" ::: "memory")
; #define BAR __builtin_amdgcn_s_barrier()
; #define LDA(dst, b, h) for (int m = 0; m < 4; ++m) for (int k = 0; k < 2; ++k) \
;     dst[m][k] = *reinterpret_cast<const bf16x8*>((char*)SA(b, h) + lds_byte(wr * 64 + m * 16 + fr, k * 32 + fq * 8))
; #define LDB(dst, b, h) for (int n = 0; n < 2; ++n) for (int k = 0; k < 2; ++k) \
;     dst[n][k] = *reinterpret_cast<const bf16x8*>((char*)SB(b, h) + lds_byte(wc * 32 + n * 16 + fr, k * 32 + fq * 8))
; #define MMA(ai, bj, At_, Bt_) do { __builtin_amdgcn_s_setprio(1); \
;     for (int m = 0; m < 4; ++m) for (int n = 0; n < 2; ++n) for (int k = 0; k < 2; ++k) \
;       acc[ai][bj][m][n] = __builtin_amdgcn_mfma_f32_16x16x32_bf16(At_[m][k], Bt_[n][k], acc[ai][bj][m][n], 0, 0, 0); \
;     __builtin_amdgcn_s_setprio(0); } while (0)
; template <int K, int LD = K>
; __device__ __forceinline__ void gemm_main(const GAS bf16* A, const GAS bf16* Bt, int brow, int bcol, f32x4 (&acc)[2][2][4][2]) {
;     ...
;     LDB(B1, 0, 1); BAR; WAIT_L(0); MMA(0, 1, At, B1); BAR;
;     LDA(At, 0, 1); WAIT_V(4); BAR; WAIT_L(0); MMA(1, 0, At, B0); MMA(1, 1, At, B1); BAR; }
;   { LDB(B0, 1, 0); LDA(At, 1, 0); WAIT_V(2); BAR; WAIT_L(0); MMA(0, 0, At, B0); BAR;
	s_waitcnt lgkmcnt(0)
	s_setprio 1
	s_waitcnt lgkmcnt(0)
	v_mfma_f32_16x16x32_bf16 v[94:97], v[162:165], v[98:101], v[94:97]
	v_mfma_f32_16x16x32_bf16 v[90:93], v[162:165], v[114:117], v[90:93]
	v_mfma_f32_16x16x32_bf16 v[78:81], v[182:185], v[98:101], v[78:81]
	v_mfma_f32_16x16x32_bf16 v[74:77], v[182:185], v[114:117], v[74:77]
	v_mfma_f32_16x16x32_bf16 v[94:97], v[166:169], v[102:105], v[94:97]
	v_mfma_f32_16x16x32_bf16 v[90:93], v[166:169], v[118:121], v[90:93]
	v_mfma_f32_16x16x32_bf16 v[86:89], v[174:177], v[98:101], v[86:89]
	v_mfma_f32_16x16x32_bf16 v[82:85], v[174:177], v[114:117], v[82:85]
	v_mfma_f32_16x16x32_bf16 v[78:81], v[186:189], v[102:105], v[78:81]
	v_mfma_f32_16x16x32_bf16 v[74:77], v[186:189], v[118:121], v[74:77]
	v_mfma_f32_16x16x32_bf16 v[70:73], v[190:193], v[98:101], v[70:73]
	v_mfma_f32_16x16x32_bf16 v[66:69], v[190:193], v[114:117], v[66:69]
	v_mfma_f32_16x16x32_bf16 v[142:145], v[178:181], v[102:105], v[86:89]
	v_mfma_f32_16x16x32_bf16 v[162:165], v[178:181], v[118:121], v[82:85]
	v_mfma_f32_16x16x32_bf16 v[166:169], v[194:197], v[102:105], v[70:73]
	v_mfma_f32_16x16x32_bf16 v[174:177], v[194:197], v[118:121], v[66:69]
	s_setprio 0
	s_barrier
	s_nop 1
	ds_read_b128 v[66:69], v139 offset:16384
	ds_read_b128 v[70:73], v139 offset:17408
	ds_read_b128 v[82:85], v138 offset:16384
	ds_read_b128 v[86:89], v138 offset:17408
	ds_read_b128 v[178:181], v137 offset:16384
	ds_read_b128 v[182:185], v137 offset:17408
	ds_read_b128 v[186:189], v136 offset:16384
	ds_read_b128 v[190:193], v136 offset:17408
	s_waitcnt vmcnt(4)
	s_barrier
	s_waitcnt lgkmcnt(0)
	s_setprio 1
	s_waitcnt lgkmcnt(0)
	v_mfma_f32_16x16x32_bf16 v[62:65], v[66:69], v[146:149], v[62:65]
	v_mfma_f32_16x16x32_bf16 v[58:61], v[66:69], v[154:157], v[58:61]
	v_mfma_f32_16x16x32_bf16 v[46:49], v[178:181], v[146:149], v[46:49]
	v_mfma_f32_16x16x32_bf16 v[38:41], v[186:189], v[146:149], v[38:41]
	v_mfma_f32_16x16x32_bf16 v[62:65], v[70:73], v[150:153], v[62:65]
	v_mfma_f32_16x16x32_bf16 v[58:61], v[70:73], v[158:161], v[58:61]
	v_mfma_f32_16x16x32_bf16 v[54:57], v[82:85], v[146:149], v[54:57]
	v_mfma_f32_16x16x32_bf16 v[50:53], v[82:85], v[154:157], v[50:53]
	v_mfma_f32_16x16x32_bf16 v[46:49], v[182:185], v[150:153], v[46:49]
	v_mfma_f32_16x16x32_bf16 v[42:45], v[178:181], v[154:157], v[42:45]
	v_mfma_f32_16x16x32_bf16 v[38:41], v[190:193], v[150:153], v[38:41]
	v_mfma_f32_16x16x32_bf16 v[34:37], v[186:189], v[154:157], v[34:37]
	v_mfma_f32_16x16x32_bf16 v[194:197], v[86:89], v[150:153], v[54:57]
	v_mfma_f32_16x16x32_bf16 v[214:217], v[86:89], v[158:161], v[50:53]
	v_mfma_f32_16x16x32_bf16 v[218:221], v[182:185], v[158:161], v[42:45]
	v_mfma_f32_16x16x32_bf16 v[146:149], v[190:193], v[158:161], v[34:37]
	s_setprio 0
	s_setprio 1
	v_mfma_f32_16x16x32_bf16 v[30:33], v[66:69], v[98:101], v[30:33]
	v_mfma_f32_16x16x32_bf16 v[26:29], v[66:69], v[114:117], v[26:29]
	v_mfma_f32_16x16x32_bf16 v[14:17], v[178:181], v[98:101], v[14:17]
	v_mfma_f32_16x16x32_bf16 v[6:9], v[186:189], v[98:101], v[6:9]
	v_mfma_f32_16x16x32_bf16 v[30:33], v[70:73], v[102:105], v[30:33]
	v_mfma_f32_16x16x32_bf16 v[26:29], v[70:73], v[118:121], v[26:29]
	v_mfma_f32_16x16x32_bf16 v[22:25], v[82:85], v[98:101], v[22:25]
	v_mfma_f32_16x16x32_bf16 v[18:21], v[82:85], v[114:117], v[18:21]
	v_mfma_f32_16x16x32_bf16 v[14:17], v[182:185], v[102:105], v[14:17]
	v_mfma_f32_16x16x32_bf16 v[10:13], v[178:181], v[114:117], v[10:13]
	v_mfma_f32_16x16x32_bf16 v[6:9], v[190:193], v[102:105], v[6:9]
	v_mfma_f32_16x16x32_bf16 v[2:5], v[186:189], v[114:117], v[2:5]
	v_mfma_f32_16x16x32_bf16 v[150:153], v[86:89], v[102:105], v[22:25]
	v_mfma_f32_16x16x32_bf16 v[154:157], v[86:89], v[118:121], v[18:21]
	v_mfma_f32_16x16x32_bf16 v[158:161], v[182:185], v[118:121], v[10:13]
	v_mfma_f32_16x16x32_bf16 v[178:181], v[190:193], v[118:121], v[2:5]
	s_setprio 0
	s_barrier
	s_nop 1
	ds_read_b128 v[2:5], v141
	ds_read_b128 v[10:13], v141 offset:1024
	ds_read_b128 v[182:185], v141 offset:2048
	ds_read_b128 v[186:189], v141 offset:3072
	ds_read_b128 v[18:21], v139 offset:32768
	ds_read_b128 v[22:25], v139 offset:33792
	ds_read_b128 v[34:37], v138 offset:32768
	ds_read_b128 v[42:45], v138 offset:33792
	ds_read_b128 v[50:53], v137 offset:32768
	ds_read_b128 v[54:57], v137 offset:33792
	ds_read_b128 v[190:193], v136 offset:32768
	ds_read_b128 v[222:225], v136 offset:33792
	s_waitcnt vmcnt(2)
	s_barrier
; #define STAGE(P, GP, ktrel) do { const GAS char* _g = (GP) + (ktrel) * (BK * 2); \
;     __builtin_amdgcn_global_load_lds((const GAS unsigned*)(_g + so0), (unsigned*)((char*)(P) + tid_ * 16), 16, 0, 0); \
;     __builtin_amdgcn_global_load_lds((const GAS unsigned*)(_g + so1), (unsigned*)((char*)(P) + tid_ * 16 + 8192), 16, 0, 0); } while (0)
; #define WAIT_V(n) asm volatile("s_waitcnt vmcnt(" #n ")" ::: "memory")
; #define WAIT_L(n) asm volatile("s_waitcnt lgkmcnt(" #n ")" ::: "memory")
; #define BAR __builtin_amdgcn_s_barrier()
; #define LDA(dst, b, h) for (int m = 0; m < 4; ++m) for (int k = 0; k < 2; ++k) \
;     dst[m][k] = *reinterpret_cast<const bf16x8*>((char*)SA(b, h) + lds_byte(wr * 64 + m * 16 + fr, k * 32 + fq * 8))
; #define LDB(dst, b, h) for (int n = 0; n < 2; ++n) for (int k = 0; k < 2; ++k) \
;     dst[n][k] = *reinterpret_cast<const bf16x8*>((char*)SB(b, h) + lds_byte(wc * 32 + n * 16 + fr, k * 32 + fq * 8))
; #define MMA(ai, bj, At_, Bt_) do { __builtin_amdgcn_s_setprio(1); \
;     for (int m = 0; m < 4; ++m) for (int n = 0; n < 2; ++n) for (int k = 0; k < 2; ++k) \
;       acc[ai][bj][m][n] = __builtin_amdgcn_mfma_f32_16x16x32_bf16(At_[m][k], Bt_[n][k], acc[ai][bj][m][n], 0, 0, 0); \
;     __builtin_amdgcn_s_setprio(0); } while (0)
; template <int K, int LD = K>
; __device__ __forceinline__ void gemm_main(const GAS bf16* A, const GAS bf16* Bt, int brow, int bcol, f32x4 (&acc)[2][2][4][2]) {
;     ...
;   { LDB(B0, 0, 0); LDA(At, 0, 0); STAGE(SA(1, 1), pA1, 1);
;     BAR; WAIT_L(0); MMA(0, 0, At, B0); BAR;
;     LDB(B1, 0, 1); BAR; WAIT_L(0); MMA(0, 1, At, B1); BAR;
;     LDA(At, 0, 1); WAIT_V(4); BAR; WAIT_L(0); MMA(1, 0, At, B0); MMA(1, 1, At, B1); BAR; }
;   { LDB(B0, 1, 0); LDA(At, 1, 0); WAIT_V(2); BAR; WAIT_L(0); MMA(0, 0, At, B0); BAR;
;     LDB(B1, 1, 1); WAIT_V(0); BAR; WAIT_L(0); MMA(0, 1, At, B1); BAR;
;     LDA(At, 1, 1); BAR; WAIT_L(0); MMA(1, 0, At, B0); MMA(1, 1, At, B1); BAR; }
;   if (wr == 0) BAR;
	s_waitcnt lgkmcnt(0)
	s_setprio 1
	s_waitcnt lgkmcnt(0)
	v_mfma_f32_16x16x32_bf16 v[66:69], v[18:21], v[2:5], v[126:129]
	v_mfma_f32_16x16x32_bf16 v[118:121], v[22:25], v[10:13], v[66:69]
	v_mfma_f32_16x16x32_bf16 v[66:69], v[18:21], v[182:185], v[122:125]
	v_mfma_f32_16x16x32_bf16 v[114:117], v[22:25], v[186:189], v[66:69]
	v_mfma_f32_16x16x32_bf16 v[66:69], v[34:37], v[2:5], v[198:201]
	v_mfma_f32_16x16x32_bf16 v[102:105], v[42:45], v[10:13], v[66:69]
	v_mfma_f32_16x16x32_bf16 v[66:69], v[34:37], v[182:185], v[202:205]
	v_mfma_f32_16x16x32_bf16 v[98:101], v[42:45], v[186:189], v[66:69]
	v_mfma_f32_16x16x32_bf16 v[66:69], v[50:53], v[2:5], v[110:113]
	v_mfma_f32_16x16x32_bf16 v[86:89], v[54:57], v[10:13], v[66:69]
	v_mfma_f32_16x16x32_bf16 v[66:69], v[50:53], v[182:185], v[106:109]
	v_mfma_f32_16x16x32_bf16 v[82:85], v[54:57], v[186:189], v[66:69]
	v_mfma_f32_16x16x32_bf16 v[66:69], v[190:193], v[2:5], v[206:209]
	v_mfma_f32_16x16x32_bf16 v[70:73], v[222:225], v[10:13], v[66:69]
	v_mfma_f32_16x16x32_bf16 v[66:69], v[190:193], v[182:185], v[210:213]
	v_mfma_f32_16x16x32_bf16 v[66:69], v[222:225], v[186:189], v[66:69]
	s_setprio 0
	s_barrier
	ds_read_b128 v[198:201], v140
	ds_read_b128 v[202:205], v140 offset:1024
	ds_read_b128 v[206:209], v140 offset:2048
	ds_read_b128 v[210:213], v140 offset:3072
	s_waitcnt vmcnt(0)
	s_barrier
	s_waitcnt lgkmcnt(0)
	s_setprio 1
	s_waitcnt lgkmcnt(0)
	v_mfma_f32_16x16x32_bf16 v[94:97], v[18:21], v[198:201], v[94:97]
	v_mfma_f32_16x16x32_bf16 v[18:21], v[18:21], v[206:209], v[90:93]
	v_mfma_f32_16x16x32_bf16 v[122:125], v[22:25], v[210:213], v[18:21]
	v_mfma_f32_16x16x32_bf16 v[18:21], v[34:37], v[198:201], v[142:145]
	v_mfma_f32_16x16x32_bf16 v[110:113], v[42:45], v[202:205], v[18:21]
	v_mfma_f32_16x16x32_bf16 v[18:21], v[34:37], v[206:209], v[162:165]
	v_mfma_f32_16x16x32_bf16 v[106:109], v[42:45], v[210:213], v[18:21]
	v_mfma_f32_16x16x32_bf16 v[18:21], v[50:53], v[198:201], v[78:81]
	v_mfma_f32_16x16x32_bf16 v[126:129], v[22:25], v[202:205], v[94:97]
	v_mfma_f32_16x16x32_bf16 v[94:97], v[54:57], v[202:205], v[18:21]
	v_mfma_f32_16x16x32_bf16 v[18:21], v[50:53], v[206:209], v[74:77]
	v_mfma_f32_16x16x32_bf16 v[90:93], v[54:57], v[210:213], v[18:21]
	v_mfma_f32_16x16x32_bf16 v[18:21], v[190:193], v[198:201], v[166:169]
	v_mfma_f32_16x16x32_bf16 v[78:81], v[222:225], v[202:205], v[18:21]
	v_mfma_f32_16x16x32_bf16 v[18:21], v[190:193], v[206:209], v[174:177]
	v_mfma_f32_16x16x32_bf16 v[74:77], v[222:225], v[210:213], v[18:21]
	s_setprio 0
	s_barrier
	ds_read_b128 v[140:143], v139 offset:49152
	ds_read_b128 v[162:165], v139 offset:50176
	ds_read_b128 v[166:169], v138 offset:49152
	ds_read_b128 v[174:177], v138 offset:50176
	ds_read_b128 v[190:193], v137 offset:49152
	ds_read_b128 v[222:225], v137 offset:50176
	ds_read_b128 v[226:229], v136 offset:49152
	ds_read_b128 v[136:139], v136 offset:50176
	s_barrier
	s_waitcnt lgkmcnt(0)
	s_setprio 1
	s_waitcnt lgkmcnt(0)
	v_mfma_f32_16x16x32_bf16 v[18:21], v[140:143], v[2:5], v[62:65]
	v_mfma_f32_16x16x32_bf16 v[54:57], v[162:165], v[10:13], v[18:21]
	v_mfma_f32_16x16x32_bf16 v[18:21], v[140:143], v[182:185], v[58:61]
	v_mfma_f32_16x16x32_bf16 v[50:53], v[162:165], v[186:189], v[18:21]
	v_mfma_f32_16x16x32_bf16 v[18:21], v[166:169], v[2:5], v[194:197]
	v_mfma_f32_16x16x32_bf16 v[42:45], v[174:177], v[10:13], v[18:21]
	v_mfma_f32_16x16x32_bf16 v[18:21], v[166:169], v[182:185], v[214:217]
	v_mfma_f32_16x16x32_bf16 v[34:37], v[174:177], v[186:189], v[18:21]
	v_mfma_f32_16x16x32_bf16 v[18:21], v[190:193], v[2:5], v[46:49]
	v_mfma_f32_16x16x32_bf16 v[2:5], v[226:229], v[2:5], v[38:41]
	v_mfma_f32_16x16x32_bf16 v[22:25], v[222:225], v[10:13], v[18:21]
	v_mfma_f32_16x16x32_bf16 v[18:21], v[190:193], v[182:185], v[218:221]
	v_mfma_f32_16x16x32_bf16 v[10:13], v[136:139], v[10:13], v[2:5]
	v_mfma_f32_16x16x32_bf16 v[2:5], v[226:229], v[182:185], v[146:149]
	v_mfma_f32_16x16x32_bf16 v[18:21], v[222:225], v[186:189], v[18:21]
	v_mfma_f32_16x16x32_bf16 v[2:5], v[136:139], v[186:189], v[2:5]
	s_setprio 0
	s_setprio 1
	v_mfma_f32_16x16x32_bf16 v[26:29], v[140:143], v[206:209], v[26:29]
	v_mfma_f32_16x16x32_bf16 v[30:33], v[140:143], v[198:201], v[30:33]
	v_mfma_f32_16x16x32_bf16 v[58:61], v[162:165], v[210:213], v[26:29]
	v_mfma_f32_16x16x32_bf16 v[26:29], v[166:169], v[198:201], v[150:153]
	v_mfma_f32_16x16x32_bf16 v[14:17], v[190:193], v[198:201], v[14:17]
	v_mfma_f32_16x16x32_bf16 v[62:65], v[162:165], v[202:205], v[30:33]
	v_mfma_f32_16x16x32_bf16 v[46:49], v[174:177], v[202:205], v[26:29]
	v_mfma_f32_16x16x32_bf16 v[26:29], v[166:169], v[206:209], v[154:157]
	v_mfma_f32_16x16x32_bf16 v[30:33], v[222:225], v[202:205], v[14:17]
	v_mfma_f32_16x16x32_bf16 v[14:17], v[190:193], v[206:209], v[158:161]
	v_mfma_f32_16x16x32_bf16 v[6:9], v[226:229], v[198:201], v[6:9]
	v_mfma_f32_16x16x32_bf16 v[38:41], v[174:177], v[210:213], v[26:29]
	v_mfma_f32_16x16x32_bf16 v[26:29], v[222:225], v[210:213], v[14:17]
	v_mfma_f32_16x16x32_bf16 v[14:17], v[136:139], v[202:205], v[6:9]
	v_mfma_f32_16x16x32_bf16 v[6:9], v[226:229], v[206:209], v[178:181]
	v_mfma_f32_16x16x32_bf16 v[6:9], v[136:139], v[210:213], v[6:9]
	s_setprio 0
	v_cmp_gt_u32_e32 vcc, s34, v135
	s_barrier
	s_and_saveexec_b64 s[12:13], vcc
	s_cbranch_execz .LBB0_887
	s_barrier

; #define STAGE(P, GP, ktrel) do { const GAS char* _g = (GP) + (ktrel) * (BK * 2); \
;     __builtin_amdgcn_global_load_lds((const GAS unsigned*)(_g + so0), (unsigned*)((char*)(P) + tid_ * 16), 16, 0, 0); \
;     __builtin_amdgcn_global_load_lds((const GAS unsigned*)(_g + so1), (unsigned*)((char*)(P) + tid_ * 16 + 8192), 16, 0, 0); } while (0)
; #define WAIT_V(n) asm volatile("s_waitcnt vmcnt(" #n ")" ::: "memory")
; #define WAIT_L(n) asm volatile("s_waitcnt lgkmcnt(" #n ")" ::: "memory")
; #define BAR __builtin_amdgcn_s_barrier()
; #define SCHED __builtin_amdgcn_sched_barrier(0)
; #define LDA(dst, b, h) for (int m = 0; m < 4; ++m) for (int k = 0; k < 2; ++k) \
;     dst[m][k] = *reinterpret_cast<const bf16x8*>((char*)SA(b, h) + lds_byte(wr * 64 + m * 16 + fr, k * 32 + fq * 8))
; #define LDB(dst, b, h) for (int n = 0; n < 2; ++n) for (int k = 0; k < 2; ++k) \
;     dst[n][k] = *reinterpret_cast<const bf16x8*>((char*)SB(b, h) + lds_byte(wc * 32 + n * 16 + fr, k * 32 + fq * 8))
; #define MMA(ai, bj, At_, Bt_) do { __builtin_amdgcn_s_setprio(1); \
;     for (int m = 0; m < 4; ++m) for (int n = 0; n < 2; ++n) for (int k = 0; k < 2; ++k) \
;       acc[ai][bj][m][n] = __builtin_amdgcn_mfma_f32_16x16x32_bf16(At_[m][k], Bt_[n][k], acc[ai][bj][m][n], 0, 0, 0); \
;     __builtin_amdgcn_s_setprio(0); } while (0)
; template <int K, int LD = K>
; __device__ __forceinline__ void gemm_main(const GAS bf16* A, const GAS bf16* Bt, int brow, int bcol, f32x4 (&acc)[2][2][4][2]) {
;     ...
;   for (int t = 0; t < nt - 2; t += 2) {
;     LDB(B0, 0, 0); SCHED; LDA(At, 0, 0); STAGE(SA(1, 1), pA1, 1);
;     WAIT_L(8); BAR; WAIT_L(0); MMA(0, 0, At, B0); BAR; SCHED;
;     LDB(B1, 0, 1); STAGE(SB(0, 0), pB0, 2);
;     BAR; WAIT_L(0); MMA(0, 1, At, B1); BAR;
;     LDA(At, 0, 1); STAGE(SA(0, 0), pA0, 2);
;     BAR; WAIT_L(0); MMA(1, 0, At, B0); BAR; SCHED;
;     STAGE(SB(0, 1), pB1, 2);
;     WAIT_V(6); BAR; MMA(1, 1, At, B1); BAR;
;     LDB(B0, 1, 0); SCHED; LDA(At, 1, 0); STAGE(SA(0, 1), pA1, 2);
.LBB0_1105:
	ds_read_b128 v[160:163], v144
	ds_read_b128 v[164:167], v144 offset:1024
	ds_read_b128 v[174:177], v144 offset:2048
	ds_read_b128 v[178:181], v144 offset:3072
	v_lshl_add_u64 v[168:169], s[12:13], 0, v[130:131]
	v_readfirstlane_b32 s23, v143
	v_lshl_add_u64 v[214:215], v[168:169], 0, s[6:7]
	s_mov_b32 m0, s23
	v_lshl_add_u64 v[230:231], s[12:13], 0, v[132:133]
	v_readfirstlane_b32 s23, v142
	ds_read_b128 v[182:185], v138
	ds_read_b128 v[186:189], v138 offset:1024
	ds_read_b128 v[190:193], v137
	ds_read_b128 v[194:197], v137 offset:1024
	ds_read_b128 v[198:201], v136
	ds_read_b128 v[202:205], v136 offset:1024
	ds_read_b128 v[206:209], v135
	ds_read_b128 v[210:213], v135 offset:1024
	global_load_lds_dwordx4 v[214:215], off
	v_lshl_add_u64 v[214:215], v[230:231], 0, s[6:7]
	s_mov_b32 m0, s23
	s_nop 0
	global_load_lds_dwordx4 v[214:215], off
	s_waitcnt lgkmcnt(8)
	s_barrier
	s_waitcnt lgkmcnt(0)
	s_setprio 1
	s_waitcnt lgkmcnt(0)
	v_mfma_f32_16x16x32_bf16 v[126:129], v[182:185], v[160:163], v[126:129]
	v_mfma_f32_16x16x32_bf16 v[122:125], v[182:185], v[174:177], v[122:125]
	v_mfma_f32_16x16x32_bf16 v[118:121], v[190:193], v[160:163], v[118:121]
	v_mfma_f32_16x16x32_bf16 v[114:117], v[190:193], v[174:177], v[114:117]
	v_mfma_f32_16x16x32_bf16 v[110:113], v[198:201], v[160:163], v[110:113]
	v_mfma_f32_16x16x32_bf16 v[106:109], v[198:201], v[174:177], v[106:109]
	v_mfma_f32_16x16x32_bf16 v[102:105], v[206:209], v[160:163], v[102:105]
	v_mfma_f32_16x16x32_bf16 v[98:101], v[206:209], v[174:177], v[98:101]
	v_mfma_f32_16x16x32_bf16 v[126:129], v[186:189], v[164:167], v[126:129]
	v_mfma_f32_16x16x32_bf16 v[122:125], v[186:189], v[178:181], v[122:125]
	v_mfma_f32_16x16x32_bf16 v[118:121], v[194:197], v[164:167], v[118:121]
	v_mfma_f32_16x16x32_bf16 v[114:117], v[194:197], v[178:181], v[114:117]
	v_mfma_f32_16x16x32_bf16 v[110:113], v[202:205], v[164:167], v[110:113]
	v_mfma_f32_16x16x32_bf16 v[106:109], v[202:205], v[178:181], v[106:109]
	v_mfma_f32_16x16x32_bf16 v[102:105], v[210:213], v[164:167], v[102:105]
	v_mfma_f32_16x16x32_bf16 v[98:101], v[210:213], v[178:181], v[98:101]
	s_setprio 0
	s_barrier
	v_lshl_add_u64 v[232:233], s[20:21], 0, v[130:131]
	v_readfirstlane_b32 s23, v151
	v_lshl_add_u64 v[234:235], v[232:233], 0, s[8:9]
	s_mov_b32 m0, s23
	ds_read_b128 v[214:217], v141
	ds_read_b128 v[218:221], v141 offset:1024
	ds_read_b128 v[222:225], v141 offset:2048
	ds_read_b128 v[226:229], v141 offset:3072
	global_load_lds_dwordx4 v[234:235], off
	v_lshl_add_u64 v[234:235], s[20:21], 0, v[132:133]
	v_readfirstlane_b32 s23, v152
	v_lshl_add_u64 v[236:237], v[234:235], 0, s[8:9]
	s_mov_b32 m0, s23
	s_add_u32 s20, s20, 0x100
	global_load_lds_dwordx4 v[236:237], off
	s_waitcnt vmcnt(10)
	s_barrier
	s_waitcnt lgkmcnt(0)
	s_addc_u32 s21, s21, 0
	s_setprio 1
	s_waitcnt lgkmcnt(0)
	v_mfma_f32_16x16x32_bf16 v[94:97], v[182:185], v[214:217], v[94:97]
	v_mfma_f32_16x16x32_bf16 v[90:93], v[182:185], v[222:225], v[90:93]
	v_mfma_f32_16x16x32_bf16 v[86:89], v[190:193], v[214:217], v[86:89]
	v_mfma_f32_16x16x32_bf16 v[82:85], v[190:193], v[222:225], v[82:85]
	v_mfma_f32_16x16x32_bf16 v[78:81], v[198:201], v[214:217], v[78:81]
	v_mfma_f32_16x16x32_bf16 v[74:77], v[198:201], v[222:225], v[74:77]
	v_mfma_f32_16x16x32_bf16 v[70:73], v[206:209], v[214:217], v[70:73]
	v_mfma_f32_16x16x32_bf16 v[66:69], v[206:209], v[222:225], v[66:69]
	v_mfma_f32_16x16x32_bf16 v[94:97], v[186:189], v[218:221], v[94:97]
	v_mfma_f32_16x16x32_bf16 v[90:93], v[186:189], v[226:229], v[90:93]
	v_mfma_f32_16x16x32_bf16 v[86:89], v[194:197], v[218:221], v[86:89]
	v_mfma_f32_16x16x32_bf16 v[82:85], v[194:197], v[226:229], v[82:85]
	v_mfma_f32_16x16x32_bf16 v[78:81], v[202:205], v[218:221], v[78:81]
	v_mfma_f32_16x16x32_bf16 v[74:77], v[202:205], v[226:229], v[74:77]
	v_mfma_f32_16x16x32_bf16 v[70:73], v[210:213], v[218:221], v[70:73]
	v_mfma_f32_16x16x32_bf16 v[66:69], v[210:213], v[226:229], v[66:69]
	s_setprio 0
	v_lshl_add_u64 v[236:237], s[18:19], 0, v[130:131]
	v_readfirstlane_b32 s23, v145
	v_lshl_add_u64 v[238:239], v[236:237], 0, s[8:9]
	s_mov_b32 m0, s23
	s_barrier
	ds_read_b128 v[182:185], v138 offset:16384
	ds_read_b128 v[186:189], v138 offset:17408
	ds_read_b128 v[190:193], v137 offset:16384
	ds_read_b128 v[194:197], v137 offset:17408
	ds_read_b128 v[198:201], v136 offset:16384
	ds_read_b128 v[202:205], v136 offset:17408
	ds_read_b128 v[206:209], v135 offset:16384
	ds_read_b128 v[210:213], v135 offset:17408
	global_load_lds_dwordx4 v[238:239], off
	v_lshl_add_u64 v[238:239], s[18:19], 0, v[132:133]
	v_readfirstlane_b32 s23, v146
	v_lshl_add_u64 v[240:241], v[238:239], 0, s[8:9]
	s_mov_b32 m0, s23
	s_add_u32 s18, s18, 0x100
	global_load_lds_dwordx4 v[240:241], off
	s_barrier
	s_waitcnt lgkmcnt(0)
	s_addc_u32 s19, s19, 0
	s_setprio 1
	s_waitcnt lgkmcnt(0)
	v_mfma_f32_16x16x32_bf16 v[62:65], v[182:185], v[160:163], v[62:65]
	v_mfma_f32_16x16x32_bf16 v[58:61], v[182:185], v[174:177], v[58:61]
	v_mfma_f32_16x16x32_bf16 v[54:57], v[190:193], v[160:163], v[54:57]
	v_mfma_f32_16x16x32_bf16 v[50:53], v[190:193], v[174:177], v[50:53]
	v_mfma_f32_16x16x32_bf16 v[46:49], v[198:201], v[160:163], v[46:49]
	v_mfma_f32_16x16x32_bf16 v[42:45], v[198:201], v[174:177], v[42:45]
	v_mfma_f32_16x16x32_bf16 v[38:41], v[206:209], v[160:163], v[38:41]
	v_mfma_f32_16x16x32_bf16 v[34:37], v[206:209], v[174:177], v[34:37]
	v_mfma_f32_16x16x32_bf16 v[62:65], v[186:189], v[164:167], v[62:65]
	v_mfma_f32_16x16x32_bf16 v[58:61], v[186:189], v[178:181], v[58:61]
	v_mfma_f32_16x16x32_bf16 v[54:57], v[194:197], v[164:167], v[54:57]
	v_mfma_f32_16x16x32_bf16 v[50:53], v[194:197], v[178:181], v[50:53]
	v_mfma_f32_16x16x32_bf16 v[46:49], v[202:205], v[164:167], v[46:49]
	v_mfma_f32_16x16x32_bf16 v[42:45], v[202:205], v[178:181], v[42:45]
	v_mfma_f32_16x16x32_bf16 v[38:41], v[210:213], v[164:167], v[38:41]
	v_mfma_f32_16x16x32_bf16 v[34:37], v[210:213], v[178:181], v[34:37]
	s_setprio 0
	s_barrier
; #define STAGE(P, GP, ktrel) do { const GAS char* _g = (GP) + (ktrel) * (BK * 2); \
;     __builtin_amdgcn_global_load_lds((const GAS unsigned*)(_g + so0), (unsigned*)((char*)(P) + tid_ * 16), 16, 0, 0); \
;     __builtin_amdgcn_global_load_lds((const GAS unsigned*)(_g + so1), (unsigned*)((char*)(P) + tid_ * 16 + 8192), 16, 0, 0); } while (0)
; #define WAIT_V(n) asm volatile("s_waitcnt vmcnt(" #n ")" ::: "memory")
; #define WAIT_L(n) asm volatile("s_waitcnt lgkmcnt(" #n ")" ::: "memory")
; #define BAR __builtin_amdgcn_s_barrier()
; #define SCHED __builtin_amdgcn_sched_barrier(0)
; #define LDA(dst, b, h) for (int m = 0; m < 4; ++m) for (int k = 0; k < 2; ++k) \
;     dst[m][k] = *reinterpret_cast<const bf16x8*>((char*)SA(b, h) + lds_byte(wr * 64 + m * 16 + fr, k * 32 + fq * 8))
; #define LDB(dst, b, h) for (int n = 0; n < 2; ++n) for (int k = 0; k < 2; ++k) \
;     dst[n][k] = *reinterpret_cast<const bf16x8*>((char*)SB(b, h) + lds_byte(wc * 32 + n * 16 + fr, k * 32 + fq * 8))
; #define MMA(ai, bj, At_, Bt_) do { __builtin_amdgcn_s_setprio(1); \
;     for (int m = 0; m < 4; ++m) for (int n = 0; n < 2; ++n) for (int k = 0; k < 2; ++k) \
;       acc[ai][bj][m][n] = __builtin_amdgcn_mfma_f32_16x16x32_bf16(At_[m][k], Bt_[n][k], acc[ai][bj][m][n], 0, 0, 0); \
;     __builtin_amdgcn_s_setprio(0); } while (0)
; template <int K, int LD = K>
; __device__ __forceinline__ void gemm_main(const GAS bf16* A, const GAS bf16* Bt, int brow, int bcol, f32x4 (&acc)[2][2][4][2]) {
;     ...
;     WAIT_V(6); BAR; MMA(1, 1, At, B1); BAR;
;     LDB(B0, 1, 0); SCHED; LDA(At, 1, 0); STAGE(SA(0, 1), pA1, 2);
;     WAIT_L(8); BAR; WAIT_L(0); MMA(0, 0, At, B0); BAR; SCHED;
;     LDB(B1, 1, 1); STAGE(SB(1, 0), pB0, 3);
;     BAR; WAIT_L(0); MMA(0, 1, At, B1); BAR;
;     LDA(At, 1, 1); STAGE(SA(1, 0), pA0, 3);
;     BAR; WAIT_L(0); MMA(1, 0, At, B0); BAR; SCHED;
	v_lshl_add_u64 v[240:241], s[16:17], 0, v[130:131]
	v_readfirstlane_b32 s23, v153
	v_lshl_add_u64 v[160:161], v[240:241], 0, s[8:9]
	s_mov_b32 m0, s23
	v_lshl_add_u64 v[242:243], s[16:17], 0, v[132:133]
	v_readfirstlane_b32 s23, v154
	global_load_lds_dwordx4 v[160:161], off
	v_lshl_add_u64 v[160:161], v[242:243], 0, s[8:9]
	s_mov_b32 m0, s23
	s_add_u32 s16, s16, 0x100
	global_load_lds_dwordx4 v[160:161], off
	s_waitcnt vmcnt(8)
	s_addc_u32 s17, s17, 0
	s_barrier
	s_setprio 1
	v_mfma_f32_16x16x32_bf16 v[30:33], v[182:185], v[214:217], v[30:33]
	v_mfma_f32_16x16x32_bf16 v[26:29], v[182:185], v[222:225], v[26:29]
	v_mfma_f32_16x16x32_bf16 v[22:25], v[190:193], v[214:217], v[22:25]
	v_mfma_f32_16x16x32_bf16 v[18:21], v[190:193], v[222:225], v[18:21]
	v_mfma_f32_16x16x32_bf16 v[14:17], v[198:201], v[214:217], v[14:17]
	v_mfma_f32_16x16x32_bf16 v[10:13], v[198:201], v[222:225], v[10:13]
	v_mfma_f32_16x16x32_bf16 v[6:9], v[206:209], v[214:217], v[6:9]
	v_mfma_f32_16x16x32_bf16 v[2:5], v[206:209], v[222:225], v[2:5]
	v_mfma_f32_16x16x32_bf16 v[30:33], v[186:189], v[218:221], v[30:33]
	v_mfma_f32_16x16x32_bf16 v[26:29], v[186:189], v[226:229], v[26:29]
	v_mfma_f32_16x16x32_bf16 v[22:25], v[194:197], v[218:221], v[22:25]
	v_mfma_f32_16x16x32_bf16 v[18:21], v[194:197], v[226:229], v[18:21]
	v_mfma_f32_16x16x32_bf16 v[14:17], v[202:205], v[218:221], v[14:17]
	v_mfma_f32_16x16x32_bf16 v[10:13], v[202:205], v[226:229], v[10:13]
	v_mfma_f32_16x16x32_bf16 v[6:9], v[210:213], v[218:221], v[6:9]
	v_mfma_f32_16x16x32_bf16 v[2:5], v[210:213], v[226:229], v[2:5]
	s_setprio 0
	s_barrier
	ds_read_b128 v[160:163], v140
	ds_read_b128 v[164:167], v140 offset:1024
	ds_read_b128 v[174:177], v140 offset:2048
	ds_read_b128 v[178:181], v140 offset:3072
	v_readfirstlane_b32 s23, v147
	v_lshl_add_u64 v[168:169], v[168:169], 0, s[8:9]
	s_mov_b32 m0, s23
	v_readfirstlane_b32 s23, v148
	ds_read_b128 v[182:185], v138 offset:32768
	ds_read_b128 v[186:189], v138 offset:33792
	ds_read_b128 v[190:193], v137 offset:32768
	ds_read_b128 v[194:197], v137 offset:33792
	ds_read_b128 v[198:201], v136 offset:32768
	ds_read_b128 v[202:205], v136 offset:33792
	ds_read_b128 v[206:209], v135 offset:32768
	ds_read_b128 v[210:213], v135 offset:33792
	global_load_lds_dwordx4 v[168:169], off
	v_lshl_add_u64 v[168:169], v[230:231], 0, s[8:9]
	s_mov_b32 m0, s23
	s_add_u32 s12, s12, 0x100
	global_load_lds_dwordx4 v[168:169], off
	s_waitcnt lgkmcnt(8)
	s_barrier
	s_waitcnt lgkmcnt(0)
	s_addc_u32 s13, s13, 0
	s_setprio 1
	s_waitcnt lgkmcnt(0)
	v_mfma_f32_16x16x32_bf16 v[126:129], v[182:185], v[160:163], v[126:129]
	v_mfma_f32_16x16x32_bf16 v[122:125], v[182:185], v[174:177], v[122:125]
	v_mfma_f32_16x16x32_bf16 v[118:121], v[190:193], v[160:163], v[118:121]
	v_mfma_f32_16x16x32_bf16 v[114:117], v[190:193], v[174:177], v[114:117]
	v_mfma_f32_16x16x32_bf16 v[110:113], v[198:201], v[160:163], v[110:113]
	v_mfma_f32_16x16x32_bf16 v[106:109], v[198:201], v[174:177], v[106:109]
	v_mfma_f32_16x16x32_bf16 v[102:105], v[206:209], v[160:163], v[102:105]
	v_mfma_f32_16x16x32_bf16 v[98:101], v[206:209], v[174:177], v[98:101]
	v_mfma_f32_16x16x32_bf16 v[126:129], v[186:189], v[164:167], v[126:129]
	v_mfma_f32_16x16x32_bf16 v[122:125], v[186:189], v[178:181], v[122:125]
	v_mfma_f32_16x16x32_bf16 v[118:121], v[194:197], v[164:167], v[118:121]
	v_mfma_f32_16x16x32_bf16 v[114:117], v[194:197], v[178:181], v[114:117]
	v_mfma_f32_16x16x32_bf16 v[110:113], v[202:205], v[164:167], v[110:113]
	v_mfma_f32_16x16x32_bf16 v[106:109], v[202:205], v[178:181], v[106:109]
	v_mfma_f32_16x16x32_bf16 v[102:105], v[210:213], v[164:167], v[102:105]
	v_mfma_f32_16x16x32_bf16 v[98:101], v[210:213], v[178:181], v[98:101]
	s_setprio 0
	s_barrier
	v_readfirstlane_b32 s23, v155
	v_lshl_add_u64 v[168:169], v[232:233], 0, s[10:11]
	s_mov_b32 m0, s23
	v_readfirstlane_b32 s23, v156
	ds_read_b128 v[214:217], v139
	ds_read_b128 v[218:221], v139 offset:1024
	ds_read_b128 v[222:225], v139 offset:2048
	ds_read_b128 v[226:229], v139 offset:3072
	global_load_lds_dwordx4 v[168:169], off
	v_lshl_add_u64 v[168:169], v[234:235], 0, s[10:11]
	s_mov_b32 m0, s23
	s_nop 0
	global_load_lds_dwordx4 v[168:169], off
	s_waitcnt vmcnt(10)
	s_barrier
	s_waitcnt lgkmcnt(0)
	s_setprio 1
	s_waitcnt lgkmcnt(0)
	v_mfma_f32_16x16x32_bf16 v[94:97], v[182:185], v[214:217], v[94:97]
	v_mfma_f32_16x16x32_bf16 v[90:93], v[182:185], v[222:225], v[90:93]
	v_mfma_f32_16x16x32_bf16 v[86:89], v[190:193], v[214:217], v[86:89]
	v_mfma_f32_16x16x32_bf16 v[82:85], v[190:193], v[222:225], v[82:85]
	v_mfma_f32_16x16x32_bf16 v[78:81], v[198:201], v[214:217], v[78:81]
	v_mfma_f32_16x16x32_bf16 v[74:77], v[198:201], v[222:225], v[74:77]
	v_mfma_f32_16x16x32_bf16 v[70:73], v[206:209], v[214:217], v[70:73]
	v_mfma_f32_16x16x32_bf16 v[66:69], v[206:209], v[222:225], v[66:69]
	v_mfma_f32_16x16x32_bf16 v[94:97], v[186:189], v[218:221], v[94:97]
	v_mfma_f32_16x16x32_bf16 v[90:93], v[186:189], v[226:229], v[90:93]
	v_mfma_f32_16x16x32_bf16 v[86:89], v[194:197], v[218:221], v[86:89]
	v_mfma_f32_16x16x32_bf16 v[82:85], v[194:197], v[226:229], v[82:85]
	v_mfma_f32_16x16x32_bf16 v[78:81], v[202:205], v[218:221], v[78:81]
	v_mfma_f32_16x16x32_bf16 v[74:77], v[202:205], v[226:229], v[74:77]
	v_mfma_f32_16x16x32_bf16 v[70:73], v[210:213], v[218:221], v[70:73]
	v_mfma_f32_16x16x32_bf16 v[66:69], v[210:213], v[226:229], v[66:69]
	s_setprio 0
	v_readfirstlane_b32 s23, v149
	v_lshl_add_u64 v[168:169], v[236:237], 0, s[10:11]
	s_mov_b32 m0, s23
	v_readfirstlane_b32 s23, v150
	s_barrier
; #define STAGE(P, GP, ktrel) do { const GAS char* _g = (GP) + (ktrel) * (BK * 2); \
;     __builtin_amdgcn_global_load_lds((const GAS unsigned*)(_g + so0), (unsigned*)((char*)(P) + tid_ * 16), 16, 0, 0); \
;     __builtin_amdgcn_global_load_lds((const GAS unsigned*)(_g + so1), (unsigned*)((char*)(P) + tid_ * 16 + 8192), 16, 0, 0); } while (0)
; #define WAIT_V(n) asm volatile("s_waitcnt vmcnt(" #n ")" ::: "memory")
; #define WAIT_L(n) asm volatile("s_waitcnt lgkmcnt(" #n ")" ::: "memory")
; #define BAR __builtin_amdgcn_s_barrier()
; #define LDA(dst, b, h) for (int m = 0; m < 4; ++m) for (int k = 0; k < 2; ++k) \
;     dst[m][k] = *reinterpret_cast<const bf16x8*>((char*)SA(b, h) + lds_byte(wr * 64 + m * 16 + fr, k * 32 + fq * 8))
; #define LDB(dst, b, h) for (int n = 0; n < 2; ++n) for (int k = 0; k < 2; ++k) \
;     dst[n][k] = *reinterpret_cast<const bf16x8*>((char*)SB(b, h) + lds_byte(wc * 32 + n * 16 + fr, k * 32 + fq * 8))
; #define MMA(ai, bj, At_, Bt_) do { __builtin_amdgcn_s_setprio(1); \
;     for (int m = 0; m < 4; ++m) for (int n = 0; n < 2; ++n) for (int k = 0; k < 2; ++k) \
;       acc[ai][bj][m][n] = __builtin_amdgcn_mfma_f32_16x16x32_bf16(At_[m][k], Bt_[n][k], acc[ai][bj][m][n], 0, 0, 0); \
;     __builtin_amdgcn_s_setprio(0); } while (0)
; template <int K, int LD = K>
; __device__ __forceinline__ void gemm_main(const GAS bf16* A, const GAS bf16* Bt, int brow, int bcol, f32x4 (&acc)[2][2][4][2]) {
;     ...
;     STAGE(SB(1, 1), pB1, 3);
;     WAIT_V(6); BAR; MMA(1, 1, At, B1); BAR;
;     pA0 += 4 * BK; pA1 += 4 * BK; pB0 += 4 * BK; pB1 += 4 * BK;
;     asm volatile("" : "+s"(pA0), "+s"(pA1), "+s"(pB0), "+s"(pB1));
;   }
;   { LDB(B0, 0, 0); LDA(At, 0, 0); STAGE(SA(1, 1), pA1, 1);
;     BAR; WAIT_L(0); MMA(0, 0, At, B0); BAR;
;     LDB(B1, 0, 1); BAR; WAIT_L(0); MMA(0, 1, At, B1); BAR;
;     LDA(At, 0, 1); WAIT_V(4); BAR; WAIT_L(0); MMA(1, 0, At, B0); MMA(1, 1, At, B1); BAR; }
	ds_read_b128 v[182:185], v138 offset:49152
	ds_read_b128 v[186:189], v138 offset:50176
	ds_read_b128 v[190:193], v137 offset:49152
	ds_read_b128 v[194:197], v137 offset:50176
	ds_read_b128 v[198:201], v136 offset:49152
	ds_read_b128 v[202:205], v136 offset:50176
	ds_read_b128 v[206:209], v135 offset:49152
	ds_read_b128 v[210:213], v135 offset:50176
	global_load_lds_dwordx4 v[168:169], off
	v_lshl_add_u64 v[168:169], v[238:239], 0, s[10:11]
	s_mov_b32 m0, s23
	s_nop 0
	global_load_lds_dwordx4 v[168:169], off
	s_barrier
	s_waitcnt lgkmcnt(0)
	s_setprio 1
	s_waitcnt lgkmcnt(0)
	v_mfma_f32_16x16x32_bf16 v[62:65], v[182:185], v[160:163], v[62:65]
	v_mfma_f32_16x16x32_bf16 v[58:61], v[182:185], v[174:177], v[58:61]
	v_mfma_f32_16x16x32_bf16 v[54:57], v[190:193], v[160:163], v[54:57]
	v_mfma_f32_16x16x32_bf16 v[50:53], v[190:193], v[174:177], v[50:53]
	v_mfma_f32_16x16x32_bf16 v[46:49], v[198:201], v[160:163], v[46:49]
	v_mfma_f32_16x16x32_bf16 v[42:45], v[198:201], v[174:177], v[42:45]
	v_mfma_f32_16x16x32_bf16 v[38:41], v[206:209], v[160:163], v[38:41]
	v_mfma_f32_16x16x32_bf16 v[34:37], v[206:209], v[174:177], v[34:37]
	v_mfma_f32_16x16x32_bf16 v[62:65], v[186:189], v[164:167], v[62:65]
	v_mfma_f32_16x16x32_bf16 v[58:61], v[186:189], v[178:181], v[58:61]
	v_mfma_f32_16x16x32_bf16 v[54:57], v[194:197], v[164:167], v[54:57]
	v_mfma_f32_16x16x32_bf16 v[50:53], v[194:197], v[178:181], v[50:53]
	v_mfma_f32_16x16x32_bf16 v[46:49], v[202:205], v[164:167], v[46:49]
	v_mfma_f32_16x16x32_bf16 v[42:45], v[202:205], v[178:181], v[42:45]
	v_mfma_f32_16x16x32_bf16 v[38:41], v[210:213], v[164:167], v[38:41]
	v_mfma_f32_16x16x32_bf16 v[34:37], v[210:213], v[178:181], v[34:37]
	s_setprio 0
	s_barrier
	v_readfirstlane_b32 s23, v157
	v_lshl_add_u64 v[160:161], v[240:241], 0, s[10:11]
	s_mov_b32 m0, s23
	v_readfirstlane_b32 s23, v158
	global_load_lds_dwordx4 v[160:161], off
	v_lshl_add_u64 v[160:161], v[242:243], 0, s[10:11]
	s_mov_b32 m0, s23
	s_nop 0
	global_load_lds_dwordx4 v[160:161], off
	s_waitcnt vmcnt(8)
	s_barrier
	s_setprio 1
	v_mfma_f32_16x16x32_bf16 v[30:33], v[182:185], v[214:217], v[30:33]
	v_mfma_f32_16x16x32_bf16 v[26:29], v[182:185], v[222:225], v[26:29]
	v_mfma_f32_16x16x32_bf16 v[22:25], v[190:193], v[214:217], v[22:25]
	v_mfma_f32_16x16x32_bf16 v[18:21], v[190:193], v[222:225], v[18:21]
	v_mfma_f32_16x16x32_bf16 v[14:17], v[198:201], v[214:217], v[14:17]
	v_mfma_f32_16x16x32_bf16 v[10:13], v[198:201], v[222:225], v[10:13]
	v_mfma_f32_16x16x32_bf16 v[6:9], v[206:209], v[214:217], v[6:9]
	v_mfma_f32_16x16x32_bf16 v[2:5], v[206:209], v[222:225], v[2:5]
	v_mfma_f32_16x16x32_bf16 v[30:33], v[186:189], v[218:221], v[30:33]
	v_mfma_f32_16x16x32_bf16 v[26:29], v[186:189], v[226:229], v[26:29]
	v_mfma_f32_16x16x32_bf16 v[22:25], v[194:197], v[218:221], v[22:25]
	v_mfma_f32_16x16x32_bf16 v[18:21], v[194:197], v[226:229], v[18:21]
	v_mfma_f32_16x16x32_bf16 v[14:17], v[202:205], v[218:221], v[14:17]
	v_mfma_f32_16x16x32_bf16 v[10:13], v[202:205], v[226:229], v[10:13]
	v_mfma_f32_16x16x32_bf16 v[6:9], v[210:213], v[218:221], v[6:9]
	v_mfma_f32_16x16x32_bf16 v[2:5], v[210:213], v[226:229], v[2:5]
	s_setprio 0
	s_add_i32 s22, s22, 2
	s_cmp_lt_u32 s22, 40
	s_barrier
	s_cbranch_scc1 .LBB0_1105
	ds_read_b128 v[146:149], v144
	ds_read_b128 v[150:153], v144 offset:1024
	ds_read_b128 v[154:157], v144 offset:2048
	ds_read_b128 v[158:161], v144 offset:3072
	ds_read_b128 v[162:165], v138
	ds_read_b128 v[166:169], v138 offset:1024
	ds_read_b128 v[174:177], v137
	ds_read_b128 v[178:181], v137 offset:1024
	ds_read_b128 v[182:185], v136
	ds_read_b128 v[186:189], v136 offset:1024
	ds_read_b128 v[190:193], v135
	ds_read_b128 v[194:197], v135 offset:1024
	v_lshl_add_u64 v[144:145], s[12:13], 0, v[130:131]
	v_readfirstlane_b32 s16, v143
	v_lshl_add_u64 v[144:145], v[144:145], 0, s[6:7]
	s_mov_b32 m0, s16
	v_lshl_add_u64 v[132:133], s[12:13], 0, v[132:133]
	v_readfirstlane_b32 s12, v142
	global_load_lds_dwordx4 v[144:145], off
	v_lshl_add_u64 v[132:133], v[132:133], 0, s[6:7]
	s_mov_b32 m0, s12
	s_nop 0
	global_load_lds_dwordx4 v[132:133], off
	s_barrier
	s_waitcnt lgkmcnt(0)
	s_setprio 1
	s_waitcnt lgkmcnt(0)
	v_mfma_f32_16x16x32_bf16 v[126:129], v[162:165], v[146:149], v[126:129]
	v_mfma_f32_16x16x32_bf16 v[122:125], v[162:165], v[154:157], v[122:125]
	v_mfma_f32_16x16x32_bf16 v[110:113], v[182:185], v[146:149], v[110:113]
	v_mfma_f32_16x16x32_bf16 v[106:109], v[182:185], v[154:157], v[106:109]
	v_mfma_f32_16x16x32_bf16 v[126:129], v[166:169], v[150:153], v[126:129]
	v_mfma_f32_16x16x32_bf16 v[122:125], v[166:169], v[158:161], v[122:125]
	v_mfma_f32_16x16x32_bf16 v[118:121], v[174:177], v[146:149], v[118:121]
	v_mfma_f32_16x16x32_bf16 v[114:117], v[174:177], v[154:157], v[114:117]
	v_mfma_f32_16x16x32_bf16 v[110:113], v[186:189], v[150:153], v[110:113]
	v_mfma_f32_16x16x32_bf16 v[106:109], v[186:189], v[158:161], v[106:109]
	v_mfma_f32_16x16x32_bf16 v[102:105], v[190:193], v[146:149], v[102:105]
	v_mfma_f32_16x16x32_bf16 v[98:101], v[190:193], v[154:157], v[98:101]
	v_mfma_f32_16x16x32_bf16 v[142:145], v[178:181], v[150:153], v[118:121]
	v_mfma_f32_16x16x32_bf16 v[198:201], v[178:181], v[158:161], v[114:117]
	v_mfma_f32_16x16x32_bf16 v[202:205], v[194:197], v[150:153], v[102:105]
	v_mfma_f32_16x16x32_bf16 v[206:209], v[194:197], v[158:161], v[98:101]
	s_setprio 0
	s_barrier
	s_nop 1
	ds_read_b128 v[98:101], v141
	ds_read_b128 v[102:105], v141 offset:1024
	ds_read_b128 v[114:117], v141 offset:2048
	ds_read_b128 v[118:121], v141 offset:3072
	s_waitcnt vmcnt(8)
	s_barrier
; #define WAIT_V(n) asm volatile("s_waitcnt vmcnt(" #n ")" ::: "memory")
; #define WAIT_L(n) asm volatile("s_waitcnt lgkmcnt(" #n ")" ::: "memory")
; #define BAR __builtin_amdgcn_s_barrier()
; #define LDA(dst, b, h) for (int m = 0; m < 4; ++m) for (int k = 0; k < 2; ++k) \
;     dst[m][k] = *reinterpret_cast<const bf16x8*>((char*)SA(b, h) + lds_byte(wr * 64 + m * 16 + fr, k * 32 + fq * 8))
; #define LDB(dst, b, h) for (int n = 0; n < 2; ++n) for (int k = 0; k < 2; ++k) \
;     dst[n][k] = *reinterpret_cast<const bf16x8*>((char*)SB(b, h) + lds_byte(wc * 32 + n * 16 + fr, k * 32 + fq * 8))
; #define MMA(ai, bj, At_, Bt_) do { __builtin_amdgcn_s_setprio(1); \
;     for (int m = 0; m < 4; ++m) for (int n = 0; n < 2; ++n) for (int k = 0; k < 2; ++k) \
;       acc[ai][bj][m][n] = __builtin_amdgcn_mfma_f32_16x16x32_bf16(At_[m][k], Bt_[n][k], acc[ai][bj][m][n], 0, 0, 0); \
;     __builtin_amdgcn_s_setprio(0); } while (0)
; template <int K, int LD = K>
; __device__ __forceinline__ void gemm_main(const GAS bf16* A, const GAS bf16* Bt, int brow, int bcol, f32x4 (&acc)[2][2][4][2]) {
;     ...
;     LDB(B1, 0, 1); BAR; WAIT_L(0); MMA(0, 1, At, B1); BAR;
;     LDA(At, 0, 1); WAIT_V(4); BAR; WAIT_L(0); MMA(1, 0, At, B0); MMA(1, 1, At, B1); BAR; }
;   { LDB(B0, 1, 0); LDA(At, 1, 0); WAIT_V(2); BAR; WAIT_L(0); MMA(0, 0, At, B0); BAR;
	s_waitcnt lgkmcnt(0)
	s_setprio 1
	s_waitcnt lgkmcnt(0)
	v_mfma_f32_16x16x32_bf16 v[94:97], v[162:165], v[98:101], v[94:97]
	v_mfma_f32_16x16x32_bf16 v[90:93], v[162:165], v[114:117], v[90:93]
	v_mfma_f32_16x16x32_bf16 v[78:81], v[182:185], v[98:101], v[78:81]
	v_mfma_f32_16x16x32_bf16 v[74:77], v[182:185], v[114:117], v[74:77]
	v_mfma_f32_16x16x32_bf16 v[94:97], v[166:169], v[102:105], v[94:97]
	v_mfma_f32_16x16x32_bf16 v[90:93], v[166:169], v[118:121], v[90:93]
	v_mfma_f32_16x16x32_bf16 v[86:89], v[174:177], v[98:101], v[86:89]
	v_mfma_f32_16x16x32_bf16 v[82:85], v[174:177], v[114:117], v[82:85]
	v_mfma_f32_16x16x32_bf16 v[78:81], v[186:189], v[102:105], v[78:81]
	v_mfma_f32_16x16x32_bf16 v[74:77], v[186:189], v[118:121], v[74:77]
	v_mfma_f32_16x16x32_bf16 v[70:73], v[190:193], v[98:101], v[70:73]
	v_mfma_f32_16x16x32_bf16 v[66:69], v[190:193], v[114:117], v[66:69]
	v_mfma_f32_16x16x32_bf16 v[162:165], v[178:181], v[102:105], v[86:89]
	v_mfma_f32_16x16x32_bf16 v[166:169], v[178:181], v[118:121], v[82:85]
	v_mfma_f32_16x16x32_bf16 v[174:177], v[194:197], v[102:105], v[70:73]
	v_mfma_f32_16x16x32_bf16 v[178:181], v[194:197], v[118:121], v[66:69]
	s_setprio 0
	s_barrier
	s_nop 1
	ds_read_b128 v[66:69], v138 offset:16384
	ds_read_b128 v[70:73], v138 offset:17408
	ds_read_b128 v[82:85], v137 offset:16384
	ds_read_b128 v[86:89], v137 offset:17408
	ds_read_b128 v[182:185], v136 offset:16384
	ds_read_b128 v[186:189], v136 offset:17408
	ds_read_b128 v[190:193], v135 offset:16384
	ds_read_b128 v[194:197], v135 offset:17408
	s_waitcnt vmcnt(4)
	s_barrier
	s_waitcnt lgkmcnt(0)
	s_setprio 1
	s_waitcnt lgkmcnt(0)
	v_mfma_f32_16x16x32_bf16 v[62:65], v[66:69], v[146:149], v[62:65]
	v_mfma_f32_16x16x32_bf16 v[58:61], v[66:69], v[154:157], v[58:61]
	v_mfma_f32_16x16x32_bf16 v[46:49], v[182:185], v[146:149], v[46:49]
	v_mfma_f32_16x16x32_bf16 v[42:45], v[182:185], v[154:157], v[42:45]
	v_mfma_f32_16x16x32_bf16 v[62:65], v[70:73], v[150:153], v[62:65]
	v_mfma_f32_16x16x32_bf16 v[58:61], v[70:73], v[158:161], v[58:61]
	v_mfma_f32_16x16x32_bf16 v[54:57], v[82:85], v[146:149], v[54:57]
	v_mfma_f32_16x16x32_bf16 v[50:53], v[82:85], v[154:157], v[50:53]
	v_mfma_f32_16x16x32_bf16 v[46:49], v[186:189], v[150:153], v[46:49]
	v_mfma_f32_16x16x32_bf16 v[42:45], v[186:189], v[158:161], v[42:45]
	v_mfma_f32_16x16x32_bf16 v[38:41], v[190:193], v[146:149], v[38:41]
	v_mfma_f32_16x16x32_bf16 v[34:37], v[190:193], v[154:157], v[34:37]
	v_mfma_f32_16x16x32_bf16 v[210:213], v[86:89], v[150:153], v[54:57]
	v_mfma_f32_16x16x32_bf16 v[214:217], v[86:89], v[158:161], v[50:53]
	v_mfma_f32_16x16x32_bf16 v[146:149], v[194:197], v[150:153], v[38:41]
	v_mfma_f32_16x16x32_bf16 v[150:153], v[194:197], v[158:161], v[34:37]
	s_setprio 0
	s_setprio 1
	v_mfma_f32_16x16x32_bf16 v[30:33], v[66:69], v[98:101], v[30:33]
	v_mfma_f32_16x16x32_bf16 v[26:29], v[66:69], v[114:117], v[26:29]
	v_mfma_f32_16x16x32_bf16 v[14:17], v[182:185], v[98:101], v[14:17]
	v_mfma_f32_16x16x32_bf16 v[10:13], v[182:185], v[114:117], v[10:13]
	v_mfma_f32_16x16x32_bf16 v[30:33], v[70:73], v[102:105], v[30:33]
	v_mfma_f32_16x16x32_bf16 v[26:29], v[70:73], v[118:121], v[26:29]
	v_mfma_f32_16x16x32_bf16 v[22:25], v[82:85], v[98:101], v[22:25]
	v_mfma_f32_16x16x32_bf16 v[18:21], v[82:85], v[114:117], v[18:21]
	v_mfma_f32_16x16x32_bf16 v[14:17], v[186:189], v[102:105], v[14:17]
	v_mfma_f32_16x16x32_bf16 v[10:13], v[186:189], v[118:121], v[10:13]
	v_mfma_f32_16x16x32_bf16 v[6:9], v[190:193], v[98:101], v[6:9]
	v_mfma_f32_16x16x32_bf16 v[2:5], v[190:193], v[114:117], v[2:5]
	v_mfma_f32_16x16x32_bf16 v[154:157], v[86:89], v[102:105], v[22:25]
	v_mfma_f32_16x16x32_bf16 v[158:161], v[86:89], v[118:121], v[18:21]
	v_mfma_f32_16x16x32_bf16 v[182:185], v[194:197], v[102:105], v[6:9]
	v_mfma_f32_16x16x32_bf16 v[186:189], v[194:197], v[118:121], v[2:5]
	s_setprio 0
	s_barrier
	s_nop 1
	ds_read_b128 v[2:5], v140
	ds_read_b128 v[6:9], v140 offset:1024
	ds_read_b128 v[190:193], v140 offset:2048
	ds_read_b128 v[194:197], v140 offset:3072
	ds_read_b128 v[18:21], v138 offset:32768
	ds_read_b128 v[22:25], v138 offset:33792
	ds_read_b128 v[34:37], v137 offset:32768
	ds_read_b128 v[38:41], v137 offset:33792
	ds_read_b128 v[50:53], v136 offset:32768
	ds_read_b128 v[54:57], v136 offset:33792
	ds_read_b128 v[218:221], v135 offset:32768
	ds_read_b128 v[222:225], v135 offset:33792
	s_waitcnt vmcnt(2)
	s_barrier
; #define WAIT_V(n) asm volatile("s_waitcnt vmcnt(" #n ")" ::: "memory")
; #define WAIT_L(n) asm volatile("s_waitcnt lgkmcnt(" #n ")" ::: "memory")
; #define BAR __builtin_amdgcn_s_barrier()
; #define LDA(dst, b, h) for (int m = 0; m < 4; ++m) for (int k = 0; k < 2; ++k) \
;     dst[m][k] = *reinterpret_cast<const bf16x8*>((char*)SA(b, h) + lds_byte(wr * 64 + m * 16 + fr, k * 32 + fq * 8))
; #define LDB(dst, b, h) for (int n = 0; n < 2; ++n) for (int k = 0; k < 2; ++k) \
;     dst[n][k] = *reinterpret_cast<const bf16x8*>((char*)SB(b, h) + lds_byte(wc * 32 + n * 16 + fr, k * 32 + fq * 8))
; #define MMA(ai, bj, At_, Bt_) do { __builtin_amdgcn_s_setprio(1); \
;     for (int m = 0; m < 4; ++m) for (int n = 0; n < 2; ++n) for (int k = 0; k < 2; ++k) \
;       acc[ai][bj][m][n] = __builtin_amdgcn_mfma_f32_16x16x32_bf16(At_[m][k], Bt_[n][k], acc[ai][bj][m][n], 0, 0, 0); \
;     __builtin_amdgcn_s_setprio(0); } while (0)
; template <int K, int LD = K>
; __device__ __forceinline__ void gemm_main(const GAS bf16* A, const GAS bf16* Bt, int brow, int bcol, f32x4 (&acc)[2][2][4][2]) {
;     ...
;   { LDB(B0, 1, 0); LDA(At, 1, 0); WAIT_V(2); BAR; WAIT_L(0); MMA(0, 0, At, B0); BAR;
;     LDB(B1, 1, 1); WAIT_V(0); BAR; WAIT_L(0); MMA(0, 1, At, B1); BAR;
;     LDA(At, 1, 1); BAR; WAIT_L(0); MMA(1, 0, At, B0); MMA(1, 1, At, B1); BAR; }
;   if (wr == 0) BAR;
	s_waitcnt lgkmcnt(0)
	s_setprio 1
	s_waitcnt lgkmcnt(0)
	v_mfma_f32_16x16x32_bf16 v[66:69], v[18:21], v[2:5], v[126:129]
	v_mfma_f32_16x16x32_bf16 v[118:121], v[22:25], v[6:9], v[66:69]
	v_mfma_f32_16x16x32_bf16 v[66:69], v[18:21], v[190:193], v[122:125]
	v_mfma_f32_16x16x32_bf16 v[114:117], v[22:25], v[194:197], v[66:69]
	v_mfma_f32_16x16x32_bf16 v[66:69], v[34:37], v[2:5], v[142:145]
	v_mfma_f32_16x16x32_bf16 v[102:105], v[38:41], v[6:9], v[66:69]
	v_mfma_f32_16x16x32_bf16 v[66:69], v[34:37], v[190:193], v[198:201]
	v_mfma_f32_16x16x32_bf16 v[98:101], v[38:41], v[194:197], v[66:69]
	v_mfma_f32_16x16x32_bf16 v[66:69], v[50:53], v[2:5], v[110:113]
	v_mfma_f32_16x16x32_bf16 v[86:89], v[54:57], v[6:9], v[66:69]
	v_mfma_f32_16x16x32_bf16 v[66:69], v[50:53], v[190:193], v[106:109]
	v_mfma_f32_16x16x32_bf16 v[82:85], v[54:57], v[194:197], v[66:69]
	v_mfma_f32_16x16x32_bf16 v[66:69], v[218:221], v[2:5], v[202:205]
	v_mfma_f32_16x16x32_bf16 v[70:73], v[222:225], v[6:9], v[66:69]
	v_mfma_f32_16x16x32_bf16 v[66:69], v[218:221], v[190:193], v[206:209]
	v_mfma_f32_16x16x32_bf16 v[66:69], v[222:225], v[194:197], v[66:69]
	s_setprio 0
	s_barrier
	ds_read_b128 v[140:143], v139
	ds_read_b128 v[198:201], v139 offset:1024
	ds_read_b128 v[202:205], v139 offset:2048
	ds_read_b128 v[206:209], v139 offset:3072
	s_waitcnt vmcnt(0)
	s_barrier
	s_waitcnt lgkmcnt(0)
	s_setprio 1
	s_waitcnt lgkmcnt(0)
	v_mfma_f32_16x16x32_bf16 v[94:97], v[18:21], v[140:143], v[94:97]
	v_mfma_f32_16x16x32_bf16 v[18:21], v[18:21], v[202:205], v[90:93]
	v_mfma_f32_16x16x32_bf16 v[122:125], v[22:25], v[206:209], v[18:21]
	v_mfma_f32_16x16x32_bf16 v[18:21], v[34:37], v[140:143], v[162:165]
	v_mfma_f32_16x16x32_bf16 v[110:113], v[38:41], v[198:201], v[18:21]
	v_mfma_f32_16x16x32_bf16 v[18:21], v[34:37], v[202:205], v[166:169]
	v_mfma_f32_16x16x32_bf16 v[106:109], v[38:41], v[206:209], v[18:21]
	v_mfma_f32_16x16x32_bf16 v[18:21], v[50:53], v[140:143], v[78:81]
	v_mfma_f32_16x16x32_bf16 v[126:129], v[22:25], v[198:201], v[94:97]
	v_mfma_f32_16x16x32_bf16 v[94:97], v[54:57], v[198:201], v[18:21]
	v_mfma_f32_16x16x32_bf16 v[18:21], v[50:53], v[202:205], v[74:77]
	v_mfma_f32_16x16x32_bf16 v[90:93], v[54:57], v[206:209], v[18:21]
	v_mfma_f32_16x16x32_bf16 v[18:21], v[218:221], v[140:143], v[174:177]
	v_mfma_f32_16x16x32_bf16 v[78:81], v[222:225], v[198:201], v[18:21]
	v_mfma_f32_16x16x32_bf16 v[18:21], v[218:221], v[202:205], v[178:181]
	v_mfma_f32_16x16x32_bf16 v[74:77], v[222:225], v[206:209], v[18:21]
	s_setprio 0
	s_barrier
	ds_read_b128 v[162:165], v138 offset:49152
	ds_read_b128 v[166:169], v138 offset:50176
	ds_read_b128 v[174:177], v137 offset:49152
	ds_read_b128 v[178:181], v137 offset:50176
	ds_read_b128 v[218:221], v136 offset:49152
	ds_read_b128 v[136:139], v136 offset:50176
	ds_read_b128 v[222:225], v135 offset:49152
	ds_read_b128 v[226:229], v135 offset:50176
	s_barrier
	s_waitcnt lgkmcnt(0)
	s_setprio 1
	s_waitcnt lgkmcnt(0)
	v_mfma_f32_16x16x32_bf16 v[18:21], v[162:165], v[2:5], v[62:65]
	v_mfma_f32_16x16x32_bf16 v[54:57], v[166:169], v[6:9], v[18:21]
	v_mfma_f32_16x16x32_bf16 v[18:21], v[162:165], v[190:193], v[58:61]
	v_mfma_f32_16x16x32_bf16 v[50:53], v[166:169], v[194:197], v[18:21]
	v_mfma_f32_16x16x32_bf16 v[18:21], v[174:177], v[2:5], v[210:213]
	v_mfma_f32_16x16x32_bf16 v[38:41], v[178:181], v[6:9], v[18:21]
	v_mfma_f32_16x16x32_bf16 v[18:21], v[174:177], v[190:193], v[214:217]
	v_mfma_f32_16x16x32_bf16 v[34:37], v[178:181], v[194:197], v[18:21]
	v_mfma_f32_16x16x32_bf16 v[18:21], v[218:221], v[2:5], v[46:49]
	v_mfma_f32_16x16x32_bf16 v[2:5], v[222:225], v[2:5], v[146:149]
	v_mfma_f32_16x16x32_bf16 v[22:25], v[136:139], v[6:9], v[18:21]
	v_mfma_f32_16x16x32_bf16 v[18:21], v[218:221], v[190:193], v[42:45]
	v_mfma_f32_16x16x32_bf16 v[6:9], v[226:229], v[6:9], v[2:5]
	v_mfma_f32_16x16x32_bf16 v[2:5], v[222:225], v[190:193], v[150:153]
	v_mfma_f32_16x16x32_bf16 v[18:21], v[136:139], v[194:197], v[18:21]
	v_mfma_f32_16x16x32_bf16 v[2:5], v[226:229], v[194:197], v[2:5]
	s_setprio 0
	s_setprio 1
	v_mfma_f32_16x16x32_bf16 v[26:29], v[162:165], v[202:205], v[26:29]
	v_mfma_f32_16x16x32_bf16 v[58:61], v[166:169], v[206:209], v[26:29]
	v_mfma_f32_16x16x32_bf16 v[26:29], v[174:177], v[140:143], v[154:157]
	v_mfma_f32_16x16x32_bf16 v[46:49], v[178:181], v[198:201], v[26:29]
	v_mfma_f32_16x16x32_bf16 v[26:29], v[174:177], v[202:205], v[158:161]
	v_mfma_f32_16x16x32_bf16 v[10:13], v[218:221], v[202:205], v[10:13]
	v_mfma_f32_16x16x32_bf16 v[30:33], v[162:165], v[140:143], v[30:33]
	v_mfma_f32_16x16x32_bf16 v[42:45], v[178:181], v[206:209], v[26:29]
	v_mfma_f32_16x16x32_bf16 v[14:17], v[218:221], v[140:143], v[14:17]
	v_mfma_f32_16x16x32_bf16 v[26:29], v[136:139], v[206:209], v[10:13]
	v_mfma_f32_16x16x32_bf16 v[10:13], v[222:225], v[140:143], v[182:185]
	v_mfma_f32_16x16x32_bf16 v[62:65], v[166:169], v[198:201], v[30:33]
	v_mfma_f32_16x16x32_bf16 v[30:33], v[136:139], v[198:201], v[14:17]
	v_mfma_f32_16x16x32_bf16 v[14:17], v[226:229], v[198:201], v[10:13]
	v_mfma_f32_16x16x32_bf16 v[10:13], v[222:225], v[202:205], v[186:189]
	v_mfma_f32_16x16x32_bf16 v[10:13], v[226:229], v[206:209], v[10:13]
	s_setprio 0
	v_cmp_gt_u32_e32 vcc, s33, v134
	s_barrier
	s_and_saveexec_b64 s[12:13], vcc
	s_cbranch_execz .LBB0_1108
	s_barrier

; #define STAGE(P, GP, ktrel) do { const GAS char* _g = (GP) + (ktrel) * (BK * 2); \
;     __builtin_amdgcn_global_load_lds((const GAS unsigned*)(_g + so0), (unsigned*)((char*)(P) + tid_ * 16), 16, 0, 0); \
;     __builtin_amdgcn_global_load_lds((const GAS unsigned*)(_g + so1), (unsigned*)((char*)(P) + tid_ * 16 + 8192), 16, 0, 0); } while (0)
; #define WAIT_V(n) asm volatile("s_waitcnt vmcnt(" #n ")" ::: "memory")
; #define WAIT_L(n) asm volatile("s_waitcnt lgkmcnt(" #n ")" ::: "memory")
; #define BAR __builtin_amdgcn_s_barrier()
; #define SCHED __builtin_amdgcn_sched_barrier(0)
; #define LDA(dst, b, h) for (int m = 0; m < 4; ++m) for (int k = 0; k < 2; ++k) \
;     dst[m][k] = *reinterpret_cast<const bf16x8*>((char*)SA(b, h) + lds_byte(wr * 64 + m * 16 + fr, k * 32 + fq * 8))
; #define LDB(dst, b, h) for (int n = 0; n < 2; ++n) for (int k = 0; k < 2; ++k) \
;     dst[n][k] = *reinterpret_cast<const bf16x8*>((char*)SB(b, h) + lds_byte(wc * 32 + n * 16 + fr, k * 32 + fq * 8))
; #define MMA(ai, bj, At_, Bt_) do { __builtin_amdgcn_s_setprio(1); \
;     for (int m = 0; m < 4; ++m) for (int n = 0; n < 2; ++n) for (int k = 0; k < 2; ++k) \
;       acc[ai][bj][m][n] = __builtin_amdgcn_mfma_f32_16x16x32_bf16(At_[m][k], Bt_[n][k], acc[ai][bj][m][n], 0, 0, 0); \
;     __builtin_amdgcn_s_setprio(0); } while (0)
; template <int K, int LD = K>
; __device__ __forceinline__ void gemm_main(const GAS bf16* A, const GAS bf16* Bt, int brow, int bcol, f32x4 (&acc)[2][2][4][2]) {
;     ...
;   for (int t = 0; t < nt - 2; t += 2) {
;     LDB(B0, 0, 0); SCHED; LDA(At, 0, 0); STAGE(SA(1, 1), pA1, 1);
;     WAIT_L(8); BAR; WAIT_L(0); MMA(0, 0, At, B0); BAR; SCHED;
;     LDB(B1, 0, 1); STAGE(SB(0, 0), pB0, 2);
;     BAR; WAIT_L(0); MMA(0, 1, At, B1); BAR;
;     LDA(At, 0, 1); STAGE(SA(0, 0), pA0, 2);
;     BAR; WAIT_L(0); MMA(1, 0, At, B0); BAR; SCHED;
;     STAGE(SB(0, 1), pB1, 2);
;     WAIT_V(6); BAR; MMA(1, 1, At, B1); BAR;
;     LDB(B0, 1, 0); SCHED; LDA(At, 1, 0); STAGE(SA(0, 1), pA1, 2);
.LBB0_1226:
	ds_read_b128 v[146:149], v143
	ds_read_b128 v[150:153], v143 offset:1024
	ds_read_b128 v[156:159], v143 offset:2048
	ds_read_b128 v[160:163], v143 offset:3072
	v_add_u32_e32 v155, 0x100, v141
	v_add_u32_e32 v144, 0xc000, v155
	v_lshl_add_u64 v[168:169], s[18:19], 0, v[138:139]
	v_readfirstlane_b32 s30, v144
	v_add_u32_e32 v145, 0xe000, v155
	v_lshl_add_u64 v[202:203], v[168:169], 0, s[8:9]
	s_mov_b32 m0, s30
	v_lshl_add_u64 v[218:219], s[18:19], 0, v[130:131]
	v_readfirstlane_b32 s30, v145
	ds_read_b128 v[164:167], v136
	ds_read_b128 v[174:177], v136 offset:1024
	ds_read_b128 v[178:181], v135
	ds_read_b128 v[182:185], v135 offset:1024
	ds_read_b128 v[186:189], v134
	ds_read_b128 v[190:193], v134 offset:1024
	ds_read_b128 v[194:197], v133
	ds_read_b128 v[198:201], v133 offset:1024
	global_load_lds_dwordx4 v[202:203], off
	v_lshl_add_u64 v[202:203], v[218:219], 0, s[8:9]
	s_mov_b32 m0, s30
	s_nop 0
	global_load_lds_dwordx4 v[202:203], off
	s_waitcnt lgkmcnt(8)
	s_barrier
	s_waitcnt lgkmcnt(0)
	s_setprio 1
	s_waitcnt lgkmcnt(0)
	v_mfma_f32_16x16x32_bf16 v[126:129], v[164:167], v[146:149], v[126:129]
	v_mfma_f32_16x16x32_bf16 v[122:125], v[164:167], v[156:159], v[122:125]
	v_mfma_f32_16x16x32_bf16 v[118:121], v[178:181], v[146:149], v[118:121]
	v_mfma_f32_16x16x32_bf16 v[114:117], v[178:181], v[156:159], v[114:117]
	v_mfma_f32_16x16x32_bf16 v[110:113], v[186:189], v[146:149], v[110:113]
	v_mfma_f32_16x16x32_bf16 v[106:109], v[186:189], v[156:159], v[106:109]
	v_mfma_f32_16x16x32_bf16 v[102:105], v[194:197], v[146:149], v[102:105]
	v_mfma_f32_16x16x32_bf16 v[98:101], v[194:197], v[156:159], v[98:101]
	v_mfma_f32_16x16x32_bf16 v[126:129], v[174:177], v[150:153], v[126:129]
	v_mfma_f32_16x16x32_bf16 v[122:125], v[174:177], v[160:163], v[122:125]
	v_mfma_f32_16x16x32_bf16 v[118:121], v[182:185], v[150:153], v[118:121]
	v_mfma_f32_16x16x32_bf16 v[114:117], v[182:185], v[160:163], v[114:117]
	v_mfma_f32_16x16x32_bf16 v[110:113], v[190:193], v[150:153], v[110:113]
	v_mfma_f32_16x16x32_bf16 v[106:109], v[190:193], v[160:163], v[106:109]
	v_mfma_f32_16x16x32_bf16 v[102:105], v[198:201], v[150:153], v[102:105]
	v_mfma_f32_16x16x32_bf16 v[98:101], v[198:201], v[160:163], v[98:101]
	s_setprio 0
	s_barrier
	v_add_u32_e32 v226, s38, v141
	v_lshl_add_u64 v[220:221], s[28:29], 0, v[138:139]
	v_readfirstlane_b32 s30, v226
	v_lshl_add_u64 v[222:223], v[220:221], 0, s[14:15]
	s_mov_b32 m0, s30
	v_add_u32_e32 v226, 0x2000, v226
	ds_read_b128 v[202:205], v142
	ds_read_b128 v[206:209], v142 offset:1024
	ds_read_b128 v[210:213], v142 offset:2048
	ds_read_b128 v[214:217], v142 offset:3072
	global_load_lds_dwordx4 v[222:223], off
	v_lshl_add_u64 v[222:223], s[28:29], 0, v[130:131]
	v_readfirstlane_b32 s30, v226
	v_lshl_add_u64 v[224:225], v[222:223], 0, s[14:15]
	s_mov_b32 m0, s30
	s_add_u32 s28, s28, 0x100
	global_load_lds_dwordx4 v[224:225], off
	s_waitcnt vmcnt(10)
	s_barrier
	s_waitcnt lgkmcnt(0)
	s_addc_u32 s29, s29, 0
	s_setprio 1
	s_waitcnt lgkmcnt(0)
	v_mfma_f32_16x16x32_bf16 v[94:97], v[164:167], v[202:205], v[94:97]
	v_mfma_f32_16x16x32_bf16 v[90:93], v[164:167], v[210:213], v[90:93]
	v_mfma_f32_16x16x32_bf16 v[86:89], v[178:181], v[202:205], v[86:89]
	v_mfma_f32_16x16x32_bf16 v[82:85], v[178:181], v[210:213], v[82:85]
	v_mfma_f32_16x16x32_bf16 v[78:81], v[186:189], v[202:205], v[78:81]
	v_mfma_f32_16x16x32_bf16 v[74:77], v[186:189], v[210:213], v[74:77]
	v_mfma_f32_16x16x32_bf16 v[70:73], v[194:197], v[202:205], v[70:73]
	v_mfma_f32_16x16x32_bf16 v[66:69], v[194:197], v[210:213], v[66:69]
	v_mfma_f32_16x16x32_bf16 v[94:97], v[174:177], v[206:209], v[94:97]
	v_mfma_f32_16x16x32_bf16 v[90:93], v[174:177], v[214:217], v[90:93]
	v_mfma_f32_16x16x32_bf16 v[86:89], v[182:185], v[206:209], v[86:89]
	v_mfma_f32_16x16x32_bf16 v[82:85], v[182:185], v[214:217], v[82:85]
	v_mfma_f32_16x16x32_bf16 v[78:81], v[190:193], v[206:209], v[78:81]
	v_mfma_f32_16x16x32_bf16 v[74:77], v[190:193], v[214:217], v[74:77]
	v_mfma_f32_16x16x32_bf16 v[70:73], v[198:201], v[206:209], v[70:73]
	v_mfma_f32_16x16x32_bf16 v[66:69], v[198:201], v[214:217], v[66:69]
	s_setprio 0
	v_lshl_add_u64 v[224:225], s[26:27], 0, v[138:139]
	v_readfirstlane_b32 s30, v155
	v_lshl_add_u64 v[226:227], v[224:225], 0, s[14:15]
	s_mov_b32 m0, s30
	v_add_u32_e32 v230, 0x2000, v155
	s_barrier
	ds_read_b128 v[164:167], v136 offset:16384
	ds_read_b128 v[174:177], v136 offset:17408
	ds_read_b128 v[178:181], v135 offset:16384
	ds_read_b128 v[182:185], v135 offset:17408
	ds_read_b128 v[186:189], v134 offset:16384
	ds_read_b128 v[190:193], v134 offset:17408
	ds_read_b128 v[194:197], v133 offset:16384
	ds_read_b128 v[198:201], v133 offset:17408
	global_load_lds_dwordx4 v[226:227], off
	v_lshl_add_u64 v[226:227], s[26:27], 0, v[130:131]
	v_readfirstlane_b32 s30, v230
	v_lshl_add_u64 v[228:229], v[226:227], 0, s[14:15]
	s_mov_b32 m0, s30
	s_add_u32 s26, s26, 0x100
	global_load_lds_dwordx4 v[228:229], off
	s_barrier
	s_waitcnt lgkmcnt(0)
	s_addc_u32 s27, s27, 0
	s_setprio 1
	s_waitcnt lgkmcnt(0)
	v_mfma_f32_16x16x32_bf16 v[62:65], v[164:167], v[146:149], v[62:65]
	v_mfma_f32_16x16x32_bf16 v[58:61], v[164:167], v[156:159], v[58:61]
	v_mfma_f32_16x16x32_bf16 v[54:57], v[178:181], v[146:149], v[54:57]
	v_mfma_f32_16x16x32_bf16 v[50:53], v[178:181], v[156:159], v[50:53]
	v_mfma_f32_16x16x32_bf16 v[46:49], v[186:189], v[146:149], v[46:49]
	v_mfma_f32_16x16x32_bf16 v[42:45], v[186:189], v[156:159], v[42:45]
	v_mfma_f32_16x16x32_bf16 v[38:41], v[194:197], v[146:149], v[38:41]
	v_mfma_f32_16x16x32_bf16 v[34:37], v[194:197], v[156:159], v[34:37]
	v_mfma_f32_16x16x32_bf16 v[62:65], v[174:177], v[150:153], v[62:65]
	v_mfma_f32_16x16x32_bf16 v[58:61], v[174:177], v[160:163], v[58:61]
	v_mfma_f32_16x16x32_bf16 v[54:57], v[182:185], v[150:153], v[54:57]
	v_mfma_f32_16x16x32_bf16 v[50:53], v[182:185], v[160:163], v[50:53]
	v_mfma_f32_16x16x32_bf16 v[46:49], v[190:193], v[150:153], v[46:49]
	v_mfma_f32_16x16x32_bf16 v[42:45], v[190:193], v[160:163], v[42:45]
	v_mfma_f32_16x16x32_bf16 v[38:41], v[198:201], v[150:153], v[38:41]
	v_mfma_f32_16x16x32_bf16 v[34:37], v[198:201], v[160:163], v[34:37]
	s_setprio 0
	s_barrier
; #define STAGE(P, GP, ktrel) do { const GAS char* _g = (GP) + (ktrel) * (BK * 2); \
;     __builtin_amdgcn_global_load_lds((const GAS unsigned*)(_g + so0), (unsigned*)((char*)(P) + tid_ * 16), 16, 0, 0); \
;     __builtin_amdgcn_global_load_lds((const GAS unsigned*)(_g + so1), (unsigned*)((char*)(P) + tid_ * 16 + 8192), 16, 0, 0); } while (0)
; #define WAIT_V(n) asm volatile("s_waitcnt vmcnt(" #n ")" ::: "memory")
; #define WAIT_L(n) asm volatile("s_waitcnt lgkmcnt(" #n ")" ::: "memory")
; #define BAR __builtin_amdgcn_s_barrier()
; #define SCHED __builtin_amdgcn_sched_barrier(0)
; #define LDA(dst, b, h) for (int m = 0; m < 4; ++m) for (int k = 0; k < 2; ++k) \
;     dst[m][k] = *reinterpret_cast<const bf16x8*>((char*)SA(b, h) + lds_byte(wr * 64 + m * 16 + fr, k * 32 + fq * 8))
; #define LDB(dst, b, h) for (int n = 0; n < 2; ++n) for (int k = 0; k < 2; ++k) \
;     dst[n][k] = *reinterpret_cast<const bf16x8*>((char*)SB(b, h) + lds_byte(wc * 32 + n * 16 + fr, k * 32 + fq * 8))
; #define MMA(ai, bj, At_, Bt_) do { __builtin_amdgcn_s_setprio(1); \
;     for (int m = 0; m < 4; ++m) for (int n = 0; n < 2; ++n) for (int k = 0; k < 2; ++k) \
;       acc[ai][bj][m][n] = __builtin_amdgcn_mfma_f32_16x16x32_bf16(At_[m][k], Bt_[n][k], acc[ai][bj][m][n], 0, 0, 0); \
;     __builtin_amdgcn_s_setprio(0); } while (0)
; template <int K, int LD = K>
; __device__ __forceinline__ void gemm_main(const GAS bf16* A, const GAS bf16* Bt, int brow, int bcol, f32x4 (&acc)[2][2][4][2]) {
;     ...
;     WAIT_V(6); BAR; MMA(1, 1, At, B1); BAR;
;     LDB(B0, 1, 0); SCHED; LDA(At, 1, 0); STAGE(SA(0, 1), pA1, 2);
;     WAIT_L(8); BAR; WAIT_L(0); MMA(0, 0, At, B0); BAR; SCHED;
;     LDB(B1, 1, 1); STAGE(SB(1, 0), pB0, 3);
;     BAR; WAIT_L(0); MMA(0, 1, At, B1); BAR;
;     LDA(At, 1, 1); STAGE(SA(1, 0), pA0, 3);
;     BAR; WAIT_L(0); MMA(1, 0, At, B0); BAR; SCHED;
	v_add_u32_e32 v148, s39, v141
	v_lshl_add_u64 v[228:229], s[24:25], 0, v[138:139]
	v_readfirstlane_b32 s30, v148
	v_add_u32_e32 v148, 0x2000, v148
	v_lshl_add_u64 v[146:147], v[228:229], 0, s[14:15]
	s_mov_b32 m0, s30
	v_lshl_add_u64 v[230:231], s[24:25], 0, v[130:131]
	v_readfirstlane_b32 s30, v148
	global_load_lds_dwordx4 v[146:147], off
	v_lshl_add_u64 v[146:147], v[230:231], 0, s[14:15]
	s_mov_b32 m0, s30
	s_add_u32 s24, s24, 0x100
	global_load_lds_dwordx4 v[146:147], off
	s_waitcnt vmcnt(8)
	s_addc_u32 s25, s25, 0
	s_barrier
	s_setprio 1
	v_mfma_f32_16x16x32_bf16 v[30:33], v[164:167], v[202:205], v[30:33]
	v_mfma_f32_16x16x32_bf16 v[26:29], v[164:167], v[210:213], v[26:29]
	v_mfma_f32_16x16x32_bf16 v[22:25], v[178:181], v[202:205], v[22:25]
	v_mfma_f32_16x16x32_bf16 v[18:21], v[178:181], v[210:213], v[18:21]
	v_mfma_f32_16x16x32_bf16 v[14:17], v[186:189], v[202:205], v[14:17]
	v_mfma_f32_16x16x32_bf16 v[10:13], v[186:189], v[210:213], v[10:13]
	v_mfma_f32_16x16x32_bf16 v[6:9], v[194:197], v[202:205], v[6:9]
	v_mfma_f32_16x16x32_bf16 v[2:5], v[194:197], v[210:213], v[2:5]
	v_mfma_f32_16x16x32_bf16 v[30:33], v[174:177], v[206:209], v[30:33]
	v_mfma_f32_16x16x32_bf16 v[26:29], v[174:177], v[214:217], v[26:29]
	v_mfma_f32_16x16x32_bf16 v[22:25], v[182:185], v[206:209], v[22:25]
	v_mfma_f32_16x16x32_bf16 v[18:21], v[182:185], v[214:217], v[18:21]
	v_mfma_f32_16x16x32_bf16 v[14:17], v[190:193], v[206:209], v[14:17]
	v_mfma_f32_16x16x32_bf16 v[10:13], v[190:193], v[214:217], v[10:13]
	v_mfma_f32_16x16x32_bf16 v[6:9], v[198:201], v[206:209], v[6:9]
	v_mfma_f32_16x16x32_bf16 v[2:5], v[198:201], v[214:217], v[2:5]
	s_setprio 0
	s_barrier
	ds_read_b128 v[146:149], v140
	ds_read_b128 v[150:153], v140 offset:1024
	ds_read_b128 v[156:159], v140 offset:2048
	ds_read_b128 v[160:163], v140 offset:3072
	v_add_u32_e32 v202, 0x4000, v155
	v_lshl_add_u64 v[168:169], v[168:169], 0, s[14:15]
	v_readfirstlane_b32 s30, v202
	v_add_u32_e32 v202, 0x6000, v155
	s_mov_b32 m0, s30
	v_readfirstlane_b32 s30, v202
	ds_read_b128 v[164:167], v136 offset:32768
	ds_read_b128 v[174:177], v136 offset:33792
	ds_read_b128 v[178:181], v135 offset:32768
	ds_read_b128 v[182:185], v135 offset:33792
	ds_read_b128 v[186:189], v134 offset:32768
	ds_read_b128 v[190:193], v134 offset:33792
	ds_read_b128 v[194:197], v133 offset:32768
	ds_read_b128 v[198:201], v133 offset:33792
	global_load_lds_dwordx4 v[168:169], off
	v_lshl_add_u64 v[168:169], v[218:219], 0, s[14:15]
	s_mov_b32 m0, s30
	s_add_u32 s18, s18, 0x100
	global_load_lds_dwordx4 v[168:169], off
	s_waitcnt lgkmcnt(8)
	s_barrier
	s_waitcnt lgkmcnt(0)
	s_addc_u32 s19, s19, 0
	s_setprio 1
	s_waitcnt lgkmcnt(0)
	v_mfma_f32_16x16x32_bf16 v[126:129], v[164:167], v[146:149], v[126:129]
	v_mfma_f32_16x16x32_bf16 v[122:125], v[164:167], v[156:159], v[122:125]
	v_mfma_f32_16x16x32_bf16 v[118:121], v[178:181], v[146:149], v[118:121]
	v_mfma_f32_16x16x32_bf16 v[114:117], v[178:181], v[156:159], v[114:117]
	v_mfma_f32_16x16x32_bf16 v[110:113], v[186:189], v[146:149], v[110:113]
	v_mfma_f32_16x16x32_bf16 v[106:109], v[186:189], v[156:159], v[106:109]
	v_mfma_f32_16x16x32_bf16 v[102:105], v[194:197], v[146:149], v[102:105]
	v_mfma_f32_16x16x32_bf16 v[98:101], v[194:197], v[156:159], v[98:101]
	v_mfma_f32_16x16x32_bf16 v[126:129], v[174:177], v[150:153], v[126:129]
	v_mfma_f32_16x16x32_bf16 v[122:125], v[174:177], v[160:163], v[122:125]
	v_mfma_f32_16x16x32_bf16 v[118:121], v[182:185], v[150:153], v[118:121]
	v_mfma_f32_16x16x32_bf16 v[114:117], v[182:185], v[160:163], v[114:117]
	v_mfma_f32_16x16x32_bf16 v[110:113], v[190:193], v[150:153], v[110:113]
	v_mfma_f32_16x16x32_bf16 v[106:109], v[190:193], v[160:163], v[106:109]
	v_mfma_f32_16x16x32_bf16 v[102:105], v[198:201], v[150:153], v[102:105]
	v_mfma_f32_16x16x32_bf16 v[98:101], v[198:201], v[160:163], v[98:101]
	s_setprio 0
	s_barrier
	v_add_u32_e32 v218, s40, v141
	v_lshl_add_u64 v[168:169], v[220:221], 0, s[16:17]
	v_readfirstlane_b32 s30, v218
	v_add_u32_e32 v218, 0x2000, v218
	s_mov_b32 m0, s30
	v_readfirstlane_b32 s30, v218
	ds_read_b128 v[202:205], v137
	ds_read_b128 v[206:209], v137 offset:1024
	ds_read_b128 v[210:213], v137 offset:2048
	ds_read_b128 v[214:217], v137 offset:3072
	global_load_lds_dwordx4 v[168:169], off
	v_lshl_add_u64 v[168:169], v[222:223], 0, s[16:17]
	s_mov_b32 m0, s30
	s_nop 0
	global_load_lds_dwordx4 v[168:169], off
	s_waitcnt vmcnt(10)
	s_barrier
	s_waitcnt lgkmcnt(0)
	s_setprio 1
	s_waitcnt lgkmcnt(0)
	v_mfma_f32_16x16x32_bf16 v[94:97], v[164:167], v[202:205], v[94:97]
	v_mfma_f32_16x16x32_bf16 v[90:93], v[164:167], v[210:213], v[90:93]
	v_mfma_f32_16x16x32_bf16 v[86:89], v[178:181], v[202:205], v[86:89]
	v_mfma_f32_16x16x32_bf16 v[82:85], v[178:181], v[210:213], v[82:85]
	v_mfma_f32_16x16x32_bf16 v[78:81], v[186:189], v[202:205], v[78:81]
	v_mfma_f32_16x16x32_bf16 v[74:77], v[186:189], v[210:213], v[74:77]
	v_mfma_f32_16x16x32_bf16 v[70:73], v[194:197], v[202:205], v[70:73]
	v_mfma_f32_16x16x32_bf16 v[66:69], v[194:197], v[210:213], v[66:69]
	v_mfma_f32_16x16x32_bf16 v[94:97], v[174:177], v[206:209], v[94:97]
	v_mfma_f32_16x16x32_bf16 v[90:93], v[174:177], v[214:217], v[90:93]
	v_mfma_f32_16x16x32_bf16 v[86:89], v[182:185], v[206:209], v[86:89]
	v_mfma_f32_16x16x32_bf16 v[82:85], v[182:185], v[214:217], v[82:85]
	v_mfma_f32_16x16x32_bf16 v[78:81], v[190:193], v[206:209], v[78:81]
	v_mfma_f32_16x16x32_bf16 v[74:77], v[190:193], v[214:217], v[74:77]
	v_mfma_f32_16x16x32_bf16 v[70:73], v[198:201], v[206:209], v[70:73]
	v_mfma_f32_16x16x32_bf16 v[66:69], v[198:201], v[214:217], v[66:69]
	s_setprio 0
	v_add_u32_e32 v218, 0x8000, v155
	v_add_u32_e32 v155, 0xa000, v155
	v_readfirstlane_b32 s30, v218
	v_lshl_add_u64 v[168:169], v[224:225], 0, s[16:17]
	s_mov_b32 m0, s30
	v_readfirstlane_b32 s30, v155
	s_barrier
; #define STAGE(P, GP, ktrel) do { const GAS char* _g = (GP) + (ktrel) * (BK * 2); \
;     __builtin_amdgcn_global_load_lds((const GAS unsigned*)(_g + so0), (unsigned*)((char*)(P) + tid_ * 16), 16, 0, 0); \
;     __builtin_amdgcn_global_load_lds((const GAS unsigned*)(_g + so1), (unsigned*)((char*)(P) + tid_ * 16 + 8192), 16, 0, 0); } while (0)
; #define WAIT_V(n) asm volatile("s_waitcnt vmcnt(" #n ")" ::: "memory")
; #define WAIT_L(n) asm volatile("s_waitcnt lgkmcnt(" #n ")" ::: "memory")
; #define BAR __builtin_amdgcn_s_barrier()
; #define LDA(dst, b, h) for (int m = 0; m < 4; ++m) for (int k = 0; k < 2; ++k) \
;     dst[m][k] = *reinterpret_cast<const bf16x8*>((char*)SA(b, h) + lds_byte(wr * 64 + m * 16 + fr, k * 32 + fq * 8))
; #define LDB(dst, b, h) for (int n = 0; n < 2; ++n) for (int k = 0; k < 2; ++k) \
;     dst[n][k] = *reinterpret_cast<const bf16x8*>((char*)SB(b, h) + lds_byte(wc * 32 + n * 16 + fr, k * 32 + fq * 8))
; #define MMA(ai, bj, At_, Bt_) do { __builtin_amdgcn_s_setprio(1); \
;     for (int m = 0; m < 4; ++m) for (int n = 0; n < 2; ++n) for (int k = 0; k < 2; ++k) \
;       acc[ai][bj][m][n] = __builtin_amdgcn_mfma_f32_16x16x32_bf16(At_[m][k], Bt_[n][k], acc[ai][bj][m][n], 0, 0, 0); \
;     __builtin_amdgcn_s_setprio(0); } while (0)
; template <int K, int LD = K>
; __device__ __forceinline__ void gemm_main(const GAS bf16* A, const GAS bf16* Bt, int brow, int bcol, f32x4 (&acc)[2][2][4][2]) {
;     ...
;     STAGE(SB(1, 1), pB1, 3);
;     WAIT_V(6); BAR; MMA(1, 1, At, B1); BAR;
;     pA0 += 4 * BK; pA1 += 4 * BK; pB0 += 4 * BK; pB1 += 4 * BK;
;     asm volatile("" : "+s"(pA0), "+s"(pA1), "+s"(pB0), "+s"(pB1));
;   }
;   { LDB(B0, 0, 0); LDA(At, 0, 0); STAGE(SA(1, 1), pA1, 1);
;     BAR; WAIT_L(0); MMA(0, 0, At, B0); BAR;
;     LDB(B1, 0, 1); BAR; WAIT_L(0); MMA(0, 1, At, B1); BAR;
;     LDA(At, 0, 1); WAIT_V(4); BAR; WAIT_L(0); MMA(1, 0, At, B0); MMA(1, 1, At, B1); BAR; }
	ds_read_b128 v[164:167], v136 offset:49152
	ds_read_b128 v[174:177], v136 offset:50176
	ds_read_b128 v[178:181], v135 offset:49152
	ds_read_b128 v[182:185], v135 offset:50176
	ds_read_b128 v[186:189], v134 offset:49152
	ds_read_b128 v[190:193], v134 offset:50176
	ds_read_b128 v[194:197], v133 offset:49152
	ds_read_b128 v[198:201], v133 offset:50176
	global_load_lds_dwordx4 v[168:169], off
	v_lshl_add_u64 v[168:169], v[226:227], 0, s[16:17]
	s_mov_b32 m0, s30
	s_nop 0
	global_load_lds_dwordx4 v[168:169], off
	s_barrier
	s_waitcnt lgkmcnt(0)
	s_setprio 1
	s_waitcnt lgkmcnt(0)
	v_mfma_f32_16x16x32_bf16 v[62:65], v[164:167], v[146:149], v[62:65]
	v_mfma_f32_16x16x32_bf16 v[58:61], v[164:167], v[156:159], v[58:61]
	v_mfma_f32_16x16x32_bf16 v[54:57], v[178:181], v[146:149], v[54:57]
	v_mfma_f32_16x16x32_bf16 v[50:53], v[178:181], v[156:159], v[50:53]
	v_mfma_f32_16x16x32_bf16 v[46:49], v[186:189], v[146:149], v[46:49]
	v_mfma_f32_16x16x32_bf16 v[42:45], v[186:189], v[156:159], v[42:45]
	v_mfma_f32_16x16x32_bf16 v[38:41], v[194:197], v[146:149], v[38:41]
	v_mfma_f32_16x16x32_bf16 v[34:37], v[194:197], v[156:159], v[34:37]
	v_mfma_f32_16x16x32_bf16 v[62:65], v[174:177], v[150:153], v[62:65]
	v_mfma_f32_16x16x32_bf16 v[58:61], v[174:177], v[160:163], v[58:61]
	v_mfma_f32_16x16x32_bf16 v[54:57], v[182:185], v[150:153], v[54:57]
	v_mfma_f32_16x16x32_bf16 v[50:53], v[182:185], v[160:163], v[50:53]
	v_mfma_f32_16x16x32_bf16 v[46:49], v[190:193], v[150:153], v[46:49]
	v_mfma_f32_16x16x32_bf16 v[42:45], v[190:193], v[160:163], v[42:45]
	v_mfma_f32_16x16x32_bf16 v[38:41], v[198:201], v[150:153], v[38:41]
	v_mfma_f32_16x16x32_bf16 v[34:37], v[198:201], v[160:163], v[34:37]
	s_setprio 0
	s_barrier
	v_add_u32_e32 v148, s41, v141
	v_lshl_add_u64 v[146:147], v[228:229], 0, s[16:17]
	v_readfirstlane_b32 s30, v148
	v_add_u32_e32 v148, 0x2000, v148
	s_mov_b32 m0, s30
	v_readfirstlane_b32 s30, v148
	global_load_lds_dwordx4 v[146:147], off
	v_lshl_add_u64 v[146:147], v[230:231], 0, s[16:17]
	s_mov_b32 m0, s30
	s_nop 0
	global_load_lds_dwordx4 v[146:147], off
	s_waitcnt vmcnt(8)
	s_barrier
	s_setprio 1
	v_mfma_f32_16x16x32_bf16 v[30:33], v[164:167], v[202:205], v[30:33]
	v_mfma_f32_16x16x32_bf16 v[26:29], v[164:167], v[210:213], v[26:29]
	v_mfma_f32_16x16x32_bf16 v[22:25], v[178:181], v[202:205], v[22:25]
	v_mfma_f32_16x16x32_bf16 v[18:21], v[178:181], v[210:213], v[18:21]
	v_mfma_f32_16x16x32_bf16 v[14:17], v[186:189], v[202:205], v[14:17]
	v_mfma_f32_16x16x32_bf16 v[10:13], v[186:189], v[210:213], v[10:13]
	v_mfma_f32_16x16x32_bf16 v[6:9], v[194:197], v[202:205], v[6:9]
	v_mfma_f32_16x16x32_bf16 v[2:5], v[194:197], v[210:213], v[2:5]
	v_mfma_f32_16x16x32_bf16 v[30:33], v[174:177], v[206:209], v[30:33]
	v_mfma_f32_16x16x32_bf16 v[26:29], v[174:177], v[214:217], v[26:29]
	v_mfma_f32_16x16x32_bf16 v[22:25], v[182:185], v[206:209], v[22:25]
	v_mfma_f32_16x16x32_bf16 v[18:21], v[182:185], v[214:217], v[18:21]
	v_mfma_f32_16x16x32_bf16 v[14:17], v[190:193], v[206:209], v[14:17]
	v_mfma_f32_16x16x32_bf16 v[10:13], v[190:193], v[214:217], v[10:13]
	v_mfma_f32_16x16x32_bf16 v[6:9], v[198:201], v[206:209], v[6:9]
	v_mfma_f32_16x16x32_bf16 v[2:5], v[198:201], v[214:217], v[2:5]
	s_setprio 0
	s_add_i32 s21, s21, 2
	s_cmp_lt_u32 s21, 12
	s_barrier
	s_cbranch_scc1 .LBB0_1226
	v_lshl_add_u64 v[168:169], s[18:19], 0, v[138:139]
	v_readfirstlane_b32 s21, v144
	v_lshl_add_u64 v[168:169], v[168:169], 0, s[8:9]
	s_mov_b32 m0, s21
	v_lshl_add_u64 v[130:131], s[18:19], 0, v[130:131]
	v_readfirstlane_b32 s18, v145
	ds_read_b128 v[146:149], v143
	ds_read_b128 v[150:153], v143 offset:1024
	ds_read_b128 v[156:159], v143 offset:2048
	ds_read_b128 v[160:163], v143 offset:3072
	ds_read_b128 v[164:167], v136
	ds_read_b128 v[174:177], v136 offset:1024
	ds_read_b128 v[178:181], v135
	ds_read_b128 v[182:185], v135 offset:1024
	ds_read_b128 v[186:189], v134
	ds_read_b128 v[190:193], v134 offset:1024
	ds_read_b128 v[194:197], v133
	ds_read_b128 v[198:201], v133 offset:1024
	global_load_lds_dwordx4 v[168:169], off
	v_lshl_add_u64 v[130:131], v[130:131], 0, s[8:9]
	s_mov_b32 m0, s18
	s_nop 0
	global_load_lds_dwordx4 v[130:131], off
	s_barrier
	s_waitcnt lgkmcnt(0)
	s_setprio 1
	s_waitcnt lgkmcnt(0)
	v_mfma_f32_16x16x32_bf16 v[126:129], v[164:167], v[146:149], v[126:129]
	v_mfma_f32_16x16x32_bf16 v[122:125], v[164:167], v[156:159], v[122:125]
	v_mfma_f32_16x16x32_bf16 v[110:113], v[186:189], v[146:149], v[110:113]
	v_mfma_f32_16x16x32_bf16 v[106:109], v[186:189], v[156:159], v[106:109]
	v_mfma_f32_16x16x32_bf16 v[126:129], v[174:177], v[150:153], v[126:129]
	v_mfma_f32_16x16x32_bf16 v[122:125], v[174:177], v[160:163], v[122:125]
	v_mfma_f32_16x16x32_bf16 v[118:121], v[178:181], v[146:149], v[118:121]
	v_mfma_f32_16x16x32_bf16 v[114:117], v[178:181], v[156:159], v[114:117]
	v_mfma_f32_16x16x32_bf16 v[110:113], v[190:193], v[150:153], v[110:113]
	v_mfma_f32_16x16x32_bf16 v[106:109], v[190:193], v[160:163], v[106:109]
	v_mfma_f32_16x16x32_bf16 v[102:105], v[194:197], v[146:149], v[102:105]
	v_mfma_f32_16x16x32_bf16 v[98:101], v[194:197], v[156:159], v[98:101]
	v_mfma_f32_16x16x32_bf16 v[202:205], v[182:185], v[150:153], v[118:121]
	v_mfma_f32_16x16x32_bf16 v[206:209], v[182:185], v[160:163], v[114:117]
	v_mfma_f32_16x16x32_bf16 v[210:213], v[198:201], v[150:153], v[102:105]
	v_mfma_f32_16x16x32_bf16 v[214:217], v[198:201], v[160:163], v[98:101]
	s_setprio 0
	s_barrier
	s_nop 1
	ds_read_b128 v[98:101], v142
	ds_read_b128 v[102:105], v142 offset:1024
	ds_read_b128 v[114:117], v142 offset:2048
	ds_read_b128 v[118:121], v142 offset:3072
	s_waitcnt vmcnt(8)
	s_barrier
; #define WAIT_V(n) asm volatile("s_waitcnt vmcnt(" #n ")" ::: "memory")
; #define WAIT_L(n) asm volatile("s_waitcnt lgkmcnt(" #n ")" ::: "memory")
; #define BAR __builtin_amdgcn_s_barrier()
; #define LDA(dst, b, h) for (int m = 0; m < 4; ++m) for (int k = 0; k < 2; ++k) \
;     dst[m][k] = *reinterpret_cast<const bf16x8*>((char*)SA(b, h) + lds_byte(wr * 64 + m * 16 + fr, k * 32 + fq * 8))
; #define LDB(dst, b, h) for (int n = 0; n < 2; ++n) for (int k = 0; k < 2; ++k) \
;     dst[n][k] = *reinterpret_cast<const bf16x8*>((char*)SB(b, h) + lds_byte(wc * 32 + n * 16 + fr, k * 32 + fq * 8))
; #define MMA(ai, bj, At_, Bt_) do { __builtin_amdgcn_s_setprio(1); \
;     for (int m = 0; m < 4; ++m) for (int n = 0; n < 2; ++n) for (int k = 0; k < 2; ++k) \
;       acc[ai][bj][m][n] = __builtin_amdgcn_mfma_f32_16x16x32_bf16(At_[m][k], Bt_[n][k], acc[ai][bj][m][n], 0, 0, 0); \
;     __builtin_amdgcn_s_setprio(0); } while (0)
; template <int K, int LD = K>
; __device__ __forceinline__ void gemm_main(const GAS bf16* A, const GAS bf16* Bt, int brow, int bcol, f32x4 (&acc)[2][2][4][2]) {
;     ...
;     LDB(B1, 0, 1); BAR; WAIT_L(0); MMA(0, 1, At, B1); BAR;
;     LDA(At, 0, 1); WAIT_V(4); BAR; WAIT_L(0); MMA(1, 0, At, B0); MMA(1, 1, At, B1); BAR; }
;   { LDB(B0, 1, 0); LDA(At, 1, 0); WAIT_V(2); BAR; WAIT_L(0); MMA(0, 0, At, B0); BAR;
	s_waitcnt lgkmcnt(0)
	s_setprio 1
	s_waitcnt lgkmcnt(0)
	v_mfma_f32_16x16x32_bf16 v[94:97], v[164:167], v[98:101], v[94:97]
	v_mfma_f32_16x16x32_bf16 v[90:93], v[164:167], v[114:117], v[90:93]
	v_mfma_f32_16x16x32_bf16 v[78:81], v[186:189], v[98:101], v[78:81]
	v_mfma_f32_16x16x32_bf16 v[74:77], v[186:189], v[114:117], v[74:77]
	v_mfma_f32_16x16x32_bf16 v[94:97], v[174:177], v[102:105], v[94:97]
	v_mfma_f32_16x16x32_bf16 v[90:93], v[174:177], v[118:121], v[90:93]
	v_mfma_f32_16x16x32_bf16 v[86:89], v[178:181], v[98:101], v[86:89]
	v_mfma_f32_16x16x32_bf16 v[82:85], v[178:181], v[114:117], v[82:85]
	v_mfma_f32_16x16x32_bf16 v[78:81], v[190:193], v[102:105], v[78:81]
	v_mfma_f32_16x16x32_bf16 v[74:77], v[190:193], v[118:121], v[74:77]
	v_mfma_f32_16x16x32_bf16 v[70:73], v[194:197], v[98:101], v[70:73]
	v_mfma_f32_16x16x32_bf16 v[66:69], v[194:197], v[114:117], v[66:69]
	v_mfma_f32_16x16x32_bf16 v[142:145], v[182:185], v[102:105], v[86:89]
	v_mfma_f32_16x16x32_bf16 v[164:167], v[182:185], v[118:121], v[82:85]
	v_mfma_f32_16x16x32_bf16 v[174:177], v[198:201], v[102:105], v[70:73]
	v_mfma_f32_16x16x32_bf16 v[178:181], v[198:201], v[118:121], v[66:69]
	s_setprio 0
	s_barrier
	s_nop 1
	ds_read_b128 v[66:69], v136 offset:16384
	ds_read_b128 v[70:73], v136 offset:17408
	ds_read_b128 v[82:85], v135 offset:16384
	ds_read_b128 v[86:89], v135 offset:17408
	ds_read_b128 v[182:185], v134 offset:16384
	ds_read_b128 v[186:189], v134 offset:17408
	ds_read_b128 v[190:193], v133 offset:16384
	ds_read_b128 v[194:197], v133 offset:17408
	s_waitcnt vmcnt(4)
	s_barrier
	s_waitcnt lgkmcnt(0)
	s_setprio 1
	s_waitcnt lgkmcnt(0)
	v_mfma_f32_16x16x32_bf16 v[62:65], v[66:69], v[146:149], v[62:65]
	v_mfma_f32_16x16x32_bf16 v[58:61], v[66:69], v[156:159], v[58:61]
	v_mfma_f32_16x16x32_bf16 v[46:49], v[182:185], v[146:149], v[46:49]
	v_mfma_f32_16x16x32_bf16 v[42:45], v[182:185], v[156:159], v[42:45]
	v_mfma_f32_16x16x32_bf16 v[62:65], v[70:73], v[150:153], v[62:65]
	v_mfma_f32_16x16x32_bf16 v[58:61], v[70:73], v[160:163], v[58:61]
	v_mfma_f32_16x16x32_bf16 v[54:57], v[82:85], v[146:149], v[54:57]
	v_mfma_f32_16x16x32_bf16 v[50:53], v[82:85], v[156:159], v[50:53]
	v_mfma_f32_16x16x32_bf16 v[46:49], v[186:189], v[150:153], v[46:49]
	v_mfma_f32_16x16x32_bf16 v[42:45], v[186:189], v[160:163], v[42:45]
	v_mfma_f32_16x16x32_bf16 v[38:41], v[190:193], v[146:149], v[38:41]
	v_mfma_f32_16x16x32_bf16 v[34:37], v[190:193], v[156:159], v[34:37]
	v_mfma_f32_16x16x32_bf16 v[198:201], v[86:89], v[150:153], v[54:57]
	v_mfma_f32_16x16x32_bf16 v[218:221], v[86:89], v[160:163], v[50:53]
	v_mfma_f32_16x16x32_bf16 v[146:149], v[194:197], v[150:153], v[38:41]
	v_mfma_f32_16x16x32_bf16 v[150:153], v[194:197], v[160:163], v[34:37]
	s_setprio 0
	s_setprio 1
	v_mfma_f32_16x16x32_bf16 v[30:33], v[66:69], v[98:101], v[30:33]
	v_mfma_f32_16x16x32_bf16 v[26:29], v[66:69], v[114:117], v[26:29]
	v_mfma_f32_16x16x32_bf16 v[10:13], v[182:185], v[114:117], v[10:13]
	v_mfma_f32_16x16x32_bf16 v[2:5], v[190:193], v[114:117], v[2:5]
	v_mfma_f32_16x16x32_bf16 v[30:33], v[70:73], v[102:105], v[30:33]
	v_mfma_f32_16x16x32_bf16 v[26:29], v[70:73], v[118:121], v[26:29]
	v_mfma_f32_16x16x32_bf16 v[22:25], v[82:85], v[98:101], v[22:25]
	v_mfma_f32_16x16x32_bf16 v[18:21], v[82:85], v[114:117], v[18:21]
	v_mfma_f32_16x16x32_bf16 v[14:17], v[182:185], v[98:101], v[14:17]
	v_mfma_f32_16x16x32_bf16 v[10:13], v[186:189], v[118:121], v[10:13]
	v_mfma_f32_16x16x32_bf16 v[6:9], v[190:193], v[98:101], v[6:9]
	v_mfma_f32_16x16x32_bf16 v[2:5], v[194:197], v[118:121], v[2:5]
	v_mfma_f32_16x16x32_bf16 v[156:159], v[86:89], v[102:105], v[22:25]
	v_mfma_f32_16x16x32_bf16 v[160:163], v[86:89], v[118:121], v[18:21]
	v_mfma_f32_16x16x32_bf16 v[222:225], v[186:189], v[102:105], v[14:17]
	v_mfma_f32_16x16x32_bf16 v[182:185], v[194:197], v[102:105], v[6:9]
	s_setprio 0
	s_barrier
	s_nop 0
	ds_read_b128 v[6:9], v140
	ds_read_b128 v[14:17], v140 offset:1024
	ds_read_b128 v[186:189], v140 offset:2048
	ds_read_b128 v[190:193], v140 offset:3072
	ds_read_b128 v[18:21], v136 offset:32768
	ds_read_b128 v[22:25], v136 offset:33792
	ds_read_b128 v[34:37], v135 offset:32768
	ds_read_b128 v[38:41], v135 offset:33792
	ds_read_b128 v[50:53], v134 offset:32768
	ds_read_b128 v[54:57], v134 offset:33792
	ds_read_b128 v[194:197], v133 offset:32768
	ds_read_b128 v[226:229], v133 offset:33792
	s_waitcnt vmcnt(2)
	s_barrier
; #define WAIT_V(n) asm volatile("s_waitcnt vmcnt(" #n ")" ::: "memory")
; #define WAIT_L(n) asm volatile("s_waitcnt lgkmcnt(" #n ")" ::: "memory")
; #define BAR __builtin_amdgcn_s_barrier()
; #define LDA(dst, b, h) for (int m = 0; m < 4; ++m) for (int k = 0; k < 2; ++k) \
;     dst[m][k] = *reinterpret_cast<const bf16x8*>((char*)SA(b, h) + lds_byte(wr * 64 + m * 16 + fr, k * 32 + fq * 8))
; #define LDB(dst, b, h) for (int n = 0; n < 2; ++n) for (int k = 0; k < 2; ++k) \
;     dst[n][k] = *reinterpret_cast<const bf16x8*>((char*)SB(b, h) + lds_byte(wc * 32 + n * 16 + fr, k * 32 + fq * 8))
; #define MMA(ai, bj, At_, Bt_) do { __builtin_amdgcn_s_setprio(1); \
;     for (int m = 0; m < 4; ++m) for (int n = 0; n < 2; ++n) for (int k = 0; k < 2; ++k) \
;       acc[ai][bj][m][n] = __builtin_amdgcn_mfma_f32_16x16x32_bf16(At_[m][k], Bt_[n][k], acc[ai][bj][m][n], 0, 0, 0); \
;     __builtin_amdgcn_s_setprio(0); } while (0)
; template <int K, int LD = K>
; __device__ __forceinline__ void gemm_main(const GAS bf16* A, const GAS bf16* Bt, int brow, int bcol, f32x4 (&acc)[2][2][4][2]) {
;     ...
;   { LDB(B0, 1, 0); LDA(At, 1, 0); WAIT_V(2); BAR; WAIT_L(0); MMA(0, 0, At, B0); BAR;
;     LDB(B1, 1, 1); WAIT_V(0); BAR; WAIT_L(0); MMA(0, 1, At, B1); BAR;
;     LDA(At, 1, 1); BAR; WAIT_L(0); MMA(1, 0, At, B0); MMA(1, 1, At, B1); BAR; }
;   if (wr == 0) BAR;
	s_waitcnt lgkmcnt(0)
	s_setprio 1
	s_waitcnt lgkmcnt(0)
	v_mfma_f32_16x16x32_bf16 v[66:69], v[18:21], v[6:9], v[126:129]
	v_mfma_f32_16x16x32_bf16 v[118:121], v[22:25], v[14:17], v[66:69]
	v_mfma_f32_16x16x32_bf16 v[66:69], v[18:21], v[186:189], v[122:125]
	v_mfma_f32_16x16x32_bf16 v[114:117], v[22:25], v[190:193], v[66:69]
	v_mfma_f32_16x16x32_bf16 v[66:69], v[34:37], v[6:9], v[202:205]
	v_mfma_f32_16x16x32_bf16 v[102:105], v[38:41], v[14:17], v[66:69]
	v_mfma_f32_16x16x32_bf16 v[66:69], v[34:37], v[186:189], v[206:209]
	v_mfma_f32_16x16x32_bf16 v[98:101], v[38:41], v[190:193], v[66:69]
	v_mfma_f32_16x16x32_bf16 v[66:69], v[50:53], v[6:9], v[110:113]
	v_mfma_f32_16x16x32_bf16 v[86:89], v[54:57], v[14:17], v[66:69]
	v_mfma_f32_16x16x32_bf16 v[66:69], v[50:53], v[186:189], v[106:109]
	v_mfma_f32_16x16x32_bf16 v[82:85], v[54:57], v[190:193], v[66:69]
	v_mfma_f32_16x16x32_bf16 v[66:69], v[194:197], v[6:9], v[210:213]
	v_mfma_f32_16x16x32_bf16 v[70:73], v[226:229], v[14:17], v[66:69]
	v_mfma_f32_16x16x32_bf16 v[66:69], v[194:197], v[186:189], v[214:217]
	v_mfma_f32_16x16x32_bf16 v[66:69], v[226:229], v[190:193], v[66:69]
	s_setprio 0
	s_barrier
	ds_read_b128 v[202:205], v137
	ds_read_b128 v[206:209], v137 offset:1024
	ds_read_b128 v[210:213], v137 offset:2048
	ds_read_b128 v[214:217], v137 offset:3072
	s_waitcnt vmcnt(0)
	s_barrier
	s_waitcnt lgkmcnt(0)
	s_setprio 1
	s_waitcnt lgkmcnt(0)
	v_mfma_f32_16x16x32_bf16 v[94:97], v[18:21], v[202:205], v[94:97]
	v_mfma_f32_16x16x32_bf16 v[18:21], v[18:21], v[210:213], v[90:93]
	v_mfma_f32_16x16x32_bf16 v[122:125], v[22:25], v[214:217], v[18:21]
	v_mfma_f32_16x16x32_bf16 v[18:21], v[34:37], v[202:205], v[142:145]
	v_mfma_f32_16x16x32_bf16 v[110:113], v[38:41], v[206:209], v[18:21]
	v_mfma_f32_16x16x32_bf16 v[18:21], v[34:37], v[210:213], v[164:167]
	v_mfma_f32_16x16x32_bf16 v[106:109], v[38:41], v[214:217], v[18:21]
	v_mfma_f32_16x16x32_bf16 v[18:21], v[50:53], v[202:205], v[78:81]
	v_mfma_f32_16x16x32_bf16 v[126:129], v[22:25], v[206:209], v[94:97]
	v_mfma_f32_16x16x32_bf16 v[94:97], v[54:57], v[206:209], v[18:21]
	v_mfma_f32_16x16x32_bf16 v[18:21], v[50:53], v[210:213], v[74:77]
	v_mfma_f32_16x16x32_bf16 v[90:93], v[54:57], v[214:217], v[18:21]
	v_mfma_f32_16x16x32_bf16 v[18:21], v[194:197], v[202:205], v[174:177]
	v_mfma_f32_16x16x32_bf16 v[78:81], v[226:229], v[206:209], v[18:21]
	v_mfma_f32_16x16x32_bf16 v[18:21], v[194:197], v[210:213], v[178:181]
	v_mfma_f32_16x16x32_bf16 v[74:77], v[226:229], v[214:217], v[18:21]
	s_setprio 0
	s_barrier
	ds_read_b128 v[140:143], v136 offset:49152
	ds_read_b128 v[164:167], v136 offset:50176
	ds_read_b128 v[174:177], v135 offset:49152
	ds_read_b128 v[178:181], v135 offset:50176
	ds_read_b128 v[194:197], v134 offset:49152
	ds_read_b128 v[134:137], v134 offset:50176
	ds_read_b128 v[226:229], v133 offset:49152
	ds_read_b128 v[230:233], v133 offset:50176
	s_barrier
	s_waitcnt lgkmcnt(0)
	s_setprio 1
	s_waitcnt lgkmcnt(0)
	v_mfma_f32_16x16x32_bf16 v[18:21], v[140:143], v[6:9], v[62:65]
	v_mfma_f32_16x16x32_bf16 v[54:57], v[164:167], v[14:17], v[18:21]
	v_mfma_f32_16x16x32_bf16 v[18:21], v[140:143], v[186:189], v[58:61]
	v_mfma_f32_16x16x32_bf16 v[50:53], v[164:167], v[190:193], v[18:21]
	v_mfma_f32_16x16x32_bf16 v[18:21], v[174:177], v[6:9], v[198:201]
	v_mfma_f32_16x16x32_bf16 v[38:41], v[178:181], v[14:17], v[18:21]
	v_mfma_f32_16x16x32_bf16 v[18:21], v[174:177], v[186:189], v[218:221]
	v_mfma_f32_16x16x32_bf16 v[34:37], v[178:181], v[190:193], v[18:21]
	v_mfma_f32_16x16x32_bf16 v[18:21], v[194:197], v[6:9], v[46:49]
	v_mfma_f32_16x16x32_bf16 v[6:9], v[226:229], v[6:9], v[146:149]
	v_mfma_f32_16x16x32_bf16 v[22:25], v[134:137], v[14:17], v[18:21]
	v_mfma_f32_16x16x32_bf16 v[18:21], v[194:197], v[186:189], v[42:45]
	v_mfma_f32_16x16x32_bf16 v[14:17], v[230:233], v[14:17], v[6:9]
	v_mfma_f32_16x16x32_bf16 v[6:9], v[226:229], v[186:189], v[150:153]
	v_mfma_f32_16x16x32_bf16 v[18:21], v[134:137], v[190:193], v[18:21]
	v_mfma_f32_16x16x32_bf16 v[6:9], v[230:233], v[190:193], v[6:9]
	s_setprio 0
	s_setprio 1
	v_mfma_f32_16x16x32_bf16 v[26:29], v[140:143], v[210:213], v[26:29]
	v_mfma_f32_16x16x32_bf16 v[58:61], v[164:167], v[214:217], v[26:29]
	v_mfma_f32_16x16x32_bf16 v[26:29], v[174:177], v[202:205], v[156:159]
	v_mfma_f32_16x16x32_bf16 v[46:49], v[178:181], v[206:209], v[26:29]
	v_mfma_f32_16x16x32_bf16 v[26:29], v[174:177], v[210:213], v[160:163]
	v_mfma_f32_16x16x32_bf16 v[30:33], v[140:143], v[202:205], v[30:33]
	v_mfma_f32_16x16x32_bf16 v[42:45], v[178:181], v[214:217], v[26:29]
	v_mfma_f32_16x16x32_bf16 v[26:29], v[194:197], v[202:205], v[222:225]
	v_mfma_f32_16x16x32_bf16 v[10:13], v[194:197], v[210:213], v[10:13]
	v_mfma_f32_16x16x32_bf16 v[62:65], v[164:167], v[206:209], v[30:33]
	v_mfma_f32_16x16x32_bf16 v[30:33], v[134:137], v[206:209], v[26:29]
	v_mfma_f32_16x16x32_bf16 v[26:29], v[134:137], v[214:217], v[10:13]
	v_mfma_f32_16x16x32_bf16 v[10:13], v[226:229], v[202:205], v[182:185]
	v_mfma_f32_16x16x32_bf16 v[2:5], v[226:229], v[210:213], v[2:5]
	v_mfma_f32_16x16x32_bf16 v[10:13], v[230:233], v[206:209], v[10:13]
	v_mfma_f32_16x16x32_bf16 v[2:5], v[230:233], v[214:217], v[2:5]
	s_setprio 0
	v_cmp_gt_u32_e32 vcc, s42, v132
	s_barrier
	s_and_saveexec_b64 s[18:19], vcc
	s_cbranch_execz .LBB0_1229
	s_barrier
